# attention O-rescale: 796 packed v_pk_mul_f32 (scalar broadcast) split into two v_mul_f32 each (bit-identical)
# baseline (speedup 1.0000x reference)
.LBB0_839:
	s_or_b64 exec, exec, s[4:5]
	s_and_b32 s4, s6, 1
	s_mul_i32 s5, s4, 0x3400
	v_add_u32_e32 v131, s5, v177
	ds_read_b128 v[32:35], v131
	ds_read_b128 v[36:39], v131 offset:32
	s_mul_i32 s5, s4, 0x2400
	s_xor_b32 s8, s4, 1
	s_mul_i32 s4, s8, 0x3400
	s_waitcnt lgkmcnt(1)
	v_mfma_f32_32x32x16_bf16 v[48:63], v[32:35], v[84:87], 0
	s_add_i32 s9, s4, 0
	s_waitcnt lgkmcnt(0)
	v_mfma_f32_32x32x16_bf16 v[48:63], v[36:39], v[80:83], v[48:63]
	ds_read_b128 v[32:35], v131 offset:64
	ds_read_b128 v[36:39], v131 offset:96
	s_waitcnt lgkmcnt(1)
	v_mfma_f32_32x32x16_bf16 v[48:63], v[32:35], v[76:79], v[48:63]
	s_waitcnt lgkmcnt(0)
	v_mfma_f32_32x32x16_bf16 v[48:63], v[36:39], v[72:75], v[48:63]
	ds_read_b128 v[32:35], v131 offset:128
	ds_read_b128 v[36:39], v131 offset:160
	s_waitcnt lgkmcnt(1)
	v_mfma_f32_32x32x16_bf16 v[48:63], v[32:35], v[68:71], v[48:63]
	ds_read_b128 v[32:35], v131 offset:6656
	ds_read_b128 v[180:183], v131 offset:6688
	s_waitcnt lgkmcnt(2)
	v_mfma_f32_32x32x16_bf16 v[48:63], v[36:39], v[64:67], v[48:63]
	s_waitcnt lgkmcnt(1)
	v_mfma_f32_32x32x16_bf16 v[32:47], v[32:35], v[84:87], 0
	s_nop 9
	v_max_f32_e32 v153, v48, v48
	s_waitcnt lgkmcnt(0)
	v_mfma_f32_32x32x16_bf16 v[32:47], v[180:183], v[80:83], v[32:47]
	ds_read_b128 v[180:183], v131 offset:6720
	ds_read_b128 v[184:187], v131 offset:6752
	s_waitcnt lgkmcnt(1)
	v_mfma_f32_32x32x16_bf16 v[32:47], v[180:183], v[76:79], v[32:47]
	s_waitcnt lgkmcnt(0)
	v_mfma_f32_32x32x16_bf16 v[32:47], v[184:187], v[72:75], v[32:47]
	ds_read_b128 v[180:183], v131 offset:6784
	ds_read_b128 v[184:187], v131 offset:6816
	v_max_f32_e32 v131, v49, v49
	v_max_f32_e32 v131, v153, v131
	v_max3_f32 v131, v131, v50, v51
	v_max3_f32 v131, v131, v52, v53
	v_max3_f32 v131, v131, v54, v55
	v_max3_f32 v131, v131, v56, v57
	s_waitcnt lgkmcnt(1)
	v_mfma_f32_32x32x16_bf16 v[32:47], v[180:183], v[68:71], v[32:47]
	v_max3_f32 v131, v131, v58, v59
	v_max3_f32 v131, v131, v60, v61
	v_max3_f32 v131, v131, v62, v63
	s_waitcnt lgkmcnt(0)
	v_mfma_f32_32x32x16_bf16 v[32:47], v[184:187], v[64:67], v[32:47]
	s_nop 11
	v_max3_f32 v131, v131, v32, v33
	v_max3_f32 v131, v131, v34, v35
	v_max3_f32 v131, v131, v36, v37
	v_max3_f32 v131, v131, v38, v39
	v_max3_f32 v131, v131, v40, v41
	v_max3_f32 v131, v131, v42, v43
	v_max3_f32 v131, v131, v44, v45
	v_max3_f32 v131, v131, v46, v47
	ds_bpermute_b32 v153, v107, v131
	s_waitcnt lgkmcnt(0)
	v_max3_f32 v153, v130, v131, v153
	v_sub_f32_e32 v32, v32, v153
	v_exp_f32_e32 v180, v32
	v_sub_f32_e32 v32, v33, v153
	v_exp_f32_e32 v181, v32
	v_sub_f32_e32 v32, v34, v153
	v_exp_f32_e32 v182, v32
	v_sub_f32_e32 v32, v35, v153
	v_sub_f32_e32 v130, v130, v153
	v_exp_f32_e32 v183, v32
	v_sub_f32_e32 v32, v36, v153
	v_exp_f32_e32 v184, v32
	v_exp_f32_e32 v36, v130
	v_sub_f32_e32 v32, v37, v153
	v_add_u32_e32 v130, s5, v178
	v_exp_f32_e32 v37, v32
	ds_read_b128 v[32:35], v130 offset:26624
	v_sub_f32_e32 v48, v48, v153
	v_sub_f32_e32 v49, v49, v153
	v_sub_f32_e32 v50, v50, v153
	v_sub_f32_e32 v51, v51, v153
	v_sub_f32_e32 v52, v52, v153
	v_sub_f32_e32 v53, v53, v153
	v_sub_f32_e32 v54, v54, v153
	v_sub_f32_e32 v55, v55, v153
	v_exp_f32_e32 v48, v48
	v_exp_f32_e32 v49, v49
	v_exp_f32_e32 v50, v50
	v_exp_f32_e32 v51, v51
	v_exp_f32_e32 v52, v52
	v_exp_f32_e32 v53, v53
	v_exp_f32_e32 v54, v54
	v_exp_f32_e32 v55, v55
	ds_read_b128 v[190:193], v130 offset:31232
	ds_read_b128 v[194:197], v130 offset:26656
	v_mul_f32_e32 v16, v16, v36
	v_mul_f32_e32 v17, v17, v36
	v_mul_f32_e32 v18, v18, v36
	v_mul_f32_e32 v19, v19, v36
	v_mul_f32_e32 v20, v20, v36
	v_mul_f32_e32 v21, v21, v36
	v_mul_f32_e32 v22, v22, v36
	v_mul_f32_e32 v23, v23, v36
	v_mul_f32_e32 v24, v24, v36
	v_mul_f32_e32 v25, v25, v36
	v_mul_f32_e32 v26, v26, v36
	v_mul_f32_e32 v27, v27, v36
	v_mul_f32_e32 v28, v28, v36
	v_mul_f32_e32 v29, v29, v36
	v_mul_f32_e32 v30, v30, v36
	v_mul_f32_e32 v31, v31, v36
	v_cvt_pk_bf16_f32 v186, v48, v49
	v_cvt_pk_bf16_f32 v187, v50, v51
	v_cvt_pk_bf16_f32 v188, v52, v53
	v_cvt_pk_bf16_f32 v189, v54, v55
	v_mul_f32_e32 v0, v0, v36
	v_mul_f32_e32 v1, v1, v36
	v_mul_f32_e32 v2, v2, v36
	v_mul_f32_e32 v3, v3, v36
	s_waitcnt lgkmcnt(2)
	v_mfma_f32_32x32x16_bf16 v[16:31], v[32:35], v[186:189], v[16:31]
	v_mul_f32_e64 v4, v4, v36
	v_mul_f32_e64 v5, v5, v36
	v_mul_f32_e64 v6, v6, v36
	v_mul_f32_e64 v7, v7, v36
	v_mul_f32_e64 v8, v8, v36
	v_mul_f32_e64 v9, v9, v36
	v_mul_f32_e32 v10, v10, v36
	v_mul_f32_e32 v11, v11, v36
	v_mul_f32_e32 v12, v12, v36
	v_mul_f32_e32 v13, v13, v36
	v_mul_f32_e32 v14, v14, v36
	v_mul_f32_e32 v15, v15, v36
	ds_read_b128 v[32:35], v130 offset:31264
	v_sub_f32_e32 v56, v56, v153
	s_waitcnt lgkmcnt(2)
	v_mfma_f32_32x32x16_bf16 v[0:15], v[190:193], v[186:189], v[0:15]
	v_sub_f32_e32 v57, v57, v153
	v_sub_f32_e32 v58, v58, v153
	v_sub_f32_e32 v59, v59, v153
	v_sub_f32_e32 v60, v60, v153
	v_sub_f32_e32 v61, v61, v153
	v_sub_f32_e32 v62, v62, v153
	v_sub_f32_e32 v63, v63, v153
	v_exp_f32_e32 v56, v56
	v_exp_f32_e32 v57, v57
	v_exp_f32_e32 v58, v58
	v_exp_f32_e32 v59, v59
	v_exp_f32_e32 v60, v60
	v_exp_f32_e32 v61, v61
	v_exp_f32_e32 v62, v62
	v_exp_f32_e32 v63, v63
	v_cvt_pk_bf16_f32 v186, v56, v57
	v_cvt_pk_bf16_f32 v187, v58, v59
	v_cvt_pk_bf16_f32 v188, v60, v61
	v_cvt_pk_bf16_f32 v189, v62, v63
	ds_read_b128 v[190:193], v130 offset:26688
	v_sub_f32_e32 v38, v38, v153
	s_waitcnt lgkmcnt(2)
	v_mfma_f32_32x32x16_bf16 v[16:31], v[194:197], v[186:189], v[16:31]
	v_sub_f32_e32 v39, v39, v153
	v_exp_f32_e32 v38, v38
	v_exp_f32_e32 v39, v39
	v_sub_f32_e32 v40, v40, v153
	v_sub_f32_e32 v41, v41, v153
	v_sub_f32_e32 v42, v42, v153
	v_sub_f32_e32 v43, v43, v153
	s_waitcnt lgkmcnt(1)
	v_mfma_f32_32x32x16_bf16 v[0:15], v[32:35], v[186:189], v[0:15]
	ds_read_b128 v[186:189], v130 offset:31296
	ds_read_b128 v[194:197], v130 offset:26720
	v_cvt_pk_bf16_f32 v32, v180, v181
	v_cvt_pk_bf16_f32 v33, v182, v183
	v_cvt_pk_bf16_f32 v34, v184, v37
	v_cvt_pk_bf16_f32 v35, v38, v39
	v_sub_f32_e32 v44, v44, v153
	v_sub_f32_e32 v45, v45, v153
	s_waitcnt lgkmcnt(2)
	v_mfma_f32_32x32x16_bf16 v[16:31], v[190:193], v[32:35], v[16:31]
	ds_read_b128 v[190:193], v130 offset:31328
	v_sub_f32_e32 v46, v46, v153
	v_exp_f32_e32 v40, v40
	v_exp_f32_e32 v41, v41
	v_exp_f32_e32 v42, v42
	v_exp_f32_e32 v43, v43
	v_exp_f32_e32 v44, v44
	s_waitcnt lgkmcnt(2)
	v_mfma_f32_32x32x16_bf16 v[0:15], v[186:189], v[32:35], v[0:15]
	v_sub_f32_e32 v32, v47, v153
	v_exp_f32_e32 v47, v32
	global_load_dwordx4 v[32:35], v[160:161], off
	v_exp_f32_e32 v45, v45
	v_exp_f32_e32 v46, v46
	v_cvt_pk_bf16_f32 v186, v40, v41
	v_cvt_pk_bf16_f32 v187, v42, v43
	v_cvt_pk_bf16_f32 v188, v44, v45
	v_cvt_pk_bf16_f32 v189, v46, v47
	s_waitcnt lgkmcnt(1)
	s_nop 0
	v_mfma_f32_32x32x16_bf16 v[16:31], v[194:197], v[186:189], v[16:31]
	s_waitcnt lgkmcnt(0)
	v_mfma_f32_32x32x16_bf16 v[0:15], v[190:193], v[186:189], v[0:15]
	s_and_saveexec_b64 s[4:5], s[46:47]
	s_cbranch_execz .LBB0_841
	v_add3_u32 v130, s9, v170, v171
	s_waitcnt vmcnt(1)
	ds_write_b128 v130, v[88:91]

.LBB0_843:
	s_or_b64 exec, exec, s[4:5]
	v_add_f32_e32 v48, 0, v48
	v_add_f32_e32 v48, v49, v48
	v_add_f32_e32 v48, v50, v48
	v_add_f32_e32 v48, v51, v48
	v_add_f32_e32 v48, v52, v48
	v_add_f32_e32 v48, v53, v48
	v_add_f32_e32 v48, v54, v48
	v_add_f32_e32 v48, v55, v48
	v_add_f32_e32 v48, v56, v48
	v_add_f32_e32 v48, v57, v48
	v_add_f32_e32 v48, v58, v48
	v_add_f32_e32 v48, v59, v48
	v_add_f32_e32 v48, v60, v48
	v_add_f32_e32 v48, v61, v48
	v_add_f32_e32 v48, v62, v48
	v_add_f32_e32 v48, v63, v48
	v_add_f32_e32 v48, v180, v48
	v_add_f32_e32 v48, v181, v48
	v_add_f32_e32 v48, v182, v48
	v_add_f32_e32 v48, v183, v48
	v_add_f32_e32 v48, v184, v48
	v_add_f32_e32 v37, v37, v48
	v_add_f32_e32 v37, v38, v37
	v_add_f32_e32 v37, v39, v37
	v_add_f32_e32 v37, v40, v37
	v_add_f32_e32 v37, v41, v37
	v_add_f32_e32 v37, v42, v37
	v_add_f32_e32 v37, v43, v37
	v_add_f32_e32 v37, v44, v37
	v_add_f32_e32 v37, v45, v37
	v_add_f32_e32 v37, v46, v37
	v_add_f32_e32 v180, v47, v37
	s_add_i32 s6, s6, 1
	s_mulk_i32 s8, 0x2400
	v_fmac_f32_e32 v180, v133, v36
	v_add_u32_e32 v36, s8, v166
	v_lshl_add_u64 v[156:157], v[156:157], 0, s[2:3]
	v_lshl_add_u64 v[158:159], v[158:159], 0, s[2:3]
	s_cmp_eq_u32 s7, s6
	v_lshl_add_u64 v[160:161], v[160:161], 0, s[34:35]
	s_waitcnt vmcnt(0)
	ds_write_b128 v36, v[32:35] offset:26624
	s_waitcnt lgkmcnt(0)
	s_barrier
	s_cbranch_scc0 .LBB0_835
	s_and_b32 s4, s7, 1
	s_mul_i32 s5, s4, 0x3400
	v_add_u32_e32 v88, s5, v177
	ds_read_b128 v[32:35], v88
	s_mulk_i32 s4, 0x2400
	s_lshl_b32 s60, s54, 7
	v_lshlrev_b32_e32 v128, 1, v110
	s_waitcnt lgkmcnt(0)
	v_mfma_f32_32x32x16_bf16 v[48:63], v[32:35], v[84:87], 0
	ds_read_b128 v[32:35], v88 offset:32
	s_waitcnt lgkmcnt(0)
	v_mfma_f32_32x32x16_bf16 v[48:63], v[32:35], v[80:83], v[48:63]
	ds_read_b128 v[32:35], v88 offset:64
	s_waitcnt lgkmcnt(0)
	v_mfma_f32_32x32x16_bf16 v[48:63], v[32:35], v[76:79], v[48:63]
	ds_read_b128 v[32:35], v88 offset:96
	s_waitcnt lgkmcnt(0)
	v_mfma_f32_32x32x16_bf16 v[48:63], v[32:35], v[72:75], v[48:63]
	ds_read_b128 v[32:35], v88 offset:128
	s_waitcnt lgkmcnt(0)
	v_mfma_f32_32x32x16_bf16 v[48:63], v[32:35], v[68:71], v[48:63]
	ds_read_b128 v[32:35], v88 offset:160
	s_waitcnt lgkmcnt(0)
	v_mfma_f32_32x32x16_bf16 v[48:63], v[32:35], v[64:67], v[48:63]
	ds_read_b128 v[32:35], v88 offset:6656
	s_waitcnt lgkmcnt(0)
	v_mfma_f32_32x32x16_bf16 v[32:47], v[32:35], v[84:87], 0
	ds_read_b128 v[84:87], v88 offset:6688
	s_waitcnt lgkmcnt(0)
	v_mfma_f32_32x32x16_bf16 v[32:47], v[84:87], v[80:83], v[32:47]
	ds_read_b128 v[80:83], v88 offset:6720
	s_waitcnt lgkmcnt(0)
	v_mfma_f32_32x32x16_bf16 v[32:47], v[80:83], v[76:79], v[32:47]
	ds_read_b128 v[76:79], v88 offset:6752
	s_nop 1
	v_max_f32_e32 v80, v49, v49
	v_max_f32_e32 v81, v48, v48
	v_max_f32_e32 v80, v81, v80
	s_waitcnt lgkmcnt(0)
	v_mfma_f32_32x32x16_bf16 v[32:47], v[76:79], v[72:75], v[32:47]
	ds_read_b128 v[72:75], v88 offset:6784
	ds_read_b128 v[76:79], v88 offset:6816
	s_waitcnt lgkmcnt(1)
	v_mfma_f32_32x32x16_bf16 v[32:47], v[72:75], v[68:71], v[32:47]
	v_max3_f32 v68, v80, v50, v51
	v_max3_f32 v68, v68, v52, v53
	v_max3_f32 v68, v68, v54, v55
	v_max3_f32 v68, v68, v56, v57
	v_max3_f32 v68, v68, v58, v59
	v_max3_f32 v68, v68, v60, v61
	v_max3_f32 v68, v68, v62, v63
	s_waitcnt lgkmcnt(0)
	v_mfma_f32_32x32x16_bf16 v[32:47], v[76:79], v[64:67], v[32:47]
	v_add_u32_e32 v75, s4, v178
	s_nop 10
	v_max3_f32 v64, v68, v32, v33
	v_max3_f32 v64, v64, v34, v35
	v_max3_f32 v64, v64, v36, v37
	v_max3_f32 v64, v64, v38, v39
	v_max3_f32 v64, v64, v40, v41
	v_max3_f32 v64, v64, v42, v43
	v_max3_f32 v64, v64, v44, v45
	v_max3_f32 v64, v64, v46, v47
	ds_bpermute_b32 v65, v107, v64
	s_waitcnt lgkmcnt(0)
	v_max3_f32 v64, v153, v64, v65
	v_sub_f32_e32 v48, v48, v64
	v_exp_f32_e32 v48, v48
	v_sub_f32_e32 v49, v49, v64
	v_exp_f32_e32 v49, v49
	v_sub_f32_e32 v50, v50, v64
	v_exp_f32_e32 v50, v50
	v_sub_f32_e32 v51, v51, v64
	v_exp_f32_e32 v51, v51
	v_sub_f32_e32 v52, v52, v64
	v_add_f32_e32 v66, 0, v48
	v_exp_f32_e32 v52, v52
	v_sub_f32_e32 v53, v53, v64
	v_add_f32_e32 v66, v49, v66
	v_exp_f32_e32 v53, v53
	v_sub_f32_e32 v54, v54, v64
	v_add_f32_e32 v66, v50, v66
	v_exp_f32_e32 v54, v54
	v_sub_f32_e32 v55, v55, v64
	v_add_f32_e32 v66, v51, v66
	v_exp_f32_e32 v55, v55
	v_sub_f32_e32 v56, v56, v64
	v_add_f32_e32 v66, v52, v66
	v_exp_f32_e32 v67, v56
	v_sub_f32_e32 v56, v57, v64
	v_add_f32_e32 v66, v53, v66
	v_exp_f32_e32 v57, v56
	v_sub_f32_e32 v56, v58, v64
	v_add_f32_e32 v66, v54, v66
	v_exp_f32_e32 v58, v56
	v_sub_f32_e32 v56, v59, v64
	v_sub_f32_e32 v32, v32, v64
	v_exp_f32_e32 v59, v56
	v_sub_f32_e32 v56, v60, v64
	v_exp_f32_e32 v68, v32
	v_sub_f32_e32 v32, v33, v64
	v_add_f32_e32 v33, v55, v66
	v_exp_f32_e32 v60, v56
	v_sub_f32_e32 v56, v61, v64
	v_add_f32_e32 v33, v67, v33
	v_exp_f32_e32 v61, v56
	v_sub_f32_e32 v56, v62, v64
	v_add_f32_e32 v33, v57, v33
	v_exp_f32_e32 v62, v56
	v_sub_f32_e32 v56, v63, v64
	v_add_f32_e32 v33, v58, v33
	v_exp_f32_e32 v63, v56
	v_add_f32_e32 v33, v59, v33
	v_add_f32_e32 v33, v60, v33
	v_exp_f32_e32 v69, v32
	v_sub_f32_e32 v32, v34, v64
	v_add_f32_e32 v33, v61, v33
	v_exp_f32_e32 v70, v32
	v_sub_f32_e32 v32, v35, v64
	v_add_f32_e32 v33, v62, v33
	v_add_f32_e32 v33, v63, v33
	v_exp_f32_e32 v66, v32
	v_sub_f32_e32 v32, v36, v64
	v_add_f32_e32 v33, v68, v33
	v_exp_f32_e32 v71, v32
	v_sub_f32_e32 v32, v37, v64
	v_add_f32_e32 v33, v69, v33
	v_exp_f32_e32 v72, v32
	v_sub_f32_e32 v32, v38, v64
	v_add_f32_e32 v33, v70, v33
	v_exp_f32_e32 v73, v32
	v_add_f32_e32 v32, v66, v33
	v_add_f32_e32 v32, v71, v32
	v_add_f32_e32 v32, v72, v32
	v_sub_f32_e32 v65, v153, v64
	v_add_f32_e32 v74, v73, v32
	v_sub_f32_e32 v32, v39, v64
	v_exp_f32_e32 v56, v65
	v_exp_f32_e32 v65, v32
	ds_read_b128 v[32:35], v75 offset:26624
	v_cvt_pk_bf16_f32 v36, v48, v49
	v_cvt_pk_bf16_f32 v37, v50, v51
	v_cvt_pk_bf16_f32 v38, v52, v53
	v_cvt_pk_bf16_f32 v39, v54, v55
	ds_read_b128 v[48:51], v75 offset:31232
	ds_read_b128 v[52:55], v75 offset:26656
	v_mul_f32_e32 v30, v30, v56
	v_mul_f32_e32 v31, v31, v56
	v_mul_f32_e32 v28, v28, v56
	v_mul_f32_e32 v29, v29, v56
	v_mul_f32_e32 v26, v26, v56
	v_mul_f32_e32 v27, v27, v56
	v_mul_f32_e32 v24, v24, v56
	v_mul_f32_e32 v25, v25, v56
	v_mul_f32_e32 v22, v22, v56
	v_mul_f32_e32 v23, v23, v56
	v_mul_f32_e32 v20, v20, v56
	v_mul_f32_e32 v21, v21, v56
	v_mul_f32_e32 v18, v18, v56
	v_mul_f32_e32 v19, v19, v56
	v_mul_f32_e32 v16, v16, v56
	v_mul_f32_e32 v17, v17, v56
	v_mul_f32_e32 v14, v14, v56
	v_mul_f32_e32 v15, v15, v56
	v_mul_f32_e32 v12, v12, v56
	v_mul_f32_e32 v13, v13, v56
	s_waitcnt lgkmcnt(2)
	v_mfma_f32_32x32x16_bf16 v[16:31], v[32:35], v[36:39], v[16:31]
	v_mul_f32_e64 v10, v10, v56
	v_mul_f32_e64 v11, v11, v56
	v_mul_f32_e64 v8, v8, v56
	v_mul_f32_e64 v9, v9, v56
	v_mul_f32_e64 v6, v6, v56
	v_mul_f32_e64 v7, v7, v56
	v_mul_f32_e32 v4, v4, v56
	v_mul_f32_e32 v5, v5, v56
	v_mul_f32_e32 v2, v2, v56
	v_mul_f32_e32 v3, v3, v56
	v_mul_f32_e32 v0, v0, v56
	v_mul_f32_e32 v1, v1, v56
	ds_read_b128 v[32:35], v75 offset:31264
	v_sub_f32_e32 v40, v40, v64
	s_waitcnt lgkmcnt(2)
	v_mfma_f32_32x32x16_bf16 v[0:15], v[48:51], v[36:39], v[0:15]
	v_exp_f32_e32 v76, v40
	v_sub_f32_e32 v36, v41, v64
	v_exp_f32_e32 v77, v36
	v_cvt_pk_bf16_f32 v36, v67, v57
	v_cvt_pk_bf16_f32 v37, v58, v59
	v_cvt_pk_bf16_f32 v38, v60, v61
	v_cvt_pk_bf16_f32 v39, v62, v63
	v_sub_f32_e32 v40, v42, v64
	ds_read_b128 v[48:51], v75 offset:26688
	s_waitcnt lgkmcnt(2)
	v_mfma_f32_32x32x16_bf16 v[16:31], v[52:55], v[36:39], v[16:31]
	v_exp_f32_e32 v52, v40
	v_add_f32_e32 v40, v65, v74
	v_add_f32_e32 v40, v76, v40
	v_add_f32_e32 v40, v77, v40
	v_add_f32_e32 v53, v52, v40
	v_sub_f32_e32 v54, v43, v64
	v_exp_f32_e32 v54, v54
	s_waitcnt lgkmcnt(1)
	v_mfma_f32_32x32x16_bf16 v[0:15], v[32:35], v[36:39], v[0:15]
	ds_read_b128 v[36:39], v75 offset:31296
	ds_read_b128 v[40:43], v75 offset:26720
	v_sub_f32_e32 v44, v44, v64
	v_cvt_pk_bf16_f32 v32, v68, v69
	v_cvt_pk_bf16_f32 v33, v70, v66
	v_cvt_pk_bf16_f32 v34, v71, v72
	v_cvt_pk_bf16_f32 v35, v73, v65
	v_exp_f32_e32 v44, v44
	v_sub_f32_e32 v45, v45, v64
	s_waitcnt lgkmcnt(2)
	v_mfma_f32_32x32x16_bf16 v[16:31], v[48:51], v[32:35], v[16:31]
	v_exp_f32_e32 v45, v45
	v_sub_f32_e32 v46, v46, v64
	ds_read_b128 v[48:51], v75 offset:31328
	s_waitcnt lgkmcnt(0)
	s_barrier
	v_mfma_f32_32x32x16_bf16 v[0:15], v[36:39], v[32:35], v[0:15]
	v_sub_f32_e32 v32, v47, v64
	v_exp_f32_e32 v36, v46
	v_exp_f32_e32 v37, v32
	v_add_f32_e32 v38, v54, v53
	v_add_f32_e32 v38, v44, v38
	v_add_f32_e32 v38, v45, v38
	v_cvt_pk_bf16_f32 v35, v36, v37
	v_add_f32_e32 v36, v36, v38
	v_add_f32_e32 v36, v37, v36
	v_fmac_f32_e32 v36, v180, v56
	ds_bpermute_b32 v37, v107, v36
	v_cvt_pk_bf16_f32 v32, v76, v77
	v_cvt_pk_bf16_f32 v33, v52, v54
	v_cvt_pk_bf16_f32 v34, v44, v45
	s_nop 1
	v_mfma_f32_32x32x16_bf16 v[16:31], v[40:43], v[32:35], v[16:31]
	v_mfma_f32_32x32x16_bf16 v[0:15], v[48:51], v[32:35], v[0:15]
	s_waitcnt lgkmcnt(0)
	v_add_f32_e32 v34, v36, v37
	v_div_scale_f32 v35, s[4:5], v34, v34, 1.0
	v_rcp_f32_e32 v36, v35
	v_lshlrev_b64 v[32:33], 11, v[154:155]
	v_lshl_add_u64 v[32:33], s[66:67], 0, v[32:33]
	v_lshl_add_u64 v[32:33], v[32:33], 0, s[60:61]
	v_fma_f32 v37, -v35, v36, 1.0
	v_fmac_f32_e32 v36, v37, v36
	v_div_scale_f32 v37, vcc, 1.0, v34, 1.0
	v_mul_f32_e32 v38, v37, v36
	v_fma_f32 v39, -v35, v38, v37
	v_fmac_f32_e32 v38, v39, v36
	v_fma_f32 v35, -v35, v38, v37
	v_div_fmas_f32 v35, v35, v36, v38
	v_div_fixup_f32 v34, v35, v34, 1.0
	v_mul_f32_e32 v16, v16, v34
	v_mul_f32_e32 v17, v17, v34
	v_mul_f32_e32 v18, v18, v34
	v_mul_f32_e32 v19, v19, v34
	v_cvt_pk_bf16_f32 v16, v16, v17
	v_cvt_pk_bf16_f32 v17, v18, v19
	v_lshl_add_u64 v[18:19], v[32:33], 0, v[128:129]
	s_mov_b64 s[4:5], 0x2d53d00
	v_lshl_add_u64 v[32:33], v[18:19], 0, s[4:5]
	s_mov_b32 s4, 0x2d53000
	v_add_co_u32_e32 v18, vcc, s4, v18
	v_mul_f32_e32 v0, v0, v34
	v_mul_f32_e32 v1, v1, v34
	v_mul_f32_e32 v2, v2, v34
	v_mul_f32_e32 v3, v3, v34
	v_addc_co_u32_e32 v19, vcc, 0, v19, vcc
	v_cvt_pk_bf16_f32 v0, v0, v1
	v_cvt_pk_bf16_f32 v1, v2, v3
	global_store_dwordx2 v[18:19], v[16:17], off offset:3328
	v_mul_f32_e32 v16, v20, v34
	v_mul_f32_e32 v17, v21, v34
	v_mul_f32_e32 v18, v22, v34
	v_mul_f32_e32 v19, v23, v34
	global_store_dwordx2 v[32:33], v[0:1], off offset:64
	v_mul_f32_e32 v0, v4, v34
	v_mul_f32_e32 v1, v5, v34
	v_mul_f32_e32 v2, v6, v34
	v_mul_f32_e32 v3, v7, v34
	v_cvt_pk_bf16_f32 v16, v16, v17
	v_cvt_pk_bf16_f32 v17, v18, v19
	v_cvt_pk_bf16_f32 v0, v0, v1
	v_cvt_pk_bf16_f32 v1, v2, v3
	global_store_dwordx2 v[32:33], v[16:17], off offset:16
	v_mul_f32_e32 v16, v24, v34
	v_mul_f32_e32 v17, v25, v34
	v_mul_f32_e32 v18, v26, v34
	v_mul_f32_e32 v19, v27, v34
	global_store_dwordx2 v[32:33], v[0:1], off offset:80
	v_mul_f32_e32 v0, v8, v34
	v_mul_f32_e32 v1, v9, v34
	v_mul_f32_e32 v2, v10, v34
	v_mul_f32_e32 v3, v11, v34
	v_cvt_pk_bf16_f32 v16, v16, v17
	v_cvt_pk_bf16_f32 v17, v18, v19
	v_cvt_pk_bf16_f32 v0, v0, v1
	v_cvt_pk_bf16_f32 v1, v2, v3
	global_store_dwordx2 v[32:33], v[16:17], off offset:32
	v_mul_f32_e32 v16, v28, v34
	v_mul_f32_e32 v17, v29, v34
	v_mul_f32_e32 v18, v30, v34
	v_mul_f32_e32 v19, v31, v34
	global_store_dwordx2 v[32:33], v[0:1], off offset:96
	v_mul_f32_e32 v0, v12, v34
	v_mul_f32_e32 v1, v13, v34
	v_mul_f32_e32 v2, v14, v34
	v_mul_f32_e32 v3, v15, v34
	v_cvt_pk_bf16_f32 v16, v16, v17
	v_cvt_pk_bf16_f32 v17, v18, v19
	v_cvt_pk_bf16_f32 v0, v0, v1
	v_cvt_pk_bf16_f32 v1, v2, v3
	s_mov_b64 s[4:5], 0
	global_store_dwordx2 v[32:33], v[16:17], off offset:48
	global_store_dwordx2 v[32:33], v[0:1], off offset:112

.LBB0_863:
	s_or_b64 exec, exec, s[4:5]
	s_and_b32 s4, s8, 1
	s_mul_i32 s5, s4, 0x2400
	v_add_u32_e32 v87, s5, v169
	ds_read_b128 v[32:35], v87
	ds_read_b128 v[88:91], v87 offset:32
	v_add_u32_e32 v107, s5, v167
	s_xor_b32 s6, s4, 1
	s_mulk_i32 s6, 0x2400
	s_waitcnt lgkmcnt(1)
	v_mfma_f32_32x32x16_bf16 v[48:63], v[32:35], v[68:71], 0
	ds_read_b128 v[32:35], v87 offset:4608
	ds_read_b128 v[154:157], v107 offset:23040
	s_waitcnt lgkmcnt(2)
	v_mfma_f32_32x32x16_bf16 v[48:63], v[88:91], v[64:67], v[48:63]
	ds_read_b128 v[88:91], v87 offset:4640
	s_waitcnt lgkmcnt(2)
	v_mfma_f32_32x32x16_bf16 v[32:47], v[32:35], v[68:71], 0
	s_nop 8
	v_max_f32_e32 v87, v49, v49
	v_max_f32_e32 v92, v48, v48
	v_max_f32_e32 v87, v92, v87
	v_max3_f32 v87, v87, v50, v51
	v_max3_f32 v87, v87, v52, v53
	v_max3_f32 v87, v87, v54, v55
	v_max3_f32 v87, v87, v56, v57
	s_waitcnt lgkmcnt(0)
	v_mfma_f32_32x32x16_bf16 v[32:47], v[88:91], v[64:67], v[32:47]
	v_max3_f32 v87, v87, v58, v59
	v_max3_f32 v87, v87, v60, v61
	v_max3_f32 v87, v87, v62, v63
	s_nop 8
	v_max3_f32 v87, v87, v32, v33
	v_max3_f32 v87, v87, v34, v35
	v_max3_f32 v87, v87, v36, v37
	v_max3_f32 v87, v87, v38, v39
	v_max3_f32 v87, v87, v40, v41
	v_max3_f32 v87, v87, v42, v43
	v_max3_f32 v87, v87, v44, v45
	v_max3_f32 v87, v87, v46, v47
	ds_bpermute_b32 v88, v82, v87
	s_waitcnt lgkmcnt(0)
	v_max3_f32 v87, v84, v87, v88
	v_sub_f32_e32 v32, v32, v87
	v_sub_f32_e32 v92, v84, v87
	v_exp_f32_e32 v84, v32
	v_sub_f32_e32 v32, v33, v87
	v_exp_f32_e32 v88, v32
	v_sub_f32_e32 v32, v34, v87
	v_exp_f32_e32 v89, v32
	v_sub_f32_e32 v32, v35, v87
	v_exp_f32_e32 v90, v32
	v_sub_f32_e32 v32, v36, v87
	v_exp_f32_e32 v91, v32
	v_sub_f32_e32 v32, v37, v87
	v_exp_f32_e32 v37, v32
	global_load_dwordx4 v[32:35], v[80:81], off
	v_exp_f32_e32 v36, v92
	ds_read_b128 v[92:95], v107 offset:18432
	v_sub_f32_e32 v48, v48, v87
	v_sub_f32_e32 v49, v49, v87
	v_sub_f32_e32 v50, v50, v87
	v_sub_f32_e32 v51, v51, v87
	v_sub_f32_e32 v52, v52, v87
	v_sub_f32_e32 v53, v53, v87
	v_sub_f32_e32 v54, v54, v87
	v_sub_f32_e32 v55, v55, v87
	v_exp_f32_e32 v48, v48
	v_exp_f32_e32 v49, v49
	v_exp_f32_e32 v50, v50
	v_exp_f32_e32 v51, v51
	v_exp_f32_e32 v52, v52
	v_exp_f32_e32 v53, v53
	v_exp_f32_e32 v54, v54
	v_exp_f32_e32 v55, v55
	v_mul_f32_e32 v0, v0, v36
	v_mul_f32_e32 v1, v1, v36
	v_mul_f32_e32 v2, v2, v36
	v_mul_f32_e32 v3, v3, v36
	v_mul_f32_e32 v4, v4, v36
	v_mul_f32_e32 v5, v5, v36
	v_mul_f32_e32 v6, v6, v36
	v_mul_f32_e32 v7, v7, v36
	v_mul_f32_e32 v8, v8, v36
	v_mul_f32_e32 v9, v9, v36
	v_mul_f32_e32 v10, v10, v36
	v_mul_f32_e32 v11, v11, v36
	v_mul_f32_e32 v12, v12, v36
	v_mul_f32_e32 v13, v13, v36
	v_mul_f32_e32 v14, v14, v36
	v_mul_f32_e32 v15, v15, v36
	v_cvt_pk_bf16_f32 v130, v48, v49
	v_cvt_pk_bf16_f32 v131, v50, v51
	v_cvt_pk_bf16_f32 v132, v52, v53
	v_cvt_pk_bf16_f32 v133, v54, v55
	v_sub_f32_e32 v56, v56, v87
	v_sub_f32_e32 v57, v57, v87
	s_waitcnt lgkmcnt(0)
	v_mfma_f32_32x32x16_bf16 v[0:15], v[92:95], v[130:133], v[0:15]
	ds_read_b128 v[92:95], v107 offset:18464
	v_sub_f32_e32 v58, v58, v87
	v_sub_f32_e32 v59, v59, v87
	v_sub_f32_e32 v60, v60, v87
	v_sub_f32_e32 v61, v61, v87
	v_sub_f32_e32 v62, v62, v87
	v_sub_f32_e32 v63, v63, v87
	v_exp_f32_e32 v56, v56
	v_exp_f32_e32 v57, v57
	v_exp_f32_e32 v58, v58
	v_exp_f32_e32 v59, v59
	v_exp_f32_e32 v60, v60
	v_exp_f32_e32 v61, v61
	v_exp_f32_e32 v62, v62
	v_exp_f32_e32 v63, v63
	v_mul_f32_e32 v16, v16, v36
	v_mul_f32_e32 v17, v17, v36
	v_mul_f32_e32 v18, v18, v36
	v_mul_f32_e32 v19, v19, v36
	v_mul_f32_e32 v20, v20, v36
	v_mul_f32_e32 v21, v21, v36
	v_mul_f32_e32 v22, v22, v36
	v_mul_f32_e32 v23, v23, v36
	v_mul_f32_e32 v24, v24, v36
	v_mul_f32_e32 v25, v25, v36
	v_mul_f32_e32 v26, v26, v36
	v_mul_f32_e32 v27, v27, v36
	v_mul_f32_e32 v28, v28, v36
	v_mul_f32_e32 v29, v29, v36
	v_mul_f32_e32 v30, v30, v36
	v_mul_f32_e32 v31, v31, v36
	v_sub_f32_e32 v38, v38, v87
	v_sub_f32_e32 v39, v39, v87
	v_mfma_f32_32x32x16_bf16 v[16:31], v[154:157], v[130:133], v[16:31]
	ds_read_b128 v[130:133], v107 offset:23072
	v_cvt_pk_bf16_f32 v154, v56, v57
	v_cvt_pk_bf16_f32 v155, v58, v59
	v_cvt_pk_bf16_f32 v156, v60, v61
	v_cvt_pk_bf16_f32 v157, v62, v63
	v_exp_f32_e32 v38, v38
	v_exp_f32_e32 v39, v39
	s_waitcnt lgkmcnt(1)
	v_mfma_f32_32x32x16_bf16 v[0:15], v[92:95], v[154:157], v[0:15]
	ds_read_b128 v[92:95], v107 offset:18496
	v_sub_f32_e32 v40, v40, v87
	v_sub_f32_e32 v41, v41, v87
	v_sub_f32_e32 v42, v42, v87
	v_sub_f32_e32 v43, v43, v87
	v_sub_f32_e32 v44, v44, v87
	v_sub_f32_e32 v45, v45, v87
	s_waitcnt lgkmcnt(1)
	v_mfma_f32_32x32x16_bf16 v[16:31], v[130:133], v[154:157], v[16:31]
	v_cvt_pk_bf16_f32 v130, v84, v88
	v_cvt_pk_bf16_f32 v131, v89, v90
	v_cvt_pk_bf16_f32 v132, v91, v37
	v_cvt_pk_bf16_f32 v133, v38, v39
	ds_read_b128 v[154:157], v107 offset:23104
	v_sub_f32_e32 v46, v46, v87
	v_sub_f32_e32 v47, v47, v87
	s_waitcnt lgkmcnt(1)
	v_mfma_f32_32x32x16_bf16 v[0:15], v[92:95], v[130:133], v[0:15]
	ds_read_b128 v[92:95], v107 offset:18528
	v_exp_f32_e32 v40, v40
	v_exp_f32_e32 v41, v41
	v_exp_f32_e32 v42, v42
	v_exp_f32_e32 v43, v43
	v_exp_f32_e32 v44, v44
	v_exp_f32_e32 v45, v45
	v_exp_f32_e32 v46, v46
	v_exp_f32_e32 v47, v47
	s_waitcnt lgkmcnt(1)
	v_mfma_f32_32x32x16_bf16 v[16:31], v[154:157], v[130:133], v[16:31]
	v_cvt_pk_bf16_f32 v130, v40, v41
	v_cvt_pk_bf16_f32 v131, v42, v43
	v_cvt_pk_bf16_f32 v132, v44, v45
	v_cvt_pk_bf16_f32 v133, v46, v47
	s_waitcnt lgkmcnt(0)
	s_nop 0
	v_mfma_f32_32x32x16_bf16 v[0:15], v[92:95], v[130:133], v[0:15]
	ds_read_b128 v[92:95], v107 offset:23136
	s_waitcnt lgkmcnt(0)
	v_mfma_f32_32x32x16_bf16 v[16:31], v[92:95], v[130:133], v[16:31]
	s_and_saveexec_b64 s[4:5], s[0:1]
	s_cbranch_execz .LBB0_865
	v_add_u32_e32 v92, s6, v85
	s_waitcnt vmcnt(1)
	ds_write_b128 v92, v[72:75]
.LBB0_865:
	s_or_b64 exec, exec, s[4:5]
	v_add_f32_e32 v48, 0, v48
	v_add_f32_e32 v48, v49, v48
	v_add_f32_e32 v48, v50, v48
	v_add_f32_e32 v48, v51, v48
	v_add_f32_e32 v48, v52, v48
	v_add_f32_e32 v48, v53, v48
	v_add_f32_e32 v48, v54, v48
	v_add_f32_e32 v48, v55, v48
	v_add_f32_e32 v48, v56, v48
	v_add_f32_e32 v48, v57, v48
	v_add_f32_e32 v48, v58, v48
	v_add_f32_e32 v48, v59, v48
	v_add_f32_e32 v48, v60, v48
	v_add_f32_e32 v48, v61, v48
	v_add_f32_e32 v48, v62, v48
	v_add_f32_e32 v48, v63, v48
	v_add_f32_e32 v48, v84, v48
	v_add_f32_e32 v48, v88, v48
	v_add_f32_e32 v48, v89, v48
	v_add_f32_e32 v48, v90, v48
	v_add_f32_e32 v48, v91, v48
	v_add_f32_e32 v37, v37, v48
	v_add_f32_e32 v37, v38, v37
	v_add_f32_e32 v37, v39, v37
	v_add_f32_e32 v37, v40, v37
	v_add_f32_e32 v37, v41, v37
	v_add_f32_e32 v37, v42, v37
	v_add_f32_e32 v37, v43, v37
	v_add_f32_e32 v37, v44, v37
	v_add_f32_e32 v37, v45, v37
	v_add_f32_e32 v37, v46, v37
	v_add_f32_e32 v84, v47, v37
	s_add_i32 s8, s8, 1
	v_fmac_f32_e32 v84, v86, v36
	v_add_u32_e32 v36, s6, v166
	v_lshl_add_u64 v[78:79], v[78:79], 0, s[62:63]
	s_cmp_eq_u32 s9, s8
	v_lshl_add_u64 v[80:81], v[80:81], 0, s[34:35]
	s_waitcnt vmcnt(0)
	ds_write_b128 v36, v[32:35] offset:18432
	s_waitcnt lgkmcnt(0)
	s_barrier
	s_cbranch_scc0 .LBB0_861
	s_bitcmp1_b32 s9, 0
	s_cselect_b32 s4, 0x2400, 0
	v_add_u32_e32 v72, s4, v169
	ds_read_b128 v[32:35], v72
	v_add_u32_e32 v74, s4, v167
	s_waitcnt lgkmcnt(0)
	v_mfma_f32_32x32x16_bf16 v[48:63], v[32:35], v[68:71], 0
	ds_read_b128 v[32:35], v72 offset:32
	s_waitcnt lgkmcnt(0)
	v_mfma_f32_32x32x16_bf16 v[48:63], v[32:35], v[64:67], v[48:63]
	ds_read_b128 v[32:35], v72 offset:4608
	s_waitcnt lgkmcnt(0)
	v_mfma_f32_32x32x16_bf16 v[32:47], v[32:35], v[68:71], 0
	ds_read_b128 v[68:71], v72 offset:4640
	s_nop 7
	v_max_f32_e32 v72, v49, v49
	v_max_f32_e32 v73, v48, v48
	v_max_f32_e32 v72, v73, v72
	v_max3_f32 v72, v72, v50, v51
	s_waitcnt lgkmcnt(0)
	v_mfma_f32_32x32x16_bf16 v[32:47], v[68:71], v[64:67], v[32:47]
	v_max3_f32 v64, v72, v52, v53
	v_max3_f32 v64, v64, v54, v55
	v_max3_f32 v64, v64, v56, v57
	v_max3_f32 v64, v64, v58, v59
	v_max3_f32 v64, v64, v60, v61
	v_max3_f32 v64, v64, v62, v63
	s_nop 5
	v_max3_f32 v64, v64, v32, v33
	v_max3_f32 v64, v64, v34, v35
	v_max3_f32 v64, v64, v36, v37
	v_max3_f32 v64, v64, v38, v39
	v_max3_f32 v64, v64, v40, v41
	v_max3_f32 v64, v64, v42, v43
	v_max3_f32 v64, v64, v44, v45
	v_max3_f32 v64, v64, v46, v47
	ds_bpermute_b32 v65, v82, v64
	s_waitcnt lgkmcnt(0)
	v_max3_f32 v64, v87, v64, v65
	v_sub_f32_e32 v48, v48, v64
	v_sub_f32_e32 v49, v49, v64
	v_exp_f32_e32 v48, v48
	v_sub_f32_e32 v50, v50, v64
	v_exp_f32_e32 v49, v49
	v_sub_f32_e32 v51, v51, v64
	v_exp_f32_e32 v50, v50
	v_sub_f32_e32 v52, v52, v64
	v_exp_f32_e32 v51, v51
	v_sub_f32_e32 v53, v53, v64
	v_exp_f32_e32 v52, v52
	v_add_f32_e32 v66, 0, v48
	v_sub_f32_e32 v54, v54, v64
	v_exp_f32_e32 v53, v53
	v_add_f32_e32 v66, v49, v66
	v_sub_f32_e32 v55, v55, v64
	v_exp_f32_e32 v54, v54
	v_add_f32_e32 v66, v50, v66
	v_sub_f32_e32 v56, v56, v64
	v_exp_f32_e32 v55, v55
	v_add_f32_e32 v66, v51, v66
	v_sub_f32_e32 v57, v57, v64
	v_exp_f32_e32 v56, v56
	v_add_f32_e32 v66, v52, v66
	v_sub_f32_e32 v58, v58, v64
	v_exp_f32_e32 v57, v57
	v_add_f32_e32 v66, v53, v66
	v_sub_f32_e32 v59, v59, v64
	v_exp_f32_e32 v58, v58
	v_add_f32_e32 v66, v54, v66
	v_exp_f32_e32 v59, v59
	v_add_f32_e32 v66, v55, v66
	v_sub_f32_e32 v60, v60, v64
	v_add_f32_e32 v66, v56, v66
	v_exp_f32_e32 v60, v60
	v_sub_f32_e32 v61, v61, v64
	v_add_f32_e32 v66, v57, v66
	v_exp_f32_e32 v61, v61
	v_sub_f32_e32 v62, v62, v64
	v_add_f32_e32 v66, v58, v66
	v_exp_f32_e32 v62, v62
	v_sub_f32_e32 v63, v63, v64
	v_add_f32_e32 v66, v59, v66
	v_exp_f32_e32 v63, v63
	v_sub_f32_e32 v32, v32, v64
	v_add_f32_e32 v66, v60, v66
	v_exp_f32_e32 v67, v32
	v_sub_f32_e32 v32, v33, v64
	v_add_f32_e32 v66, v61, v66
	v_exp_f32_e32 v33, v32
	v_sub_f32_e32 v34, v34, v64
	v_add_f32_e32 v32, v62, v66
	v_exp_f32_e32 v66, v34
	v_sub_f32_e32 v34, v35, v64
	v_add_f32_e32 v32, v63, v32
	v_exp_f32_e32 v68, v34
	v_sub_f32_e32 v34, v36, v64
	v_add_f32_e32 v32, v67, v32
	v_exp_f32_e32 v69, v34
	v_sub_f32_e32 v34, v37, v64
	v_add_f32_e32 v32, v33, v32
	v_exp_f32_e32 v70, v34
	v_add_f32_e32 v32, v66, v32
	v_add_f32_e32 v32, v68, v32
	v_add_f32_e32 v32, v69, v32
	v_sub_f32_e32 v65, v87, v64
	v_add_f32_e32 v71, v70, v32
	v_sub_f32_e32 v32, v38, v64
	v_sub_f32_e32 v34, v39, v64
	v_exp_f32_e32 v72, v32
	v_exp_f32_e32 v32, v65
	v_exp_f32_e32 v65, v34
	v_sub_f32_e32 v34, v40, v64
	v_exp_f32_e32 v73, v34
	ds_read_b128 v[34:37], v74 offset:18432
	v_mul_f32_e32 v14, v14, v32
	v_mul_f32_e32 v15, v15, v32
	v_mul_f32_e32 v12, v12, v32
	v_mul_f32_e32 v13, v13, v32
	v_mul_f32_e32 v10, v10, v32
	v_mul_f32_e32 v11, v11, v32
	v_mul_f32_e32 v8, v8, v32
	v_mul_f32_e32 v9, v9, v32
	v_mul_f32_e32 v6, v6, v32
	v_mul_f32_e32 v7, v7, v32
	v_mul_f32_e32 v4, v4, v32
	v_mul_f32_e32 v5, v5, v32
	v_mul_f32_e32 v2, v2, v32
	v_mul_f32_e32 v3, v3, v32
	v_mul_f32_e32 v0, v0, v32
	v_mul_f32_e32 v1, v1, v32
	v_cvt_pk_bf16_f32 v48, v48, v49
	v_cvt_pk_bf16_f32 v49, v50, v51
	v_cvt_pk_bf16_f32 v50, v52, v53
	v_cvt_pk_bf16_f32 v51, v54, v55
	ds_read_b128 v[52:55], v74 offset:23040
	v_mul_f32_e32 v30, v30, v32
	v_mul_f32_e32 v31, v31, v32
	s_waitcnt lgkmcnt(1)
	v_mfma_f32_32x32x16_bf16 v[0:15], v[34:37], v[48:51], v[0:15]
	ds_read_b128 v[34:37], v74 offset:18464
	v_mul_f32_e64 v28, v28, v32
	v_mul_f32_e64 v29, v29, v32
	v_mul_f32_e64 v26, v26, v32
	v_mul_f32_e64 v27, v27, v32
	v_mul_f32_e32 v24, v24, v32
	v_mul_f32_e32 v25, v25, v32
	v_mul_f32_e32 v22, v22, v32
	v_mul_f32_e32 v23, v23, v32
	v_mul_f32_e32 v20, v20, v32
	v_mul_f32_e32 v21, v21, v32
	v_mul_f32_e32 v18, v18, v32
	v_mul_f32_e32 v19, v19, v32
	v_mul_f32_e32 v16, v16, v32
	v_mul_f32_e32 v17, v17, v32
	v_sub_f32_e32 v38, v41, v64
	v_cvt_pk_bf16_f32 v39, v58, v59
	s_waitcnt lgkmcnt(1)
	v_mfma_f32_32x32x16_bf16 v[16:31], v[52:55], v[48:51], v[16:31]
	v_exp_f32_e32 v52, v38
	v_cvt_pk_bf16_f32 v38, v56, v57
	v_cvt_pk_bf16_f32 v40, v60, v61
	v_cvt_pk_bf16_f32 v41, v62, v63
	ds_read_b128 v[48:51], v74 offset:23072
	s_waitcnt lgkmcnt(1)
	v_mfma_f32_32x32x16_bf16 v[0:15], v[34:37], v[38:41], v[0:15]
	v_add_f32_e32 v34, v72, v71
	v_add_f32_e32 v34, v65, v34
	v_add_f32_e32 v34, v73, v34
	v_add_f32_e32 v53, v52, v34
	v_sub_f32_e32 v34, v42, v64
	v_exp_f32_e32 v54, v34
	ds_read_b128 v[34:37], v74 offset:18496
	s_waitcnt lgkmcnt(1)
	v_mfma_f32_32x32x16_bf16 v[16:31], v[48:51], v[38:41], v[16:31]
	ds_read_b128 v[48:51], v74 offset:23104
	v_sub_f32_e32 v38, v43, v64
	v_exp_f32_e32 v55, v38
	v_cvt_pk_bf16_f32 v38, v67, v33
	v_cvt_pk_bf16_f32 v39, v66, v68
	v_cvt_pk_bf16_f32 v40, v69, v70
	v_cvt_pk_bf16_f32 v41, v72, v65
	v_sub_f32_e32 v33, v44, v64
	v_exp_f32_e32 v33, v33
	s_waitcnt lgkmcnt(1)
	v_mfma_f32_32x32x16_bf16 v[0:15], v[34:37], v[38:41], v[0:15]
	v_sub_f32_e32 v34, v45, v64
	v_exp_f32_e32 v56, v34
	v_sub_f32_e32 v34, v46, v64
	v_exp_f32_e32 v46, v34
	ds_read_b128 v[34:37], v74 offset:18528
	ds_read_b128 v[42:45], v74 offset:23136
	s_waitcnt lgkmcnt(0)
	v_mfma_f32_32x32x16_bf16 v[16:31], v[48:51], v[38:41], v[16:31]
	v_sub_f32_e32 v38, v47, v64
	v_exp_f32_e32 v47, v38
	v_cvt_pk_bf16_f32 v38, v73, v52
	v_cvt_pk_bf16_f32 v39, v54, v55
	v_cvt_pk_bf16_f32 v40, v33, v56
	v_cvt_pk_bf16_f32 v41, v46, v47
	s_barrier
	s_nop 0
	v_mfma_f32_32x32x16_bf16 v[0:15], v[34:37], v[38:41], v[0:15]
	v_add_f32_e32 v34, v54, v53
	v_add_f32_e32 v34, v55, v34
	v_add_f32_e32 v33, v33, v34
	v_add_f32_e32 v33, v56, v33
	v_add_f32_e32 v33, v46, v33
	v_add_f32_e32 v34, v47, v33
	v_fmac_f32_e32 v34, v84, v32
	v_mfma_f32_32x32x16_bf16 v[16:31], v[42:45], v[38:41], v[16:31]
	ds_bpermute_b32 v35, v82, v34
	v_mov_b32_e32 v32, 0
	v_mov_b32_e32 v33, 0
	s_and_saveexec_b64 s[4:5], s[38:39]
	s_cbranch_execz .LBB0_868
	global_load_dword v33, v[126:127], off
	global_load_dword v37, v[134:135], off
	global_load_dword v32, v[136:137], off
	global_load_dword v36, v[138:139], off
	s_waitcnt vmcnt(0)
	v_pk_mul_f32 v[32:33], v[32:33], v[36:37]

.LBB0_870:
	s_or_b64 exec, exec, s[4:5]
	s_waitcnt lgkmcnt(0)
	s_barrier
	s_and_saveexec_b64 s[4:5], s[40:41]
	s_cbranch_execz .LBB0_800
	v_div_scale_f32 v41, s[6:7], v38, v38, 1.0
	v_rcp_f32_e32 v42, v41
	v_div_scale_f32 v43, vcc, 1.0, v38, 1.0
	s_mov_b32 s6, 0x800000
	v_fma_f32 v44, -v41, v42, 1.0
	v_fmac_f32_e32 v42, v44, v42
	v_mul_f32_e32 v44, v43, v42
	v_fma_f32 v45, -v41, v44, v43
	v_fmac_f32_e32 v44, v45, v42
	v_fma_f32 v41, -v41, v44, v43
	v_div_fmas_f32 v41, v41, v42, v44
	v_div_fixup_f32 v38, v41, v38, 1.0
	ds_read2_b32 v[42:43], v179 offset1:33
	ds_read2_b32 v[44:45], v179 offset0:66 offset1:99
	ds_read2_b32 v[46:47], v40 offset0:8 offset1:41
	ds_read2_b32 v[40:41], v40 offset0:74 offset1:107
	ds_read2_b32 v[48:49], v39 offset0:16 offset1:49
	ds_read2_b32 v[50:51], v39 offset0:82 offset1:115
	ds_read2_b32 v[52:53], v37 offset0:24 offset1:57
	ds_read2_b32 v[54:55], v37 offset0:90 offset1:123
	ds_read2_b32 v[36:37], v36 offset0:65 offset1:98
	v_add_u32_e32 v39, 0x1200, v179
	ds_read2_b32 v[56:57], v39 offset0:3 offset1:168
	ds_read2_b32 v[58:59], v35 offset0:73 offset1:106
	v_add_u32_e32 v35, 0x1a00, v179
	ds_read2_b32 v[60:61], v35 offset0:19 offset1:184
	v_add_u32_e32 v35, 0x1600, v179
	ds_read2_b32 v[62:63], v35 offset0:11 offset1:176
	ds_read2_b32 v[34:35], v34 offset0:89 offset1:122
	ds_read2_b32 v[64:65], v33 offset0:81 offset1:114
	ds_read_b32 v68, v145
	ds_read_b32 v71, v179 offset:7788
	s_waitcnt lgkmcnt(14)
	v_pk_fma_f32 v[0:1], v[0:1], v[38:39], v[42:43] op_sel_hi:[1,0,1] neg_lo:[0,0,1] neg_hi:[0,0,1]
	s_waitcnt lgkmcnt(5)
	v_mov_b32_e32 v66, v61
	s_waitcnt lgkmcnt(3)
	v_mov_b32_e32 v67, v34
	v_mov_b32_e32 v70, v35
	v_pk_fma_f32 v[66:67], v[28:29], v[38:39], v[66:67] op_sel_hi:[1,0,1] neg_lo:[0,0,1] neg_hi:[0,0,1]
	s_waitcnt lgkmcnt(0)
	v_pk_fma_f32 v[34:35], v[30:31], v[38:39], v[70:71] op_sel_hi:[1,0,1] neg_lo:[0,0,1] neg_hi:[0,0,1]
	global_load_dwordx4 v[28:31], v[140:141], off
	v_pk_fma_f32 v[2:3], v[2:3], v[38:39], v[44:45] op_sel_hi:[1,0,1] neg_lo:[0,0,1] neg_hi:[0,0,1]
	v_pk_mul_f32 v[42:43], v[0:1], v[0:1]
	v_pk_mul_f32 v[44:45], v[2:3], v[2:3]
	v_add_f32_e32 v33, v42, v43
	v_pk_fma_f32 v[4:5], v[4:5], v[38:39], v[46:47] op_sel_hi:[1,0,1] neg_lo:[0,0,1] neg_hi:[0,0,1]
	v_add_f32_e32 v33, v33, v44
	v_pk_mul_f32 v[46:47], v[4:5], v[4:5]
	v_add_f32_e32 v33, v33, v45
	v_pk_fma_f32 v[6:7], v[6:7], v[38:39], v[40:41] op_sel_hi:[1,0,1] neg_lo:[0,0,1] neg_hi:[0,0,1]
	v_add_f32_e32 v33, v33, v46
	v_pk_mul_f32 v[40:41], v[6:7], v[6:7]
	v_add_f32_e32 v33, v33, v47
	v_pk_fma_f32 v[8:9], v[8:9], v[38:39], v[48:49] op_sel_hi:[1,0,1] neg_lo:[0,0,1] neg_hi:[0,0,1]
	v_add_f32_e32 v33, v33, v40
	v_pk_mul_f32 v[48:49], v[8:9], v[8:9]
	v_add_f32_e32 v33, v33, v41
	v_pk_fma_f32 v[10:11], v[10:11], v[38:39], v[50:51] op_sel_hi:[1,0,1] neg_lo:[0,0,1] neg_hi:[0,0,1]
	v_add_f32_e32 v33, v33, v48
	v_pk_mul_f32 v[50:51], v[10:11], v[10:11]
	v_add_f32_e32 v33, v33, v49
	v_pk_fma_f32 v[12:13], v[12:13], v[38:39], v[52:53] op_sel_hi:[1,0,1] neg_lo:[0,0,1] neg_hi:[0,0,1]
	v_add_f32_e32 v33, v33, v50
	v_pk_mul_f32 v[52:53], v[12:13], v[12:13]
	v_add_f32_e32 v33, v33, v51
	v_pk_fma_f32 v[14:15], v[14:15], v[38:39], v[54:55] op_sel_hi:[1,0,1] neg_lo:[0,0,1] neg_hi:[0,0,1]
	v_add_f32_e32 v33, v33, v52
	v_pk_mul_f32 v[54:55], v[14:15], v[14:15]
	v_mov_b32_e32 v69, v36
	v_add_f32_e32 v33, v33, v53
	v_pk_fma_f32 v[16:17], v[16:17], v[38:39], v[68:69] op_sel_hi:[1,0,1] neg_lo:[0,0,1] neg_hi:[0,0,1]
	v_add_f32_e32 v33, v33, v54
	v_mov_b32_e32 v74, v37
	v_mov_b32_e32 v75, v56
	v_pk_mul_f32 v[36:37], v[16:17], v[16:17]
	v_add_f32_e32 v33, v33, v55
	v_pk_fma_f32 v[18:19], v[18:19], v[38:39], v[74:75] op_sel_hi:[1,0,1] neg_lo:[0,0,1] neg_hi:[0,0,1]
	v_add_f32_e32 v33, v33, v36
	v_pk_mul_f32 v[74:75], v[18:19], v[18:19]
	v_mov_b32_e32 v56, v57
	v_mov_b32_e32 v57, v58
	v_add_f32_e32 v33, v33, v37
	v_pk_fma_f32 v[20:21], v[20:21], v[38:39], v[56:57] op_sel_hi:[1,0,1] neg_lo:[0,0,1] neg_hi:[0,0,1]
	v_add_f32_e32 v33, v33, v74
	v_mov_b32_e32 v68, v59
	v_mov_b32_e32 v69, v62
	v_pk_mul_f32 v[56:57], v[20:21], v[20:21]
	v_add_f32_e32 v33, v33, v75
	v_pk_fma_f32 v[22:23], v[22:23], v[38:39], v[68:69] op_sel_hi:[1,0,1] neg_lo:[0,0,1] neg_hi:[0,0,1]
	v_add_f32_e32 v33, v33, v56
	v_pk_mul_f32 v[68:69], v[22:23], v[22:23]
	v_mov_b32_e32 v59, v60
	v_mov_b32_e32 v60, v63
	v_mov_b32_e32 v61, v64
	v_add_f32_e32 v33, v33, v57
	v_mov_b32_e32 v58, v65
	v_pk_fma_f32 v[24:25], v[24:25], v[38:39], v[60:61] op_sel_hi:[1,0,1] neg_lo:[0,0,1] neg_hi:[0,0,1]
	v_add_f32_e32 v33, v33, v68
	v_pk_fma_f32 v[26:27], v[26:27], v[38:39], v[58:59] op_sel_hi:[1,0,1] neg_lo:[0,0,1] neg_hi:[0,0,1]
	v_pk_mul_f32 v[38:39], v[24:25], v[24:25]
	v_add_f32_e32 v33, v33, v69
	v_add_f32_e32 v33, v33, v38
	v_pk_mul_f32 v[58:59], v[26:27], v[26:27]
	v_add_f32_e32 v33, v33, v39
	v_add_f32_e32 v33, v33, v58
	v_pk_mul_f32 v[72:73], v[66:67], v[66:67]
	v_add_f32_e32 v33, v33, v59
	v_add_f32_e32 v33, v33, v72
	v_pk_mul_f32 v[70:71], v[34:35], v[34:35]
	v_add_f32_e32 v33, v33, v73
	v_add_f32_e32 v33, v33, v70
	v_add_f32_e32 v36, v33, v71
	ds_bpermute_b32 v37, v82, v36
	v_sub_f32_e32 v38, 1.0, v32
	v_lshlrev_b64 v[32:33], 11, v[76:77]
	v_lshl_add_u64 v[32:33], s[52:53], 0, v[32:33]
	s_lshl_b32 s60, s14, 1
	s_waitcnt lgkmcnt(0)
	v_add_f32_e32 v36, v36, v37
	v_fmamk_f32 v36, v36, 0x3c800000, v225
	v_mul_f32_e32 v37, 0x4b800000, v36
	v_cmp_gt_f32_e32 vcc, s6, v36
	v_lshl_add_u64 v[32:33], v[32:33], 0, s[60:61]
	v_lshlrev_b32_e32 v128, 1, v110
	v_cndmask_b32_e32 v36, v36, v37, vcc
	v_rsq_f32_e32 v36, v36
	v_lshl_add_u64 v[32:33], v[32:33], 0, v[128:129]
	v_mul_f32_e32 v37, 0x45800000, v36
	v_cndmask_b32_e32 v36, v36, v37, vcc
	v_mul_f32_e32 v36, v38, v36
	v_mul_f32_e32 v0, v0, v36
	v_mul_f32_e32 v1, v1, v36
	v_mul_f32_e32 v2, v2, v36
	v_mul_f32_e32 v3, v3, v36
	s_waitcnt vmcnt(0)
	v_pk_mul_f32 v[0:1], v[28:29], v[0:1]
	v_pk_mul_f32 v[2:3], v[30:31], v[2:3]
	v_cvt_pk_bf16_f32 v0, v0, v1
	v_cvt_pk_bf16_f32 v1, v2, v3
	global_store_dwordx2 v[32:33], v[0:1], off
	global_load_dwordx4 v[0:3], v[140:141], off offset:32
	v_mul_f32_e32 v4, v4, v36
	v_mul_f32_e32 v5, v5, v36
	v_mul_f32_e32 v6, v6, v36
	v_mul_f32_e32 v7, v7, v36
	s_waitcnt vmcnt(0)
	v_pk_mul_f32 v[0:1], v[0:1], v[4:5]
	v_pk_mul_f32 v[2:3], v[2:3], v[6:7]
	v_cvt_pk_bf16_f32 v0, v0, v1
	v_cvt_pk_bf16_f32 v1, v2, v3
	global_store_dwordx2 v[32:33], v[0:1], off offset:16
	global_load_dwordx4 v[0:3], v[140:141], off offset:64
	v_mul_f32_e32 v4, v8, v36
	v_mul_f32_e32 v5, v9, v36
	v_mul_f32_e32 v6, v10, v36
	v_mul_f32_e32 v7, v11, v36
	s_waitcnt vmcnt(0)
	v_pk_mul_f32 v[0:1], v[0:1], v[4:5]
	v_pk_mul_f32 v[2:3], v[2:3], v[6:7]
	v_cvt_pk_bf16_f32 v0, v0, v1
	v_cvt_pk_bf16_f32 v1, v2, v3
	global_store_dwordx2 v[32:33], v[0:1], off offset:32
	global_load_dwordx4 v[0:3], v[140:141], off offset:96
	v_mul_f32_e32 v4, v12, v36
	v_mul_f32_e32 v5, v13, v36
	v_mul_f32_e32 v6, v14, v36
	v_mul_f32_e32 v7, v15, v36
	s_waitcnt vmcnt(0)
	v_pk_mul_f32 v[0:1], v[0:1], v[4:5]
	v_pk_mul_f32 v[2:3], v[2:3], v[6:7]
	v_cvt_pk_bf16_f32 v0, v0, v1
	v_cvt_pk_bf16_f32 v1, v2, v3
	global_store_dwordx2 v[32:33], v[0:1], off offset:48
	global_load_dwordx4 v[0:3], v[140:141], off offset:128
	v_mul_f32_e32 v4, v16, v36
	v_mul_f32_e32 v5, v17, v36
	v_mul_f32_e32 v6, v18, v36
	v_mul_f32_e32 v7, v19, v36
	s_waitcnt vmcnt(0)
	v_pk_mul_f32 v[0:1], v[0:1], v[4:5]
	v_pk_mul_f32 v[2:3], v[2:3], v[6:7]
	v_cvt_pk_bf16_f32 v0, v0, v1
	v_cvt_pk_bf16_f32 v1, v2, v3
	global_store_dwordx2 v[32:33], v[0:1], off offset:64
	global_load_dwordx4 v[0:3], v[140:141], off offset:160
	v_mul_f32_e32 v4, v20, v36
	v_mul_f32_e32 v5, v21, v36
	v_mul_f32_e32 v6, v22, v36
	v_mul_f32_e32 v7, v23, v36
	s_waitcnt vmcnt(0)
	v_pk_mul_f32 v[0:1], v[0:1], v[4:5]
	v_pk_mul_f32 v[2:3], v[2:3], v[6:7]
	v_cvt_pk_bf16_f32 v0, v0, v1
	v_cvt_pk_bf16_f32 v1, v2, v3
	global_store_dwordx2 v[32:33], v[0:1], off offset:80
	global_load_dwordx4 v[0:3], v[140:141], off offset:192
	v_mul_f32_e32 v4, v24, v36
	v_mul_f32_e32 v5, v25, v36
	v_mul_f32_e32 v6, v26, v36
	v_mul_f32_e32 v7, v27, v36
	s_waitcnt vmcnt(0)
	v_pk_mul_f32 v[0:1], v[4:5], v[0:1]
	v_pk_mul_f32 v[2:3], v[6:7], v[2:3]
	v_cvt_pk_bf16_f32 v0, v0, v1
	v_cvt_pk_bf16_f32 v1, v2, v3
	global_store_dwordx2 v[32:33], v[0:1], off offset:96
	global_load_dwordx4 v[0:3], v[140:141], off offset:224
	v_mul_f32_e32 v4, v66, v36
	v_mul_f32_e32 v5, v67, v36
	v_mul_f32_e32 v6, v34, v36
	v_mul_f32_e32 v7, v35, v36
	s_waitcnt vmcnt(0)
	v_pk_mul_f32 v[0:1], v[4:5], v[0:1]
	v_pk_mul_f32 v[2:3], v[6:7], v[2:3]
	v_cvt_pk_bf16_f32 v0, v0, v1
	v_cvt_pk_bf16_f32 v1, v2, v3
	global_store_dwordx2 v[32:33], v[0:1], off offset:112
	s_branch .LBB0_800

.LBB0_883:
	s_or_b64 exec, exec, s[4:5]
	s_and_b32 s4, s9, 1
	s_mul_i32 s5, s4, 0x2400
	v_add_u32_e32 v153, s5, v167
	ds_read_b128 v[32:35], v153
	ds_read_b128 v[36:39], v153 offset:32
	s_xor_b32 s6, s4, 1
	s_mulk_i32 s6, 0x2400
	s_waitcnt lgkmcnt(1)
	v_mfma_f32_32x32x16_bf16 v[48:63], v[32:35], v[76:79], 0
	s_waitcnt lgkmcnt(0)
	v_mfma_f32_32x32x16_bf16 v[48:63], v[36:39], v[72:75], v[48:63]
	ds_read_b128 v[32:35], v153 offset:64
	ds_read_b128 v[36:39], v153 offset:96
	s_waitcnt lgkmcnt(1)
	v_mfma_f32_32x32x16_bf16 v[48:63], v[32:35], v[68:71], v[48:63]
	ds_read_b128 v[32:35], v153 offset:4608
	ds_read_b128 v[130:133], v153 offset:4640
	s_waitcnt lgkmcnt(2)
	v_mfma_f32_32x32x16_bf16 v[48:63], v[36:39], v[64:67], v[48:63]
	s_waitcnt lgkmcnt(1)
	v_mfma_f32_32x32x16_bf16 v[32:47], v[32:35], v[76:79], 0
	s_nop 9
	v_max_f32_e32 v93, v49, v49
	v_max_f32_e32 v95, v48, v48
	v_max_f32_e32 v93, v95, v93
	v_max3_f32 v93, v93, v50, v51
	v_max3_f32 v93, v93, v52, v53
	v_max3_f32 v93, v93, v54, v55
	v_max3_f32 v93, v93, v56, v57
	s_waitcnt lgkmcnt(0)
	v_mfma_f32_32x32x16_bf16 v[32:47], v[130:133], v[72:75], v[32:47]
	ds_read_b128 v[130:133], v153 offset:4672
	ds_read_b128 v[154:157], v153 offset:4704
	v_max3_f32 v93, v93, v58, v59
	v_max3_f32 v93, v93, v60, v61
	v_max3_f32 v93, v93, v62, v63
	s_waitcnt lgkmcnt(1)
	v_mfma_f32_32x32x16_bf16 v[32:47], v[130:133], v[68:71], v[32:47]
	s_waitcnt lgkmcnt(0)
	v_mfma_f32_32x32x16_bf16 v[32:47], v[154:157], v[64:67], v[32:47]
	s_nop 11
	v_max3_f32 v93, v93, v32, v33
	v_max3_f32 v93, v93, v34, v35
	v_max3_f32 v93, v93, v36, v37
	v_max3_f32 v93, v93, v38, v39
	v_max3_f32 v93, v93, v40, v41
	v_max3_f32 v93, v93, v42, v43
	v_max3_f32 v93, v93, v44, v45
	v_max3_f32 v93, v93, v46, v47
	ds_bpermute_b32 v95, v90, v93
	s_waitcnt lgkmcnt(0)
	v_max3_f32 v93, v94, v93, v95
	v_sub_f32_e32 v32, v32, v93
	v_sub_f32_e32 v130, v94, v93
	v_exp_f32_e32 v94, v32
	v_sub_f32_e32 v32, v33, v93
	v_exp_f32_e32 v95, v32
	v_sub_f32_e32 v32, v34, v93
	v_exp_f32_e32 v107, v32
	v_sub_f32_e32 v32, v35, v93
	v_exp_f32_e32 v128, v32
	v_sub_f32_e32 v32, v36, v93
	v_exp_f32_e32 v132, v32
	v_sub_f32_e32 v32, v37, v93
	v_exp_f32_e32 v37, v32
	ds_read_b128 v[32:35], v153 offset:18432
	v_sub_f32_e32 v48, v48, v93
	v_sub_f32_e32 v49, v49, v93
	v_sub_f32_e32 v50, v50, v93
	v_sub_f32_e32 v51, v51, v93
	v_sub_f32_e32 v52, v52, v93
	v_sub_f32_e32 v53, v53, v93
	v_sub_f32_e32 v54, v54, v93
	v_sub_f32_e32 v55, v55, v93
	v_exp_f32_e32 v48, v48
	v_exp_f32_e32 v49, v49
	v_exp_f32_e32 v50, v50
	v_exp_f32_e32 v51, v51
	v_exp_f32_e32 v52, v52
	v_exp_f32_e32 v53, v53
	v_exp_f32_e32 v54, v54
	v_exp_f32_e32 v55, v55
	v_exp_f32_e32 v36, v130
	ds_read_b128 v[158:161], v153 offset:23040
	ds_read_b128 v[180:183], v153 offset:18464
	v_cvt_pk_bf16_f32 v154, v48, v49
	v_cvt_pk_bf16_f32 v155, v50, v51
	v_mul_f32_e32 v16, v16, v36
	v_mul_f32_e32 v17, v17, v36
	v_mul_f32_e32 v18, v18, v36
	v_mul_f32_e32 v19, v19, v36
	v_mul_f32_e32 v20, v20, v36
	v_mul_f32_e32 v21, v21, v36
	v_mul_f32_e32 v22, v22, v36
	v_mul_f32_e32 v23, v23, v36
	v_mul_f32_e32 v24, v24, v36
	v_mul_f32_e32 v25, v25, v36
	v_mul_f32_e32 v26, v26, v36
	v_mul_f32_e32 v27, v27, v36
	v_mul_f32_e32 v28, v28, v36
	v_mul_f32_e32 v29, v29, v36
	v_mul_f32_e32 v30, v30, v36
	v_mul_f32_e32 v31, v31, v36
	v_cvt_pk_bf16_f32 v156, v52, v53
	v_cvt_pk_bf16_f32 v157, v54, v55
	v_mul_f32_e32 v0, v0, v36
	v_mul_f32_e32 v1, v1, v36
	v_mul_f32_e32 v2, v2, v36
	v_mul_f32_e32 v3, v3, v36
	s_waitcnt lgkmcnt(2)
	v_mfma_f32_32x32x16_bf16 v[16:31], v[32:35], v[154:157], v[16:31]
	v_mul_f32_e64 v4, v4, v36
	v_mul_f32_e64 v5, v5, v36
	v_mul_f32_e64 v6, v6, v36
	v_mul_f32_e64 v7, v7, v36
	v_mul_f32_e64 v8, v8, v36
	v_mul_f32_e64 v9, v9, v36
	v_mul_f32_e32 v10, v10, v36
	v_mul_f32_e32 v11, v11, v36
	v_mul_f32_e32 v12, v12, v36
	v_mul_f32_e32 v13, v13, v36
	v_mul_f32_e32 v14, v14, v36
	v_mul_f32_e32 v15, v15, v36
	ds_read_b128 v[32:35], v153 offset:23072
	v_sub_f32_e32 v56, v56, v93
	s_waitcnt lgkmcnt(2)
	v_mfma_f32_32x32x16_bf16 v[0:15], v[158:161], v[154:157], v[0:15]
	v_sub_f32_e32 v57, v57, v93
	v_sub_f32_e32 v58, v58, v93
	v_sub_f32_e32 v59, v59, v93
	v_sub_f32_e32 v60, v60, v93
	v_sub_f32_e32 v61, v61, v93
	v_sub_f32_e32 v62, v62, v93
	v_sub_f32_e32 v63, v63, v93
	v_exp_f32_e32 v56, v56
	v_exp_f32_e32 v57, v57
	v_exp_f32_e32 v58, v58
	v_exp_f32_e32 v59, v59
	v_exp_f32_e32 v60, v60
	v_exp_f32_e32 v61, v61
	v_exp_f32_e32 v62, v62
	v_exp_f32_e32 v63, v63
	v_cvt_pk_bf16_f32 v154, v56, v57
	v_cvt_pk_bf16_f32 v155, v58, v59
	v_cvt_pk_bf16_f32 v156, v60, v61
	v_cvt_pk_bf16_f32 v157, v62, v63
	ds_read_b128 v[158:161], v153 offset:18496
	v_sub_f32_e32 v38, v38, v93
	s_waitcnt lgkmcnt(2)
	v_mfma_f32_32x32x16_bf16 v[16:31], v[180:183], v[154:157], v[16:31]
	v_sub_f32_e32 v39, v39, v93
	v_exp_f32_e32 v38, v38
	v_exp_f32_e32 v39, v39
	v_sub_f32_e32 v40, v40, v93
	v_sub_f32_e32 v41, v41, v93
	v_sub_f32_e32 v42, v42, v93
	v_sub_f32_e32 v43, v43, v93
	s_waitcnt lgkmcnt(1)
	v_mfma_f32_32x32x16_bf16 v[0:15], v[32:35], v[154:157], v[0:15]
	ds_read_b128 v[154:157], v153 offset:23104
	ds_read_b128 v[180:183], v153 offset:18528
	v_cvt_pk_bf16_f32 v32, v94, v95
	v_cvt_pk_bf16_f32 v33, v107, v128
	v_cvt_pk_bf16_f32 v34, v132, v37
	v_cvt_pk_bf16_f32 v35, v38, v39
	v_sub_f32_e32 v44, v44, v93
	v_sub_f32_e32 v45, v45, v93
	s_waitcnt lgkmcnt(2)
	v_mfma_f32_32x32x16_bf16 v[16:31], v[158:161], v[32:35], v[16:31]
	ds_read_b128 v[158:161], v153 offset:23136
	v_sub_f32_e32 v46, v46, v93
	v_exp_f32_e32 v40, v40
	v_exp_f32_e32 v41, v41
	v_exp_f32_e32 v42, v42
	v_exp_f32_e32 v43, v43
	v_exp_f32_e32 v44, v44
	s_waitcnt lgkmcnt(2)
	v_mfma_f32_32x32x16_bf16 v[0:15], v[154:157], v[32:35], v[0:15]
	v_sub_f32_e32 v32, v47, v93
	v_exp_f32_e32 v47, v32
	global_load_dwordx4 v[32:35], v[88:89], off
	v_exp_f32_e32 v45, v45
	v_exp_f32_e32 v46, v46
	v_cvt_pk_bf16_f32 v154, v40, v41
	v_cvt_pk_bf16_f32 v155, v42, v43
	v_cvt_pk_bf16_f32 v156, v44, v45
	v_cvt_pk_bf16_f32 v157, v46, v47
	s_waitcnt lgkmcnt(1)
	s_nop 0
	v_mfma_f32_32x32x16_bf16 v[16:31], v[180:183], v[154:157], v[16:31]
	s_waitcnt lgkmcnt(0)
	v_mfma_f32_32x32x16_bf16 v[0:15], v[158:161], v[154:157], v[0:15]
	s_and_saveexec_b64 s[4:5], s[0:1]
	s_cbranch_execz .LBB0_885
	v_add_u32_e32 v130, s6, v91
	s_waitcnt vmcnt(1)
	ds_write_b128 v130, v[80:83]
.LBB0_885:
	s_or_b64 exec, exec, s[4:5]
	v_add_f32_e32 v48, 0, v48
	v_add_f32_e32 v48, v49, v48
	v_add_f32_e32 v48, v50, v48
	v_add_f32_e32 v48, v51, v48
	v_add_f32_e32 v48, v52, v48
	v_add_f32_e32 v48, v53, v48
	v_add_f32_e32 v48, v54, v48
	v_add_f32_e32 v48, v55, v48
	v_add_f32_e32 v48, v56, v48
	v_add_f32_e32 v48, v57, v48
	v_add_f32_e32 v48, v58, v48
	v_add_f32_e32 v48, v59, v48
	v_add_f32_e32 v48, v60, v48
	v_add_f32_e32 v48, v61, v48
	v_add_f32_e32 v48, v62, v48
	v_add_f32_e32 v48, v63, v48
	v_add_f32_e32 v48, v94, v48
	v_add_f32_e32 v48, v95, v48
	v_add_f32_e32 v48, v107, v48
	v_add_f32_e32 v48, v128, v48
	v_add_f32_e32 v48, v132, v48
	v_add_f32_e32 v37, v37, v48
	v_add_f32_e32 v37, v38, v37
	v_add_f32_e32 v37, v39, v37
	v_add_f32_e32 v37, v40, v37
	v_add_f32_e32 v37, v41, v37
	v_add_f32_e32 v37, v42, v37
	v_add_f32_e32 v37, v43, v37
	v_add_f32_e32 v37, v44, v37
	v_add_f32_e32 v37, v45, v37
	v_add_f32_e32 v37, v46, v37
	v_add_f32_e32 v94, v47, v37
	s_add_i32 s9, s9, 1
	s_mov_b64 s[4:5], 0x4000
	v_fmac_f32_e32 v94, v92, v36
	v_add_u32_e32 v36, s6, v166
	v_lshl_add_u64 v[86:87], v[86:87], 0, s[4:5]
	s_cmp_eq_u32 s16, s9
	v_lshl_add_u64 v[88:89], v[88:89], 0, s[34:35]
	s_waitcnt vmcnt(0)
	ds_write_b128 v36, v[32:35] offset:18432
	s_waitcnt lgkmcnt(0)
	s_barrier
	s_cbranch_scc0 .LBB0_881
	s_bitcmp1_b32 s16, 0
	s_cselect_b32 s4, 0x2400, 0
	v_add_u32_e32 v80, s4, v167
	ds_read_b128 v[32:35], v80
	s_lshl_b32 s60, s8, 1
	v_lshlrev_b32_e32 v128, 1, v110
	s_waitcnt lgkmcnt(0)
	v_mfma_f32_32x32x16_bf16 v[48:63], v[32:35], v[76:79], 0
	ds_read_b128 v[32:35], v80 offset:32
	s_waitcnt lgkmcnt(0)
	v_mfma_f32_32x32x16_bf16 v[48:63], v[32:35], v[72:75], v[48:63]
	ds_read_b128 v[32:35], v80 offset:64
	s_waitcnt lgkmcnt(0)
	v_mfma_f32_32x32x16_bf16 v[48:63], v[32:35], v[68:71], v[48:63]
	ds_read_b128 v[32:35], v80 offset:96
	s_waitcnt lgkmcnt(0)
	v_mfma_f32_32x32x16_bf16 v[48:63], v[32:35], v[64:67], v[48:63]
	ds_read_b128 v[32:35], v80 offset:4608
	s_waitcnt lgkmcnt(0)
	v_mfma_f32_32x32x16_bf16 v[32:47], v[32:35], v[76:79], 0
	ds_read_b128 v[76:79], v80 offset:4640
	s_nop 7
	v_max_f32_e32 v81, v49, v49
	v_max_f32_e32 v82, v48, v48
	v_max_f32_e32 v81, v82, v81
	s_waitcnt lgkmcnt(0)
	v_mfma_f32_32x32x16_bf16 v[32:47], v[76:79], v[72:75], v[32:47]
	ds_read_b128 v[72:75], v80 offset:4672
	ds_read_b128 v[76:79], v80 offset:4704
	s_waitcnt lgkmcnt(1)
	v_mfma_f32_32x32x16_bf16 v[32:47], v[72:75], v[68:71], v[32:47]
	v_max3_f32 v68, v81, v50, v51
	v_max3_f32 v68, v68, v52, v53
	v_max3_f32 v68, v68, v54, v55
	v_max3_f32 v68, v68, v56, v57
	v_max3_f32 v68, v68, v58, v59
	v_max3_f32 v68, v68, v60, v61
	v_max3_f32 v68, v68, v62, v63
	s_waitcnt lgkmcnt(0)
	v_mfma_f32_32x32x16_bf16 v[32:47], v[76:79], v[64:67], v[32:47]
	s_nop 11
	v_max3_f32 v64, v68, v32, v33
	v_max3_f32 v64, v64, v34, v35
	v_max3_f32 v64, v64, v36, v37
	v_max3_f32 v64, v64, v38, v39
	v_max3_f32 v64, v64, v40, v41
	v_max3_f32 v64, v64, v42, v43
	v_max3_f32 v64, v64, v44, v45
	v_max3_f32 v64, v64, v46, v47
	ds_bpermute_b32 v65, v90, v64
	s_waitcnt lgkmcnt(0)
	v_max3_f32 v64, v93, v64, v65
	v_sub_f32_e32 v48, v48, v64
	v_sub_f32_e32 v49, v49, v64
	v_exp_f32_e32 v48, v48
	v_sub_f32_e32 v50, v50, v64
	v_exp_f32_e32 v49, v49
	v_sub_f32_e32 v51, v51, v64
	v_exp_f32_e32 v50, v50
	v_sub_f32_e32 v52, v52, v64
	v_sub_f32_e32 v56, v56, v64
	v_exp_f32_e32 v51, v51
	v_sub_f32_e32 v53, v53, v64
	v_exp_f32_e32 v52, v52
	v_exp_f32_e32 v66, v56
	v_add_f32_e32 v56, 0, v48
	v_sub_f32_e32 v54, v54, v64
	v_exp_f32_e32 v53, v53
	v_add_f32_e32 v56, v49, v56
	v_sub_f32_e32 v55, v55, v64
	v_exp_f32_e32 v54, v54
	v_add_f32_e32 v56, v50, v56
	v_exp_f32_e32 v55, v55
	v_add_f32_e32 v56, v51, v56
	v_sub_f32_e32 v57, v57, v64
	v_add_f32_e32 v56, v52, v56
	v_sub_f32_e32 v58, v58, v64
	v_exp_f32_e32 v57, v57
	v_add_f32_e32 v56, v53, v56
	v_sub_f32_e32 v59, v59, v64
	v_exp_f32_e32 v58, v58
	v_add_f32_e32 v56, v54, v56
	v_sub_f32_e32 v60, v60, v64
	v_exp_f32_e32 v59, v59
	v_add_f32_e32 v56, v55, v56
	v_sub_f32_e32 v61, v61, v64
	v_exp_f32_e32 v60, v60
	v_add_f32_e32 v56, v66, v56
	v_sub_f32_e32 v62, v62, v64
	v_exp_f32_e32 v61, v61
	v_add_f32_e32 v56, v57, v56
	v_sub_f32_e32 v63, v63, v64
	v_exp_f32_e32 v62, v62
	v_add_f32_e32 v56, v58, v56
	v_exp_f32_e32 v63, v63
	v_add_f32_e32 v56, v59, v56
	v_sub_f32_e32 v32, v32, v64
	v_add_f32_e32 v56, v60, v56
	v_exp_f32_e32 v67, v32
	v_sub_f32_e32 v32, v33, v64
	v_add_f32_e32 v56, v61, v56
	v_exp_f32_e32 v68, v32
	v_sub_f32_e32 v32, v34, v64
	v_add_f32_e32 v56, v62, v56
	v_exp_f32_e32 v69, v32
	v_sub_f32_e32 v33, v35, v64
	v_add_f32_e32 v32, v63, v56
	v_exp_f32_e32 v70, v33
	v_sub_f32_e32 v33, v36, v64
	v_add_f32_e32 v32, v67, v32
	v_exp_f32_e32 v71, v33
	v_sub_f32_e32 v33, v37, v64
	v_add_f32_e32 v32, v68, v32
	v_exp_f32_e32 v72, v33
	v_sub_f32_e32 v33, v38, v64
	v_add_f32_e32 v32, v69, v32
	v_exp_f32_e32 v73, v33
	v_add_f32_e32 v32, v70, v32
	v_add_f32_e32 v32, v71, v32
	v_add_f32_e32 v32, v72, v32
	v_sub_f32_e32 v65, v93, v64
	v_add_f32_e32 v74, v73, v32
	v_sub_f32_e32 v32, v39, v64
	v_exp_f32_e32 v56, v65
	v_exp_f32_e32 v65, v32
	ds_read_b128 v[32:35], v80 offset:18432
	v_cvt_pk_bf16_f32 v36, v48, v49
	v_cvt_pk_bf16_f32 v37, v50, v51
	v_cvt_pk_bf16_f32 v38, v52, v53
	v_cvt_pk_bf16_f32 v39, v54, v55
	ds_read_b128 v[48:51], v80 offset:23040
	ds_read_b128 v[52:55], v80 offset:18464
	v_mul_f32_e32 v30, v30, v56
	v_mul_f32_e32 v31, v31, v56
	v_mul_f32_e32 v28, v28, v56
	v_mul_f32_e32 v29, v29, v56
	v_mul_f32_e32 v26, v26, v56
	v_mul_f32_e32 v27, v27, v56
	v_mul_f32_e32 v24, v24, v56
	v_mul_f32_e32 v25, v25, v56
	v_mul_f32_e32 v22, v22, v56
	v_mul_f32_e32 v23, v23, v56
	v_mul_f32_e32 v20, v20, v56
	v_mul_f32_e32 v21, v21, v56
	v_mul_f32_e32 v18, v18, v56
	v_mul_f32_e32 v19, v19, v56
	v_mul_f32_e32 v16, v16, v56
	v_mul_f32_e32 v17, v17, v56
	v_mul_f32_e32 v14, v14, v56
	v_mul_f32_e32 v15, v15, v56
	v_mul_f32_e32 v12, v12, v56
	v_mul_f32_e32 v13, v13, v56
	s_waitcnt lgkmcnt(2)
	v_mfma_f32_32x32x16_bf16 v[16:31], v[32:35], v[36:39], v[16:31]
	v_mul_f32_e64 v10, v10, v56
	v_mul_f32_e64 v11, v11, v56
	v_mul_f32_e64 v8, v8, v56
	v_mul_f32_e64 v9, v9, v56
	v_mul_f32_e64 v6, v6, v56
	v_mul_f32_e64 v7, v7, v56
	v_mul_f32_e32 v4, v4, v56
	v_mul_f32_e32 v5, v5, v56
	v_mul_f32_e32 v2, v2, v56
	v_mul_f32_e32 v3, v3, v56
	v_mul_f32_e32 v0, v0, v56
	v_mul_f32_e32 v1, v1, v56
	ds_read_b128 v[32:35], v80 offset:23072
	v_sub_f32_e32 v40, v40, v64
	s_waitcnt lgkmcnt(2)
	v_mfma_f32_32x32x16_bf16 v[0:15], v[48:51], v[36:39], v[0:15]
	v_exp_f32_e32 v75, v40
	v_sub_f32_e32 v36, v41, v64
	v_exp_f32_e32 v76, v36
	v_cvt_pk_bf16_f32 v36, v66, v57
	v_cvt_pk_bf16_f32 v37, v58, v59
	v_cvt_pk_bf16_f32 v38, v60, v61
	v_cvt_pk_bf16_f32 v39, v62, v63
	v_sub_f32_e32 v40, v42, v64
	ds_read_b128 v[48:51], v80 offset:18496
	s_waitcnt lgkmcnt(2)
	v_mfma_f32_32x32x16_bf16 v[16:31], v[52:55], v[36:39], v[16:31]
	v_exp_f32_e32 v52, v40
	v_add_f32_e32 v40, v65, v74
	v_add_f32_e32 v40, v75, v40
	v_add_f32_e32 v40, v76, v40
	v_add_f32_e32 v53, v52, v40
	v_sub_f32_e32 v54, v43, v64
	v_exp_f32_e32 v54, v54
	s_waitcnt lgkmcnt(1)
	v_mfma_f32_32x32x16_bf16 v[0:15], v[32:35], v[36:39], v[0:15]
	ds_read_b128 v[36:39], v80 offset:23104
	ds_read_b128 v[40:43], v80 offset:18528
	v_sub_f32_e32 v44, v44, v64
	v_cvt_pk_bf16_f32 v32, v67, v68
	v_cvt_pk_bf16_f32 v33, v69, v70
	v_cvt_pk_bf16_f32 v34, v71, v72
	v_cvt_pk_bf16_f32 v35, v73, v65
	v_exp_f32_e32 v44, v44
	v_sub_f32_e32 v45, v45, v64
	s_waitcnt lgkmcnt(2)
	v_mfma_f32_32x32x16_bf16 v[16:31], v[48:51], v[32:35], v[16:31]
	v_exp_f32_e32 v45, v45
	v_sub_f32_e32 v46, v46, v64
	ds_read_b128 v[48:51], v80 offset:23136
	s_waitcnt lgkmcnt(0)
	s_barrier
	v_mfma_f32_32x32x16_bf16 v[0:15], v[36:39], v[32:35], v[0:15]
	v_sub_f32_e32 v32, v47, v64
	v_exp_f32_e32 v36, v46
	v_exp_f32_e32 v37, v32
	v_add_f32_e32 v38, v54, v53
	v_add_f32_e32 v38, v44, v38
	v_add_f32_e32 v38, v45, v38
	v_cvt_pk_bf16_f32 v35, v36, v37
	v_add_f32_e32 v36, v36, v38
	v_add_f32_e32 v36, v37, v36
	v_fmac_f32_e32 v36, v94, v56
	ds_bpermute_b32 v37, v90, v36
	v_cvt_pk_bf16_f32 v32, v75, v76
	v_cvt_pk_bf16_f32 v33, v52, v54
	v_cvt_pk_bf16_f32 v34, v44, v45
	s_nop 1
	v_mfma_f32_32x32x16_bf16 v[16:31], v[40:43], v[32:35], v[16:31]
	v_mfma_f32_32x32x16_bf16 v[0:15], v[48:51], v[32:35], v[0:15]
	s_waitcnt lgkmcnt(0)
	v_add_f32_e32 v34, v36, v37
	v_div_scale_f32 v35, s[4:5], v34, v34, 1.0
	v_rcp_f32_e32 v36, v35
	v_lshlrev_b64 v[32:33], 11, v[84:85]
	v_lshl_add_u64 v[32:33], s[66:67], 0, v[32:33]
	v_lshl_add_u64 v[32:33], v[32:33], 0, s[60:61]
	v_fma_f32 v37, -v35, v36, 1.0
	v_fmac_f32_e32 v36, v37, v36
	v_div_scale_f32 v37, vcc, 1.0, v34, 1.0
	v_mul_f32_e32 v38, v37, v36
	v_fma_f32 v39, -v35, v38, v37
	v_fmac_f32_e32 v38, v39, v36
	v_fma_f32 v35, -v35, v38, v37
	v_div_fmas_f32 v35, v35, v36, v38
	v_div_fixup_f32 v34, v35, v34, 1.0
	v_mul_f32_e32 v16, v16, v34
	v_mul_f32_e32 v17, v17, v34
	v_mul_f32_e32 v18, v18, v34
	v_mul_f32_e32 v19, v19, v34
	v_cvt_pk_bf16_f32 v16, v16, v17
	v_cvt_pk_bf16_f32 v17, v18, v19
	v_lshl_add_u64 v[18:19], v[32:33], 0, v[128:129]
	s_mov_b64 s[4:5], 0x2d53900
	v_lshl_add_u64 v[32:33], v[18:19], 0, s[4:5]
	s_mov_b32 s4, 0x2d53000
	v_add_co_u32_e32 v18, vcc, s4, v18
	v_mul_f32_e32 v0, v0, v34
	v_mul_f32_e32 v1, v1, v34
	v_mul_f32_e32 v2, v2, v34
	v_mul_f32_e32 v3, v3, v34
	v_addc_co_u32_e32 v19, vcc, 0, v19, vcc
	v_cvt_pk_bf16_f32 v0, v0, v1
	v_cvt_pk_bf16_f32 v1, v2, v3
	global_store_dwordx2 v[18:19], v[16:17], off offset:2304
	v_mul_f32_e32 v16, v20, v34
	v_mul_f32_e32 v17, v21, v34
	v_mul_f32_e32 v18, v22, v34
	v_mul_f32_e32 v19, v23, v34
	global_store_dwordx2 v[32:33], v[0:1], off offset:64
	v_mul_f32_e32 v0, v4, v34
	v_mul_f32_e32 v1, v5, v34
	v_mul_f32_e32 v2, v6, v34
	v_mul_f32_e32 v3, v7, v34
	v_cvt_pk_bf16_f32 v16, v16, v17
	v_cvt_pk_bf16_f32 v17, v18, v19
	v_cvt_pk_bf16_f32 v0, v0, v1
	v_cvt_pk_bf16_f32 v1, v2, v3
	global_store_dwordx2 v[32:33], v[16:17], off offset:16
	v_mul_f32_e32 v16, v24, v34
	v_mul_f32_e32 v17, v25, v34
	v_mul_f32_e32 v18, v26, v34
	v_mul_f32_e32 v19, v27, v34
	global_store_dwordx2 v[32:33], v[0:1], off offset:80
	v_mul_f32_e32 v0, v8, v34
	v_mul_f32_e32 v1, v9, v34
	v_mul_f32_e32 v2, v10, v34
	v_mul_f32_e32 v3, v11, v34
	v_cvt_pk_bf16_f32 v16, v16, v17
	v_cvt_pk_bf16_f32 v17, v18, v19
	v_cvt_pk_bf16_f32 v0, v0, v1
	v_cvt_pk_bf16_f32 v1, v2, v3
	global_store_dwordx2 v[32:33], v[16:17], off offset:32
	v_mul_f32_e32 v16, v28, v34
	v_mul_f32_e32 v17, v29, v34
	v_mul_f32_e32 v18, v30, v34
	v_mul_f32_e32 v19, v31, v34
	global_store_dwordx2 v[32:33], v[0:1], off offset:96
	v_mul_f32_e32 v0, v12, v34
	v_mul_f32_e32 v1, v13, v34
	v_mul_f32_e32 v2, v14, v34
	v_mul_f32_e32 v3, v15, v34
	v_cvt_pk_bf16_f32 v16, v16, v17
	v_cvt_pk_bf16_f32 v17, v18, v19
	v_cvt_pk_bf16_f32 v0, v0, v1
	v_cvt_pk_bf16_f32 v1, v2, v3
	global_store_dwordx2 v[32:33], v[16:17], off offset:48
	global_store_dwordx2 v[32:33], v[0:1], off offset:112
	s_cbranch_execnz .LBB0_801
	s_branch .LBB0_850

.LBB0_906:
	s_or_b64 exec, exec, s[4:5]
	s_and_b32 s4, s6, 1
	s_mul_i32 s5, s4, 0x3400
	v_add_u32_e32 v118, s5, v113
	ds_read_b128 v[32:35], v118
	ds_read_b128 v[120:123], v118 offset:6688
	s_mul_i32 s5, s4, 0x2400
	s_xor_b32 s7, s4, 1
	s_mul_i32 s4, s7, 0x3400
	s_add_i32 s8, s4, 0
	s_waitcnt lgkmcnt(1)
	v_mfma_f32_32x32x16_bf16 v[48:63], v[32:35], v[84:87], 0
	ds_read_b128 v[32:35], v118 offset:32
	s_waitcnt lgkmcnt(0)
	v_mfma_f32_32x32x16_bf16 v[48:63], v[32:35], v[80:83], v[48:63]
	ds_read_b128 v[32:35], v118 offset:64
	s_waitcnt lgkmcnt(0)
	v_mfma_f32_32x32x16_bf16 v[48:63], v[32:35], v[76:79], v[48:63]
	ds_read_b128 v[32:35], v118 offset:96
	s_waitcnt lgkmcnt(0)
	v_mfma_f32_32x32x16_bf16 v[48:63], v[32:35], v[72:75], v[48:63]
	ds_read_b128 v[32:35], v118 offset:128
	s_waitcnt lgkmcnt(0)
	v_mfma_f32_32x32x16_bf16 v[48:63], v[32:35], v[68:71], v[48:63]
	ds_read_b128 v[32:35], v118 offset:160
	s_waitcnt lgkmcnt(0)
	v_mfma_f32_32x32x16_bf16 v[48:63], v[32:35], v[64:67], v[48:63]
	ds_read_b128 v[32:35], v118 offset:6656
	s_waitcnt lgkmcnt(0)
	v_mfma_f32_32x32x16_bf16 v[32:47], v[32:35], v[84:87], 0
	s_nop 8
	v_max_f32_e32 v128, v48, v48
	v_mfma_f32_32x32x16_bf16 v[32:47], v[120:123], v[80:83], v[32:47]
	ds_read_b128 v[120:123], v118 offset:6720
	s_waitcnt lgkmcnt(0)
	v_mfma_f32_32x32x16_bf16 v[32:47], v[120:123], v[76:79], v[32:47]
	ds_read_b128 v[120:123], v118 offset:6752
	s_waitcnt lgkmcnt(0)
	v_mfma_f32_32x32x16_bf16 v[32:47], v[120:123], v[72:75], v[32:47]
	ds_read_b128 v[120:123], v118 offset:6784
	ds_read_b128 v[124:127], v118 offset:6816
	v_max_f32_e32 v118, v49, v49
	v_max_f32_e32 v118, v128, v118
	v_max3_f32 v118, v118, v50, v51
	v_max3_f32 v118, v118, v52, v53
	v_max3_f32 v118, v118, v54, v55
	v_max3_f32 v118, v118, v56, v57
	s_waitcnt lgkmcnt(1)
	v_mfma_f32_32x32x16_bf16 v[32:47], v[120:123], v[68:71], v[32:47]
	v_max3_f32 v118, v118, v58, v59
	v_max3_f32 v118, v118, v60, v61
	v_max3_f32 v118, v118, v62, v63
	v_add_u32_e32 v128, s5, v106
	ds_read_b128 v[134:137], v128 offset:31232
	s_waitcnt lgkmcnt(1)
	v_mfma_f32_32x32x16_bf16 v[32:47], v[124:127], v[64:67], v[32:47]
	v_lshl_add_u64 v[124:125], s[60:61], 1, v[98:99]
	s_nop 10
	v_max3_f32 v118, v118, v32, v33
	v_max3_f32 v118, v118, v34, v35
	v_max3_f32 v118, v118, v36, v37
	v_max3_f32 v118, v118, v38, v39
	v_max3_f32 v118, v118, v40, v41
	v_max3_f32 v118, v118, v42, v43
	v_max3_f32 v118, v118, v44, v45
	v_max3_f32 v118, v118, v46, v47
	ds_bpermute_b32 v120, v105, v118
	s_waitcnt lgkmcnt(0)
	v_max3_f32 v118, v119, v118, v120
	v_sub_f32_e32 v32, v32, v118
	v_sub_f32_e32 v126, v119, v118
	v_exp_f32_e32 v119, v32
	v_sub_f32_e32 v32, v33, v118
	v_exp_f32_e32 v120, v32
	v_sub_f32_e32 v32, v34, v118
	v_exp_f32_e32 v121, v32
	v_sub_f32_e32 v32, v35, v118
	v_exp_f32_e32 v122, v32
	v_sub_f32_e32 v32, v36, v118
	v_exp_f32_e32 v123, v32
	v_sub_f32_e32 v32, v37, v118
	v_exp_f32_e32 v37, v32
	global_load_dwordx4 v[32:35], v[124:125], off
	v_exp_f32_e32 v36, v126
	ds_read_b128 v[124:127], v128 offset:26624
	v_sub_f32_e32 v48, v48, v118
	v_sub_f32_e32 v49, v49, v118
	v_sub_f32_e32 v50, v50, v118
	v_sub_f32_e32 v51, v51, v118
	v_sub_f32_e32 v52, v52, v118
	v_sub_f32_e32 v53, v53, v118
	v_sub_f32_e32 v54, v54, v118
	v_sub_f32_e32 v55, v55, v118
	v_exp_f32_e32 v48, v48
	v_exp_f32_e32 v49, v49
	v_exp_f32_e32 v50, v50
	v_exp_f32_e32 v51, v51
	v_exp_f32_e32 v52, v52
	v_exp_f32_e32 v53, v53
	v_exp_f32_e32 v54, v54
	v_exp_f32_e32 v55, v55
	v_mul_f32_e32 v16, v16, v36
	v_mul_f32_e32 v17, v17, v36
	v_mul_f32_e32 v18, v18, v36
	v_mul_f32_e32 v19, v19, v36
	v_mul_f32_e32 v20, v20, v36
	v_mul_f32_e32 v21, v21, v36
	v_mul_f32_e32 v22, v22, v36
	v_mul_f32_e32 v23, v23, v36
	v_mul_f32_e32 v24, v24, v36
	v_mul_f32_e32 v25, v25, v36
	v_mul_f32_e32 v26, v26, v36
	v_mul_f32_e32 v27, v27, v36
	v_mul_f32_e32 v28, v28, v36
	v_mul_f32_e32 v29, v29, v36
	v_mul_f32_e32 v30, v30, v36
	v_mul_f32_e32 v31, v31, v36
	v_cvt_pk_bf16_f32 v130, v48, v49
	v_cvt_pk_bf16_f32 v131, v50, v51
	v_cvt_pk_bf16_f32 v132, v52, v53
	v_cvt_pk_bf16_f32 v133, v54, v55
	v_sub_f32_e32 v56, v56, v118
	v_sub_f32_e32 v57, v57, v118
	s_waitcnt lgkmcnt(0)
	v_mfma_f32_32x32x16_bf16 v[16:31], v[124:127], v[130:133], v[16:31]
	ds_read_b128 v[124:127], v128 offset:26656
	v_sub_f32_e32 v58, v58, v118
	v_sub_f32_e32 v59, v59, v118
	v_sub_f32_e32 v60, v60, v118
	v_sub_f32_e32 v61, v61, v118
	v_sub_f32_e32 v62, v62, v118
	v_sub_f32_e32 v63, v63, v118
	v_exp_f32_e32 v56, v56
	v_exp_f32_e32 v57, v57
	v_exp_f32_e32 v58, v58
	v_exp_f32_e32 v59, v59
	v_exp_f32_e32 v60, v60
	v_exp_f32_e32 v61, v61
	v_exp_f32_e32 v62, v62
	v_exp_f32_e32 v63, v63
	v_mul_f32_e32 v0, v0, v36
	v_mul_f32_e32 v1, v1, v36
	v_mul_f32_e32 v2, v2, v36
	v_mul_f32_e32 v3, v3, v36
	v_mul_f32_e32 v4, v4, v36
	v_mul_f32_e32 v5, v5, v36
	v_mul_f32_e32 v6, v6, v36
	v_mul_f32_e32 v7, v7, v36
	v_mul_f32_e32 v8, v8, v36
	v_mul_f32_e32 v9, v9, v36
	v_mul_f32_e32 v10, v10, v36
	v_mul_f32_e32 v11, v11, v36
	v_mul_f32_e32 v12, v12, v36
	v_mul_f32_e32 v13, v13, v36
	v_mul_f32_e32 v14, v14, v36
	v_mul_f32_e32 v15, v15, v36
	v_sub_f32_e32 v38, v38, v118
	v_sub_f32_e32 v39, v39, v118
	v_mfma_f32_32x32x16_bf16 v[0:15], v[134:137], v[130:133], v[0:15]
	ds_read_b128 v[130:133], v128 offset:31264
	v_cvt_pk_bf16_f32 v134, v56, v57
	v_cvt_pk_bf16_f32 v135, v58, v59
	v_cvt_pk_bf16_f32 v136, v60, v61
	v_cvt_pk_bf16_f32 v137, v62, v63
	v_exp_f32_e32 v38, v38
	v_exp_f32_e32 v39, v39
	s_waitcnt lgkmcnt(1)
	v_mfma_f32_32x32x16_bf16 v[16:31], v[124:127], v[134:137], v[16:31]
	ds_read_b128 v[124:127], v128 offset:26688
	v_sub_f32_e32 v40, v40, v118
	v_sub_f32_e32 v41, v41, v118
	v_sub_f32_e32 v42, v42, v118
	v_sub_f32_e32 v43, v43, v118
	v_sub_f32_e32 v44, v44, v118
	v_sub_f32_e32 v45, v45, v118
	s_waitcnt lgkmcnt(1)
	v_mfma_f32_32x32x16_bf16 v[0:15], v[130:133], v[134:137], v[0:15]
	v_cvt_pk_bf16_f32 v130, v119, v120
	v_cvt_pk_bf16_f32 v131, v121, v122
	v_cvt_pk_bf16_f32 v132, v123, v37
	v_cvt_pk_bf16_f32 v133, v38, v39
	ds_read_b128 v[134:137], v128 offset:31296
	v_sub_f32_e32 v46, v46, v118
	v_sub_f32_e32 v47, v47, v118
	s_waitcnt lgkmcnt(1)
	v_mfma_f32_32x32x16_bf16 v[16:31], v[124:127], v[130:133], v[16:31]
	ds_read_b128 v[124:127], v128 offset:26720
	v_exp_f32_e32 v40, v40
	v_exp_f32_e32 v41, v41
	v_exp_f32_e32 v42, v42
	v_exp_f32_e32 v43, v43
	v_exp_f32_e32 v44, v44
	v_exp_f32_e32 v45, v45
	v_exp_f32_e32 v46, v46
	v_exp_f32_e32 v47, v47
	s_waitcnt lgkmcnt(1)
	v_mfma_f32_32x32x16_bf16 v[0:15], v[134:137], v[130:133], v[0:15]
	v_cvt_pk_bf16_f32 v130, v40, v41
	v_cvt_pk_bf16_f32 v131, v42, v43
	v_cvt_pk_bf16_f32 v132, v44, v45
	v_cvt_pk_bf16_f32 v133, v46, v47
	s_waitcnt lgkmcnt(0)
	s_nop 0
	v_mfma_f32_32x32x16_bf16 v[16:31], v[124:127], v[130:133], v[16:31]
	ds_read_b128 v[124:127], v128 offset:31328
	s_waitcnt lgkmcnt(0)
	v_mfma_f32_32x32x16_bf16 v[0:15], v[124:127], v[130:133], v[0:15]
	s_and_saveexec_b64 s[4:5], s[0:1]
	s_cbranch_execz .LBB0_908
	v_add3_u32 v124, s8, v115, v116
	s_waitcnt vmcnt(1)
	ds_write_b128 v124, v[88:91]

.LBB0_910:
	s_or_b64 exec, exec, s[4:5]
	v_add_f32_e32 v48, 0, v48
	v_add_f32_e32 v48, v49, v48
	v_add_f32_e32 v48, v50, v48
	v_add_f32_e32 v48, v51, v48
	v_add_f32_e32 v48, v52, v48
	v_add_f32_e32 v48, v53, v48
	v_add_f32_e32 v48, v54, v48
	v_add_f32_e32 v48, v55, v48
	v_add_f32_e32 v48, v56, v48
	v_add_f32_e32 v48, v57, v48
	v_add_f32_e32 v48, v58, v48
	v_add_f32_e32 v48, v59, v48
	v_add_f32_e32 v48, v60, v48
	v_add_f32_e32 v48, v61, v48
	v_add_f32_e32 v48, v62, v48
	v_add_f32_e32 v48, v63, v48
	v_add_f32_e32 v48, v119, v48
	v_add_f32_e32 v48, v120, v48
	v_add_f32_e32 v48, v121, v48
	v_add_f32_e32 v48, v122, v48
	v_add_f32_e32 v48, v123, v48
	v_add_f32_e32 v37, v37, v48
	v_add_f32_e32 v37, v38, v37
	v_add_f32_e32 v37, v39, v37
	v_add_f32_e32 v37, v40, v37
	v_add_f32_e32 v37, v41, v37
	v_add_f32_e32 v37, v42, v37
	v_add_f32_e32 v37, v43, v37
	v_add_f32_e32 v37, v44, v37
	v_add_f32_e32 v37, v45, v37
	v_add_f32_e32 v37, v46, v37
	v_add_f32_e32 v119, v47, v37
	s_add_i32 s6, s6, 1
	s_mulk_i32 s7, 0x2400
	s_add_i32 s60, s60, 64
	v_readlane_b32 s4, v253, 47
	v_fmac_f32_e32 v119, v117, v36
	v_add_u32_e32 v36, s7, v112
	s_cmp_eq_u32 s4, s6
	s_waitcnt vmcnt(0)
	ds_write_b128 v36, v[32:35] offset:26624
	s_waitcnt lgkmcnt(0)
	s_barrier
	s_cbranch_scc0 .LBB0_902
	v_readlane_b32 s0, v253, 47
	s_and_b32 s0, s0, 1
	s_mul_i32 s1, s0, 0x3400
	v_add_u32_e32 v88, s1, v113
	ds_read_b128 v[32:35], v88
	s_mulk_i32 s0, 0x2400
	v_lshlrev_b32_e32 v128, 3, v108
	s_waitcnt lgkmcnt(0)
	v_mfma_f32_32x32x16_bf16 v[48:63], v[32:35], v[84:87], 0
	ds_read_b128 v[32:35], v88 offset:32
	s_waitcnt lgkmcnt(0)
	v_mfma_f32_32x32x16_bf16 v[48:63], v[32:35], v[80:83], v[48:63]
	ds_read_b128 v[32:35], v88 offset:64
	s_waitcnt lgkmcnt(0)
	v_mfma_f32_32x32x16_bf16 v[48:63], v[32:35], v[76:79], v[48:63]
	ds_read_b128 v[32:35], v88 offset:96
	s_waitcnt lgkmcnt(0)
	v_mfma_f32_32x32x16_bf16 v[48:63], v[32:35], v[72:75], v[48:63]
	ds_read_b128 v[32:35], v88 offset:128
	s_waitcnt lgkmcnt(0)
	v_mfma_f32_32x32x16_bf16 v[48:63], v[32:35], v[68:71], v[48:63]
	ds_read_b128 v[32:35], v88 offset:160
	s_waitcnt lgkmcnt(0)
	v_mfma_f32_32x32x16_bf16 v[48:63], v[32:35], v[64:67], v[48:63]
	ds_read_b128 v[32:35], v88 offset:6656
	s_waitcnt lgkmcnt(0)
	v_mfma_f32_32x32x16_bf16 v[32:47], v[32:35], v[84:87], 0
	ds_read_b128 v[84:87], v88 offset:6688
	s_waitcnt lgkmcnt(0)
	v_mfma_f32_32x32x16_bf16 v[32:47], v[84:87], v[80:83], v[32:47]
	ds_read_b128 v[80:83], v88 offset:6720
	s_waitcnt lgkmcnt(0)
	v_mfma_f32_32x32x16_bf16 v[32:47], v[80:83], v[76:79], v[32:47]
	ds_read_b128 v[76:79], v88 offset:6752
	s_nop 1
	v_max_f32_e32 v80, v49, v49
	v_max_f32_e32 v81, v48, v48
	v_max_f32_e32 v80, v81, v80
	s_waitcnt lgkmcnt(0)
	v_mfma_f32_32x32x16_bf16 v[32:47], v[76:79], v[72:75], v[32:47]
	ds_read_b128 v[72:75], v88 offset:6784
	ds_read_b128 v[76:79], v88 offset:6816
	s_waitcnt lgkmcnt(1)
	v_mfma_f32_32x32x16_bf16 v[32:47], v[72:75], v[68:71], v[32:47]
	v_max3_f32 v68, v80, v50, v51
	v_max3_f32 v68, v68, v52, v53
	v_max3_f32 v68, v68, v54, v55
	v_max3_f32 v68, v68, v56, v57
	v_max3_f32 v68, v68, v58, v59
	v_max3_f32 v68, v68, v60, v61
	v_max3_f32 v68, v68, v62, v63
	s_waitcnt lgkmcnt(0)
	v_mfma_f32_32x32x16_bf16 v[32:47], v[76:79], v[64:67], v[32:47]
	v_add_u32_e32 v75, s0, v106
	s_nop 10
	v_max3_f32 v64, v68, v32, v33
	v_max3_f32 v64, v64, v34, v35
	v_max3_f32 v64, v64, v36, v37
	v_max3_f32 v64, v64, v38, v39
	v_max3_f32 v64, v64, v40, v41
	v_max3_f32 v64, v64, v42, v43
	v_max3_f32 v64, v64, v44, v45
	v_max3_f32 v64, v64, v46, v47
	ds_bpermute_b32 v65, v105, v64
	s_waitcnt lgkmcnt(0)
	v_max3_f32 v64, v118, v64, v65
	v_sub_f32_e32 v48, v48, v64
	v_exp_f32_e32 v48, v48
	v_sub_f32_e32 v49, v49, v64
	v_exp_f32_e32 v49, v49
	v_sub_f32_e32 v50, v50, v64
	v_exp_f32_e32 v50, v50
	v_sub_f32_e32 v51, v51, v64
	v_exp_f32_e32 v51, v51
	v_sub_f32_e32 v52, v52, v64
	v_add_f32_e32 v66, 0, v48
	v_exp_f32_e32 v52, v52
	v_sub_f32_e32 v53, v53, v64
	v_add_f32_e32 v66, v49, v66
	v_exp_f32_e32 v53, v53
	v_sub_f32_e32 v54, v54, v64
	v_add_f32_e32 v66, v50, v66
	v_exp_f32_e32 v54, v54
	v_sub_f32_e32 v55, v55, v64
	v_add_f32_e32 v66, v51, v66
	v_exp_f32_e32 v55, v55
	v_sub_f32_e32 v56, v56, v64
	v_add_f32_e32 v66, v52, v66
	v_exp_f32_e32 v67, v56
	v_sub_f32_e32 v56, v57, v64
	v_add_f32_e32 v66, v53, v66
	v_exp_f32_e32 v57, v56
	v_sub_f32_e32 v56, v58, v64
	v_add_f32_e32 v66, v54, v66
	v_exp_f32_e32 v58, v56
	v_sub_f32_e32 v56, v59, v64
	v_sub_f32_e32 v32, v32, v64
	v_exp_f32_e32 v59, v56
	v_sub_f32_e32 v56, v60, v64
	v_exp_f32_e32 v68, v32
	v_sub_f32_e32 v32, v33, v64
	v_add_f32_e32 v33, v55, v66
	v_exp_f32_e32 v60, v56
	v_sub_f32_e32 v56, v61, v64
	v_add_f32_e32 v33, v67, v33
	v_exp_f32_e32 v61, v56
	v_sub_f32_e32 v56, v62, v64
	v_add_f32_e32 v33, v57, v33
	v_exp_f32_e32 v62, v56
	v_sub_f32_e32 v56, v63, v64
	v_add_f32_e32 v33, v58, v33
	v_exp_f32_e32 v63, v56
	v_add_f32_e32 v33, v59, v33
	v_add_f32_e32 v33, v60, v33
	v_exp_f32_e32 v69, v32
	v_sub_f32_e32 v32, v34, v64
	v_add_f32_e32 v33, v61, v33
	v_exp_f32_e32 v70, v32
	v_sub_f32_e32 v32, v35, v64
	v_add_f32_e32 v33, v62, v33
	v_add_f32_e32 v33, v63, v33
	v_exp_f32_e32 v66, v32
	v_sub_f32_e32 v32, v36, v64
	v_add_f32_e32 v33, v68, v33
	v_exp_f32_e32 v71, v32
	v_sub_f32_e32 v32, v37, v64
	v_add_f32_e32 v33, v69, v33
	v_exp_f32_e32 v72, v32
	v_sub_f32_e32 v32, v38, v64
	v_add_f32_e32 v33, v70, v33
	v_exp_f32_e32 v73, v32
	v_add_f32_e32 v32, v66, v33
	v_add_f32_e32 v32, v71, v32
	v_add_f32_e32 v32, v72, v32
	v_sub_f32_e32 v65, v118, v64
	v_add_f32_e32 v74, v73, v32
	v_sub_f32_e32 v32, v39, v64
	v_exp_f32_e32 v56, v65
	v_exp_f32_e32 v65, v32
	ds_read_b128 v[32:35], v75 offset:26624
	v_cvt_pk_bf16_f32 v36, v48, v49
	v_cvt_pk_bf16_f32 v37, v50, v51
	v_cvt_pk_bf16_f32 v38, v52, v53
	v_cvt_pk_bf16_f32 v39, v54, v55
	ds_read_b128 v[48:51], v75 offset:31232
	ds_read_b128 v[52:55], v75 offset:26656
	v_mul_f32_e32 v30, v30, v56
	v_mul_f32_e32 v31, v31, v56
	v_mul_f32_e32 v28, v28, v56
	v_mul_f32_e32 v29, v29, v56
	v_mul_f32_e32 v26, v26, v56
	v_mul_f32_e32 v27, v27, v56
	v_mul_f32_e32 v24, v24, v56
	v_mul_f32_e32 v25, v25, v56
	v_mul_f32_e32 v22, v22, v56
	v_mul_f32_e32 v23, v23, v56
	v_mul_f32_e32 v20, v20, v56
	v_mul_f32_e32 v21, v21, v56
	v_mul_f32_e32 v18, v18, v56
	v_mul_f32_e32 v19, v19, v56
	v_mul_f32_e32 v16, v16, v56
	v_mul_f32_e32 v17, v17, v56
	v_mul_f32_e32 v14, v14, v56
	v_mul_f32_e32 v15, v15, v56
	v_mul_f32_e32 v12, v12, v56
	v_mul_f32_e32 v13, v13, v56
	s_waitcnt lgkmcnt(2)
	v_mfma_f32_32x32x16_bf16 v[16:31], v[32:35], v[36:39], v[16:31]
	v_mul_f32_e64 v10, v10, v56
	v_mul_f32_e64 v11, v11, v56
	v_mul_f32_e64 v8, v8, v56
	v_mul_f32_e64 v9, v9, v56
	v_mul_f32_e64 v6, v6, v56
	v_mul_f32_e64 v7, v7, v56
	v_mul_f32_e32 v4, v4, v56
	v_mul_f32_e32 v5, v5, v56
	v_mul_f32_e32 v2, v2, v56
	v_mul_f32_e32 v3, v3, v56
	v_mul_f32_e32 v0, v0, v56
	v_mul_f32_e32 v1, v1, v56
	ds_read_b128 v[32:35], v75 offset:31264
	v_sub_f32_e32 v40, v40, v64
	s_waitcnt lgkmcnt(2)
	v_mfma_f32_32x32x16_bf16 v[0:15], v[48:51], v[36:39], v[0:15]
	v_exp_f32_e32 v76, v40
	v_sub_f32_e32 v36, v41, v64
	v_exp_f32_e32 v77, v36
	v_cvt_pk_bf16_f32 v36, v67, v57
	v_cvt_pk_bf16_f32 v37, v58, v59
	v_cvt_pk_bf16_f32 v38, v60, v61
	v_cvt_pk_bf16_f32 v39, v62, v63
	v_sub_f32_e32 v40, v42, v64
	ds_read_b128 v[48:51], v75 offset:26688
	s_waitcnt lgkmcnt(2)
	v_mfma_f32_32x32x16_bf16 v[16:31], v[52:55], v[36:39], v[16:31]
	v_exp_f32_e32 v52, v40
	v_add_f32_e32 v40, v65, v74
	v_add_f32_e32 v40, v76, v40
	v_add_f32_e32 v40, v77, v40
	v_add_f32_e32 v53, v52, v40
	v_sub_f32_e32 v54, v43, v64
	v_exp_f32_e32 v54, v54
	s_waitcnt lgkmcnt(1)
	v_mfma_f32_32x32x16_bf16 v[0:15], v[32:35], v[36:39], v[0:15]
	ds_read_b128 v[36:39], v75 offset:31296
	ds_read_b128 v[40:43], v75 offset:26720
	v_sub_f32_e32 v44, v44, v64
	v_cvt_pk_bf16_f32 v32, v68, v69
	v_cvt_pk_bf16_f32 v33, v70, v66
	v_cvt_pk_bf16_f32 v34, v71, v72
	v_cvt_pk_bf16_f32 v35, v73, v65
	v_exp_f32_e32 v44, v44
	v_sub_f32_e32 v45, v45, v64
	s_waitcnt lgkmcnt(2)
	v_mfma_f32_32x32x16_bf16 v[16:31], v[48:51], v[32:35], v[16:31]
	v_exp_f32_e32 v45, v45
	v_sub_f32_e32 v46, v46, v64
	ds_read_b128 v[48:51], v75 offset:31328
	s_waitcnt lgkmcnt(0)
	s_barrier
	v_mfma_f32_32x32x16_bf16 v[0:15], v[36:39], v[32:35], v[0:15]
	v_sub_f32_e32 v32, v47, v64
	v_exp_f32_e32 v36, v46
	v_exp_f32_e32 v37, v32
	v_add_f32_e32 v38, v54, v53
	v_add_f32_e32 v38, v44, v38
	v_add_f32_e32 v38, v45, v38
	v_cvt_pk_bf16_f32 v35, v36, v37
	v_add_f32_e32 v36, v36, v38
	v_add_f32_e32 v36, v37, v36
	v_fmac_f32_e32 v36, v119, v56
	ds_bpermute_b32 v37, v105, v36
	v_cvt_pk_bf16_f32 v32, v76, v77
	v_cvt_pk_bf16_f32 v33, v52, v54
	v_cvt_pk_bf16_f32 v34, v44, v45
	s_nop 1
	v_mfma_f32_32x32x16_bf16 v[16:31], v[40:43], v[32:35], v[16:31]
	v_mfma_f32_32x32x16_bf16 v[0:15], v[48:51], v[32:35], v[0:15]
	s_waitcnt lgkmcnt(0)
	v_add_f32_e32 v34, v36, v37
	v_div_scale_f32 v35, s[0:1], v34, v34, 1.0
	v_rcp_f32_e32 v36, v35
	v_lshlrev_b64 v[32:33], 11, v[96:97]
	v_readlane_b32 s0, v252, 46
	v_lshl_add_u64 v[32:33], s[66:67], 0, v[32:33]
	v_fma_f32 v37, -v35, v36, 1.0
	v_fmac_f32_e32 v36, v37, v36
	v_div_scale_f32 v37, vcc, 1.0, v34, 1.0
	v_mul_f32_e32 v38, v37, v36
	v_fma_f32 v39, -v35, v38, v37
	v_fmac_f32_e32 v38, v39, v36
	v_fma_f32 v35, -v35, v38, v37
	v_div_fmas_f32 v35, v35, v36, v38
	s_lshl_b32 s60, s0, 1
	v_div_fixup_f32 v34, v35, v34, 1.0
	v_lshl_add_u64 v[32:33], v[32:33], 0, s[60:61]
	v_mul_f32_e32 v16, v16, v34
	v_mul_f32_e32 v17, v17, v34
	v_mul_f32_e32 v18, v18, v34
	v_mul_f32_e32 v19, v19, v34
	v_cvt_pk_bf16_f32 v16, v16, v17
	v_cvt_pk_bf16_f32 v17, v18, v19
	v_lshl_add_u64 v[18:19], v[32:33], 0, v[128:129]
	s_mov_b64 s[0:1], 0x2d53d00
	v_lshl_add_u64 v[32:33], v[18:19], 0, s[0:1]
	s_mov_b32 s0, 0x2d53000
	v_add_co_u32_e32 v18, vcc, s0, v18
	v_mul_f32_e32 v0, v0, v34
	v_mul_f32_e32 v1, v1, v34
	v_mul_f32_e32 v2, v2, v34
	v_mul_f32_e32 v3, v3, v34
	v_addc_co_u32_e32 v19, vcc, 0, v19, vcc
	v_cvt_pk_bf16_f32 v0, v0, v1
	v_cvt_pk_bf16_f32 v1, v2, v3
	global_store_dwordx2 v[18:19], v[16:17], off offset:3328
	v_mul_f32_e32 v16, v20, v34
	v_mul_f32_e32 v17, v21, v34
	v_mul_f32_e32 v18, v22, v34
	v_mul_f32_e32 v19, v23, v34
	global_store_dwordx2 v[32:33], v[0:1], off offset:64
	v_mul_f32_e32 v0, v4, v34
	v_mul_f32_e32 v1, v5, v34
	v_mul_f32_e32 v2, v6, v34
	v_mul_f32_e32 v3, v7, v34
	v_cvt_pk_bf16_f32 v16, v16, v17
	v_cvt_pk_bf16_f32 v17, v18, v19
	v_cvt_pk_bf16_f32 v0, v0, v1
	v_cvt_pk_bf16_f32 v1, v2, v3
	global_store_dwordx2 v[32:33], v[16:17], off offset:16
	v_mul_f32_e32 v16, v24, v34
	v_mul_f32_e32 v17, v25, v34
	v_mul_f32_e32 v18, v26, v34
	v_mul_f32_e32 v19, v27, v34
	global_store_dwordx2 v[32:33], v[0:1], off offset:80
	v_mul_f32_e32 v0, v8, v34
	v_mul_f32_e32 v1, v9, v34
	v_mul_f32_e32 v2, v10, v34
	v_mul_f32_e32 v3, v11, v34
	v_cvt_pk_bf16_f32 v16, v16, v17
	v_cvt_pk_bf16_f32 v17, v18, v19
	v_cvt_pk_bf16_f32 v0, v0, v1
	v_cvt_pk_bf16_f32 v1, v2, v3
	global_store_dwordx2 v[32:33], v[16:17], off offset:32
	v_mul_f32_e32 v16, v28, v34
	v_mul_f32_e32 v17, v29, v34
	v_mul_f32_e32 v18, v30, v34
	v_mul_f32_e32 v19, v31, v34
	global_store_dwordx2 v[32:33], v[0:1], off offset:96
	v_mul_f32_e32 v0, v12, v34
	v_mul_f32_e32 v1, v13, v34
	v_mul_f32_e32 v2, v14, v34
	v_mul_f32_e32 v3, v15, v34
	v_cvt_pk_bf16_f32 v16, v16, v17
	v_cvt_pk_bf16_f32 v17, v18, v19
	v_cvt_pk_bf16_f32 v0, v0, v1
	v_cvt_pk_bf16_f32 v1, v2, v3
	s_mov_b64 s[0:1], 0
	global_store_dwordx2 v[32:33], v[16:17], off offset:48
	global_store_dwordx2 v[32:33], v[0:1], off offset:112

.LBB0_922:
	s_or_b64 exec, exec, s[6:7]
	s_and_b32 s6, s5, 1
	s_mul_i32 s7, s6, 0x2400
	v_add_u32_e32 v105, s7, v93
	ds_read_b128 v[32:35], v105
	ds_read_b128 v[98:101], v105 offset:4640
	s_xor_b32 s8, s6, 1
	s_mulk_i32 s8, 0x2400
	s_waitcnt lgkmcnt(1)
	v_mfma_f32_32x32x16_bf16 v[48:63], v[32:35], v[76:79], 0
	ds_read_b128 v[32:35], v105 offset:32
	s_waitcnt lgkmcnt(0)
	v_mfma_f32_32x32x16_bf16 v[48:63], v[32:35], v[72:75], v[48:63]
	ds_read_b128 v[32:35], v105 offset:64
	s_waitcnt lgkmcnt(0)
	v_mfma_f32_32x32x16_bf16 v[48:63], v[32:35], v[68:71], v[48:63]
	ds_read_b128 v[32:35], v105 offset:96
	s_waitcnt lgkmcnt(0)
	v_mfma_f32_32x32x16_bf16 v[48:63], v[32:35], v[64:67], v[48:63]
	ds_read_b128 v[32:35], v105 offset:4608
	s_waitcnt lgkmcnt(0)
	v_mfma_f32_32x32x16_bf16 v[32:47], v[32:35], v[76:79], 0
	s_nop 8
	v_max_f32_e32 v96, v49, v49
	v_max_f32_e32 v102, v48, v48
	v_max_f32_e32 v96, v102, v96
	v_max3_f32 v96, v96, v50, v51
	v_max3_f32 v96, v96, v52, v53
	v_max3_f32 v96, v96, v54, v55
	v_max3_f32 v96, v96, v56, v57
	v_mfma_f32_32x32x16_bf16 v[32:47], v[98:101], v[72:75], v[32:47]
	ds_read_b128 v[98:101], v105 offset:4672
	ds_read_b128 v[112:115], v105 offset:4704
	v_max3_f32 v96, v96, v58, v59
	v_max3_f32 v96, v96, v60, v61
	v_max3_f32 v96, v96, v62, v63
	v_lshl_add_u64 v[102:103], s[60:61], 1, v[86:87]
	ds_read_b128 v[120:123], v105 offset:23040
	s_waitcnt lgkmcnt(2)
	v_mfma_f32_32x32x16_bf16 v[32:47], v[98:101], v[68:71], v[32:47]
	s_waitcnt lgkmcnt(1)
	v_mfma_f32_32x32x16_bf16 v[32:47], v[112:115], v[64:67], v[32:47]
	ds_read_b128 v[112:115], v105 offset:18432
	s_nop 10
	v_max3_f32 v96, v96, v32, v33
	v_max3_f32 v96, v96, v34, v35
	v_max3_f32 v96, v96, v36, v37
	v_max3_f32 v96, v96, v38, v39
	v_max3_f32 v96, v96, v40, v41
	v_max3_f32 v96, v96, v42, v43
	v_max3_f32 v96, v96, v44, v45
	v_max3_f32 v96, v96, v46, v47
	ds_bpermute_b32 v98, v90, v96
	s_waitcnt lgkmcnt(0)
	v_max3_f32 v96, v97, v96, v98
	v_sub_f32_e32 v32, v32, v96
	v_sub_f32_e32 v106, v97, v96
	v_exp_f32_e32 v97, v32
	v_sub_f32_e32 v32, v33, v96
	v_exp_f32_e32 v98, v32
	v_sub_f32_e32 v32, v34, v96
	v_exp_f32_e32 v99, v32
	v_sub_f32_e32 v32, v35, v96
	v_exp_f32_e32 v100, v32
	v_sub_f32_e32 v32, v36, v96
	v_exp_f32_e32 v101, v32
	v_sub_f32_e32 v32, v37, v96
	v_exp_f32_e32 v37, v32
	global_load_dwordx4 v[32:35], v[102:103], off
	v_sub_f32_e32 v48, v48, v96
	v_sub_f32_e32 v49, v49, v96
	v_sub_f32_e32 v50, v50, v96
	v_sub_f32_e32 v51, v51, v96
	v_sub_f32_e32 v52, v52, v96
	v_sub_f32_e32 v53, v53, v96
	v_sub_f32_e32 v54, v54, v96
	v_sub_f32_e32 v55, v55, v96
	v_exp_f32_e32 v48, v48
	v_exp_f32_e32 v49, v49
	v_exp_f32_e32 v50, v50
	v_exp_f32_e32 v51, v51
	v_exp_f32_e32 v52, v52
	v_exp_f32_e32 v53, v53
	v_exp_f32_e32 v54, v54
	v_exp_f32_e32 v55, v55
	v_exp_f32_e32 v36, v106
	v_cvt_pk_bf16_f32 v116, v48, v49
	v_cvt_pk_bf16_f32 v117, v50, v51
	v_cvt_pk_bf16_f32 v118, v52, v53
	v_mul_f32_e32 v16, v16, v36
	v_mul_f32_e32 v17, v17, v36
	v_mul_f32_e32 v18, v18, v36
	v_mul_f32_e32 v19, v19, v36
	v_mul_f32_e32 v20, v20, v36
	v_mul_f32_e32 v21, v21, v36
	v_mul_f32_e32 v22, v22, v36
	v_mul_f32_e32 v23, v23, v36
	v_mul_f32_e32 v24, v24, v36
	v_mul_f32_e32 v25, v25, v36
	v_mul_f32_e32 v26, v26, v36
	v_mul_f32_e32 v27, v27, v36
	v_mul_f32_e32 v28, v28, v36
	v_mul_f32_e32 v29, v29, v36
	v_mul_f32_e32 v30, v30, v36
	v_mul_f32_e32 v31, v31, v36
	v_cvt_pk_bf16_f32 v119, v54, v55
	v_sub_f32_e32 v56, v56, v96
	v_sub_f32_e32 v57, v57, v96
	v_mfma_f32_32x32x16_bf16 v[16:31], v[112:115], v[116:119], v[16:31]
	ds_read_b128 v[112:115], v105 offset:18464
	v_sub_f32_e32 v58, v58, v96
	v_sub_f32_e32 v59, v59, v96
	v_sub_f32_e32 v60, v60, v96
	v_sub_f32_e32 v61, v61, v96
	v_sub_f32_e32 v62, v62, v96
	v_sub_f32_e32 v63, v63, v96
	v_exp_f32_e32 v56, v56
	v_exp_f32_e32 v57, v57
	v_exp_f32_e32 v58, v58
	v_exp_f32_e32 v59, v59
	v_exp_f32_e32 v60, v60
	v_exp_f32_e32 v61, v61
	v_exp_f32_e32 v62, v62
	v_exp_f32_e32 v63, v63
	v_mul_f32_e32 v0, v0, v36
	v_mul_f32_e32 v1, v1, v36
	v_mul_f32_e32 v2, v2, v36
	v_mul_f32_e32 v3, v3, v36
	v_mul_f32_e32 v4, v4, v36
	v_mul_f32_e32 v5, v5, v36
	v_mul_f32_e32 v6, v6, v36
	v_mul_f32_e32 v7, v7, v36
	v_mul_f32_e32 v8, v8, v36
	v_mul_f32_e32 v9, v9, v36
	v_mul_f32_e32 v10, v10, v36
	v_mul_f32_e32 v11, v11, v36
	v_mul_f32_e32 v12, v12, v36
	v_mul_f32_e32 v13, v13, v36
	v_mul_f32_e32 v14, v14, v36
	v_mul_f32_e32 v15, v15, v36
	v_sub_f32_e32 v38, v38, v96
	v_sub_f32_e32 v39, v39, v96
	v_mfma_f32_32x32x16_bf16 v[0:15], v[120:123], v[116:119], v[0:15]
	ds_read_b128 v[116:119], v105 offset:23072
	v_cvt_pk_bf16_f32 v120, v56, v57
	v_cvt_pk_bf16_f32 v121, v58, v59
	v_cvt_pk_bf16_f32 v122, v60, v61
	v_cvt_pk_bf16_f32 v123, v62, v63
	v_exp_f32_e32 v38, v38
	v_exp_f32_e32 v39, v39
	s_waitcnt lgkmcnt(1)
	v_mfma_f32_32x32x16_bf16 v[16:31], v[112:115], v[120:123], v[16:31]
	ds_read_b128 v[112:115], v105 offset:18496
	v_sub_f32_e32 v40, v40, v96
	v_sub_f32_e32 v41, v41, v96
	v_sub_f32_e32 v42, v42, v96
	v_sub_f32_e32 v43, v43, v96
	v_sub_f32_e32 v44, v44, v96
	v_sub_f32_e32 v45, v45, v96
	s_waitcnt lgkmcnt(1)
	v_mfma_f32_32x32x16_bf16 v[0:15], v[116:119], v[120:123], v[0:15]
	v_cvt_pk_bf16_f32 v116, v97, v98
	v_cvt_pk_bf16_f32 v117, v99, v100
	v_cvt_pk_bf16_f32 v118, v101, v37
	v_cvt_pk_bf16_f32 v119, v38, v39
	ds_read_b128 v[120:123], v105 offset:23104
	v_sub_f32_e32 v46, v46, v96
	v_sub_f32_e32 v47, v47, v96
	s_waitcnt lgkmcnt(1)
	v_mfma_f32_32x32x16_bf16 v[16:31], v[112:115], v[116:119], v[16:31]
	ds_read_b128 v[112:115], v105 offset:18528
	v_exp_f32_e32 v40, v40
	v_exp_f32_e32 v41, v41
	v_exp_f32_e32 v42, v42
	v_exp_f32_e32 v43, v43
	v_exp_f32_e32 v44, v44
	v_exp_f32_e32 v45, v45
	v_exp_f32_e32 v46, v46
	v_exp_f32_e32 v47, v47
	s_waitcnt lgkmcnt(1)
	v_mfma_f32_32x32x16_bf16 v[0:15], v[120:123], v[116:119], v[0:15]
	v_cvt_pk_bf16_f32 v116, v40, v41
	v_cvt_pk_bf16_f32 v117, v42, v43
	v_cvt_pk_bf16_f32 v118, v44, v45
	v_cvt_pk_bf16_f32 v119, v46, v47
	s_waitcnt lgkmcnt(0)
	s_nop 0
	v_mfma_f32_32x32x16_bf16 v[16:31], v[112:115], v[116:119], v[16:31]
	ds_read_b128 v[112:115], v105 offset:23136
	s_waitcnt lgkmcnt(0)
	v_mfma_f32_32x32x16_bf16 v[0:15], v[112:115], v[116:119], v[0:15]
	s_and_saveexec_b64 s[6:7], s[0:1]
	s_cbranch_execz .LBB0_924
	v_add_u32_e32 v102, s8, v94
	s_waitcnt vmcnt(1)
	ds_write_b128 v102, v[80:83]
.LBB0_924:
	s_or_b64 exec, exec, s[6:7]
	v_add_f32_e32 v48, 0, v48
	v_add_f32_e32 v48, v49, v48
	v_add_f32_e32 v48, v50, v48
	v_add_f32_e32 v48, v51, v48
	v_add_f32_e32 v48, v52, v48
	v_add_f32_e32 v48, v53, v48
	v_add_f32_e32 v48, v54, v48
	v_add_f32_e32 v48, v55, v48
	v_add_f32_e32 v48, v56, v48
	v_add_f32_e32 v48, v57, v48
	v_add_f32_e32 v48, v58, v48
	v_add_f32_e32 v48, v59, v48
	v_add_f32_e32 v48, v60, v48
	v_add_f32_e32 v48, v61, v48
	v_add_f32_e32 v48, v62, v48
	v_add_f32_e32 v48, v63, v48
	v_add_f32_e32 v48, v97, v48
	v_add_f32_e32 v48, v98, v48
	v_add_f32_e32 v48, v99, v48
	v_add_f32_e32 v48, v100, v48
	v_add_f32_e32 v48, v101, v48
	v_add_f32_e32 v37, v37, v48
	v_add_f32_e32 v37, v38, v37
	v_add_f32_e32 v37, v39, v37
	v_add_f32_e32 v37, v40, v37
	v_add_f32_e32 v37, v41, v37
	v_add_f32_e32 v37, v42, v37
	v_add_f32_e32 v37, v43, v37
	v_add_f32_e32 v37, v44, v37
	v_add_f32_e32 v37, v45, v37
	v_add_f32_e32 v37, v46, v37
	v_add_f32_e32 v97, v47, v37
	s_add_i32 s5, s5, 1
	s_add_i32 s60, s60, 64
	v_readlane_b32 s6, v253, 47
	v_fmac_f32_e32 v97, v95, v36
	v_add_u32_e32 v36, s8, v92
	s_cmp_eq_u32 s6, s5
	s_waitcnt vmcnt(0)
	ds_write_b128 v36, v[32:35] offset:18432
	s_waitcnt lgkmcnt(0)
	s_barrier
	s_cbranch_scc0 .LBB0_920
	v_readlane_b32 s0, v253, 47
	s_bitcmp1_b32 s0, 0
	s_cselect_b32 s0, 0x2400, 0
	v_add_u32_e32 v80, s0, v93
	ds_read_b128 v[32:35], v80
	s_mov_b32 s5, s61
	v_lshlrev_b32_e32 v128, 3, v108
	s_waitcnt lgkmcnt(0)
	v_mfma_f32_32x32x16_bf16 v[48:63], v[32:35], v[76:79], 0
	ds_read_b128 v[32:35], v80 offset:32
	s_waitcnt lgkmcnt(0)
	v_mfma_f32_32x32x16_bf16 v[48:63], v[32:35], v[72:75], v[48:63]
	ds_read_b128 v[32:35], v80 offset:64
	s_waitcnt lgkmcnt(0)
	v_mfma_f32_32x32x16_bf16 v[48:63], v[32:35], v[68:71], v[48:63]
	ds_read_b128 v[32:35], v80 offset:96
	s_waitcnt lgkmcnt(0)
	v_mfma_f32_32x32x16_bf16 v[48:63], v[32:35], v[64:67], v[48:63]
	ds_read_b128 v[32:35], v80 offset:4608
	s_waitcnt lgkmcnt(0)
	v_mfma_f32_32x32x16_bf16 v[32:47], v[32:35], v[76:79], 0
	ds_read_b128 v[76:79], v80 offset:4640
	s_nop 7
	v_max_f32_e32 v81, v49, v49
	v_max_f32_e32 v82, v48, v48
	v_max_f32_e32 v81, v82, v81
	s_waitcnt lgkmcnt(0)
	v_mfma_f32_32x32x16_bf16 v[32:47], v[76:79], v[72:75], v[32:47]
	ds_read_b128 v[72:75], v80 offset:4672
	ds_read_b128 v[76:79], v80 offset:4704
	s_waitcnt lgkmcnt(1)
	v_mfma_f32_32x32x16_bf16 v[32:47], v[72:75], v[68:71], v[32:47]
	v_max3_f32 v68, v81, v50, v51
	v_max3_f32 v68, v68, v52, v53
	v_max3_f32 v68, v68, v54, v55
	v_max3_f32 v68, v68, v56, v57
	v_max3_f32 v68, v68, v58, v59
	v_max3_f32 v68, v68, v60, v61
	v_max3_f32 v68, v68, v62, v63
	s_waitcnt lgkmcnt(0)
	v_mfma_f32_32x32x16_bf16 v[32:47], v[76:79], v[64:67], v[32:47]
	s_nop 11
	v_max3_f32 v64, v68, v32, v33
	v_max3_f32 v64, v64, v34, v35
	v_max3_f32 v64, v64, v36, v37
	v_max3_f32 v64, v64, v38, v39
	v_max3_f32 v64, v64, v40, v41
	v_max3_f32 v64, v64, v42, v43
	v_max3_f32 v64, v64, v44, v45
	v_max3_f32 v64, v64, v46, v47
	ds_bpermute_b32 v65, v90, v64
	s_waitcnt lgkmcnt(0)
	v_max3_f32 v64, v96, v64, v65
	v_sub_f32_e32 v48, v48, v64
	v_sub_f32_e32 v49, v49, v64
	v_exp_f32_e32 v48, v48
	v_sub_f32_e32 v50, v50, v64
	v_exp_f32_e32 v49, v49
	v_sub_f32_e32 v51, v51, v64
	v_exp_f32_e32 v50, v50
	v_sub_f32_e32 v52, v52, v64
	v_sub_f32_e32 v56, v56, v64
	v_exp_f32_e32 v51, v51
	v_sub_f32_e32 v53, v53, v64
	v_exp_f32_e32 v52, v52
	v_exp_f32_e32 v66, v56
	v_add_f32_e32 v56, 0, v48
	v_sub_f32_e32 v54, v54, v64
	v_exp_f32_e32 v53, v53
	v_add_f32_e32 v56, v49, v56
	v_sub_f32_e32 v55, v55, v64
	v_exp_f32_e32 v54, v54
	v_add_f32_e32 v56, v50, v56
	v_exp_f32_e32 v55, v55
	v_add_f32_e32 v56, v51, v56
	v_sub_f32_e32 v57, v57, v64
	v_add_f32_e32 v56, v52, v56
	v_sub_f32_e32 v58, v58, v64
	v_exp_f32_e32 v57, v57
	v_add_f32_e32 v56, v53, v56
	v_sub_f32_e32 v59, v59, v64
	v_exp_f32_e32 v58, v58
	v_add_f32_e32 v56, v54, v56
	v_sub_f32_e32 v60, v60, v64
	v_exp_f32_e32 v59, v59
	v_add_f32_e32 v56, v55, v56
	v_sub_f32_e32 v61, v61, v64
	v_exp_f32_e32 v60, v60
	v_add_f32_e32 v56, v66, v56
	v_sub_f32_e32 v62, v62, v64
	v_exp_f32_e32 v61, v61
	v_add_f32_e32 v56, v57, v56
	v_sub_f32_e32 v63, v63, v64
	v_exp_f32_e32 v62, v62
	v_add_f32_e32 v56, v58, v56
	v_exp_f32_e32 v63, v63
	v_add_f32_e32 v56, v59, v56
	v_sub_f32_e32 v32, v32, v64
	v_add_f32_e32 v56, v60, v56
	v_exp_f32_e32 v67, v32
	v_sub_f32_e32 v32, v33, v64
	v_add_f32_e32 v56, v61, v56
	v_exp_f32_e32 v68, v32
	v_sub_f32_e32 v32, v34, v64
	v_add_f32_e32 v56, v62, v56
	v_exp_f32_e32 v69, v32
	v_sub_f32_e32 v33, v35, v64
	v_add_f32_e32 v32, v63, v56
	v_exp_f32_e32 v70, v33
	v_sub_f32_e32 v33, v36, v64
	v_add_f32_e32 v32, v67, v32
	v_exp_f32_e32 v71, v33
	v_sub_f32_e32 v33, v37, v64
	v_add_f32_e32 v32, v68, v32
	v_exp_f32_e32 v72, v33
	v_sub_f32_e32 v33, v38, v64
	v_add_f32_e32 v32, v69, v32
	v_exp_f32_e32 v73, v33
	v_add_f32_e32 v32, v70, v32
	v_add_f32_e32 v32, v71, v32
	v_add_f32_e32 v32, v72, v32
	v_sub_f32_e32 v65, v96, v64
	v_add_f32_e32 v74, v73, v32
	v_sub_f32_e32 v32, v39, v64
	v_exp_f32_e32 v56, v65
	v_exp_f32_e32 v65, v32
	ds_read_b128 v[32:35], v80 offset:18432
	v_cvt_pk_bf16_f32 v36, v48, v49
	v_cvt_pk_bf16_f32 v37, v50, v51
	v_cvt_pk_bf16_f32 v38, v52, v53
	v_cvt_pk_bf16_f32 v39, v54, v55
	ds_read_b128 v[48:51], v80 offset:23040
	ds_read_b128 v[52:55], v80 offset:18464
	v_mul_f32_e32 v30, v30, v56
	v_mul_f32_e32 v31, v31, v56
	v_mul_f32_e32 v28, v28, v56
	v_mul_f32_e32 v29, v29, v56
	v_mul_f32_e32 v26, v26, v56
	v_mul_f32_e32 v27, v27, v56
	v_mul_f32_e32 v24, v24, v56
	v_mul_f32_e32 v25, v25, v56
	v_mul_f32_e32 v22, v22, v56
	v_mul_f32_e32 v23, v23, v56
	v_mul_f32_e32 v20, v20, v56
	v_mul_f32_e32 v21, v21, v56
	v_mul_f32_e32 v18, v18, v56
	v_mul_f32_e32 v19, v19, v56
	v_mul_f32_e32 v16, v16, v56
	v_mul_f32_e32 v17, v17, v56
	v_mul_f32_e32 v14, v14, v56
	v_mul_f32_e32 v15, v15, v56
	v_mul_f32_e32 v12, v12, v56
	v_mul_f32_e32 v13, v13, v56
	s_waitcnt lgkmcnt(2)
	v_mfma_f32_32x32x16_bf16 v[16:31], v[32:35], v[36:39], v[16:31]
	v_mul_f32_e64 v10, v10, v56
	v_mul_f32_e64 v11, v11, v56
	v_mul_f32_e64 v8, v8, v56
	v_mul_f32_e64 v9, v9, v56
	v_mul_f32_e64 v6, v6, v56
	v_mul_f32_e64 v7, v7, v56
	v_mul_f32_e32 v4, v4, v56
	v_mul_f32_e32 v5, v5, v56
	v_mul_f32_e32 v2, v2, v56
	v_mul_f32_e32 v3, v3, v56
	v_mul_f32_e32 v0, v0, v56
	v_mul_f32_e32 v1, v1, v56
	ds_read_b128 v[32:35], v80 offset:23072
	v_sub_f32_e32 v40, v40, v64
	s_waitcnt lgkmcnt(2)
	v_mfma_f32_32x32x16_bf16 v[0:15], v[48:51], v[36:39], v[0:15]
	v_exp_f32_e32 v75, v40
	v_sub_f32_e32 v36, v41, v64
	v_exp_f32_e32 v76, v36
	v_cvt_pk_bf16_f32 v36, v66, v57
	v_cvt_pk_bf16_f32 v37, v58, v59
	v_cvt_pk_bf16_f32 v38, v60, v61
	v_cvt_pk_bf16_f32 v39, v62, v63
	v_sub_f32_e32 v40, v42, v64
	ds_read_b128 v[48:51], v80 offset:18496
	s_waitcnt lgkmcnt(2)
	v_mfma_f32_32x32x16_bf16 v[16:31], v[52:55], v[36:39], v[16:31]
	v_exp_f32_e32 v52, v40
	v_add_f32_e32 v40, v65, v74
	v_add_f32_e32 v40, v75, v40
	v_add_f32_e32 v40, v76, v40
	v_add_f32_e32 v53, v52, v40
	v_sub_f32_e32 v54, v43, v64
	v_exp_f32_e32 v54, v54
	s_waitcnt lgkmcnt(1)
	v_mfma_f32_32x32x16_bf16 v[0:15], v[32:35], v[36:39], v[0:15]
	ds_read_b128 v[36:39], v80 offset:23104
	ds_read_b128 v[40:43], v80 offset:18528
	v_sub_f32_e32 v44, v44, v64
	v_cvt_pk_bf16_f32 v32, v67, v68
	v_cvt_pk_bf16_f32 v33, v69, v70
	v_cvt_pk_bf16_f32 v34, v71, v72
	v_cvt_pk_bf16_f32 v35, v73, v65
	v_exp_f32_e32 v44, v44
	v_sub_f32_e32 v45, v45, v64
	s_waitcnt lgkmcnt(2)
	v_mfma_f32_32x32x16_bf16 v[16:31], v[48:51], v[32:35], v[16:31]
	v_exp_f32_e32 v45, v45
	v_sub_f32_e32 v46, v46, v64
	ds_read_b128 v[48:51], v80 offset:23136
	s_waitcnt lgkmcnt(0)
	s_barrier
	v_mfma_f32_32x32x16_bf16 v[0:15], v[36:39], v[32:35], v[0:15]
	v_sub_f32_e32 v32, v47, v64
	v_exp_f32_e32 v36, v46
	v_exp_f32_e32 v37, v32
	v_add_f32_e32 v38, v54, v53
	v_add_f32_e32 v38, v44, v38
	v_add_f32_e32 v38, v45, v38
	v_cvt_pk_bf16_f32 v35, v36, v37
	v_add_f32_e32 v36, v36, v38
	v_add_f32_e32 v36, v37, v36
	v_fmac_f32_e32 v36, v97, v56
	ds_bpermute_b32 v37, v90, v36
	v_cvt_pk_bf16_f32 v32, v75, v76
	v_cvt_pk_bf16_f32 v33, v52, v54
	v_cvt_pk_bf16_f32 v34, v44, v45
	s_nop 1
	v_mfma_f32_32x32x16_bf16 v[16:31], v[40:43], v[32:35], v[16:31]
	v_mfma_f32_32x32x16_bf16 v[0:15], v[48:51], v[32:35], v[0:15]
	s_waitcnt lgkmcnt(0)
	v_add_f32_e32 v34, v36, v37
	v_div_scale_f32 v35, s[0:1], v34, v34, 1.0
	v_rcp_f32_e32 v36, v35
	v_lshlrev_b64 v[32:33], 11, v[84:85]
	v_lshl_add_u64 v[32:33], s[66:67], 0, v[32:33]
	v_lshl_add_u64 v[32:33], v[32:33], 0, s[4:5]
	v_fma_f32 v37, -v35, v36, 1.0
	v_fmac_f32_e32 v36, v37, v36
	v_div_scale_f32 v37, vcc, 1.0, v34, 1.0
	v_mul_f32_e32 v38, v37, v36
	v_fma_f32 v39, -v35, v38, v37
	v_fmac_f32_e32 v38, v39, v36
	v_fma_f32 v35, -v35, v38, v37
	v_div_fmas_f32 v35, v35, v36, v38
	v_div_fixup_f32 v34, v35, v34, 1.0
	v_mul_f32_e32 v16, v16, v34
	v_mul_f32_e32 v17, v17, v34
	v_mul_f32_e32 v18, v18, v34
	v_mul_f32_e32 v19, v19, v34
	v_cvt_pk_bf16_f32 v16, v16, v17
	v_cvt_pk_bf16_f32 v17, v18, v19
	v_lshl_add_u64 v[18:19], v[32:33], 0, v[128:129]
	s_mov_b64 s[0:1], 0x2d53900
	v_lshl_add_u64 v[32:33], v[18:19], 0, s[0:1]
	s_mov_b32 s0, 0x2d53000
	v_add_co_u32_e32 v18, vcc, s0, v18
	v_mul_f32_e32 v0, v0, v34
	v_mul_f32_e32 v1, v1, v34
	v_mul_f32_e32 v2, v2, v34
	v_mul_f32_e32 v3, v3, v34
	v_addc_co_u32_e32 v19, vcc, 0, v19, vcc
	v_cvt_pk_bf16_f32 v0, v0, v1
	v_cvt_pk_bf16_f32 v1, v2, v3
	global_store_dwordx2 v[18:19], v[16:17], off offset:2304
	v_mul_f32_e32 v16, v20, v34
	v_mul_f32_e32 v17, v21, v34
	v_mul_f32_e32 v18, v22, v34
	v_mul_f32_e32 v19, v23, v34
	global_store_dwordx2 v[32:33], v[0:1], off offset:64
	v_mul_f32_e32 v0, v4, v34
	v_mul_f32_e32 v1, v5, v34
	v_mul_f32_e32 v2, v6, v34
	v_mul_f32_e32 v3, v7, v34
	v_cvt_pk_bf16_f32 v16, v16, v17
	v_cvt_pk_bf16_f32 v17, v18, v19
	v_cvt_pk_bf16_f32 v0, v0, v1
	v_cvt_pk_bf16_f32 v1, v2, v3
	global_store_dwordx2 v[32:33], v[16:17], off offset:16
	v_mul_f32_e32 v16, v24, v34
	v_mul_f32_e32 v17, v25, v34
	v_mul_f32_e32 v18, v26, v34
	v_mul_f32_e32 v19, v27, v34
	global_store_dwordx2 v[32:33], v[0:1], off offset:80
	v_mul_f32_e32 v0, v8, v34
	v_mul_f32_e32 v1, v9, v34
	v_mul_f32_e32 v2, v10, v34
	v_mul_f32_e32 v3, v11, v34
	v_cvt_pk_bf16_f32 v16, v16, v17
	v_cvt_pk_bf16_f32 v17, v18, v19
	v_cvt_pk_bf16_f32 v0, v0, v1
	v_cvt_pk_bf16_f32 v1, v2, v3
	global_store_dwordx2 v[32:33], v[16:17], off offset:32
	v_mul_f32_e32 v16, v28, v34
	v_mul_f32_e32 v17, v29, v34
	v_mul_f32_e32 v18, v30, v34
	v_mul_f32_e32 v19, v31, v34
	global_store_dwordx2 v[32:33], v[0:1], off offset:96
	v_mul_f32_e32 v0, v12, v34
	v_mul_f32_e32 v1, v13, v34
	v_mul_f32_e32 v2, v14, v34
	v_mul_f32_e32 v3, v15, v34
	v_cvt_pk_bf16_f32 v16, v16, v17
	v_cvt_pk_bf16_f32 v17, v18, v19
	v_cvt_pk_bf16_f32 v0, v0, v1
	v_cvt_pk_bf16_f32 v1, v2, v3
	global_store_dwordx2 v[32:33], v[16:17], off offset:48
	global_store_dwordx2 v[32:33], v[0:1], off offset:112

.LBB0_937:
	s_or_b64 exec, exec, s[4:5]
	s_and_b32 s4, s6, 1
	s_mul_i32 s5, s4, 0x2400
	v_add_u32_e32 v91, s5, v88
	ds_read_b128 v[32:35], v91
	ds_read_b128 v[92:95], v91 offset:32
	v_lshl_add_u64 v[100:101], s[60:61], 1, v[78:79]
	s_xor_b32 s7, s4, 1
	s_mulk_i32 s7, 0x2400
	s_waitcnt lgkmcnt(1)
	v_mfma_f32_32x32x16_bf16 v[48:63], v[32:35], v[68:71], 0
	ds_read_b128 v[32:35], v91 offset:4608
	s_waitcnt lgkmcnt(1)
	v_mfma_f32_32x32x16_bf16 v[48:63], v[92:95], v[64:67], v[48:63]
	ds_read_b128 v[92:95], v91 offset:4640
	s_waitcnt lgkmcnt(1)
	v_mfma_f32_32x32x16_bf16 v[32:47], v[32:35], v[68:71], 0
	s_nop 8
	v_max_f32_e32 v91, v49, v49
	v_max_f32_e32 v97, v48, v48
	v_max_f32_e32 v91, v97, v91
	v_max3_f32 v91, v91, v50, v51
	v_max3_f32 v91, v91, v52, v53
	v_max3_f32 v91, v91, v54, v55
	v_max3_f32 v91, v91, v56, v57
	s_waitcnt lgkmcnt(0)
	v_mfma_f32_32x32x16_bf16 v[32:47], v[92:95], v[64:67], v[32:47]
	v_max3_f32 v91, v91, v58, v59
	v_max3_f32 v91, v91, v60, v61
	v_max3_f32 v91, v91, v62, v63
	s_nop 8
	v_max3_f32 v91, v91, v32, v33
	v_max3_f32 v91, v91, v34, v35
	v_max3_f32 v91, v91, v36, v37
	v_max3_f32 v91, v91, v38, v39
	v_max3_f32 v91, v91, v40, v41
	v_max3_f32 v91, v91, v42, v43
	v_max3_f32 v91, v91, v44, v45
	v_max3_f32 v91, v91, v46, v47
	ds_bpermute_b32 v92, v82, v91
	s_waitcnt lgkmcnt(0)
	v_max3_f32 v91, v86, v91, v92
	v_sub_f32_e32 v32, v32, v91
	v_sub_f32_e32 v97, v86, v91
	v_exp_f32_e32 v86, v32
	v_sub_f32_e32 v32, v33, v91
	v_exp_f32_e32 v92, v32
	v_sub_f32_e32 v32, v34, v91
	v_exp_f32_e32 v93, v32
	v_sub_f32_e32 v32, v35, v91
	v_exp_f32_e32 v94, v32
	v_sub_f32_e32 v32, v36, v91
	v_exp_f32_e32 v95, v32
	v_sub_f32_e32 v32, v37, v91
	v_exp_f32_e32 v37, v32
	global_load_dwordx4 v[32:35], v[100:101], off
	v_exp_f32_e32 v36, v97
	v_add_u32_e32 v97, s5, v84
	ds_read_b128 v[100:103], v97 offset:18432
	ds_read_b128 v[118:121], v97 offset:23040
	v_sub_f32_e32 v48, v48, v91
	v_sub_f32_e32 v49, v49, v91
	v_sub_f32_e32 v50, v50, v91
	v_sub_f32_e32 v51, v51, v91
	v_sub_f32_e32 v52, v52, v91
	v_sub_f32_e32 v53, v53, v91
	v_sub_f32_e32 v54, v54, v91
	v_sub_f32_e32 v55, v55, v91
	v_exp_f32_e32 v48, v48
	v_exp_f32_e32 v49, v49
	v_exp_f32_e32 v50, v50
	v_exp_f32_e32 v51, v51
	v_exp_f32_e32 v52, v52
	v_exp_f32_e32 v53, v53
	v_exp_f32_e32 v54, v54
	v_exp_f32_e32 v55, v55
	v_mul_f32_e32 v0, v0, v36
	v_mul_f32_e32 v1, v1, v36
	v_mul_f32_e32 v2, v2, v36
	v_mul_f32_e32 v3, v3, v36
	v_mul_f32_e32 v4, v4, v36
	v_mul_f32_e32 v5, v5, v36
	v_mul_f32_e32 v6, v6, v36
	v_mul_f32_e32 v7, v7, v36
	v_mul_f32_e32 v8, v8, v36
	v_mul_f32_e32 v9, v9, v36
	v_mul_f32_e32 v10, v10, v36
	v_mul_f32_e32 v11, v11, v36
	v_mul_f32_e32 v12, v12, v36
	v_mul_f32_e32 v13, v13, v36
	v_mul_f32_e32 v14, v14, v36
	v_mul_f32_e32 v15, v15, v36
	v_cvt_pk_bf16_f32 v114, v48, v49
	v_cvt_pk_bf16_f32 v115, v50, v51
	v_cvt_pk_bf16_f32 v116, v52, v53
	v_cvt_pk_bf16_f32 v117, v54, v55
	v_sub_f32_e32 v56, v56, v91
	v_sub_f32_e32 v57, v57, v91
	s_waitcnt lgkmcnt(1)
	v_mfma_f32_32x32x16_bf16 v[0:15], v[100:103], v[114:117], v[0:15]
	ds_read_b128 v[100:103], v97 offset:18464
	v_sub_f32_e32 v58, v58, v91
	v_sub_f32_e32 v59, v59, v91
	v_sub_f32_e32 v60, v60, v91
	v_sub_f32_e32 v61, v61, v91
	v_sub_f32_e32 v62, v62, v91
	v_sub_f32_e32 v63, v63, v91
	v_exp_f32_e32 v56, v56
	v_exp_f32_e32 v57, v57
	v_exp_f32_e32 v58, v58
	v_exp_f32_e32 v59, v59
	v_exp_f32_e32 v60, v60
	v_exp_f32_e32 v61, v61
	v_exp_f32_e32 v62, v62
	v_exp_f32_e32 v63, v63
	v_mul_f32_e32 v16, v16, v36
	v_mul_f32_e32 v17, v17, v36
	v_mul_f32_e32 v18, v18, v36
	v_mul_f32_e32 v19, v19, v36
	v_mul_f32_e32 v20, v20, v36
	v_mul_f32_e32 v21, v21, v36
	v_mul_f32_e32 v22, v22, v36
	v_mul_f32_e32 v23, v23, v36
	v_mul_f32_e32 v24, v24, v36
	v_mul_f32_e32 v25, v25, v36
	v_mul_f32_e32 v26, v26, v36
	v_mul_f32_e32 v27, v27, v36
	v_mul_f32_e32 v28, v28, v36
	v_mul_f32_e32 v29, v29, v36
	v_mul_f32_e32 v30, v30, v36
	v_mul_f32_e32 v31, v31, v36
	v_sub_f32_e32 v38, v38, v91
	v_sub_f32_e32 v39, v39, v91
	s_waitcnt lgkmcnt(1)
	v_mfma_f32_32x32x16_bf16 v[16:31], v[118:121], v[114:117], v[16:31]
	ds_read_b128 v[114:117], v97 offset:23072
	v_cvt_pk_bf16_f32 v118, v56, v57
	v_cvt_pk_bf16_f32 v119, v58, v59
	v_cvt_pk_bf16_f32 v120, v60, v61
	v_cvt_pk_bf16_f32 v121, v62, v63
	v_exp_f32_e32 v38, v38
	v_exp_f32_e32 v39, v39
	s_waitcnt lgkmcnt(1)
	v_mfma_f32_32x32x16_bf16 v[0:15], v[100:103], v[118:121], v[0:15]
	ds_read_b128 v[100:103], v97 offset:18496
	v_sub_f32_e32 v40, v40, v91
	v_sub_f32_e32 v41, v41, v91
	v_sub_f32_e32 v42, v42, v91
	v_sub_f32_e32 v43, v43, v91
	v_sub_f32_e32 v44, v44, v91
	v_sub_f32_e32 v45, v45, v91
	s_waitcnt lgkmcnt(1)
	v_mfma_f32_32x32x16_bf16 v[16:31], v[114:117], v[118:121], v[16:31]
	v_cvt_pk_bf16_f32 v114, v86, v92
	v_cvt_pk_bf16_f32 v115, v93, v94
	v_cvt_pk_bf16_f32 v116, v95, v37
	v_cvt_pk_bf16_f32 v117, v38, v39
	ds_read_b128 v[118:121], v97 offset:23104
	v_sub_f32_e32 v46, v46, v91
	v_sub_f32_e32 v47, v47, v91
	s_waitcnt lgkmcnt(1)
	v_mfma_f32_32x32x16_bf16 v[0:15], v[100:103], v[114:117], v[0:15]
	ds_read_b128 v[100:103], v97 offset:18528
	v_exp_f32_e32 v40, v40
	v_exp_f32_e32 v41, v41
	v_exp_f32_e32 v42, v42
	v_exp_f32_e32 v43, v43
	v_exp_f32_e32 v44, v44
	v_exp_f32_e32 v45, v45
	v_exp_f32_e32 v46, v46
	v_exp_f32_e32 v47, v47
	s_waitcnt lgkmcnt(1)
	v_mfma_f32_32x32x16_bf16 v[16:31], v[118:121], v[114:117], v[16:31]
	v_cvt_pk_bf16_f32 v114, v40, v41
	v_cvt_pk_bf16_f32 v115, v42, v43
	v_cvt_pk_bf16_f32 v116, v44, v45
	v_cvt_pk_bf16_f32 v117, v46, v47
	s_waitcnt lgkmcnt(0)
	s_nop 0
	v_mfma_f32_32x32x16_bf16 v[0:15], v[100:103], v[114:117], v[0:15]
	ds_read_b128 v[100:103], v97 offset:23136
	s_waitcnt lgkmcnt(0)
	v_mfma_f32_32x32x16_bf16 v[16:31], v[100:103], v[114:117], v[16:31]
	s_and_saveexec_b64 s[4:5], s[0:1]
	s_cbranch_execz .LBB0_939
	v_add_u32_e32 v97, s7, v89
	s_waitcnt vmcnt(1)
	ds_write_b128 v97, v[72:75]
.LBB0_939:
	s_or_b64 exec, exec, s[4:5]
	v_add_f32_e32 v48, 0, v48
	v_add_f32_e32 v48, v49, v48
	v_add_f32_e32 v48, v50, v48
	v_add_f32_e32 v48, v51, v48
	v_add_f32_e32 v48, v52, v48
	v_add_f32_e32 v48, v53, v48
	v_add_f32_e32 v48, v54, v48
	v_add_f32_e32 v48, v55, v48
	v_add_f32_e32 v48, v56, v48
	v_add_f32_e32 v48, v57, v48
	v_add_f32_e32 v48, v58, v48
	v_add_f32_e32 v48, v59, v48
	v_add_f32_e32 v48, v60, v48
	v_add_f32_e32 v48, v61, v48
	v_add_f32_e32 v48, v62, v48
	v_add_f32_e32 v48, v63, v48
	v_add_f32_e32 v48, v86, v48
	v_add_f32_e32 v48, v92, v48
	v_add_f32_e32 v48, v93, v48
	v_add_f32_e32 v48, v94, v48
	v_add_f32_e32 v48, v95, v48
	v_add_f32_e32 v37, v37, v48
	v_add_f32_e32 v37, v38, v37
	v_add_f32_e32 v37, v39, v37
	v_add_f32_e32 v37, v40, v37
	v_add_f32_e32 v37, v41, v37
	v_add_f32_e32 v37, v42, v37
	v_add_f32_e32 v37, v43, v37
	v_add_f32_e32 v37, v44, v37
	v_add_f32_e32 v37, v45, v37
	v_add_f32_e32 v37, v46, v37
	v_add_f32_e32 v86, v47, v37
	s_add_i32 s6, s6, 1
	s_add_i32 s60, s60, 64
	v_readlane_b32 s4, v253, 47
	v_fmac_f32_e32 v86, v90, v36
	v_add_u32_e32 v36, s7, v87
	s_cmp_eq_u32 s4, s6
	s_waitcnt vmcnt(0)
	ds_write_b128 v36, v[32:35] offset:18432
	s_waitcnt lgkmcnt(0)
	s_barrier
	s_cbranch_scc0 .LBB0_935
	v_readlane_b32 s0, v253, 47
	s_bitcmp1_b32 s0, 0
	s_cselect_b32 s0, 0x2400, 0
	v_add_u32_e32 v72, s0, v88
	ds_read_b128 v[32:35], v72
	v_add_u32_e32 v74, s0, v84
	v_cmp_gt_u32_e32 vcc, 32, v112
	s_waitcnt lgkmcnt(0)
	v_mfma_f32_32x32x16_bf16 v[48:63], v[32:35], v[68:71], 0
	ds_read_b128 v[32:35], v72 offset:32
	s_waitcnt lgkmcnt(0)
	v_mfma_f32_32x32x16_bf16 v[48:63], v[32:35], v[64:67], v[48:63]
	ds_read_b128 v[32:35], v72 offset:4608
	s_waitcnt lgkmcnt(0)
	v_mfma_f32_32x32x16_bf16 v[32:47], v[32:35], v[68:71], 0
	ds_read_b128 v[68:71], v72 offset:4640
	s_nop 7
	v_max_f32_e32 v72, v49, v49
	v_max_f32_e32 v73, v48, v48
	v_max_f32_e32 v72, v73, v72
	v_max3_f32 v72, v72, v50, v51
	s_waitcnt lgkmcnt(0)
	v_mfma_f32_32x32x16_bf16 v[32:47], v[68:71], v[64:67], v[32:47]
	v_max3_f32 v64, v72, v52, v53
	v_max3_f32 v64, v64, v54, v55
	v_max3_f32 v64, v64, v56, v57
	v_max3_f32 v64, v64, v58, v59
	v_max3_f32 v64, v64, v60, v61
	v_max3_f32 v64, v64, v62, v63
	s_nop 5
	v_max3_f32 v64, v64, v32, v33
	v_max3_f32 v64, v64, v34, v35
	v_max3_f32 v64, v64, v36, v37
	v_max3_f32 v64, v64, v38, v39
	v_max3_f32 v64, v64, v40, v41
	v_max3_f32 v64, v64, v42, v43
	v_max3_f32 v64, v64, v44, v45
	v_max3_f32 v64, v64, v46, v47
	ds_bpermute_b32 v65, v82, v64
	s_waitcnt lgkmcnt(0)
	v_max3_f32 v64, v91, v64, v65
	v_sub_f32_e32 v48, v48, v64
	v_sub_f32_e32 v49, v49, v64
	v_exp_f32_e32 v48, v48
	v_sub_f32_e32 v50, v50, v64
	v_exp_f32_e32 v49, v49
	v_sub_f32_e32 v51, v51, v64
	v_exp_f32_e32 v50, v50
	v_sub_f32_e32 v52, v52, v64
	v_exp_f32_e32 v51, v51
	v_sub_f32_e32 v53, v53, v64
	v_exp_f32_e32 v52, v52
	v_add_f32_e32 v66, 0, v48
	v_sub_f32_e32 v54, v54, v64
	v_exp_f32_e32 v53, v53
	v_add_f32_e32 v66, v49, v66
	v_sub_f32_e32 v55, v55, v64
	v_exp_f32_e32 v54, v54
	v_add_f32_e32 v66, v50, v66
	v_sub_f32_e32 v56, v56, v64
	v_exp_f32_e32 v55, v55
	v_add_f32_e32 v66, v51, v66
	v_sub_f32_e32 v57, v57, v64
	v_exp_f32_e32 v56, v56
	v_add_f32_e32 v66, v52, v66
	v_sub_f32_e32 v58, v58, v64
	v_exp_f32_e32 v57, v57
	v_add_f32_e32 v66, v53, v66
	v_sub_f32_e32 v59, v59, v64
	v_exp_f32_e32 v58, v58
	v_add_f32_e32 v66, v54, v66
	v_exp_f32_e32 v59, v59
	v_add_f32_e32 v66, v55, v66
	v_sub_f32_e32 v60, v60, v64
	v_add_f32_e32 v66, v56, v66
	v_exp_f32_e32 v60, v60
	v_sub_f32_e32 v61, v61, v64
	v_add_f32_e32 v66, v57, v66
	v_exp_f32_e32 v61, v61
	v_sub_f32_e32 v62, v62, v64
	v_add_f32_e32 v66, v58, v66
	v_exp_f32_e32 v62, v62
	v_sub_f32_e32 v63, v63, v64
	v_add_f32_e32 v66, v59, v66
	v_exp_f32_e32 v63, v63
	v_sub_f32_e32 v32, v32, v64
	v_add_f32_e32 v66, v60, v66
	v_exp_f32_e32 v67, v32
	v_sub_f32_e32 v32, v33, v64
	v_add_f32_e32 v66, v61, v66
	v_exp_f32_e32 v33, v32
	v_sub_f32_e32 v34, v34, v64
	v_add_f32_e32 v32, v62, v66
	v_exp_f32_e32 v66, v34
	v_sub_f32_e32 v34, v35, v64
	v_add_f32_e32 v32, v63, v32
	v_exp_f32_e32 v68, v34
	v_sub_f32_e32 v34, v36, v64
	v_add_f32_e32 v32, v67, v32
	v_exp_f32_e32 v69, v34
	v_sub_f32_e32 v34, v37, v64
	v_add_f32_e32 v32, v33, v32
	v_exp_f32_e32 v70, v34
	v_add_f32_e32 v32, v66, v32
	v_add_f32_e32 v32, v68, v32
	v_add_f32_e32 v32, v69, v32
	v_sub_f32_e32 v65, v91, v64
	v_add_f32_e32 v71, v70, v32
	v_sub_f32_e32 v32, v38, v64
	v_sub_f32_e32 v34, v39, v64
	v_exp_f32_e32 v72, v32
	v_exp_f32_e32 v32, v65
	v_exp_f32_e32 v65, v34
	v_sub_f32_e32 v34, v40, v64
	v_exp_f32_e32 v73, v34
	ds_read_b128 v[34:37], v74 offset:18432
	v_mul_f32_e32 v14, v14, v32
	v_mul_f32_e32 v15, v15, v32
	v_mul_f32_e32 v12, v12, v32
	v_mul_f32_e32 v13, v13, v32
	v_mul_f32_e32 v10, v10, v32
	v_mul_f32_e32 v11, v11, v32
	v_mul_f32_e32 v8, v8, v32
	v_mul_f32_e32 v9, v9, v32
	v_mul_f32_e32 v6, v6, v32
	v_mul_f32_e32 v7, v7, v32
	v_mul_f32_e32 v4, v4, v32
	v_mul_f32_e32 v5, v5, v32
	v_mul_f32_e32 v2, v2, v32
	v_mul_f32_e32 v3, v3, v32
	v_mul_f32_e32 v0, v0, v32
	v_mul_f32_e32 v1, v1, v32
	v_cvt_pk_bf16_f32 v48, v48, v49
	v_cvt_pk_bf16_f32 v49, v50, v51
	v_cvt_pk_bf16_f32 v50, v52, v53
	v_cvt_pk_bf16_f32 v51, v54, v55
	ds_read_b128 v[52:55], v74 offset:23040
	v_mul_f32_e32 v30, v30, v32
	v_mul_f32_e32 v31, v31, v32
	s_waitcnt lgkmcnt(1)
	v_mfma_f32_32x32x16_bf16 v[0:15], v[34:37], v[48:51], v[0:15]
	ds_read_b128 v[34:37], v74 offset:18464
	v_mul_f32_e64 v28, v28, v32
	v_mul_f32_e64 v29, v29, v32
	v_mul_f32_e64 v26, v26, v32
	v_mul_f32_e64 v27, v27, v32
	v_mul_f32_e32 v24, v24, v32
	v_mul_f32_e32 v25, v25, v32
	v_mul_f32_e32 v22, v22, v32
	v_mul_f32_e32 v23, v23, v32
	v_mul_f32_e32 v20, v20, v32
	v_mul_f32_e32 v21, v21, v32
	v_mul_f32_e32 v18, v18, v32
	v_mul_f32_e32 v19, v19, v32
	v_mul_f32_e32 v16, v16, v32
	v_mul_f32_e32 v17, v17, v32
	v_sub_f32_e32 v38, v41, v64
	v_cvt_pk_bf16_f32 v39, v58, v59
	s_waitcnt lgkmcnt(1)
	v_mfma_f32_32x32x16_bf16 v[16:31], v[52:55], v[48:51], v[16:31]
	v_exp_f32_e32 v52, v38
	v_cvt_pk_bf16_f32 v38, v56, v57
	v_cvt_pk_bf16_f32 v40, v60, v61
	v_cvt_pk_bf16_f32 v41, v62, v63
	ds_read_b128 v[48:51], v74 offset:23072
	s_waitcnt lgkmcnt(1)
	v_mfma_f32_32x32x16_bf16 v[0:15], v[34:37], v[38:41], v[0:15]
	v_add_f32_e32 v34, v72, v71
	v_add_f32_e32 v34, v65, v34
	v_add_f32_e32 v34, v73, v34
	v_add_f32_e32 v53, v52, v34
	v_sub_f32_e32 v34, v42, v64
	v_exp_f32_e32 v54, v34
	ds_read_b128 v[34:37], v74 offset:18496
	s_waitcnt lgkmcnt(1)
	v_mfma_f32_32x32x16_bf16 v[16:31], v[48:51], v[38:41], v[16:31]
	ds_read_b128 v[48:51], v74 offset:23104
	v_sub_f32_e32 v38, v43, v64
	v_exp_f32_e32 v55, v38
	v_cvt_pk_bf16_f32 v38, v67, v33
	v_cvt_pk_bf16_f32 v39, v66, v68
	v_cvt_pk_bf16_f32 v40, v69, v70
	v_cvt_pk_bf16_f32 v41, v72, v65
	v_sub_f32_e32 v33, v44, v64
	v_exp_f32_e32 v33, v33
	s_waitcnt lgkmcnt(1)
	v_mfma_f32_32x32x16_bf16 v[0:15], v[34:37], v[38:41], v[0:15]
	v_sub_f32_e32 v34, v45, v64
	v_exp_f32_e32 v56, v34
	v_sub_f32_e32 v34, v46, v64
	v_exp_f32_e32 v46, v34
	ds_read_b128 v[34:37], v74 offset:18528
	ds_read_b128 v[42:45], v74 offset:23136
	s_waitcnt lgkmcnt(0)
	v_mfma_f32_32x32x16_bf16 v[16:31], v[48:51], v[38:41], v[16:31]
	v_sub_f32_e32 v38, v47, v64
	v_exp_f32_e32 v47, v38
	v_cvt_pk_bf16_f32 v38, v73, v52
	v_cvt_pk_bf16_f32 v39, v54, v55
	v_cvt_pk_bf16_f32 v40, v33, v56
	v_cvt_pk_bf16_f32 v41, v46, v47
	s_barrier
	s_nop 0
	v_mfma_f32_32x32x16_bf16 v[0:15], v[34:37], v[38:41], v[0:15]
	v_add_f32_e32 v34, v54, v53
	v_add_f32_e32 v34, v55, v34
	v_add_f32_e32 v33, v33, v34
	v_add_f32_e32 v33, v56, v33
	v_add_f32_e32 v33, v46, v33
	v_add_f32_e32 v34, v47, v33
	v_fmac_f32_e32 v34, v86, v32
	v_mfma_f32_32x32x16_bf16 v[16:31], v[42:45], v[38:41], v[16:31]
	ds_bpermute_b32 v35, v82, v34
	v_mov_b32_e32 v32, 0
	v_mov_b32_e32 v33, 0
	s_and_saveexec_b64 s[0:1], vcc
	s_cbranch_execz .LBB0_942
	v_or_b32_e32 v128, s27, v112
	v_readlane_b32 s36, v250, 21
	v_lshlrev_b64 v[32:33], 2, v[128:129]
	v_readlane_b32 s40, v250, 25
	v_readlane_b32 s41, v250, 26
	v_readlane_b32 s42, v250, 27
	v_readlane_b32 s43, v250, 28
	v_readlane_b32 s44, v250, 29
	v_readlane_b32 s45, v250, 30
	v_readlane_b32 s46, v250, 31
	v_readlane_b32 s47, v250, 32
	v_lshl_add_u64 v[36:37], s[40:41], 0, v[32:33]
	v_lshl_add_u64 v[38:39], s[42:43], 0, v[32:33]
	v_lshl_add_u64 v[40:41], s[44:45], 0, v[32:33]
	v_lshl_add_u64 v[32:33], s[46:47], 0, v[32:33]
	global_load_dword v37, v[36:37], off
	v_readlane_b32 s37, v250, 22
	global_load_dword v39, v[38:39], off
	v_readlane_b32 s38, v250, 23
	global_load_dword v36, v[40:41], off
	global_load_dword v38, v[32:33], off
	v_readlane_b32 s39, v250, 24
	v_readlane_b32 s48, v250, 33
	v_readlane_b32 s49, v250, 34
	v_readlane_b32 s50, v250, 35
	v_readlane_b32 s51, v250, 36
	s_waitcnt vmcnt(0)
	v_pk_mul_f32 v[32:33], v[36:37], v[38:39]

.LBB0_944:
	s_or_b64 exec, exec, s[4:5]
	s_waitcnt lgkmcnt(0)
	s_barrier
	s_and_saveexec_b64 s[4:5], s[0:1]
	s_cbranch_execz .LBB0_946
	v_div_scale_f32 v35, s[0:1], v33, v33, 1.0
	v_rcp_f32_e32 v36, v35
	v_div_scale_f32 v37, vcc, 1.0, v33, 1.0
	s_movk_i32 s0, 0x210
	v_fma_f32 v38, -v35, v36, 1.0
	v_fmac_f32_e32 v36, v38, v36
	v_mul_f32_e32 v38, v37, v36
	v_fma_f32 v39, -v35, v38, v37
	v_fmac_f32_e32 v38, v39, v36
	v_fma_f32 v35, -v35, v38, v37
	v_div_fmas_f32 v35, v35, v36, v38
	v_div_fixup_f32 v38, v35, v33, 1.0
	v_lshl_add_u32 v33, v162, 2, v34
	v_mad_u32_u24 v37, v108, s0, v33
	v_add_u32_e32 v34, 0x400, v37
	ds_read2_b32 v[40:41], v37 offset1:33
	ds_read2_b32 v[42:43], v37 offset0:66 offset1:99
	ds_read2_b32 v[44:45], v34 offset0:8 offset1:41
	ds_read2_b32 v[46:47], v34 offset0:74 offset1:107
	v_add_u32_e32 v34, 0x800, v37
	ds_read2_b32 v[48:49], v34 offset0:16 offset1:49
	ds_read2_b32 v[50:51], v34 offset0:82 offset1:115
	v_add_u32_e32 v34, 0xc00, v37
	ds_read2_b32 v[52:53], v34 offset0:24 offset1:57
	ds_read2_b32 v[54:55], v34 offset0:90 offset1:123
	v_lshl_or_b32 v34, v108, 2, 32
	s_movk_i32 s0, 0x84
	v_mad_u32_u24 v33, v34, s0, v33
	v_add_u32_e32 v34, 0x1000, v37
	ds_read2_b32 v[56:57], v34 offset0:65 offset1:98
	v_add_u32_e32 v34, 0x1200, v37
	ds_read2_b32 v[58:59], v34 offset0:3 offset1:168
	v_add_u32_e32 v34, 0x1400, v37
	ds_read2_b32 v[60:61], v34 offset0:73 offset1:106
	v_add_u32_e32 v34, 0x1600, v37
	ds_read2_b32 v[62:63], v34 offset0:11 offset1:176
	v_add_u32_e32 v34, 0x1a00, v37
	ds_read2_b32 v[64:65], v34 offset0:19 offset1:184
	v_add_u32_e32 v34, 0x1c00, v37
	v_add_u32_e32 v36, 0x1800, v37
	ds_read2_b32 v[34:35], v34 offset0:89 offset1:122
	ds_read2_b32 v[66:67], v36 offset0:81 offset1:114
	v_readlane_b32 s6, v254, 29
	s_waitcnt lgkmcnt(2)
	v_mov_b32_e32 v36, v65
	ds_read_b32 v68, v33
	ds_read_b32 v71, v37 offset:7788
	s_waitcnt lgkmcnt(3)
	v_mov_b32_e32 v37, v34
	v_readlane_b32 s7, v254, 30
	v_pk_fma_f32 v[28:29], v[28:29], v[38:39], v[36:37] op_sel_hi:[1,0,1] neg_lo:[0,0,1] neg_hi:[0,0,1]
	v_mov_b32_e32 v70, v35
	v_pk_fma_f32 v[0:1], v[0:1], v[38:39], v[40:41] op_sel_hi:[1,0,1] neg_lo:[0,0,1] neg_hi:[0,0,1]
	v_pk_fma_f32 v[2:3], v[2:3], v[38:39], v[42:43] op_sel_hi:[1,0,1] neg_lo:[0,0,1] neg_hi:[0,0,1]
	v_pk_mul_f32 v[40:41], v[0:1], v[0:1]
	global_load_dwordx4 v[34:37], v96, s[6:7]
	v_pk_mul_f32 v[42:43], v[2:3], v[2:3]
	v_add_f32_e32 v33, v40, v41
	v_pk_fma_f32 v[4:5], v[4:5], v[38:39], v[44:45] op_sel_hi:[1,0,1] neg_lo:[0,0,1] neg_hi:[0,0,1]
	v_add_f32_e32 v33, v33, v42
	v_pk_mul_f32 v[44:45], v[4:5], v[4:5]
	v_add_f32_e32 v33, v33, v43
	v_pk_fma_f32 v[6:7], v[6:7], v[38:39], v[46:47] op_sel_hi:[1,0,1] neg_lo:[0,0,1] neg_hi:[0,0,1]
	v_add_f32_e32 v33, v33, v44
	v_pk_mul_f32 v[46:47], v[6:7], v[6:7]
	v_add_f32_e32 v33, v33, v45
	v_pk_fma_f32 v[8:9], v[8:9], v[38:39], v[48:49] op_sel_hi:[1,0,1] neg_lo:[0,0,1] neg_hi:[0,0,1]
	v_add_f32_e32 v33, v33, v46
	v_pk_mul_f32 v[48:49], v[8:9], v[8:9]
	v_add_f32_e32 v33, v33, v47
	v_pk_fma_f32 v[10:11], v[10:11], v[38:39], v[50:51] op_sel_hi:[1,0,1] neg_lo:[0,0,1] neg_hi:[0,0,1]
	v_add_f32_e32 v33, v33, v48
	v_pk_mul_f32 v[50:51], v[10:11], v[10:11]
	v_add_f32_e32 v33, v33, v49
	v_pk_fma_f32 v[12:13], v[12:13], v[38:39], v[52:53] op_sel_hi:[1,0,1] neg_lo:[0,0,1] neg_hi:[0,0,1]
	v_add_f32_e32 v33, v33, v50
	v_pk_mul_f32 v[52:53], v[12:13], v[12:13]
	v_add_f32_e32 v33, v33, v51
	v_pk_fma_f32 v[14:15], v[14:15], v[38:39], v[54:55] op_sel_hi:[1,0,1] neg_lo:[0,0,1] neg_hi:[0,0,1]
	v_add_f32_e32 v33, v33, v52
	v_pk_mul_f32 v[54:55], v[14:15], v[14:15]
	v_mov_b32_e32 v69, v56
	v_add_f32_e32 v33, v33, v53
	s_waitcnt lgkmcnt(1)
	v_pk_fma_f32 v[16:17], v[16:17], v[38:39], v[68:69] op_sel_hi:[1,0,1] neg_lo:[0,0,1] neg_hi:[0,0,1]
	v_add_f32_e32 v33, v33, v54
	v_mov_b32_e32 v74, v57
	v_mov_b32_e32 v75, v58
	v_pk_mul_f32 v[56:57], v[16:17], v[16:17]
	v_add_f32_e32 v33, v33, v55
	v_pk_fma_f32 v[18:19], v[18:19], v[38:39], v[74:75] op_sel_hi:[1,0,1] neg_lo:[0,0,1] neg_hi:[0,0,1]
	v_add_f32_e32 v33, v33, v56
	v_pk_mul_f32 v[74:75], v[18:19], v[18:19]
	v_mov_b32_e32 v58, v59
	v_mov_b32_e32 v59, v60
	v_add_f32_e32 v33, v33, v57
	v_pk_fma_f32 v[20:21], v[20:21], v[38:39], v[58:59] op_sel_hi:[1,0,1] neg_lo:[0,0,1] neg_hi:[0,0,1]
	v_add_f32_e32 v33, v33, v74
	v_mov_b32_e32 v68, v61
	v_mov_b32_e32 v69, v62
	v_pk_mul_f32 v[58:59], v[20:21], v[20:21]
	v_add_f32_e32 v33, v33, v75
	v_pk_fma_f32 v[22:23], v[22:23], v[38:39], v[68:69] op_sel_hi:[1,0,1] neg_lo:[0,0,1] neg_hi:[0,0,1]
	v_add_f32_e32 v33, v33, v58
	v_pk_mul_f32 v[68:69], v[22:23], v[22:23]
	v_mov_b32_e32 v62, v63
	v_mov_b32_e32 v63, v66
	v_add_f32_e32 v33, v33, v59
	v_mov_b32_e32 v60, v67
	v_mov_b32_e32 v61, v64
	v_pk_fma_f32 v[24:25], v[24:25], v[38:39], v[62:63] op_sel_hi:[1,0,1] neg_lo:[0,0,1] neg_hi:[0,0,1]
	v_add_f32_e32 v33, v33, v68
	s_waitcnt lgkmcnt(0)
	v_pk_fma_f32 v[30:31], v[30:31], v[38:39], v[70:71] op_sel_hi:[1,0,1] neg_lo:[0,0,1] neg_hi:[0,0,1]
	v_pk_fma_f32 v[26:27], v[26:27], v[38:39], v[60:61] op_sel_hi:[1,0,1] neg_lo:[0,0,1] neg_hi:[0,0,1]
	v_pk_mul_f32 v[38:39], v[24:25], v[24:25]
	v_add_f32_e32 v33, v33, v69
	v_add_f32_e32 v33, v33, v38
	v_pk_mul_f32 v[60:61], v[26:27], v[26:27]
	v_add_f32_e32 v33, v33, v39
	v_add_f32_e32 v33, v33, v60
	v_pk_mul_f32 v[72:73], v[28:29], v[28:29]
	v_add_f32_e32 v33, v33, v61
	v_add_f32_e32 v33, v33, v72
	v_pk_mul_f32 v[70:71], v[30:31], v[30:31]
	v_add_f32_e32 v33, v33, v73
	v_add_f32_e32 v33, v33, v70
	v_add_f32_e32 v38, v33, v71
	ds_bpermute_b32 v39, v82, v38
	s_mov_b32 s0, 0x800000
	v_sub_f32_e32 v40, 1.0, v32
	v_lshlrev_b64 v[32:33], 11, v[76:77]
	v_lshl_add_u64 v[32:33], s[66:67], 0, v[32:33]
	s_waitcnt lgkmcnt(0)
	v_add_f32_e32 v38, v38, v39
	v_fmamk_f32 v38, v38, 0x3c800000, v225
	v_mul_f32_e32 v39, 0x4b800000, v38
	v_cmp_gt_f32_e32 vcc, s0, v38
	s_mov_b32 s31, s61
	v_lshl_add_u64 v[32:33], v[32:33], 0, s[30:31]
	v_cndmask_b32_e32 v38, v38, v39, vcc
	v_rsq_f32_e32 v38, v38
	v_lshlrev_b32_e32 v128, 3, v108
	v_lshl_add_u64 v[32:33], v[32:33], 0, v[128:129]
	s_mov_b32 s0, 0x2d53000
	v_mul_f32_e32 v39, 0x45800000, v38
	v_cndmask_b32_e32 v38, v38, v39, vcc
	v_mul_f32_e32 v38, v40, v38
	v_mul_f32_e32 v0, v0, v38
	v_mul_f32_e32 v1, v1, v38
	v_mul_f32_e32 v2, v2, v38
	v_mul_f32_e32 v3, v3, v38
	s_waitcnt vmcnt(0)
	v_pk_mul_f32 v[0:1], v[34:35], v[0:1]
	v_pk_mul_f32 v[2:3], v[36:37], v[2:3]
	v_cvt_pk_bf16_f32 v0, v0, v1
	v_cvt_pk_bf16_f32 v1, v2, v3
	v_add_co_u32_e32 v2, vcc, s0, v32
	v_mul_f32_e32 v4, v4, v38
	v_mul_f32_e32 v5, v5, v38
	s_nop 0
	v_addc_co_u32_e32 v3, vcc, 0, v33, vcc
	global_store_dwordx2 v[2:3], v[0:1], off offset:1792
	global_load_dwordx4 v[0:3], v96, s[6:7] offset:32
	v_mul_f32_e32 v6, v6, v38
	v_mul_f32_e32 v7, v7, v38
	s_mov_b64 s[0:1], 0x2d53700
	v_lshl_add_u64 v[32:33], v[32:33], 0, s[0:1]
	s_waitcnt vmcnt(0)
	v_pk_mul_f32 v[0:1], v[0:1], v[4:5]
	v_pk_mul_f32 v[2:3], v[2:3], v[6:7]
	v_cvt_pk_bf16_f32 v0, v0, v1
	v_cvt_pk_bf16_f32 v1, v2, v3
	global_store_dwordx2 v[32:33], v[0:1], off offset:16
	global_load_dwordx4 v[0:3], v96, s[6:7] offset:64
	v_mul_f32_e32 v4, v8, v38
	v_mul_f32_e32 v5, v9, v38
	v_mul_f32_e32 v6, v10, v38
	v_mul_f32_e32 v7, v11, v38
	s_waitcnt vmcnt(0)
	v_pk_mul_f32 v[0:1], v[0:1], v[4:5]
	v_pk_mul_f32 v[2:3], v[2:3], v[6:7]
	v_cvt_pk_bf16_f32 v0, v0, v1
	v_cvt_pk_bf16_f32 v1, v2, v3
	global_store_dwordx2 v[32:33], v[0:1], off offset:32
	global_load_dwordx4 v[0:3], v96, s[6:7] offset:96
	v_mul_f32_e32 v4, v12, v38
	v_mul_f32_e32 v5, v13, v38
	v_mul_f32_e32 v6, v14, v38
	v_mul_f32_e32 v7, v15, v38
	s_waitcnt vmcnt(0)
	v_pk_mul_f32 v[0:1], v[0:1], v[4:5]
	v_pk_mul_f32 v[2:3], v[2:3], v[6:7]
	v_cvt_pk_bf16_f32 v0, v0, v1
	v_cvt_pk_bf16_f32 v1, v2, v3
	global_store_dwordx2 v[32:33], v[0:1], off offset:48
	global_load_dwordx4 v[0:3], v96, s[6:7] offset:128
	v_mul_f32_e32 v4, v16, v38
	v_mul_f32_e32 v5, v17, v38
	v_mul_f32_e32 v6, v18, v38
	v_mul_f32_e32 v7, v19, v38
	s_waitcnt vmcnt(0)
	v_pk_mul_f32 v[0:1], v[0:1], v[4:5]
	v_pk_mul_f32 v[2:3], v[2:3], v[6:7]
	v_cvt_pk_bf16_f32 v0, v0, v1
	v_cvt_pk_bf16_f32 v1, v2, v3
	global_store_dwordx2 v[32:33], v[0:1], off offset:64
	global_load_dwordx4 v[0:3], v96, s[6:7] offset:160
	v_mul_f32_e32 v4, v20, v38
	v_mul_f32_e32 v5, v21, v38
	v_mul_f32_e32 v6, v22, v38
	v_mul_f32_e32 v7, v23, v38
	s_waitcnt vmcnt(0)
	v_pk_mul_f32 v[0:1], v[0:1], v[4:5]
	v_pk_mul_f32 v[2:3], v[2:3], v[6:7]
	v_cvt_pk_bf16_f32 v0, v0, v1
	v_cvt_pk_bf16_f32 v1, v2, v3
	global_store_dwordx2 v[32:33], v[0:1], off offset:80
	global_load_dwordx4 v[0:3], v96, s[6:7] offset:192
	v_mul_f32_e32 v4, v24, v38
	v_mul_f32_e32 v5, v25, v38
	v_mul_f32_e32 v6, v26, v38
	v_mul_f32_e32 v7, v27, v38
	s_waitcnt vmcnt(0)
	v_pk_mul_f32 v[0:1], v[4:5], v[0:1]
	v_pk_mul_f32 v[2:3], v[6:7], v[2:3]
	v_cvt_pk_bf16_f32 v0, v0, v1
	v_cvt_pk_bf16_f32 v1, v2, v3
	global_store_dwordx2 v[32:33], v[0:1], off offset:96
	global_load_dwordx4 v[0:3], v96, s[6:7] offset:224
	v_mul_f32_e32 v4, v28, v38
	v_mul_f32_e32 v5, v29, v38
	v_mul_f32_e32 v6, v30, v38
	v_mul_f32_e32 v7, v31, v38
	s_waitcnt vmcnt(0)
	v_pk_mul_f32 v[0:1], v[4:5], v[0:1]
	v_pk_mul_f32 v[2:3], v[6:7], v[2:3]
	v_cvt_pk_bf16_f32 v0, v0, v1
	v_cvt_pk_bf16_f32 v1, v2, v3
	global_store_dwordx2 v[32:33], v[0:1], off offset:112

.LBB0_961:
	s_or_b64 exec, exec, s[0:1]
	global_load_dwordx4 v[78:81], v[82:83], off offset:256
	ds_read_b128 v[2:5], v95 offset:9216
	ds_read_b128 v[6:9], v95 offset:9248
	s_waitcnt lgkmcnt(1)
	v_mfma_f32_32x32x16_bf16 v[50:65], v[2:5], v[70:73], 0
	ds_read_b128 v[2:5], v95 offset:13824
	ds_read_b128 v[130:133], v95 offset:13856
	s_waitcnt lgkmcnt(2)
	v_mfma_f32_32x32x16_bf16 v[50:65], v[6:9], v[66:69], v[50:65]
	s_waitcnt lgkmcnt(1)
	v_mfma_f32_32x32x16_bf16 v[2:17], v[2:5], v[70:73], 0
	s_waitcnt lgkmcnt(0)
	v_mfma_f32_32x32x16_bf16 v[2:17], v[130:133], v[66:69], v[2:17]
	s_nop 7
	v_max_f32_e32 v130, v51, v51
	v_max_f32_e32 v131, v50, v50
	v_max_f32_e32 v130, v131, v130
	v_max3_f32 v130, v130, v52, v53
	v_max3_f32 v130, v130, v54, v55
	v_max3_f32 v130, v130, v56, v57
	v_max3_f32 v130, v130, v58, v59
	v_max3_f32 v130, v130, v60, v61
	v_max3_f32 v130, v130, v62, v63
	v_max3_f32 v130, v130, v64, v65
	v_max3_f32 v130, v130, v2, v3
	v_max3_f32 v130, v130, v4, v5
	v_max3_f32 v130, v130, v6, v7
	v_max3_f32 v130, v130, v8, v9
	v_max3_f32 v130, v130, v10, v11
	v_max3_f32 v130, v130, v12, v13
	v_max3_f32 v130, v130, v14, v15
	v_max3_f32 v130, v130, v16, v17
	ds_bpermute_b32 v131, v93, v130
	s_waitcnt lgkmcnt(0)
	v_max3_f32 v132, v92, v130, v131
	v_sub_f32_e32 v2, v2, v132
	v_exp_f32_e32 v164, v2
	v_sub_f32_e32 v2, v3, v132
	v_exp_f32_e32 v165, v2
	v_sub_f32_e32 v2, v4, v132
	v_exp_f32_e32 v166, v2
	v_sub_f32_e32 v2, v5, v132
	v_exp_f32_e32 v167, v2
	v_sub_f32_e32 v2, v6, v132
	v_sub_f32_e32 v50, v50, v132
	v_exp_f32_e32 v168, v2
	v_sub_f32_e32 v2, v7, v132
	v_exp_f32_e32 v147, v50
	v_sub_f32_e32 v50, v51, v132
	v_exp_f32_e32 v169, v2
	v_sub_f32_e32 v2, v8, v132
	v_exp_f32_e32 v148, v50
	v_sub_f32_e32 v50, v52, v132
	v_exp_f32_e32 v170, v2
	v_sub_f32_e32 v2, v9, v132
	v_exp_f32_e32 v149, v50
	v_sub_f32_e32 v50, v53, v132
	v_exp_f32_e32 v171, v2
	v_sub_f32_e32 v2, v10, v132
	v_exp_f32_e32 v150, v50
	v_sub_f32_e32 v50, v54, v132
	v_exp_f32_e32 v172, v2
	v_sub_f32_e32 v2, v11, v132
	v_sub_f32_e32 v92, v92, v132
	v_exp_f32_e32 v151, v50
	v_sub_f32_e32 v50, v55, v132
	v_exp_f32_e32 v173, v2
	v_sub_f32_e32 v2, v12, v132
	v_exp_f32_e32 v152, v50
	v_sub_f32_e32 v50, v56, v132
	v_exp_f32_e32 v174, v2
	v_sub_f32_e32 v2, v13, v132
	v_exp_f32_e32 v92, v92
	v_exp_f32_e32 v153, v50
	v_sub_f32_e32 v50, v57, v132
	v_exp_f32_e32 v175, v2
	v_sub_f32_e32 v2, v14, v132
	v_exp_f32_e32 v154, v50
	v_exp_f32_e32 v176, v2
	v_sub_f32_e32 v2, v15, v132
	v_sub_f32_e32 v50, v58, v132
	v_exp_f32_e32 v177, v2
	v_sub_f32_e32 v2, v16, v132
	v_exp_f32_e32 v155, v50
	v_sub_f32_e32 v50, v59, v132
	v_exp_f32_e32 v178, v2
	v_sub_f32_e32 v2, v17, v132
	v_mul_f32_e32 v16, v32, v92
	v_mul_f32_e32 v17, v33, v92
	v_mul_f32_e32 v14, v30, v92
	v_mul_f32_e32 v15, v31, v92
	v_mul_f32_e32 v12, v28, v92
	v_mul_f32_e32 v13, v29, v92
	v_mul_f32_e32 v10, v26, v92
	v_mul_f32_e32 v11, v27, v92
	v_mul_f32_e32 v8, v24, v92
	v_mul_f32_e32 v9, v25, v92
	v_mul_f32_e32 v6, v22, v92
	v_mul_f32_e32 v7, v23, v92
	v_mul_f32_e32 v32, v48, v92
	v_mul_f32_e32 v33, v49, v92
	v_mul_f32_e32 v30, v46, v92
	v_mul_f32_e32 v31, v47, v92
	v_mul_f32_e32 v28, v44, v92
	v_mul_f32_e32 v29, v45, v92
	v_mul_f32_e32 v26, v42, v92
	v_mul_f32_e32 v27, v43, v92
	v_mul_f32_e32 v24, v40, v92
	v_mul_f32_e32 v25, v41, v92
	v_mul_f32_e32 v22, v38, v92
	v_mul_f32_e32 v23, v39, v92
	ds_read_b128 v[38:41], v94 offset:32256
	ds_read_b128 v[42:45], v94 offset:27648
	ds_read_b128 v[46:49], v94 offset:27680
	v_exp_f32_e32 v156, v50
	v_sub_f32_e32 v50, v60, v132
	v_exp_f32_e32 v157, v50
	v_sub_f32_e32 v50, v61, v132
	v_exp_f32_e32 v179, v2
	v_mul_f32_e32 v4, v20, v92
	v_mul_f32_e32 v5, v21, v92
	v_mul_f32_e32 v2, v18, v92
	v_mul_f32_e32 v3, v19, v92
	v_mul_f32_e32 v20, v36, v92
	v_mul_f32_e32 v21, v37, v92
	v_mul_f32_e32 v18, v34, v92
	v_mul_f32_e32 v19, v35, v92
	v_cvt_pk_bf16_f32 v34, v147, v148
	v_cvt_pk_bf16_f32 v35, v149, v150
	v_cvt_pk_bf16_f32 v36, v151, v152
	v_cvt_pk_bf16_f32 v37, v153, v154
	v_exp_f32_e32 v158, v50
	v_sub_f32_e32 v50, v62, v132
	s_waitcnt lgkmcnt(2)
	v_mfma_f32_32x32x16_bf16 v[18:33], v[38:41], v[34:37], v[18:33]
	ds_read_b128 v[38:41], v94 offset:32288
	v_exp_f32_e32 v159, v50
	v_sub_f32_e32 v50, v63, v132
	v_exp_f32_e32 v160, v50
	v_sub_f32_e32 v50, v64, v132
	v_exp_f32_e32 v161, v50
	v_sub_f32_e32 v50, v65, v132
	s_waitcnt lgkmcnt(2)
	v_mfma_f32_32x32x16_bf16 v[2:17], v[42:45], v[34:37], v[2:17]
	v_exp_f32_e32 v163, v50
	v_cvt_pk_bf16_f32 v34, v155, v156
	v_cvt_pk_bf16_f32 v35, v157, v158
	v_cvt_pk_bf16_f32 v36, v159, v160
	v_cvt_pk_bf16_f32 v37, v161, v163
	s_waitcnt lgkmcnt(1)
	s_nop 0
	v_mfma_f32_32x32x16_bf16 v[2:17], v[46:49], v[34:37], v[2:17]
	s_waitcnt lgkmcnt(0)
	v_mfma_f32_32x32x16_bf16 v[18:33], v[38:41], v[34:37], v[18:33]
	ds_read_b128 v[38:41], v94 offset:27712
	ds_read_b128 v[42:45], v94 offset:32320
	v_cvt_pk_bf16_f32 v34, v164, v165
	v_cvt_pk_bf16_f32 v35, v166, v167
	v_cvt_pk_bf16_f32 v36, v168, v169
	v_cvt_pk_bf16_f32 v37, v170, v171
	s_waitcnt lgkmcnt(1)
	s_nop 0
	v_mfma_f32_32x32x16_bf16 v[2:17], v[38:41], v[34:37], v[2:17]
	s_waitcnt lgkmcnt(0)
	v_mfma_f32_32x32x16_bf16 v[18:33], v[42:45], v[34:37], v[18:33]
	ds_read_b128 v[38:41], v94 offset:27744
	ds_read_b128 v[42:45], v94 offset:32352
	v_cvt_pk_bf16_f32 v34, v172, v173
	v_cvt_pk_bf16_f32 v35, v174, v175
	v_cvt_pk_bf16_f32 v36, v176, v177
	v_cvt_pk_bf16_f32 v37, v178, v179
	s_waitcnt lgkmcnt(1)
	s_nop 0
	v_mfma_f32_32x32x16_bf16 v[2:17], v[38:41], v[34:37], v[2:17]
	s_waitcnt lgkmcnt(0)
	v_mfma_f32_32x32x16_bf16 v[18:33], v[42:45], v[34:37], v[18:33]
	s_and_saveexec_b64 s[0:1], s[36:37]
	s_cbranch_execz .LBB0_963
	s_waitcnt vmcnt(1)
	ds_write_b128 v1, v[74:77]

.LBB0_965:
	s_or_b64 exec, exec, s[0:1]
	global_load_dwordx4 v[78:81], v[82:83], off offset:384
	ds_read_b128 v[34:37], v95
	ds_read_b128 v[38:41], v95 offset:32
	s_waitcnt lgkmcnt(1)
	v_mfma_f32_32x32x16_bf16 v[50:65], v[34:37], v[70:73], 0
	ds_read_b128 v[34:37], v95 offset:4608
	ds_read_b128 v[88:91], v95 offset:4640
	s_waitcnt lgkmcnt(2)
	v_mfma_f32_32x32x16_bf16 v[50:65], v[38:41], v[66:69], v[50:65]
	s_waitcnt lgkmcnt(1)
	v_mfma_f32_32x32x16_bf16 v[34:49], v[34:37], v[70:73], 0
	s_nop 9
	v_max_f32_e32 v82, v51, v51
	v_max_f32_e32 v83, v50, v50
	v_max_f32_e32 v82, v83, v82
	v_max3_f32 v82, v82, v52, v53
	v_max3_f32 v82, v82, v54, v55
	v_max3_f32 v82, v82, v56, v57
	v_max3_f32 v82, v82, v58, v59
	s_waitcnt lgkmcnt(0)
	v_mfma_f32_32x32x16_bf16 v[34:49], v[88:91], v[66:69], v[34:49]
	v_max3_f32 v82, v82, v60, v61
	v_max3_f32 v82, v82, v62, v63
	v_max3_f32 v82, v82, v64, v65
	s_nop 8
	v_max3_f32 v82, v82, v34, v35
	v_max3_f32 v82, v82, v36, v37
	v_max3_f32 v82, v82, v38, v39
	v_max3_f32 v82, v82, v40, v41
	v_max3_f32 v82, v82, v42, v43
	v_max3_f32 v82, v82, v44, v45
	v_max3_f32 v82, v82, v46, v47
	v_max3_f32 v82, v82, v48, v49
	ds_bpermute_b32 v83, v93, v82
	s_waitcnt lgkmcnt(0)
	v_max3_f32 v82, v132, v82, v83
	v_sub_f32_e32 v34, v34, v82
	v_exp_f32_e32 v83, v34
	v_sub_f32_e32 v34, v35, v82
	v_exp_f32_e32 v35, v34
	v_sub_f32_e32 v34, v36, v82
	v_exp_f32_e32 v36, v34
	v_sub_f32_e32 v34, v37, v82
	v_exp_f32_e32 v37, v34
	v_sub_f32_e32 v34, v38, v82
	v_exp_f32_e32 v38, v34
	v_sub_f32_e32 v34, v39, v82
	v_exp_f32_e32 v39, v34
	v_sub_f32_e32 v34, v40, v82
	v_exp_f32_e32 v40, v34
	v_sub_f32_e32 v34, v41, v82
	v_exp_f32_e32 v41, v34
	v_sub_f32_e32 v34, v42, v82
	v_exp_f32_e32 v42, v34
	v_sub_f32_e32 v34, v43, v82
	v_exp_f32_e32 v43, v34
	v_sub_f32_e32 v34, v44, v82
	v_exp_f32_e32 v44, v34
	v_sub_f32_e32 v34, v45, v82
	v_exp_f32_e32 v45, v34
	v_sub_f32_e32 v34, v46, v82
	v_exp_f32_e32 v46, v34
	v_sub_f32_e32 v34, v47, v82
	v_exp_f32_e32 v47, v34
	v_sub_f32_e32 v34, v48, v82
	v_sub_f32_e32 v88, v132, v82
	v_sub_f32_e32 v50, v50, v82
	v_sub_f32_e32 v51, v51, v82
	v_sub_f32_e32 v52, v52, v82
	v_sub_f32_e32 v53, v53, v82
	v_sub_f32_e32 v54, v54, v82
	v_sub_f32_e32 v55, v55, v82
	v_sub_f32_e32 v56, v56, v82
	v_sub_f32_e32 v57, v57, v82
	v_exp_f32_e32 v48, v34
	v_sub_f32_e32 v34, v49, v82
	v_exp_f32_e32 v50, v50
	v_exp_f32_e32 v51, v51
	v_exp_f32_e32 v52, v52
	v_exp_f32_e32 v53, v53
	v_exp_f32_e32 v54, v54
	v_exp_f32_e32 v55, v55
	v_exp_f32_e32 v56, v56
	v_exp_f32_e32 v57, v57
	v_exp_f32_e32 v49, v34
	v_exp_f32_e32 v34, v88
	ds_read_b128 v[130:133], v94 offset:23040
	ds_read_b128 v[180:183], v94 offset:18432
	ds_read_b128 v[184:187], v94 offset:18464
	v_cvt_pk_bf16_f32 v88, v50, v51
	v_cvt_pk_bf16_f32 v89, v52, v53
	v_mul_f32_e32 v32, v32, v34
	v_mul_f32_e32 v33, v33, v34
	v_mul_f32_e32 v30, v30, v34
	v_mul_f32_e32 v31, v31, v34
	v_mul_f32_e32 v28, v28, v34
	v_mul_f32_e32 v29, v29, v34
	v_mul_f32_e32 v26, v26, v34
	v_mul_f32_e32 v27, v27, v34
	v_mul_f32_e32 v24, v24, v34
	v_mul_f32_e32 v25, v25, v34
	v_mul_f32_e32 v22, v22, v34
	v_mul_f32_e32 v23, v23, v34
	v_mul_f32_e32 v20, v20, v34
	v_mul_f32_e32 v21, v21, v34
	v_mul_f32_e32 v18, v18, v34
	v_mul_f32_e32 v19, v19, v34
	v_cvt_pk_bf16_f32 v90, v54, v55
	v_cvt_pk_bf16_f32 v91, v56, v57
	v_mul_f32_e32 v16, v16, v34
	v_mul_f32_e32 v17, v17, v34
	v_mul_f32_e32 v14, v14, v34
	v_mul_f32_e32 v15, v15, v34
	v_mul_f32_e32 v12, v12, v34
	v_mul_f32_e32 v13, v13, v34
	v_mul_f32_e32 v10, v10, v34
	v_mul_f32_e32 v11, v11, v34
	v_mul_f32_e32 v8, v8, v34
	v_mul_f32_e32 v9, v9, v34
	v_mul_f32_e32 v6, v6, v34
	v_mul_f32_e32 v7, v7, v34
	v_mul_f32_e32 v4, v4, v34
	v_mul_f32_e32 v5, v5, v34
	v_mul_f32_e32 v2, v2, v34
	v_mul_f32_e32 v3, v3, v34
	s_waitcnt lgkmcnt(2)
	v_mfma_f32_32x32x16_bf16 v[18:33], v[130:133], v[88:91], v[18:33]
	ds_read_b128 v[130:133], v94 offset:23072
	v_sub_f32_e32 v58, v58, v82
	v_sub_f32_e32 v59, v59, v82
	v_sub_f32_e32 v60, v60, v82
	v_sub_f32_e32 v61, v61, v82
	v_sub_f32_e32 v62, v62, v82
	v_sub_f32_e32 v63, v63, v82
	s_waitcnt lgkmcnt(2)
	v_mfma_f32_32x32x16_bf16 v[2:17], v[180:183], v[88:91], v[2:17]
	v_sub_f32_e32 v64, v64, v82
	v_sub_f32_e32 v65, v65, v82
	v_exp_f32_e32 v58, v58
	v_exp_f32_e32 v59, v59
	v_exp_f32_e32 v60, v60
	v_exp_f32_e32 v61, v61
	v_exp_f32_e32 v62, v62
	v_exp_f32_e32 v63, v63
	v_exp_f32_e32 v64, v64
	v_exp_f32_e32 v65, v65
	v_cvt_pk_bf16_f32 v88, v58, v59
	v_cvt_pk_bf16_f32 v89, v60, v61
	v_cvt_pk_bf16_f32 v90, v62, v63
	v_cvt_pk_bf16_f32 v91, v64, v65
	s_waitcnt lgkmcnt(1)
	s_nop 0
	v_mfma_f32_32x32x16_bf16 v[2:17], v[184:187], v[88:91], v[2:17]
	s_waitcnt lgkmcnt(0)
	v_mfma_f32_32x32x16_bf16 v[18:33], v[130:133], v[88:91], v[18:33]
	ds_read_b128 v[130:133], v94 offset:18496
	ds_read_b128 v[180:183], v94 offset:23104
	v_cvt_pk_bf16_f32 v88, v83, v35
	v_cvt_pk_bf16_f32 v89, v36, v37
	v_cvt_pk_bf16_f32 v90, v38, v39
	v_cvt_pk_bf16_f32 v91, v40, v41
	s_waitcnt lgkmcnt(1)
	s_nop 0
	v_mfma_f32_32x32x16_bf16 v[2:17], v[130:133], v[88:91], v[2:17]
	s_waitcnt lgkmcnt(0)
	v_mfma_f32_32x32x16_bf16 v[18:33], v[180:183], v[88:91], v[18:33]
	ds_read_b128 v[130:133], v94 offset:18528
	ds_read_b128 v[180:183], v94 offset:23136
	v_cvt_pk_bf16_f32 v88, v42, v43
	v_cvt_pk_bf16_f32 v89, v44, v45
	v_cvt_pk_bf16_f32 v90, v46, v47
	v_cvt_pk_bf16_f32 v91, v48, v49
	s_waitcnt lgkmcnt(1)
	s_nop 0
	v_mfma_f32_32x32x16_bf16 v[2:17], v[130:133], v[88:91], v[2:17]
	s_waitcnt lgkmcnt(0)
	v_mfma_f32_32x32x16_bf16 v[18:33], v[180:183], v[88:91], v[18:33]
	s_and_saveexec_b64 s[0:1], s[36:37]
	s_cbranch_execz .LBB0_967
	s_waitcnt vmcnt(1)
	ds_write_b128 v1, v[74:77] offset:9216
.LBB0_967:
	s_or_b64 exec, exec, s[0:1]
	v_add_f32_e32 v1, 0, v100
	v_add_f32_e32 v1, v101, v1
	v_add_f32_e32 v1, v102, v1
	v_add_f32_e32 v1, v103, v1
	v_add_f32_e32 v1, v105, v1
	v_add_f32_e32 v1, v106, v1
	v_add_f32_e32 v1, v107, v1
	v_add_f32_e32 v1, v116, v1
	v_add_f32_e32 v1, v117, v1
	v_add_f32_e32 v1, v118, v1
	v_add_f32_e32 v1, v119, v1
	v_add_f32_e32 v1, v120, v1
	v_add_f32_e32 v1, v121, v1
	v_add_f32_e32 v1, v122, v1
	v_add_f32_e32 v1, v123, v1
	v_add_f32_e32 v1, v124, v1
	v_add_f32_e32 v1, v125, v1
	v_add_f32_e32 v1, v126, v1
	v_add_f32_e32 v1, v127, v1
	v_add_f32_e32 v1, v134, v1
	v_add_f32_e32 v1, v135, v1
	v_add_f32_e32 v1, v136, v1
	v_add_f32_e32 v1, v137, v1
	v_add_f32_e32 v1, v138, v1
	v_add_f32_e32 v1, v139, v1
	v_add_f32_e32 v1, v140, v1
	v_add_f32_e32 v1, v141, v1
	v_add_f32_e32 v1, v142, v1
	v_add_f32_e32 v1, v143, v1
	v_add_f32_e32 v1, v144, v1
	v_add_f32_e32 v1, v145, v1
	v_add_f32_e32 v1, v146, v1
	v_add_f32_e32 v0, v0, v1
	v_add_f32_e32 v1, 0, v147
	v_add_f32_e32 v1, v148, v1
	v_add_f32_e32 v1, v149, v1
	v_add_f32_e32 v1, v150, v1
	v_add_f32_e32 v1, v151, v1
	v_add_f32_e32 v1, v152, v1
	v_add_f32_e32 v1, v153, v1
	v_add_f32_e32 v1, v154, v1
	v_add_f32_e32 v1, v155, v1
	v_add_f32_e32 v1, v156, v1
	v_add_f32_e32 v1, v157, v1
	v_add_f32_e32 v1, v158, v1
	v_add_f32_e32 v1, v159, v1
	v_add_f32_e32 v1, v160, v1
	v_add_f32_e32 v1, v161, v1
	v_add_f32_e32 v1, v163, v1
	v_add_f32_e32 v1, v164, v1
	v_add_f32_e32 v1, v165, v1
	v_add_f32_e32 v1, v166, v1
	v_add_f32_e32 v1, v167, v1
	v_add_f32_e32 v1, v168, v1
	v_add_f32_e32 v1, v169, v1
	v_add_f32_e32 v1, v170, v1
	v_add_f32_e32 v1, v171, v1
	v_add_f32_e32 v1, v172, v1
	v_add_f32_e32 v1, v173, v1
	v_add_f32_e32 v1, v174, v1
	v_add_f32_e32 v1, v175, v1
	v_add_f32_e32 v1, v176, v1
	v_add_f32_e32 v1, v177, v1
	v_add_f32_e32 v1, v178, v1
	v_add_f32_e32 v1, v179, v1
	v_fmac_f32_e32 v1, v0, v92
	v_add_f32_e32 v0, 0, v50
	v_add_f32_e32 v0, v51, v0
	v_add_f32_e32 v0, v52, v0
	v_add_f32_e32 v0, v53, v0
	v_add_f32_e32 v0, v54, v0
	v_add_f32_e32 v0, v55, v0
	v_add_f32_e32 v0, v56, v0
	v_add_f32_e32 v0, v57, v0
	v_add_f32_e32 v0, v58, v0
	v_add_f32_e32 v0, v59, v0
	v_add_f32_e32 v0, v60, v0
	v_add_f32_e32 v0, v61, v0
	v_add_f32_e32 v0, v62, v0
	v_add_f32_e32 v0, v63, v0
	v_add_f32_e32 v0, v64, v0
	v_add_f32_e32 v0, v65, v0
	v_add_f32_e32 v0, v83, v0
	v_add_f32_e32 v0, v35, v0
	v_add_f32_e32 v0, v36, v0
	v_add_f32_e32 v0, v37, v0
	v_add_f32_e32 v0, v38, v0
	v_add_f32_e32 v0, v39, v0
	v_add_f32_e32 v0, v40, v0
	v_add_f32_e32 v0, v41, v0
	v_add_f32_e32 v0, v42, v0
	v_add_f32_e32 v0, v43, v0
	v_add_f32_e32 v0, v44, v0
	v_add_f32_e32 v0, v45, v0
	v_add_f32_e32 v0, v46, v0
	v_add_f32_e32 v0, v47, v0
	v_add_f32_e32 v0, v48, v0
	v_add_f32_e32 v0, v49, v0
	v_fmac_f32_e32 v0, v1, v34
	s_waitcnt vmcnt(0)
	ds_write_b128 v97, v[78:81] offset:27648
	s_waitcnt lgkmcnt(0)
	s_barrier
	ds_read_b128 v[34:37], v95 offset:9216
	ds_read_b128 v[38:41], v95 offset:9248
	s_waitcnt lgkmcnt(1)
	v_mfma_f32_32x32x16_bf16 v[50:65], v[34:37], v[70:73], 0
	ds_read_b128 v[34:37], v95 offset:13824
	ds_read_b128 v[74:77], v95 offset:13856
	v_cmp_gt_u32_e64 s[16:17], 32, v112
	s_waitcnt lgkmcnt(2)
	v_mfma_f32_32x32x16_bf16 v[50:65], v[38:41], v[66:69], v[50:65]
	s_waitcnt lgkmcnt(1)
	v_mfma_f32_32x32x16_bf16 v[34:49], v[34:37], v[70:73], 0
	s_nop 9
	v_max_f32_e32 v1, v51, v51
	s_waitcnt lgkmcnt(0)
	v_mfma_f32_32x32x16_bf16 v[34:49], v[74:77], v[66:69], v[34:49]
	v_max_f32_e32 v66, v50, v50
	v_max_f32_e32 v1, v66, v1
	v_max3_f32 v1, v1, v52, v53
	v_max3_f32 v1, v1, v54, v55
	v_max3_f32 v1, v1, v56, v57
	v_max3_f32 v1, v1, v58, v59
	v_max3_f32 v1, v1, v60, v61
	v_max3_f32 v1, v1, v62, v63
	v_max3_f32 v1, v1, v64, v65
	s_nop 2
	v_max3_f32 v1, v1, v34, v35
	v_max3_f32 v1, v1, v36, v37
	v_max3_f32 v1, v1, v38, v39
	v_max3_f32 v1, v1, v40, v41
	v_max3_f32 v1, v1, v42, v43
	v_max3_f32 v1, v1, v44, v45
	v_max3_f32 v1, v1, v46, v47
	v_max3_f32 v1, v1, v48, v49
	ds_bpermute_b32 v66, v93, v1
	s_waitcnt lgkmcnt(0)
	v_max3_f32 v1, v82, v1, v66
	v_sub_f32_e32 v50, v50, v1
	v_exp_f32_e32 v67, v50
	v_sub_f32_e32 v51, v51, v1
	v_exp_f32_e32 v51, v51
	v_sub_f32_e32 v52, v52, v1
	v_exp_f32_e32 v68, v52
	v_sub_f32_e32 v52, v53, v1
	v_exp_f32_e32 v53, v52
	v_sub_f32_e32 v52, v54, v1
	v_add_f32_e32 v50, 0, v67
	v_exp_f32_e32 v54, v52
	v_sub_f32_e32 v52, v55, v1
	v_add_f32_e32 v50, v51, v50
	v_exp_f32_e32 v55, v52
	v_sub_f32_e32 v52, v56, v1
	v_add_f32_e32 v50, v68, v50
	v_exp_f32_e32 v56, v52
	v_sub_f32_e32 v52, v57, v1
	v_add_f32_e32 v50, v53, v50
	v_exp_f32_e32 v57, v52
	v_sub_f32_e32 v52, v58, v1
	v_add_f32_e32 v50, v54, v50
	v_exp_f32_e32 v58, v52
	v_sub_f32_e32 v52, v59, v1
	v_add_f32_e32 v50, v55, v50
	v_exp_f32_e32 v59, v52
	v_sub_f32_e32 v52, v60, v1
	v_add_f32_e32 v50, v56, v50
	v_exp_f32_e32 v60, v52
	v_sub_f32_e32 v52, v61, v1
	v_add_f32_e32 v50, v57, v50
	v_exp_f32_e32 v61, v52
	v_sub_f32_e32 v52, v62, v1
	v_add_f32_e32 v50, v58, v50
	v_exp_f32_e32 v62, v52
	v_sub_f32_e32 v52, v63, v1
	v_add_f32_e32 v50, v59, v50
	v_exp_f32_e32 v63, v52
	v_sub_f32_e32 v52, v64, v1
	v_add_f32_e32 v50, v60, v50
	v_exp_f32_e32 v64, v52
	v_sub_f32_e32 v52, v65, v1
	v_add_f32_e32 v50, v61, v50
	v_exp_f32_e32 v65, v52
	v_sub_f32_e32 v34, v34, v1
	v_add_f32_e32 v50, v62, v50
	v_exp_f32_e32 v69, v34
	v_sub_f32_e32 v35, v35, v1
	v_add_f32_e32 v50, v63, v50
	v_exp_f32_e32 v70, v35
	v_sub_f32_e32 v35, v36, v1
	v_add_f32_e32 v50, v64, v50
	v_exp_f32_e32 v71, v35
	v_sub_f32_e32 v35, v37, v1
	v_add_f32_e32 v50, v65, v50
	v_exp_f32_e32 v72, v35
	v_sub_f32_e32 v35, v38, v1
	v_add_f32_e32 v34, v69, v50
	v_exp_f32_e32 v73, v35
	v_sub_f32_e32 v35, v39, v1
	v_add_f32_e32 v34, v70, v34
	v_exp_f32_e32 v74, v35
	v_sub_f32_e32 v35, v40, v1
	v_add_f32_e32 v34, v71, v34
	v_exp_f32_e32 v75, v35
	v_sub_f32_e32 v35, v41, v1
	v_add_f32_e32 v34, v72, v34
	v_exp_f32_e32 v76, v35
	v_sub_f32_e32 v35, v42, v1
	v_add_f32_e32 v34, v73, v34
	v_exp_f32_e32 v77, v35
	v_sub_f32_e32 v35, v43, v1
	v_add_f32_e32 v34, v74, v34
	v_exp_f32_e32 v78, v35
	v_sub_f32_e32 v35, v44, v1
	v_add_f32_e32 v34, v75, v34
	v_exp_f32_e32 v79, v35
	v_sub_f32_e32 v35, v45, v1
	v_add_f32_e32 v34, v76, v34
	v_exp_f32_e32 v80, v35
	v_sub_f32_e32 v35, v46, v1
	v_add_f32_e32 v34, v77, v34
	v_exp_f32_e32 v81, v35
	v_sub_f32_e32 v35, v47, v1
	v_sub_f32_e32 v66, v82, v1
	v_add_f32_e32 v34, v78, v34
	v_exp_f32_e32 v82, v35
	v_sub_f32_e32 v35, v48, v1
	v_add_f32_e32 v34, v79, v34
	v_exp_f32_e32 v83, v35
	v_sub_f32_e32 v1, v49, v1
	v_add_f32_e32 v34, v80, v34
	v_exp_f32_e32 v88, v1
	v_exp_f32_e32 v52, v66
	v_add_f32_e32 v34, v81, v34
	v_add_f32_e32 v34, v82, v34
	v_add_f32_e32 v34, v83, v34
	v_add_f32_e32 v50, v88, v34
	v_mul_f32_e32 v44, v12, v52
	v_mul_f32_e32 v45, v13, v52
	v_mul_f32_e32 v42, v10, v52
	v_mul_f32_e32 v43, v11, v52
	v_mul_f32_e32 v40, v8, v52
	v_mul_f32_e32 v41, v9, v52
	v_mul_f32_e32 v38, v6, v52
	v_mul_f32_e32 v39, v7, v52
	v_mul_f32_e32 v36, v4, v52
	v_mul_f32_e32 v37, v5, v52
	v_mul_f32_e32 v34, v2, v52
	v_mul_f32_e32 v35, v3, v52
	v_mul_f32_e32 v12, v30, v52
	v_mul_f32_e32 v13, v31, v52
	v_mul_f32_e32 v10, v28, v52
	v_mul_f32_e32 v11, v29, v52
	v_mul_f32_e32 v8, v26, v52
	v_mul_f32_e32 v9, v27, v52
	v_mul_f32_e32 v6, v24, v52
	v_mul_f32_e32 v7, v25, v52
	v_mul_f32_e32 v4, v22, v52
	v_mul_f32_e32 v5, v23, v52
	v_mul_f32_e32 v2, v20, v52
	v_mul_f32_e32 v3, v21, v52
	ds_read_b128 v[20:23], v94 offset:32256
	ds_read_b128 v[24:27], v94 offset:27648
	ds_read_b128 v[28:31], v94 offset:27680
	v_fmac_f32_e32 v50, v0, v52
	v_mul_f32_e32 v48, v16, v52
	v_mul_f32_e32 v49, v17, v52
	v_mul_f32_e32 v46, v14, v52
	v_mul_f32_e32 v47, v15, v52
	v_mul_f32_e32 v14, v32, v52
	v_mul_f32_e32 v15, v33, v52
	v_mul_f32_e32 v0, v18, v52
	v_mul_f32_e32 v1, v19, v52
	v_cvt_pk_bf16_f32 v16, v67, v51
	v_cvt_pk_bf16_f32 v17, v68, v53
	v_cvt_pk_bf16_f32 v18, v54, v55
	v_cvt_pk_bf16_f32 v19, v56, v57
	s_waitcnt lgkmcnt(2)
	s_nop 0
	v_mfma_f32_32x32x16_bf16 v[0:15], v[20:23], v[16:19], v[0:15]
	ds_read_b128 v[20:23], v94 offset:32288
	s_waitcnt lgkmcnt(2)
	v_mfma_f32_32x32x16_bf16 v[34:49], v[24:27], v[16:19], v[34:49]
	v_cvt_pk_bf16_f32 v16, v58, v59
	v_cvt_pk_bf16_f32 v17, v60, v61
	v_cvt_pk_bf16_f32 v18, v62, v63
	v_cvt_pk_bf16_f32 v19, v64, v65
	s_waitcnt lgkmcnt(1)
	s_nop 0
	v_mfma_f32_32x32x16_bf16 v[34:49], v[28:31], v[16:19], v[34:49]
	s_waitcnt lgkmcnt(0)
	v_mfma_f32_32x32x16_bf16 v[0:15], v[20:23], v[16:19], v[0:15]
	ds_read_b128 v[20:23], v94 offset:27712
	ds_read_b128 v[24:27], v94 offset:32320
	v_cvt_pk_bf16_f32 v16, v69, v70
	v_cvt_pk_bf16_f32 v17, v71, v72
	v_cvt_pk_bf16_f32 v18, v73, v74
	v_cvt_pk_bf16_f32 v19, v75, v76
	s_waitcnt lgkmcnt(1)
	s_nop 0
	v_mfma_f32_32x32x16_bf16 v[34:49], v[20:23], v[16:19], v[34:49]
	s_waitcnt lgkmcnt(0)
	v_mfma_f32_32x32x16_bf16 v[0:15], v[24:27], v[16:19], v[0:15]
	ds_read_b128 v[20:23], v94 offset:27744
	ds_read_b128 v[24:27], v94 offset:32352
	v_cvt_pk_bf16_f32 v16, v77, v78
	v_cvt_pk_bf16_f32 v17, v79, v80
	v_cvt_pk_bf16_f32 v18, v81, v82
	v_cvt_pk_bf16_f32 v19, v83, v88
	s_waitcnt lgkmcnt(0)
	s_barrier
	v_mfma_f32_32x32x16_bf16 v[34:49], v[20:23], v[16:19], v[34:49]
	v_mfma_f32_32x32x16_bf16 v[0:15], v[24:27], v[16:19], v[0:15]
	ds_bpermute_b32 v18, v93, v50
	v_mov_b32_e32 v16, 0
	v_mov_b32_e32 v17, 0
	s_and_saveexec_b64 s[0:1], s[16:17]
	s_cbranch_execz .LBB0_969
	v_or_b32_e32 v16, s27, v112
	v_mov_b32_e32 v17, v129
	v_readlane_b32 s40, v250, 21
	v_lshlrev_b64 v[16:17], 2, v[16:17]
	v_readlane_b32 s44, v250, 25
	v_readlane_b32 s45, v250, 26
	v_readlane_b32 s46, v250, 27
	v_readlane_b32 s47, v250, 28
	v_readlane_b32 s48, v250, 29
	v_readlane_b32 s49, v250, 30
	v_readlane_b32 s50, v250, 31
	v_readlane_b32 s51, v250, 32
	v_lshl_add_u64 v[20:21], s[44:45], 0, v[16:17]
	v_lshl_add_u64 v[22:23], s[46:47], 0, v[16:17]
	v_lshl_add_u64 v[24:25], s[48:49], 0, v[16:17]
	v_lshl_add_u64 v[16:17], s[50:51], 0, v[16:17]
	global_load_dword v21, v[20:21], off
	v_readlane_b32 s41, v250, 22
	global_load_dword v23, v[22:23], off
	v_readlane_b32 s42, v250, 23
	global_load_dword v20, v[24:25], off
	global_load_dword v22, v[16:17], off
	v_readlane_b32 s43, v250, 24
	v_readlane_b32 s52, v250, 33
	v_readlane_b32 s53, v250, 34
	v_readlane_b32 s54, v250, 35
	v_readlane_b32 s55, v250, 36
	s_waitcnt vmcnt(0)
	v_pk_mul_f32 v[16:17], v[20:21], v[22:23]

.LBB0_971:
	s_or_b64 exec, exec, s[4:5]
	v_lshl_add_u32 v101, v162, 2, v100
	s_movk_i32 s4, 0x210
	v_lshlrev_b32_e32 v82, 3, v108
	v_mad_u32_u24 v99, v108, s4, v101
	s_waitcnt lgkmcnt(0)
	s_barrier
	s_and_saveexec_b64 s[4:5], s[0:1]
	s_cbranch_execz .LBB0_973
	v_div_scale_f32 v18, s[14:15], v17, v17, 1.0
	v_rcp_f32_e32 v19, v18
	v_div_scale_f32 v20, vcc, 1.0, v17, 1.0
	s_movk_i32 s14, 0x84
	v_fma_f32 v21, -v18, v19, 1.0
	v_fmac_f32_e32 v19, v21, v19
	v_mul_f32_e32 v21, v20, v19
	v_fma_f32 v22, -v18, v21, v20
	v_fmac_f32_e32 v21, v22, v19
	v_fma_f32 v18, -v18, v21, v20
	v_div_fmas_f32 v18, v18, v19, v21
	v_div_fixup_f32 v18, v18, v17, 1.0
	v_add_u32_e32 v17, 0x400, v99
	ds_read2_b32 v[20:21], v99 offset1:33
	ds_read2_b32 v[22:23], v99 offset0:66 offset1:99
	ds_read2_b32 v[24:25], v17 offset0:8 offset1:41
	ds_read2_b32 v[26:27], v17 offset0:74 offset1:107
	v_add_u32_e32 v17, 0x800, v99
	ds_read2_b32 v[28:29], v17 offset0:16 offset1:49
	ds_read2_b32 v[30:31], v17 offset0:82 offset1:115
	v_add_u32_e32 v17, 0xc00, v99
	ds_read2_b32 v[32:33], v17 offset0:24 offset1:57
	ds_read2_b32 v[50:51], v17 offset0:90 offset1:123
	v_lshl_or_b32 v17, v108, 2, 32
	v_mad_u32_u24 v17, v17, s14, v101
	ds_read_b32 v52, v17
	ds_read_b32 v71, v99 offset:7788
	v_add_u32_e32 v17, 0x1000, v99
	ds_read2_b32 v[54:55], v17 offset0:65 offset1:98
	v_add_u32_e32 v17, 0x1200, v99
	ds_read2_b32 v[56:57], v17 offset0:3 offset1:168
	v_add_u32_e32 v17, 0x1400, v99
	ds_read2_b32 v[58:59], v17 offset0:73 offset1:106
	v_add_u32_e32 v17, 0x1600, v99
	ds_read2_b32 v[60:61], v17 offset0:11 offset1:176
	v_add_u32_e32 v17, 0x1a00, v99
	ds_read2_b32 v[62:63], v17 offset0:19 offset1:184
	v_add_u32_e32 v17, 0x1c00, v99
	ds_read2_b32 v[64:65], v17 offset0:89 offset1:122
	v_readlane_b32 s40, v254, 29
	v_readlane_b32 s41, v254, 30
	s_waitcnt lgkmcnt(1)
	v_mov_b32_e32 v68, v63
	v_pk_fma_f32 v[20:21], v[34:35], v[18:19], v[20:21] op_sel_hi:[1,0,1] neg_lo:[0,0,1] neg_hi:[0,0,1]
	s_waitcnt lgkmcnt(0)
	v_mov_b32_e32 v69, v64
	v_mov_b32_e32 v70, v65
	v_pk_fma_f32 v[68:69], v[12:13], v[18:19], v[68:69] op_sel_hi:[1,0,1] neg_lo:[0,0,1] neg_hi:[0,0,1]
	v_pk_fma_f32 v[64:65], v[14:15], v[18:19], v[70:71] op_sel_hi:[1,0,1] neg_lo:[0,0,1] neg_hi:[0,0,1]
	global_load_dwordx4 v[12:15], v96, s[40:41]
	v_add_u32_e32 v17, 0x1800, v99
	v_pk_fma_f32 v[22:23], v[36:37], v[18:19], v[22:23] op_sel_hi:[1,0,1] neg_lo:[0,0,1] neg_hi:[0,0,1]
	v_pk_mul_f32 v[34:35], v[20:21], v[20:21]
	ds_read2_b32 v[66:67], v17 offset0:81 offset1:114
	v_pk_mul_f32 v[36:37], v[22:23], v[22:23]
	v_add_f32_e32 v17, v34, v35
	v_pk_fma_f32 v[24:25], v[38:39], v[18:19], v[24:25] op_sel_hi:[1,0,1] neg_lo:[0,0,1] neg_hi:[0,0,1]
	v_add_f32_e32 v17, v17, v36
	v_pk_mul_f32 v[38:39], v[24:25], v[24:25]
	v_add_f32_e32 v17, v17, v37
	v_pk_fma_f32 v[26:27], v[40:41], v[18:19], v[26:27] op_sel_hi:[1,0,1] neg_lo:[0,0,1] neg_hi:[0,0,1]
	v_add_f32_e32 v17, v17, v38
	v_pk_mul_f32 v[40:41], v[26:27], v[26:27]
	v_add_f32_e32 v17, v17, v39
	v_pk_fma_f32 v[28:29], v[42:43], v[18:19], v[28:29] op_sel_hi:[1,0,1] neg_lo:[0,0,1] neg_hi:[0,0,1]
	v_add_f32_e32 v17, v17, v40
	v_pk_mul_f32 v[42:43], v[28:29], v[28:29]
	v_add_f32_e32 v17, v17, v41
	v_pk_fma_f32 v[30:31], v[44:45], v[18:19], v[30:31] op_sel_hi:[1,0,1] neg_lo:[0,0,1] neg_hi:[0,0,1]
	v_add_f32_e32 v17, v17, v42
	v_pk_mul_f32 v[44:45], v[30:31], v[30:31]
	v_add_f32_e32 v17, v17, v43
	v_pk_fma_f32 v[32:33], v[46:47], v[18:19], v[32:33] op_sel_hi:[1,0,1] neg_lo:[0,0,1] neg_hi:[0,0,1]
	v_add_f32_e32 v17, v17, v44
	v_pk_mul_f32 v[46:47], v[32:33], v[32:33]
	v_add_f32_e32 v17, v17, v45
	v_pk_fma_f32 v[48:49], v[48:49], v[18:19], v[50:51] op_sel_hi:[1,0,1] neg_lo:[0,0,1] neg_hi:[0,0,1]
	v_add_f32_e32 v17, v17, v46
	v_pk_mul_f32 v[50:51], v[48:49], v[48:49]
	v_mov_b32_e32 v53, v54
	v_add_f32_e32 v17, v17, v47
	v_pk_fma_f32 v[52:53], v[0:1], v[18:19], v[52:53] op_sel_hi:[1,0,1] neg_lo:[0,0,1] neg_hi:[0,0,1]
	v_add_f32_e32 v17, v17, v50
	v_mov_b32_e32 v74, v55
	v_mov_b32_e32 v75, v56
	v_pk_mul_f32 v[0:1], v[52:53], v[52:53]
	v_add_f32_e32 v17, v17, v51
	v_pk_fma_f32 v[74:75], v[2:3], v[18:19], v[74:75] op_sel_hi:[1,0,1] neg_lo:[0,0,1] neg_hi:[0,0,1]
	v_add_f32_e32 v0, v17, v0
	v_pk_mul_f32 v[2:3], v[74:75], v[74:75]
	v_mov_b32_e32 v56, v57
	v_mov_b32_e32 v57, v58
	v_add_f32_e32 v0, v0, v1
	v_pk_fma_f32 v[4:5], v[4:5], v[18:19], v[56:57] op_sel_hi:[1,0,1] neg_lo:[0,0,1] neg_hi:[0,0,1]
	v_add_f32_e32 v0, v0, v2
	v_mov_b32_e32 v54, v59
	v_mov_b32_e32 v55, v60
	v_pk_mul_f32 v[56:57], v[4:5], v[4:5]
	v_add_f32_e32 v0, v0, v3
	v_pk_fma_f32 v[6:7], v[6:7], v[18:19], v[54:55] op_sel_hi:[1,0,1] neg_lo:[0,0,1] neg_hi:[0,0,1]
	v_add_f32_e32 v0, v0, v56
	v_pk_mul_f32 v[54:55], v[6:7], v[6:7]
	v_mov_b32_e32 v60, v61
	s_waitcnt lgkmcnt(0)
	v_mov_b32_e32 v61, v66
	v_add_f32_e32 v0, v0, v57
	v_mov_b32_e32 v58, v67
	v_mov_b32_e32 v59, v62
	v_pk_fma_f32 v[8:9], v[8:9], v[18:19], v[60:61] op_sel_hi:[1,0,1] neg_lo:[0,0,1] neg_hi:[0,0,1]
	v_add_f32_e32 v0, v0, v54
	v_pk_fma_f32 v[10:11], v[10:11], v[18:19], v[58:59] op_sel_hi:[1,0,1] neg_lo:[0,0,1] neg_hi:[0,0,1]
	v_pk_mul_f32 v[18:19], v[8:9], v[8:9]
	v_add_f32_e32 v0, v0, v55
	v_add_f32_e32 v0, v0, v18
	v_pk_mul_f32 v[58:59], v[10:11], v[10:11]
	v_add_f32_e32 v0, v0, v19
	v_add_f32_e32 v0, v0, v58
	v_pk_mul_f32 v[72:73], v[68:69], v[68:69]
	v_add_f32_e32 v0, v0, v59
	v_add_f32_e32 v0, v0, v72
	v_pk_mul_f32 v[70:71], v[64:65], v[64:65]
	v_add_f32_e32 v0, v0, v73
	v_add_f32_e32 v0, v0, v70
	v_add_f32_e32 v2, v0, v71
	ds_bpermute_b32 v3, v93, v2
	s_mov_b32 s14, 0x800000
	v_lshlrev_b64 v[0:1], 11, v[86:87]
	v_lshl_add_u64 v[0:1], s[66:67], 0, v[0:1]
	v_lshl_add_u64 v[0:1], v[0:1], 0, s[60:61]
	s_waitcnt lgkmcnt(0)
	v_add_f32_e32 v2, v2, v3
	v_fmamk_f32 v2, v2, 0x3c800000, v225
	v_mul_f32_e32 v3, 0x4b800000, v2
	v_cmp_gt_f32_e32 vcc, s14, v2
	v_mov_b32_e32 v83, v129
	v_sub_f32_e32 v18, 1.0, v16
	v_cndmask_b32_e32 v2, v2, v3, vcc
	v_rsq_f32_e32 v2, v2
	v_lshl_add_u64 v[16:17], v[0:1], 0, v[82:83]
	s_mov_b32 s14, 0x2d53000
	v_mul_f32_e32 v0, 0x45800000, v2
	v_cndmask_b32_e32 v0, v2, v0, vcc
	v_mul_f32_e32 v18, v18, v0
	v_mul_f32_e32 v0, v20, v18
	v_mul_f32_e32 v1, v21, v18
	v_mul_f32_e32 v2, v22, v18
	v_mul_f32_e32 v3, v23, v18
	s_waitcnt vmcnt(0)
	v_pk_mul_f32 v[0:1], v[12:13], v[0:1]
	v_pk_mul_f32 v[2:3], v[14:15], v[2:3]
	v_cvt_pk_bf16_f32 v0, v0, v1
	v_cvt_pk_bf16_f32 v1, v2, v3
	v_add_co_u32_e32 v2, vcc, s14, v16
	s_mov_b64 s[14:15], 0x2d53700
	s_nop 0
	v_addc_co_u32_e32 v3, vcc, 0, v17, vcc
	global_store_dwordx2 v[2:3], v[0:1], off offset:1792
	global_load_dwordx4 v[0:3], v96, s[40:41] offset:32
	v_lshl_add_u64 v[12:13], v[16:17], 0, s[14:15]
	v_mul_f32_e32 v14, v24, v18
	v_mul_f32_e32 v15, v25, v18
	v_mul_f32_e32 v16, v26, v18
	v_mul_f32_e32 v17, v27, v18
	v_mul_f32_e32 v4, v4, v18
	v_mul_f32_e32 v5, v5, v18
	v_mul_f32_e32 v6, v6, v18
	v_mul_f32_e32 v7, v7, v18
	s_waitcnt vmcnt(0)
	v_pk_mul_f32 v[0:1], v[0:1], v[14:15]
	v_pk_mul_f32 v[2:3], v[2:3], v[16:17]
	v_cvt_pk_bf16_f32 v0, v0, v1
	v_cvt_pk_bf16_f32 v1, v2, v3
	global_store_dwordx2 v[12:13], v[0:1], off offset:16
	global_load_dwordx4 v[0:3], v96, s[40:41] offset:64
	v_mul_f32_e32 v14, v28, v18
	v_mul_f32_e32 v15, v29, v18
	v_mul_f32_e32 v16, v30, v18
	v_mul_f32_e32 v17, v31, v18
	s_waitcnt vmcnt(0)
	v_pk_mul_f32 v[0:1], v[0:1], v[14:15]
	v_pk_mul_f32 v[2:3], v[2:3], v[16:17]
	v_cvt_pk_bf16_f32 v0, v0, v1
	v_cvt_pk_bf16_f32 v1, v2, v3
	global_store_dwordx2 v[12:13], v[0:1], off offset:32
	global_load_dwordx4 v[0:3], v96, s[40:41] offset:96
	v_mul_f32_e32 v14, v32, v18
	v_mul_f32_e32 v15, v33, v18
	v_mul_f32_e32 v16, v48, v18
	v_mul_f32_e32 v17, v49, v18
	s_waitcnt vmcnt(0)
	v_pk_mul_f32 v[0:1], v[0:1], v[14:15]
	v_pk_mul_f32 v[2:3], v[2:3], v[16:17]
	v_cvt_pk_bf16_f32 v0, v0, v1
	v_cvt_pk_bf16_f32 v1, v2, v3
	global_store_dwordx2 v[12:13], v[0:1], off offset:48
	global_load_dwordx4 v[0:3], v96, s[40:41] offset:128
	v_mul_f32_e32 v14, v52, v18
	v_mul_f32_e32 v15, v53, v18
	v_mul_f32_e32 v16, v74, v18
	v_mul_f32_e32 v17, v75, v18
	s_waitcnt vmcnt(0)
	v_pk_mul_f32 v[0:1], v[0:1], v[14:15]
	v_pk_mul_f32 v[2:3], v[2:3], v[16:17]
	v_cvt_pk_bf16_f32 v0, v0, v1
	v_cvt_pk_bf16_f32 v1, v2, v3
	global_store_dwordx2 v[12:13], v[0:1], off offset:64
	global_load_dwordx4 v[0:3], v96, s[40:41] offset:160
	s_waitcnt vmcnt(0)
	v_pk_mul_f32 v[0:1], v[0:1], v[4:5]
	v_pk_mul_f32 v[2:3], v[2:3], v[6:7]
	v_cvt_pk_bf16_f32 v0, v0, v1
	v_cvt_pk_bf16_f32 v1, v2, v3
	global_store_dwordx2 v[12:13], v[0:1], off offset:80
	global_load_dwordx4 v[0:3], v96, s[40:41] offset:192
	v_mul_f32_e32 v4, v8, v18
	v_mul_f32_e32 v5, v9, v18
	v_mul_f32_e32 v6, v10, v18
	v_mul_f32_e32 v7, v11, v18
	s_waitcnt vmcnt(0)
	v_pk_mul_f32 v[0:1], v[4:5], v[0:1]
	v_pk_mul_f32 v[2:3], v[6:7], v[2:3]
	v_cvt_pk_bf16_f32 v0, v0, v1
	v_cvt_pk_bf16_f32 v1, v2, v3
	global_store_dwordx2 v[12:13], v[0:1], off offset:96
	global_load_dwordx4 v[0:3], v96, s[40:41] offset:224
	v_mul_f32_e32 v4, v68, v18
	v_mul_f32_e32 v5, v69, v18
	v_mul_f32_e32 v6, v64, v18
	v_mul_f32_e32 v7, v65, v18
	s_waitcnt vmcnt(0)
	v_pk_mul_f32 v[0:1], v[4:5], v[0:1]
	v_pk_mul_f32 v[2:3], v[6:7], v[2:3]
	v_cvt_pk_bf16_f32 v0, v0, v1
	v_cvt_pk_bf16_f32 v1, v2, v3
	global_store_dwordx2 v[12:13], v[0:1], off offset:112

.LBB0_985:
	s_or_b64 exec, exec, s[4:5]
	global_load_dwordx4 v[78:81], v[84:85], off offset:256
	ds_read_b128 v[2:5], v95 offset:9216
	ds_read_b128 v[6:9], v95 offset:9248
	s_waitcnt lgkmcnt(1)
	v_mfma_f32_32x32x16_bf16 v[50:65], v[2:5], v[70:73], 0
	ds_read_b128 v[2:5], v95 offset:13824
	ds_read_b128 v[130:133], v95 offset:13856
	s_waitcnt lgkmcnt(2)
	v_mfma_f32_32x32x16_bf16 v[50:65], v[6:9], v[66:69], v[50:65]
	s_waitcnt lgkmcnt(1)
	v_mfma_f32_32x32x16_bf16 v[2:17], v[2:5], v[70:73], 0
	s_waitcnt lgkmcnt(0)
	v_mfma_f32_32x32x16_bf16 v[2:17], v[130:133], v[66:69], v[2:17]
	s_nop 7
	v_max_f32_e32 v130, v51, v51
	v_max_f32_e32 v131, v50, v50
	v_max_f32_e32 v130, v131, v130
	v_max3_f32 v130, v130, v52, v53
	v_max3_f32 v130, v130, v54, v55
	v_max3_f32 v130, v130, v56, v57
	v_max3_f32 v130, v130, v58, v59
	v_max3_f32 v130, v130, v60, v61
	v_max3_f32 v130, v130, v62, v63
	v_max3_f32 v130, v130, v64, v65
	v_max3_f32 v130, v130, v2, v3
	v_max3_f32 v130, v130, v4, v5
	v_max3_f32 v130, v130, v6, v7
	v_max3_f32 v130, v130, v8, v9
	v_max3_f32 v130, v130, v10, v11
	v_max3_f32 v130, v130, v12, v13
	v_max3_f32 v130, v130, v14, v15
	v_max3_f32 v130, v130, v16, v17
	ds_bpermute_b32 v131, v93, v130
	s_waitcnt lgkmcnt(0)
	v_max3_f32 v132, v92, v130, v131
	v_sub_f32_e32 v2, v2, v132
	v_exp_f32_e32 v167, v2
	v_sub_f32_e32 v2, v3, v132
	v_exp_f32_e32 v168, v2
	v_sub_f32_e32 v2, v4, v132
	v_exp_f32_e32 v169, v2
	v_sub_f32_e32 v2, v5, v132
	v_exp_f32_e32 v170, v2
	v_sub_f32_e32 v2, v6, v132
	v_sub_f32_e32 v50, v50, v132
	v_exp_f32_e32 v171, v2
	v_sub_f32_e32 v2, v7, v132
	v_exp_f32_e32 v150, v50
	v_sub_f32_e32 v50, v51, v132
	v_exp_f32_e32 v172, v2
	v_sub_f32_e32 v2, v8, v132
	v_exp_f32_e32 v151, v50
	v_sub_f32_e32 v50, v52, v132
	v_exp_f32_e32 v173, v2
	v_sub_f32_e32 v2, v9, v132
	v_exp_f32_e32 v152, v50
	v_sub_f32_e32 v50, v53, v132
	v_exp_f32_e32 v174, v2
	v_sub_f32_e32 v2, v10, v132
	v_exp_f32_e32 v153, v50
	v_sub_f32_e32 v50, v54, v132
	v_exp_f32_e32 v175, v2
	v_sub_f32_e32 v2, v11, v132
	v_sub_f32_e32 v92, v92, v132
	v_exp_f32_e32 v154, v50
	v_sub_f32_e32 v50, v55, v132
	v_exp_f32_e32 v176, v2
	v_sub_f32_e32 v2, v12, v132
	v_exp_f32_e32 v155, v50
	v_sub_f32_e32 v50, v56, v132
	v_exp_f32_e32 v177, v2
	v_sub_f32_e32 v2, v13, v132
	v_exp_f32_e32 v92, v92
	v_exp_f32_e32 v156, v50
	v_sub_f32_e32 v50, v57, v132
	v_exp_f32_e32 v178, v2
	v_sub_f32_e32 v2, v14, v132
	v_exp_f32_e32 v157, v50
	v_exp_f32_e32 v179, v2
	v_sub_f32_e32 v2, v15, v132
	v_sub_f32_e32 v50, v58, v132
	v_exp_f32_e32 v180, v2
	v_sub_f32_e32 v2, v16, v132
	v_exp_f32_e32 v158, v50
	v_sub_f32_e32 v50, v59, v132
	v_exp_f32_e32 v181, v2
	v_sub_f32_e32 v2, v17, v132
	v_mul_f32_e32 v16, v32, v92
	v_mul_f32_e32 v17, v33, v92
	v_mul_f32_e32 v14, v30, v92
	v_mul_f32_e32 v15, v31, v92
	v_mul_f32_e32 v12, v28, v92
	v_mul_f32_e32 v13, v29, v92
	v_mul_f32_e32 v10, v26, v92
	v_mul_f32_e32 v11, v27, v92
	v_mul_f32_e32 v8, v24, v92
	v_mul_f32_e32 v9, v25, v92
	v_mul_f32_e32 v6, v22, v92
	v_mul_f32_e32 v7, v23, v92
	v_mul_f32_e32 v32, v48, v92
	v_mul_f32_e32 v33, v49, v92
	v_mul_f32_e32 v30, v46, v92
	v_mul_f32_e32 v31, v47, v92
	v_mul_f32_e32 v28, v44, v92
	v_mul_f32_e32 v29, v45, v92
	v_mul_f32_e32 v26, v42, v92
	v_mul_f32_e32 v27, v43, v92
	v_mul_f32_e32 v24, v40, v92
	v_mul_f32_e32 v25, v41, v92
	v_mul_f32_e32 v22, v38, v92
	v_mul_f32_e32 v23, v39, v92
	ds_read_b128 v[38:41], v94 offset:32256
	ds_read_b128 v[42:45], v94 offset:27648
	ds_read_b128 v[46:49], v94 offset:27680
	v_exp_f32_e32 v159, v50
	v_sub_f32_e32 v50, v60, v132
	v_exp_f32_e32 v160, v50
	v_sub_f32_e32 v50, v61, v132
	v_exp_f32_e32 v182, v2
	v_mul_f32_e32 v4, v20, v92
	v_mul_f32_e32 v5, v21, v92
	v_mul_f32_e32 v2, v18, v92
	v_mul_f32_e32 v3, v19, v92
	v_mul_f32_e32 v20, v36, v92
	v_mul_f32_e32 v21, v37, v92
	v_mul_f32_e32 v18, v34, v92
	v_mul_f32_e32 v19, v35, v92
	v_cvt_pk_bf16_f32 v34, v150, v151
	v_cvt_pk_bf16_f32 v35, v152, v153
	v_cvt_pk_bf16_f32 v36, v154, v155
	v_cvt_pk_bf16_f32 v37, v156, v157
	v_exp_f32_e32 v161, v50
	v_sub_f32_e32 v50, v62, v132
	s_waitcnt lgkmcnt(2)
	v_mfma_f32_32x32x16_bf16 v[18:33], v[38:41], v[34:37], v[18:33]
	ds_read_b128 v[38:41], v94 offset:32288
	v_exp_f32_e32 v163, v50
	v_sub_f32_e32 v50, v63, v132
	v_exp_f32_e32 v164, v50
	v_sub_f32_e32 v50, v64, v132
	v_exp_f32_e32 v165, v50
	v_sub_f32_e32 v50, v65, v132
	s_waitcnt lgkmcnt(2)
	v_mfma_f32_32x32x16_bf16 v[2:17], v[42:45], v[34:37], v[2:17]
	v_exp_f32_e32 v166, v50
	v_cvt_pk_bf16_f32 v34, v158, v159
	v_cvt_pk_bf16_f32 v35, v160, v161
	v_cvt_pk_bf16_f32 v36, v163, v164
	v_cvt_pk_bf16_f32 v37, v165, v166
	s_waitcnt lgkmcnt(1)
	s_nop 0
	v_mfma_f32_32x32x16_bf16 v[2:17], v[46:49], v[34:37], v[2:17]
	s_waitcnt lgkmcnt(0)
	v_mfma_f32_32x32x16_bf16 v[18:33], v[38:41], v[34:37], v[18:33]
	ds_read_b128 v[38:41], v94 offset:27712
	ds_read_b128 v[42:45], v94 offset:32320
	v_cvt_pk_bf16_f32 v34, v167, v168
	v_cvt_pk_bf16_f32 v35, v169, v170
	v_cvt_pk_bf16_f32 v36, v171, v172
	v_cvt_pk_bf16_f32 v37, v173, v174
	s_waitcnt lgkmcnt(1)
	s_nop 0
	v_mfma_f32_32x32x16_bf16 v[2:17], v[38:41], v[34:37], v[2:17]
	s_waitcnt lgkmcnt(0)
	v_mfma_f32_32x32x16_bf16 v[18:33], v[42:45], v[34:37], v[18:33]
	ds_read_b128 v[38:41], v94 offset:27744
	ds_read_b128 v[42:45], v94 offset:32352
	v_cvt_pk_bf16_f32 v34, v175, v176
	v_cvt_pk_bf16_f32 v35, v177, v178
	v_cvt_pk_bf16_f32 v36, v179, v180
	v_cvt_pk_bf16_f32 v37, v181, v182
	s_waitcnt lgkmcnt(1)
	s_nop 0
	v_mfma_f32_32x32x16_bf16 v[2:17], v[38:41], v[34:37], v[2:17]
	s_waitcnt lgkmcnt(0)
	v_mfma_f32_32x32x16_bf16 v[18:33], v[42:45], v[34:37], v[18:33]
	s_and_saveexec_b64 s[4:5], s[36:37]
	s_cbranch_execz .LBB0_987
	s_waitcnt vmcnt(1)
	ds_write_b128 v1, v[74:77]

.LBB0_989:
	s_or_b64 exec, exec, s[4:5]
	global_load_dwordx4 v[78:81], v[84:85], off offset:384
	ds_read_b128 v[34:37], v95
	ds_read_b128 v[38:41], v95 offset:32
	s_waitcnt lgkmcnt(1)
	v_mfma_f32_32x32x16_bf16 v[50:65], v[34:37], v[70:73], 0
	ds_read_b128 v[34:37], v95 offset:4608
	ds_read_b128 v[88:91], v95 offset:4640
	s_waitcnt lgkmcnt(2)
	v_mfma_f32_32x32x16_bf16 v[50:65], v[38:41], v[66:69], v[50:65]
	s_waitcnt lgkmcnt(1)
	v_mfma_f32_32x32x16_bf16 v[34:49], v[34:37], v[70:73], 0
	s_nop 9
	v_max_f32_e32 v84, v51, v51
	v_max_f32_e32 v85, v50, v50
	v_max_f32_e32 v84, v85, v84
	v_max3_f32 v84, v84, v52, v53
	v_max3_f32 v84, v84, v54, v55
	v_max3_f32 v84, v84, v56, v57
	v_max3_f32 v84, v84, v58, v59
	s_waitcnt lgkmcnt(0)
	v_mfma_f32_32x32x16_bf16 v[34:49], v[88:91], v[66:69], v[34:49]
	v_max3_f32 v84, v84, v60, v61
	v_max3_f32 v84, v84, v62, v63
	v_max3_f32 v84, v84, v64, v65
	s_nop 8
	v_max3_f32 v84, v84, v34, v35
	v_max3_f32 v84, v84, v36, v37
	v_max3_f32 v84, v84, v38, v39
	v_max3_f32 v84, v84, v40, v41
	v_max3_f32 v84, v84, v42, v43
	v_max3_f32 v84, v84, v44, v45
	v_max3_f32 v84, v84, v46, v47
	v_max3_f32 v84, v84, v48, v49
	ds_bpermute_b32 v85, v93, v84
	s_waitcnt lgkmcnt(0)
	v_max3_f32 v84, v132, v84, v85
	v_sub_f32_e32 v34, v34, v84
	v_exp_f32_e32 v85, v34
	v_sub_f32_e32 v34, v35, v84
	v_exp_f32_e32 v35, v34
	v_sub_f32_e32 v34, v36, v84
	v_exp_f32_e32 v36, v34
	v_sub_f32_e32 v34, v37, v84
	v_exp_f32_e32 v37, v34
	v_sub_f32_e32 v34, v38, v84
	v_exp_f32_e32 v38, v34
	v_sub_f32_e32 v34, v39, v84
	v_exp_f32_e32 v39, v34
	v_sub_f32_e32 v34, v40, v84
	v_exp_f32_e32 v40, v34
	v_sub_f32_e32 v34, v41, v84
	v_exp_f32_e32 v41, v34
	v_sub_f32_e32 v34, v42, v84
	v_exp_f32_e32 v42, v34
	v_sub_f32_e32 v34, v43, v84
	v_exp_f32_e32 v43, v34
	v_sub_f32_e32 v34, v44, v84
	v_exp_f32_e32 v44, v34
	v_sub_f32_e32 v34, v45, v84
	v_exp_f32_e32 v45, v34
	v_sub_f32_e32 v34, v46, v84
	v_exp_f32_e32 v46, v34
	v_sub_f32_e32 v34, v47, v84
	v_exp_f32_e32 v47, v34
	v_sub_f32_e32 v34, v48, v84
	v_sub_f32_e32 v88, v132, v84
	v_sub_f32_e32 v50, v50, v84
	v_sub_f32_e32 v51, v51, v84
	v_sub_f32_e32 v52, v52, v84
	v_sub_f32_e32 v53, v53, v84
	v_sub_f32_e32 v54, v54, v84
	v_sub_f32_e32 v55, v55, v84
	v_sub_f32_e32 v56, v56, v84
	v_sub_f32_e32 v57, v57, v84
	v_exp_f32_e32 v48, v34
	v_sub_f32_e32 v34, v49, v84
	v_exp_f32_e32 v50, v50
	v_exp_f32_e32 v51, v51
	v_exp_f32_e32 v52, v52
	v_exp_f32_e32 v53, v53
	v_exp_f32_e32 v54, v54
	v_exp_f32_e32 v55, v55
	v_exp_f32_e32 v56, v56
	v_exp_f32_e32 v57, v57
	v_exp_f32_e32 v49, v34
	v_exp_f32_e32 v34, v88
	ds_read_b128 v[130:133], v94 offset:23040
	ds_read_b128 v[184:187], v94 offset:18432
	ds_read_b128 v[188:191], v94 offset:18464
	v_cvt_pk_bf16_f32 v88, v50, v51
	v_cvt_pk_bf16_f32 v89, v52, v53
	v_mul_f32_e32 v32, v32, v34
	v_mul_f32_e32 v33, v33, v34
	v_mul_f32_e32 v30, v30, v34
	v_mul_f32_e32 v31, v31, v34
	v_mul_f32_e32 v28, v28, v34
	v_mul_f32_e32 v29, v29, v34
	v_mul_f32_e32 v26, v26, v34
	v_mul_f32_e32 v27, v27, v34
	v_mul_f32_e32 v24, v24, v34
	v_mul_f32_e32 v25, v25, v34
	v_mul_f32_e32 v22, v22, v34
	v_mul_f32_e32 v23, v23, v34
	v_mul_f32_e32 v20, v20, v34
	v_mul_f32_e32 v21, v21, v34
	v_mul_f32_e32 v18, v18, v34
	v_mul_f32_e32 v19, v19, v34
	v_cvt_pk_bf16_f32 v90, v54, v55
	v_cvt_pk_bf16_f32 v91, v56, v57
	v_mul_f32_e32 v16, v16, v34
	v_mul_f32_e32 v17, v17, v34
	v_mul_f32_e32 v14, v14, v34
	v_mul_f32_e32 v15, v15, v34
	v_mul_f32_e32 v12, v12, v34
	v_mul_f32_e32 v13, v13, v34
	v_mul_f32_e32 v10, v10, v34
	v_mul_f32_e32 v11, v11, v34
	v_mul_f32_e32 v8, v8, v34
	v_mul_f32_e32 v9, v9, v34
	v_mul_f32_e32 v6, v6, v34
	v_mul_f32_e32 v7, v7, v34
	v_mul_f32_e32 v4, v4, v34
	v_mul_f32_e32 v5, v5, v34
	v_mul_f32_e32 v2, v2, v34
	v_mul_f32_e32 v3, v3, v34
	s_waitcnt lgkmcnt(2)
	v_mfma_f32_32x32x16_bf16 v[18:33], v[130:133], v[88:91], v[18:33]
	ds_read_b128 v[130:133], v94 offset:23072
	v_sub_f32_e32 v58, v58, v84
	v_sub_f32_e32 v59, v59, v84
	v_sub_f32_e32 v60, v60, v84
	v_sub_f32_e32 v61, v61, v84
	v_sub_f32_e32 v62, v62, v84
	v_sub_f32_e32 v63, v63, v84
	s_waitcnt lgkmcnt(2)
	v_mfma_f32_32x32x16_bf16 v[2:17], v[184:187], v[88:91], v[2:17]
	v_sub_f32_e32 v64, v64, v84
	v_sub_f32_e32 v65, v65, v84
	v_exp_f32_e32 v58, v58
	v_exp_f32_e32 v59, v59
	v_exp_f32_e32 v60, v60
	v_exp_f32_e32 v61, v61
	v_exp_f32_e32 v62, v62
	v_exp_f32_e32 v63, v63
	v_exp_f32_e32 v64, v64
	v_exp_f32_e32 v65, v65
	v_cvt_pk_bf16_f32 v88, v58, v59
	v_cvt_pk_bf16_f32 v89, v60, v61
	v_cvt_pk_bf16_f32 v90, v62, v63
	v_cvt_pk_bf16_f32 v91, v64, v65
	s_waitcnt lgkmcnt(1)
	s_nop 0
	v_mfma_f32_32x32x16_bf16 v[2:17], v[188:191], v[88:91], v[2:17]
	s_waitcnt lgkmcnt(0)
	v_mfma_f32_32x32x16_bf16 v[18:33], v[130:133], v[88:91], v[18:33]
	ds_read_b128 v[130:133], v94 offset:18496
	ds_read_b128 v[184:187], v94 offset:23104
	v_cvt_pk_bf16_f32 v88, v85, v35
	v_cvt_pk_bf16_f32 v89, v36, v37
	v_cvt_pk_bf16_f32 v90, v38, v39
	v_cvt_pk_bf16_f32 v91, v40, v41
	s_waitcnt lgkmcnt(1)
	s_nop 0
	v_mfma_f32_32x32x16_bf16 v[2:17], v[130:133], v[88:91], v[2:17]
	s_waitcnt lgkmcnt(0)
	v_mfma_f32_32x32x16_bf16 v[18:33], v[184:187], v[88:91], v[18:33]
	ds_read_b128 v[130:133], v94 offset:18528
	ds_read_b128 v[184:187], v94 offset:23136
	v_cvt_pk_bf16_f32 v88, v42, v43
	v_cvt_pk_bf16_f32 v89, v44, v45
	v_cvt_pk_bf16_f32 v90, v46, v47
	v_cvt_pk_bf16_f32 v91, v48, v49
	s_waitcnt lgkmcnt(1)
	s_nop 0
	v_mfma_f32_32x32x16_bf16 v[2:17], v[130:133], v[88:91], v[2:17]
	s_waitcnt lgkmcnt(0)
	v_mfma_f32_32x32x16_bf16 v[18:33], v[184:187], v[88:91], v[18:33]
	s_and_saveexec_b64 s[4:5], s[36:37]
	s_cbranch_execz .LBB0_991
	s_waitcnt vmcnt(1)
	ds_write_b128 v1, v[74:77] offset:9216
.LBB0_991:
	s_or_b64 exec, exec, s[4:5]
	v_add_f32_e32 v1, 0, v83
	v_add_f32_e32 v1, v114, v1
	v_add_f32_e32 v1, v115, v1
	v_add_f32_e32 v1, v116, v1
	v_add_f32_e32 v1, v117, v1
	v_add_f32_e32 v1, v118, v1
	v_add_f32_e32 v1, v119, v1
	v_add_f32_e32 v1, v120, v1
	v_add_f32_e32 v1, v121, v1
	v_add_f32_e32 v1, v122, v1
	v_add_f32_e32 v1, v123, v1
	v_add_f32_e32 v1, v124, v1
	v_add_f32_e32 v1, v125, v1
	v_add_f32_e32 v1, v126, v1
	v_add_f32_e32 v1, v127, v1
	v_add_f32_e32 v1, v128, v1
	v_add_f32_e32 v1, v134, v1
	v_add_f32_e32 v1, v135, v1
	v_add_f32_e32 v1, v136, v1
	v_add_f32_e32 v1, v137, v1
	v_add_f32_e32 v1, v138, v1
	v_add_f32_e32 v1, v139, v1
	v_add_f32_e32 v1, v140, v1
	v_add_f32_e32 v1, v141, v1
	v_add_f32_e32 v1, v142, v1
	v_add_f32_e32 v1, v143, v1
	v_add_f32_e32 v1, v144, v1
	v_add_f32_e32 v1, v145, v1
	v_add_f32_e32 v1, v146, v1
	v_add_f32_e32 v1, v147, v1
	v_add_f32_e32 v1, v148, v1
	v_add_f32_e32 v1, v149, v1
	v_add_f32_e32 v0, v0, v1
	v_add_f32_e32 v1, 0, v150
	v_add_f32_e32 v1, v151, v1
	v_add_f32_e32 v1, v152, v1
	v_add_f32_e32 v1, v153, v1
	v_add_f32_e32 v1, v154, v1
	v_add_f32_e32 v1, v155, v1
	v_add_f32_e32 v1, v156, v1
	v_add_f32_e32 v1, v157, v1
	v_add_f32_e32 v1, v158, v1
	v_add_f32_e32 v1, v159, v1
	v_add_f32_e32 v1, v160, v1
	v_add_f32_e32 v1, v161, v1
	v_add_f32_e32 v1, v163, v1
	v_add_f32_e32 v1, v164, v1
	v_add_f32_e32 v1, v165, v1
	v_add_f32_e32 v1, v166, v1
	v_add_f32_e32 v1, v167, v1
	v_add_f32_e32 v1, v168, v1
	v_add_f32_e32 v1, v169, v1
	v_add_f32_e32 v1, v170, v1
	v_add_f32_e32 v1, v171, v1
	v_add_f32_e32 v1, v172, v1
	v_add_f32_e32 v1, v173, v1
	v_add_f32_e32 v1, v174, v1
	v_add_f32_e32 v1, v175, v1
	v_add_f32_e32 v1, v176, v1
	v_add_f32_e32 v1, v177, v1
	v_add_f32_e32 v1, v178, v1
	v_add_f32_e32 v1, v179, v1
	v_add_f32_e32 v1, v180, v1
	v_add_f32_e32 v1, v181, v1
	v_add_f32_e32 v1, v182, v1
	v_fmac_f32_e32 v1, v0, v92
	v_add_f32_e32 v0, 0, v50
	v_add_f32_e32 v0, v51, v0
	v_add_f32_e32 v0, v52, v0
	v_add_f32_e32 v0, v53, v0
	v_add_f32_e32 v0, v54, v0
	v_add_f32_e32 v0, v55, v0
	v_add_f32_e32 v0, v56, v0
	v_add_f32_e32 v0, v57, v0
	v_add_f32_e32 v0, v58, v0
	v_add_f32_e32 v0, v59, v0
	v_add_f32_e32 v0, v60, v0
	v_add_f32_e32 v0, v61, v0
	v_add_f32_e32 v0, v62, v0
	v_add_f32_e32 v0, v63, v0
	v_add_f32_e32 v0, v64, v0
	v_add_f32_e32 v0, v65, v0
	v_add_f32_e32 v0, v85, v0
	v_add_f32_e32 v0, v35, v0
	v_add_f32_e32 v0, v36, v0
	v_add_f32_e32 v0, v37, v0
	v_add_f32_e32 v0, v38, v0
	v_add_f32_e32 v0, v39, v0
	v_add_f32_e32 v0, v40, v0
	v_add_f32_e32 v0, v41, v0
	v_add_f32_e32 v0, v42, v0
	v_add_f32_e32 v0, v43, v0
	v_add_f32_e32 v0, v44, v0
	v_add_f32_e32 v0, v45, v0
	v_add_f32_e32 v0, v46, v0
	v_add_f32_e32 v0, v47, v0
	v_add_f32_e32 v0, v48, v0
	v_add_f32_e32 v0, v49, v0
	v_fmac_f32_e32 v0, v1, v34
	s_waitcnt vmcnt(0)
	ds_write_b128 v97, v[78:81] offset:27648
	s_waitcnt lgkmcnt(0)
	s_barrier
	ds_read_b128 v[34:37], v95 offset:9216
	ds_read_b128 v[38:41], v95 offset:9248
	s_waitcnt lgkmcnt(1)
	v_mfma_f32_32x32x16_bf16 v[50:65], v[34:37], v[70:73], 0
	ds_read_b128 v[34:37], v95 offset:13824
	ds_read_b128 v[74:77], v95 offset:13856
	s_waitcnt lgkmcnt(2)
	v_mfma_f32_32x32x16_bf16 v[50:65], v[38:41], v[66:69], v[50:65]
	s_waitcnt lgkmcnt(1)
	v_mfma_f32_32x32x16_bf16 v[34:49], v[34:37], v[70:73], 0
	s_nop 9
	v_max_f32_e32 v1, v51, v51
	s_waitcnt lgkmcnt(0)
	v_mfma_f32_32x32x16_bf16 v[34:49], v[74:77], v[66:69], v[34:49]
	v_max_f32_e32 v66, v50, v50
	v_max_f32_e32 v1, v66, v1
	v_max3_f32 v1, v1, v52, v53
	v_max3_f32 v1, v1, v54, v55
	v_max3_f32 v1, v1, v56, v57
	v_max3_f32 v1, v1, v58, v59
	v_max3_f32 v1, v1, v60, v61
	v_max3_f32 v1, v1, v62, v63
	v_max3_f32 v1, v1, v64, v65
	s_nop 2
	v_max3_f32 v1, v1, v34, v35
	v_max3_f32 v1, v1, v36, v37
	v_max3_f32 v1, v1, v38, v39
	v_max3_f32 v1, v1, v40, v41
	v_max3_f32 v1, v1, v42, v43
	v_max3_f32 v1, v1, v44, v45
	v_max3_f32 v1, v1, v46, v47
	v_max3_f32 v1, v1, v48, v49
	ds_bpermute_b32 v66, v93, v1
	s_waitcnt lgkmcnt(0)
	v_max3_f32 v1, v84, v1, v66
	v_sub_f32_e32 v50, v50, v1
	v_exp_f32_e32 v67, v50
	v_sub_f32_e32 v51, v51, v1
	v_exp_f32_e32 v51, v51
	v_sub_f32_e32 v52, v52, v1
	v_exp_f32_e32 v68, v52
	v_sub_f32_e32 v52, v53, v1
	v_exp_f32_e32 v53, v52
	v_sub_f32_e32 v52, v54, v1
	v_add_f32_e32 v50, 0, v67
	v_exp_f32_e32 v54, v52
	v_sub_f32_e32 v52, v55, v1
	v_add_f32_e32 v50, v51, v50
	v_exp_f32_e32 v55, v52
	v_sub_f32_e32 v52, v56, v1
	v_add_f32_e32 v50, v68, v50
	v_exp_f32_e32 v56, v52
	v_sub_f32_e32 v52, v57, v1
	v_add_f32_e32 v50, v53, v50
	v_exp_f32_e32 v57, v52
	v_sub_f32_e32 v52, v58, v1
	v_add_f32_e32 v50, v54, v50
	v_exp_f32_e32 v58, v52
	v_sub_f32_e32 v52, v59, v1
	v_add_f32_e32 v50, v55, v50
	v_exp_f32_e32 v59, v52
	v_sub_f32_e32 v52, v60, v1
	v_add_f32_e32 v50, v56, v50
	v_exp_f32_e32 v60, v52
	v_sub_f32_e32 v52, v61, v1
	v_add_f32_e32 v50, v57, v50
	v_exp_f32_e32 v61, v52
	v_sub_f32_e32 v52, v62, v1
	v_add_f32_e32 v50, v58, v50
	v_exp_f32_e32 v62, v52
	v_sub_f32_e32 v52, v63, v1
	v_add_f32_e32 v50, v59, v50
	v_exp_f32_e32 v63, v52
	v_sub_f32_e32 v52, v64, v1
	v_add_f32_e32 v50, v60, v50
	v_exp_f32_e32 v64, v52
	v_sub_f32_e32 v52, v65, v1
	v_add_f32_e32 v50, v61, v50
	v_exp_f32_e32 v65, v52
	v_sub_f32_e32 v34, v34, v1
	v_add_f32_e32 v50, v62, v50
	v_exp_f32_e32 v69, v34
	v_sub_f32_e32 v35, v35, v1
	v_add_f32_e32 v50, v63, v50
	v_exp_f32_e32 v70, v35
	v_sub_f32_e32 v35, v36, v1
	v_add_f32_e32 v50, v64, v50
	v_exp_f32_e32 v71, v35
	v_sub_f32_e32 v35, v37, v1
	v_add_f32_e32 v50, v65, v50
	v_exp_f32_e32 v72, v35
	v_sub_f32_e32 v35, v38, v1
	v_add_f32_e32 v34, v69, v50
	v_exp_f32_e32 v73, v35
	v_sub_f32_e32 v35, v39, v1
	v_add_f32_e32 v34, v70, v34
	v_exp_f32_e32 v74, v35
	v_sub_f32_e32 v35, v40, v1
	v_add_f32_e32 v34, v71, v34
	v_exp_f32_e32 v75, v35
	v_sub_f32_e32 v35, v41, v1
	v_add_f32_e32 v34, v72, v34
	v_exp_f32_e32 v76, v35
	v_sub_f32_e32 v35, v42, v1
	v_add_f32_e32 v34, v73, v34
	v_exp_f32_e32 v77, v35
	v_sub_f32_e32 v35, v43, v1
	v_add_f32_e32 v34, v74, v34
	v_exp_f32_e32 v78, v35
	v_sub_f32_e32 v35, v44, v1
	v_add_f32_e32 v34, v75, v34
	v_exp_f32_e32 v79, v35
	v_sub_f32_e32 v35, v45, v1
	v_add_f32_e32 v34, v76, v34
	v_exp_f32_e32 v80, v35
	v_sub_f32_e32 v35, v46, v1
	v_add_f32_e32 v34, v77, v34
	v_exp_f32_e32 v81, v35
	v_sub_f32_e32 v35, v47, v1
	v_add_f32_e32 v34, v78, v34
	v_exp_f32_e32 v83, v35
	v_sub_f32_e32 v35, v48, v1
	v_sub_f32_e32 v66, v84, v1
	v_add_f32_e32 v34, v79, v34
	v_exp_f32_e32 v84, v35
	v_sub_f32_e32 v1, v49, v1
	v_add_f32_e32 v34, v80, v34
	v_exp_f32_e32 v85, v1
	v_exp_f32_e32 v52, v66
	v_add_f32_e32 v34, v81, v34
	v_add_f32_e32 v34, v83, v34
	v_add_f32_e32 v34, v84, v34
	v_add_f32_e32 v50, v85, v34
	v_mul_f32_e32 v44, v12, v52
	v_mul_f32_e32 v45, v13, v52
	v_mul_f32_e32 v42, v10, v52
	v_mul_f32_e32 v43, v11, v52
	v_mul_f32_e32 v40, v8, v52
	v_mul_f32_e32 v41, v9, v52
	v_mul_f32_e32 v38, v6, v52
	v_mul_f32_e32 v39, v7, v52
	v_mul_f32_e32 v36, v4, v52
	v_mul_f32_e32 v37, v5, v52
	v_mul_f32_e32 v34, v2, v52
	v_mul_f32_e32 v35, v3, v52
	v_mul_f32_e32 v12, v30, v52
	v_mul_f32_e32 v13, v31, v52
	v_mul_f32_e32 v10, v28, v52
	v_mul_f32_e32 v11, v29, v52
	v_mul_f32_e32 v8, v26, v52
	v_mul_f32_e32 v9, v27, v52
	v_mul_f32_e32 v6, v24, v52
	v_mul_f32_e32 v7, v25, v52
	v_mul_f32_e32 v4, v22, v52
	v_mul_f32_e32 v5, v23, v52
	v_mul_f32_e32 v2, v20, v52
	v_mul_f32_e32 v3, v21, v52
	ds_read_b128 v[20:23], v94 offset:32256
	ds_read_b128 v[24:27], v94 offset:27648
	ds_read_b128 v[28:31], v94 offset:27680
	v_fmac_f32_e32 v50, v0, v52
	v_mul_f32_e32 v48, v16, v52
	v_mul_f32_e32 v49, v17, v52
	v_mul_f32_e32 v46, v14, v52
	v_mul_f32_e32 v47, v15, v52
	v_mul_f32_e32 v14, v32, v52
	v_mul_f32_e32 v15, v33, v52
	v_mul_f32_e32 v0, v18, v52
	v_mul_f32_e32 v1, v19, v52
	v_cvt_pk_bf16_f32 v16, v67, v51
	v_cvt_pk_bf16_f32 v17, v68, v53
	v_cvt_pk_bf16_f32 v18, v54, v55
	v_cvt_pk_bf16_f32 v19, v56, v57
	s_waitcnt lgkmcnt(2)
	s_nop 0
	v_mfma_f32_32x32x16_bf16 v[0:15], v[20:23], v[16:19], v[0:15]
	ds_read_b128 v[20:23], v94 offset:32288
	s_waitcnt lgkmcnt(2)
	v_mfma_f32_32x32x16_bf16 v[34:49], v[24:27], v[16:19], v[34:49]
	v_cvt_pk_bf16_f32 v16, v58, v59
	v_cvt_pk_bf16_f32 v17, v60, v61
	v_cvt_pk_bf16_f32 v18, v62, v63
	v_cvt_pk_bf16_f32 v19, v64, v65
	s_waitcnt lgkmcnt(1)
	s_nop 0
	v_mfma_f32_32x32x16_bf16 v[34:49], v[28:31], v[16:19], v[34:49]
	s_waitcnt lgkmcnt(0)
	v_mfma_f32_32x32x16_bf16 v[0:15], v[20:23], v[16:19], v[0:15]
	ds_read_b128 v[20:23], v94 offset:27712
	ds_read_b128 v[24:27], v94 offset:32320
	v_cvt_pk_bf16_f32 v16, v69, v70
	v_cvt_pk_bf16_f32 v17, v71, v72
	v_cvt_pk_bf16_f32 v18, v73, v74
	v_cvt_pk_bf16_f32 v19, v75, v76
	s_waitcnt lgkmcnt(1)
	s_nop 0
	v_mfma_f32_32x32x16_bf16 v[34:49], v[20:23], v[16:19], v[34:49]
	s_waitcnt lgkmcnt(0)
	v_mfma_f32_32x32x16_bf16 v[0:15], v[24:27], v[16:19], v[0:15]
	ds_read_b128 v[20:23], v94 offset:27744
	ds_read_b128 v[24:27], v94 offset:32352
	v_cvt_pk_bf16_f32 v16, v77, v78
	v_cvt_pk_bf16_f32 v17, v79, v80
	v_cvt_pk_bf16_f32 v18, v81, v83
	v_cvt_pk_bf16_f32 v19, v84, v85
	s_waitcnt lgkmcnt(0)
	s_barrier
	v_mfma_f32_32x32x16_bf16 v[34:49], v[20:23], v[16:19], v[34:49]
	v_mfma_f32_32x32x16_bf16 v[0:15], v[24:27], v[16:19], v[0:15]
	ds_bpermute_b32 v18, v93, v50
	v_mov_b32_e32 v16, 0
	v_mov_b32_e32 v17, 0
	s_and_saveexec_b64 s[4:5], s[16:17]
	s_cbranch_execz .LBB0_993
	v_or_b32_e32 v128, s27, v112
	v_readlane_b32 s40, v250, 21
	v_lshlrev_b64 v[16:17], 2, v[128:129]
	v_readlane_b32 s44, v250, 25
	v_readlane_b32 s45, v250, 26
	v_readlane_b32 s46, v250, 27
	v_readlane_b32 s47, v250, 28
	v_readlane_b32 s48, v250, 29
	v_readlane_b32 s49, v250, 30
	v_readlane_b32 s50, v250, 31
	v_readlane_b32 s51, v250, 32
	v_lshl_add_u64 v[20:21], s[44:45], 0, v[16:17]
	v_lshl_add_u64 v[22:23], s[46:47], 0, v[16:17]
	v_lshl_add_u64 v[24:25], s[48:49], 0, v[16:17]
	v_lshl_add_u64 v[16:17], s[50:51], 0, v[16:17]
	global_load_dword v21, v[20:21], off
	v_readlane_b32 s41, v250, 22
	global_load_dword v23, v[22:23], off
	v_readlane_b32 s42, v250, 23
	global_load_dword v20, v[24:25], off
	global_load_dword v22, v[16:17], off
	v_readlane_b32 s43, v250, 24
	v_readlane_b32 s52, v250, 33
	v_readlane_b32 s53, v250, 34
	v_readlane_b32 s54, v250, 35
	v_readlane_b32 s55, v250, 36
	s_waitcnt vmcnt(0)
	v_pk_mul_f32 v[16:17], v[20:21], v[22:23]

.LBB0_995:
	s_or_b64 exec, exec, s[4:5]
	s_waitcnt lgkmcnt(0)
	s_barrier
	s_and_saveexec_b64 s[4:5], s[0:1]
	s_cbranch_execz .LBB0_997
	v_div_scale_f32 v17, s[0:1], v18, v18, 1.0
	v_rcp_f32_e32 v19, v17
	v_div_scale_f32 v20, vcc, 1.0, v18, 1.0
	s_movk_i32 s0, 0x84
	v_fma_f32 v21, -v17, v19, 1.0
	v_fmac_f32_e32 v19, v21, v19
	v_mul_f32_e32 v21, v20, v19
	v_fma_f32 v22, -v17, v21, v20
	v_fmac_f32_e32 v21, v22, v19
	v_fma_f32 v17, -v17, v21, v20
	v_div_fmas_f32 v17, v17, v19, v21
	v_div_fixup_f32 v18, v17, v18, 1.0
	v_add_u32_e32 v17, 0x400, v99
	ds_read2_b32 v[20:21], v99 offset1:33
	ds_read2_b32 v[22:23], v99 offset0:66 offset1:99
	ds_read2_b32 v[24:25], v17 offset0:8 offset1:41
	ds_read2_b32 v[26:27], v17 offset0:74 offset1:107
	v_add_u32_e32 v17, 0x800, v99
	ds_read2_b32 v[28:29], v17 offset0:16 offset1:49
	ds_read2_b32 v[30:31], v17 offset0:82 offset1:115
	v_add_u32_e32 v17, 0xc00, v99
	ds_read2_b32 v[32:33], v17 offset0:24 offset1:57
	ds_read2_b32 v[50:51], v17 offset0:90 offset1:123
	v_lshl_or_b32 v17, v108, 2, 32
	v_mad_u32_u24 v17, v17, s0, v101
	ds_read_b32 v52, v17
	ds_read_b32 v71, v99 offset:7788
	v_add_u32_e32 v17, 0x1000, v99
	ds_read2_b32 v[54:55], v17 offset0:65 offset1:98
	v_add_u32_e32 v17, 0x1200, v99
	ds_read2_b32 v[56:57], v17 offset0:3 offset1:168
	v_add_u32_e32 v17, 0x1400, v99
	ds_read2_b32 v[58:59], v17 offset0:73 offset1:106
	v_add_u32_e32 v17, 0x1600, v99
	ds_read2_b32 v[60:61], v17 offset0:11 offset1:176
	v_add_u32_e32 v17, 0x1a00, v99
	ds_read2_b32 v[62:63], v17 offset0:19 offset1:184
	v_add_u32_e32 v17, 0x1c00, v99
	ds_read2_b32 v[64:65], v17 offset0:89 offset1:122
	v_readlane_b32 s6, v254, 29
	v_readlane_b32 s7, v254, 30
	s_waitcnt lgkmcnt(1)
	v_mov_b32_e32 v68, v63
	v_pk_fma_f32 v[20:21], v[34:35], v[18:19], v[20:21] op_sel_hi:[1,0,1] neg_lo:[0,0,1] neg_hi:[0,0,1]
	s_waitcnt lgkmcnt(0)
	v_mov_b32_e32 v69, v64
	v_mov_b32_e32 v70, v65
	v_pk_fma_f32 v[68:69], v[12:13], v[18:19], v[68:69] op_sel_hi:[1,0,1] neg_lo:[0,0,1] neg_hi:[0,0,1]
	v_pk_fma_f32 v[64:65], v[14:15], v[18:19], v[70:71] op_sel_hi:[1,0,1] neg_lo:[0,0,1] neg_hi:[0,0,1]
	global_load_dwordx4 v[12:15], v96, s[6:7]
	v_add_u32_e32 v17, 0x1800, v99
	v_pk_fma_f32 v[22:23], v[36:37], v[18:19], v[22:23] op_sel_hi:[1,0,1] neg_lo:[0,0,1] neg_hi:[0,0,1]
	v_pk_mul_f32 v[34:35], v[20:21], v[20:21]
	ds_read2_b32 v[66:67], v17 offset0:81 offset1:114
	v_pk_mul_f32 v[36:37], v[22:23], v[22:23]
	v_add_f32_e32 v17, v34, v35
	v_pk_fma_f32 v[24:25], v[38:39], v[18:19], v[24:25] op_sel_hi:[1,0,1] neg_lo:[0,0,1] neg_hi:[0,0,1]
	v_add_f32_e32 v17, v17, v36
	v_pk_mul_f32 v[38:39], v[24:25], v[24:25]
	v_add_f32_e32 v17, v17, v37
	v_pk_fma_f32 v[26:27], v[40:41], v[18:19], v[26:27] op_sel_hi:[1,0,1] neg_lo:[0,0,1] neg_hi:[0,0,1]
	v_add_f32_e32 v17, v17, v38
	v_pk_mul_f32 v[40:41], v[26:27], v[26:27]
	v_add_f32_e32 v17, v17, v39
	v_pk_fma_f32 v[28:29], v[42:43], v[18:19], v[28:29] op_sel_hi:[1,0,1] neg_lo:[0,0,1] neg_hi:[0,0,1]
	v_add_f32_e32 v17, v17, v40
	v_pk_mul_f32 v[42:43], v[28:29], v[28:29]
	v_add_f32_e32 v17, v17, v41
	v_pk_fma_f32 v[30:31], v[44:45], v[18:19], v[30:31] op_sel_hi:[1,0,1] neg_lo:[0,0,1] neg_hi:[0,0,1]
	v_add_f32_e32 v17, v17, v42
	v_pk_mul_f32 v[44:45], v[30:31], v[30:31]
	v_add_f32_e32 v17, v17, v43
	v_pk_fma_f32 v[32:33], v[46:47], v[18:19], v[32:33] op_sel_hi:[1,0,1] neg_lo:[0,0,1] neg_hi:[0,0,1]
	v_add_f32_e32 v17, v17, v44
	v_pk_mul_f32 v[46:47], v[32:33], v[32:33]
	v_add_f32_e32 v17, v17, v45
	v_pk_fma_f32 v[48:49], v[48:49], v[18:19], v[50:51] op_sel_hi:[1,0,1] neg_lo:[0,0,1] neg_hi:[0,0,1]
	v_add_f32_e32 v17, v17, v46
	v_pk_mul_f32 v[50:51], v[48:49], v[48:49]
	v_mov_b32_e32 v53, v54
	v_add_f32_e32 v17, v17, v47
	v_pk_fma_f32 v[52:53], v[0:1], v[18:19], v[52:53] op_sel_hi:[1,0,1] neg_lo:[0,0,1] neg_hi:[0,0,1]
	v_add_f32_e32 v17, v17, v50
	v_mov_b32_e32 v74, v55
	v_mov_b32_e32 v75, v56
	v_pk_mul_f32 v[0:1], v[52:53], v[52:53]
	v_add_f32_e32 v17, v17, v51
	v_pk_fma_f32 v[74:75], v[2:3], v[18:19], v[74:75] op_sel_hi:[1,0,1] neg_lo:[0,0,1] neg_hi:[0,0,1]
	v_add_f32_e32 v0, v17, v0
	v_pk_mul_f32 v[2:3], v[74:75], v[74:75]
	v_mov_b32_e32 v56, v57
	v_mov_b32_e32 v57, v58
	v_add_f32_e32 v0, v0, v1
	v_pk_fma_f32 v[4:5], v[4:5], v[18:19], v[56:57] op_sel_hi:[1,0,1] neg_lo:[0,0,1] neg_hi:[0,0,1]
	v_add_f32_e32 v0, v0, v2
	v_mov_b32_e32 v54, v59
	v_mov_b32_e32 v55, v60
	v_pk_mul_f32 v[56:57], v[4:5], v[4:5]
	v_add_f32_e32 v0, v0, v3
	v_pk_fma_f32 v[6:7], v[6:7], v[18:19], v[54:55] op_sel_hi:[1,0,1] neg_lo:[0,0,1] neg_hi:[0,0,1]
	v_add_f32_e32 v0, v0, v56
	v_pk_mul_f32 v[54:55], v[6:7], v[6:7]
	v_mov_b32_e32 v60, v61
	s_waitcnt lgkmcnt(0)
	v_mov_b32_e32 v61, v66
	v_add_f32_e32 v0, v0, v57
	v_mov_b32_e32 v58, v67
	v_mov_b32_e32 v59, v62
	v_pk_fma_f32 v[8:9], v[8:9], v[18:19], v[60:61] op_sel_hi:[1,0,1] neg_lo:[0,0,1] neg_hi:[0,0,1]
	v_add_f32_e32 v0, v0, v54
	v_pk_fma_f32 v[10:11], v[10:11], v[18:19], v[58:59] op_sel_hi:[1,0,1] neg_lo:[0,0,1] neg_hi:[0,0,1]
	v_pk_mul_f32 v[18:19], v[8:9], v[8:9]
	v_add_f32_e32 v0, v0, v55
	v_add_f32_e32 v0, v0, v18
	v_pk_mul_f32 v[58:59], v[10:11], v[10:11]
	v_add_f32_e32 v0, v0, v19
	v_add_f32_e32 v0, v0, v58
	v_pk_mul_f32 v[72:73], v[68:69], v[68:69]
	v_add_f32_e32 v0, v0, v59
	v_add_f32_e32 v0, v0, v72
	v_pk_mul_f32 v[70:71], v[64:65], v[64:65]
	v_add_f32_e32 v0, v0, v73
	v_add_f32_e32 v0, v0, v70
	v_add_f32_e32 v2, v0, v71
	ds_bpermute_b32 v3, v93, v2
	s_mov_b32 s0, 0x800000
	v_lshlrev_b64 v[0:1], 11, v[86:87]
	v_lshl_add_u64 v[0:1], s[66:67], 0, v[0:1]
	v_lshl_add_u64 v[0:1], v[0:1], 0, s[60:61]
	s_waitcnt lgkmcnt(0)
	v_add_f32_e32 v2, v2, v3
	v_fmamk_f32 v2, v2, 0x3c800000, v225
	v_mul_f32_e32 v3, 0x4b800000, v2
	v_cmp_gt_f32_e32 vcc, s0, v2
	v_mov_b32_e32 v83, v129
	v_sub_f32_e32 v18, 1.0, v16
	v_cndmask_b32_e32 v2, v2, v3, vcc
	v_rsq_f32_e32 v2, v2
	v_lshl_add_u64 v[16:17], v[0:1], 0, v[82:83]
	s_mov_b32 s0, 0x2d53000
	v_mul_f32_e32 v0, 0x45800000, v2
	v_cndmask_b32_e32 v0, v2, v0, vcc
	v_mul_f32_e32 v18, v18, v0
	v_mul_f32_e32 v0, v20, v18
	v_mul_f32_e32 v1, v21, v18
	v_mul_f32_e32 v2, v22, v18
	v_mul_f32_e32 v3, v23, v18
	s_waitcnt vmcnt(0)
	v_pk_mul_f32 v[0:1], v[12:13], v[0:1]
	v_pk_mul_f32 v[2:3], v[14:15], v[2:3]
	v_cvt_pk_bf16_f32 v0, v0, v1
	v_cvt_pk_bf16_f32 v1, v2, v3
	v_add_co_u32_e32 v2, vcc, s0, v16
	s_mov_b64 s[0:1], 0x2d53700
	s_nop 0
	v_addc_co_u32_e32 v3, vcc, 0, v17, vcc
	global_store_dwordx2 v[2:3], v[0:1], off offset:1792
	global_load_dwordx4 v[0:3], v96, s[6:7] offset:32
	v_lshl_add_u64 v[12:13], v[16:17], 0, s[0:1]
	v_mul_f32_e32 v14, v24, v18
	v_mul_f32_e32 v15, v25, v18
	v_mul_f32_e32 v16, v26, v18
	v_mul_f32_e32 v17, v27, v18
	v_mul_f32_e32 v4, v4, v18
	v_mul_f32_e32 v5, v5, v18
	v_mul_f32_e32 v6, v6, v18
	v_mul_f32_e32 v7, v7, v18
	s_waitcnt vmcnt(0)
	v_pk_mul_f32 v[0:1], v[0:1], v[14:15]
	v_pk_mul_f32 v[2:3], v[2:3], v[16:17]
	v_cvt_pk_bf16_f32 v0, v0, v1
	v_cvt_pk_bf16_f32 v1, v2, v3
	global_store_dwordx2 v[12:13], v[0:1], off offset:16
	global_load_dwordx4 v[0:3], v96, s[6:7] offset:64
	v_mul_f32_e32 v14, v28, v18
	v_mul_f32_e32 v15, v29, v18
	v_mul_f32_e32 v16, v30, v18
	v_mul_f32_e32 v17, v31, v18
	s_waitcnt vmcnt(0)
	v_pk_mul_f32 v[0:1], v[0:1], v[14:15]
	v_pk_mul_f32 v[2:3], v[2:3], v[16:17]
	v_cvt_pk_bf16_f32 v0, v0, v1
	v_cvt_pk_bf16_f32 v1, v2, v3
	global_store_dwordx2 v[12:13], v[0:1], off offset:32
	global_load_dwordx4 v[0:3], v96, s[6:7] offset:96
	v_mul_f32_e32 v14, v32, v18
	v_mul_f32_e32 v15, v33, v18
	v_mul_f32_e32 v16, v48, v18
	v_mul_f32_e32 v17, v49, v18
	s_waitcnt vmcnt(0)
	v_pk_mul_f32 v[0:1], v[0:1], v[14:15]
	v_pk_mul_f32 v[2:3], v[2:3], v[16:17]
	v_cvt_pk_bf16_f32 v0, v0, v1
	v_cvt_pk_bf16_f32 v1, v2, v3
	global_store_dwordx2 v[12:13], v[0:1], off offset:48
	global_load_dwordx4 v[0:3], v96, s[6:7] offset:128
	v_mul_f32_e32 v14, v52, v18
	v_mul_f32_e32 v15, v53, v18
	v_mul_f32_e32 v16, v74, v18
	v_mul_f32_e32 v17, v75, v18
	s_waitcnt vmcnt(0)
	v_pk_mul_f32 v[0:1], v[0:1], v[14:15]
	v_pk_mul_f32 v[2:3], v[2:3], v[16:17]
	v_cvt_pk_bf16_f32 v0, v0, v1
	v_cvt_pk_bf16_f32 v1, v2, v3
	global_store_dwordx2 v[12:13], v[0:1], off offset:64
	global_load_dwordx4 v[0:3], v96, s[6:7] offset:160
	s_waitcnt vmcnt(0)
	v_pk_mul_f32 v[0:1], v[0:1], v[4:5]
	v_pk_mul_f32 v[2:3], v[2:3], v[6:7]
	v_cvt_pk_bf16_f32 v0, v0, v1
	v_cvt_pk_bf16_f32 v1, v2, v3
	global_store_dwordx2 v[12:13], v[0:1], off offset:80
	global_load_dwordx4 v[0:3], v96, s[6:7] offset:192
	v_mul_f32_e32 v4, v8, v18
	v_mul_f32_e32 v5, v9, v18
	v_mul_f32_e32 v6, v10, v18
	v_mul_f32_e32 v7, v11, v18
	s_waitcnt vmcnt(0)
	v_pk_mul_f32 v[0:1], v[4:5], v[0:1]
	v_pk_mul_f32 v[2:3], v[6:7], v[2:3]
	v_cvt_pk_bf16_f32 v0, v0, v1
	v_cvt_pk_bf16_f32 v1, v2, v3
	global_store_dwordx2 v[12:13], v[0:1], off offset:96
	global_load_dwordx4 v[0:3], v96, s[6:7] offset:224
	v_mul_f32_e32 v4, v68, v18
	v_mul_f32_e32 v5, v69, v18
	v_mul_f32_e32 v6, v64, v18
	v_mul_f32_e32 v7, v65, v18
	s_waitcnt vmcnt(0)
	v_pk_mul_f32 v[0:1], v[4:5], v[0:1]
	v_pk_mul_f32 v[2:3], v[6:7], v[2:3]
	v_cvt_pk_bf16_f32 v0, v0, v1
	v_cvt_pk_bf16_f32 v1, v2, v3
	global_store_dwordx2 v[12:13], v[0:1], off offset:112

.LBB0_1022:
	s_or_b64 exec, exec, s[6:7]
	s_and_b32 s6, s16, 1
	s_mul_i32 s7, s6, 0x2400
	v_add_u32_e32 v105, s7, v92
	ds_read_b128 v[32:35], v105
	ds_read_b128 v[36:39], v105 offset:32
	s_xor_b32 s31, s6, 1
	s_mulk_i32 s31, 0x2400
	s_waitcnt lgkmcnt(1)
	v_mfma_f32_32x32x16_bf16 v[48:63], v[32:35], v[76:79], 0
	s_waitcnt lgkmcnt(0)
	v_mfma_f32_32x32x16_bf16 v[48:63], v[36:39], v[72:75], v[48:63]
	ds_read_b128 v[32:35], v105 offset:64
	ds_read_b128 v[36:39], v105 offset:96
	s_waitcnt lgkmcnt(1)
	v_mfma_f32_32x32x16_bf16 v[48:63], v[32:35], v[68:71], v[48:63]
	ds_read_b128 v[32:35], v105 offset:4608
	ds_read_b128 v[100:103], v105 offset:4640
	s_waitcnt lgkmcnt(2)
	v_mfma_f32_32x32x16_bf16 v[48:63], v[36:39], v[64:67], v[48:63]
	s_waitcnt lgkmcnt(1)
	v_mfma_f32_32x32x16_bf16 v[32:47], v[32:35], v[76:79], 0
	s_nop 9
	v_max_f32_e32 v95, v49, v49
	v_max_f32_e32 v99, v48, v48
	v_max_f32_e32 v95, v99, v95
	v_max3_f32 v95, v95, v50, v51
	v_max3_f32 v95, v95, v52, v53
	v_max3_f32 v95, v95, v54, v55
	v_max3_f32 v95, v95, v56, v57
	s_waitcnt lgkmcnt(0)
	v_mfma_f32_32x32x16_bf16 v[32:47], v[100:103], v[72:75], v[32:47]
	ds_read_b128 v[100:103], v105 offset:4672
	ds_read_b128 v[114:117], v105 offset:4704
	v_max3_f32 v95, v95, v58, v59
	v_max3_f32 v95, v95, v60, v61
	v_max3_f32 v95, v95, v62, v63
	s_waitcnt lgkmcnt(1)
	v_mfma_f32_32x32x16_bf16 v[32:47], v[100:103], v[68:71], v[32:47]
	s_waitcnt lgkmcnt(0)
	v_mfma_f32_32x32x16_bf16 v[32:47], v[114:117], v[64:67], v[32:47]
	s_nop 11
	v_max3_f32 v95, v95, v32, v33
	v_max3_f32 v95, v95, v34, v35
	v_max3_f32 v95, v95, v36, v37
	v_max3_f32 v95, v95, v38, v39
	v_max3_f32 v95, v95, v40, v41
	v_max3_f32 v95, v95, v42, v43
	v_max3_f32 v95, v95, v44, v45
	v_max3_f32 v95, v95, v46, v47
	ds_bpermute_b32 v99, v90, v95
	s_waitcnt lgkmcnt(0)
	v_max3_f32 v95, v97, v95, v99
	v_sub_f32_e32 v32, v32, v95
	v_sub_f32_e32 v103, v97, v95
	v_exp_f32_e32 v97, v32
	v_sub_f32_e32 v32, v33, v95
	v_exp_f32_e32 v99, v32
	v_sub_f32_e32 v32, v34, v95
	v_exp_f32_e32 v100, v32
	v_sub_f32_e32 v32, v35, v95
	v_exp_f32_e32 v101, v32
	v_sub_f32_e32 v32, v36, v95
	v_exp_f32_e32 v102, v32
	v_sub_f32_e32 v32, v37, v95
	v_exp_f32_e32 v37, v32
	ds_read_b128 v[32:35], v105 offset:18432
	v_sub_f32_e32 v48, v48, v95
	v_sub_f32_e32 v49, v49, v95
	v_sub_f32_e32 v50, v50, v95
	v_sub_f32_e32 v51, v51, v95
	v_sub_f32_e32 v52, v52, v95
	v_sub_f32_e32 v53, v53, v95
	v_sub_f32_e32 v54, v54, v95
	v_sub_f32_e32 v55, v55, v95
	v_exp_f32_e32 v48, v48
	v_exp_f32_e32 v49, v49
	v_exp_f32_e32 v50, v50
	v_exp_f32_e32 v51, v51
	v_exp_f32_e32 v52, v52
	v_exp_f32_e32 v53, v53
	v_exp_f32_e32 v54, v54
	v_exp_f32_e32 v55, v55
	v_exp_f32_e32 v36, v103
	ds_read_b128 v[118:121], v105 offset:23040
	ds_read_b128 v[122:125], v105 offset:18464
	v_cvt_pk_bf16_f32 v114, v48, v49
	v_cvt_pk_bf16_f32 v115, v50, v51
	v_mul_f32_e32 v16, v16, v36
	v_mul_f32_e32 v17, v17, v36
	v_mul_f32_e32 v18, v18, v36
	v_mul_f32_e32 v19, v19, v36
	v_mul_f32_e32 v20, v20, v36
	v_mul_f32_e32 v21, v21, v36
	v_mul_f32_e32 v22, v22, v36
	v_mul_f32_e32 v23, v23, v36
	v_mul_f32_e32 v24, v24, v36
	v_mul_f32_e32 v25, v25, v36
	v_mul_f32_e32 v26, v26, v36
	v_mul_f32_e32 v27, v27, v36
	v_mul_f32_e32 v28, v28, v36
	v_mul_f32_e32 v29, v29, v36
	v_mul_f32_e32 v30, v30, v36
	v_mul_f32_e32 v31, v31, v36
	v_cvt_pk_bf16_f32 v116, v52, v53
	v_cvt_pk_bf16_f32 v117, v54, v55
	v_mul_f32_e32 v0, v0, v36
	v_mul_f32_e32 v1, v1, v36
	v_mul_f32_e32 v2, v2, v36
	v_mul_f32_e32 v3, v3, v36
	s_waitcnt lgkmcnt(2)
	v_mfma_f32_32x32x16_bf16 v[16:31], v[32:35], v[114:117], v[16:31]
	v_mul_f32_e64 v4, v4, v36
	v_mul_f32_e64 v5, v5, v36
	v_mul_f32_e64 v6, v6, v36
	v_mul_f32_e64 v7, v7, v36
	v_mul_f32_e64 v8, v8, v36
	v_mul_f32_e64 v9, v9, v36
	v_mul_f32_e32 v10, v10, v36
	v_mul_f32_e32 v11, v11, v36
	v_mul_f32_e32 v12, v12, v36
	v_mul_f32_e32 v13, v13, v36
	v_mul_f32_e32 v14, v14, v36
	v_mul_f32_e32 v15, v15, v36
	ds_read_b128 v[32:35], v105 offset:23072
	v_sub_f32_e32 v56, v56, v95
	s_waitcnt lgkmcnt(2)
	v_mfma_f32_32x32x16_bf16 v[0:15], v[118:121], v[114:117], v[0:15]
	v_sub_f32_e32 v57, v57, v95
	v_sub_f32_e32 v58, v58, v95
	v_sub_f32_e32 v59, v59, v95
	v_sub_f32_e32 v60, v60, v95
	v_sub_f32_e32 v61, v61, v95
	v_sub_f32_e32 v62, v62, v95
	v_sub_f32_e32 v63, v63, v95
	v_exp_f32_e32 v56, v56
	v_exp_f32_e32 v57, v57
	v_exp_f32_e32 v58, v58
	v_exp_f32_e32 v59, v59
	v_exp_f32_e32 v60, v60
	v_exp_f32_e32 v61, v61
	v_exp_f32_e32 v62, v62
	v_exp_f32_e32 v63, v63
	v_cvt_pk_bf16_f32 v114, v56, v57
	v_cvt_pk_bf16_f32 v115, v58, v59
	v_cvt_pk_bf16_f32 v116, v60, v61
	v_cvt_pk_bf16_f32 v117, v62, v63
	ds_read_b128 v[118:121], v105 offset:18496
	v_sub_f32_e32 v38, v38, v95
	s_waitcnt lgkmcnt(2)
	v_mfma_f32_32x32x16_bf16 v[16:31], v[122:125], v[114:117], v[16:31]
	v_sub_f32_e32 v39, v39, v95
	v_exp_f32_e32 v38, v38
	v_exp_f32_e32 v39, v39
	v_sub_f32_e32 v40, v40, v95
	v_sub_f32_e32 v41, v41, v95
	v_sub_f32_e32 v42, v42, v95
	v_sub_f32_e32 v43, v43, v95
	s_waitcnt lgkmcnt(1)
	v_mfma_f32_32x32x16_bf16 v[0:15], v[32:35], v[114:117], v[0:15]
	ds_read_b128 v[114:117], v105 offset:23104
	ds_read_b128 v[122:125], v105 offset:18528
	v_cvt_pk_bf16_f32 v32, v97, v99
	v_cvt_pk_bf16_f32 v33, v100, v101
	v_cvt_pk_bf16_f32 v34, v102, v37
	v_cvt_pk_bf16_f32 v35, v38, v39
	v_sub_f32_e32 v44, v44, v95
	v_sub_f32_e32 v45, v45, v95
	s_waitcnt lgkmcnt(2)
	v_mfma_f32_32x32x16_bf16 v[16:31], v[118:121], v[32:35], v[16:31]
	ds_read_b128 v[118:121], v105 offset:23136
	v_sub_f32_e32 v46, v46, v95
	v_exp_f32_e32 v40, v40
	v_exp_f32_e32 v41, v41
	v_exp_f32_e32 v42, v42
	v_exp_f32_e32 v43, v43
	v_exp_f32_e32 v44, v44
	s_waitcnt lgkmcnt(2)
	v_mfma_f32_32x32x16_bf16 v[0:15], v[114:117], v[32:35], v[0:15]
	v_sub_f32_e32 v32, v47, v95
	v_exp_f32_e32 v47, v32
	global_load_dwordx4 v[32:35], v[88:89], off
	v_exp_f32_e32 v45, v45
	v_exp_f32_e32 v46, v46
	v_cvt_pk_bf16_f32 v114, v40, v41
	v_cvt_pk_bf16_f32 v115, v42, v43
	v_cvt_pk_bf16_f32 v116, v44, v45
	v_cvt_pk_bf16_f32 v117, v46, v47
	s_waitcnt lgkmcnt(1)
	s_nop 0
	v_mfma_f32_32x32x16_bf16 v[16:31], v[122:125], v[114:117], v[16:31]
	s_waitcnt lgkmcnt(0)
	v_mfma_f32_32x32x16_bf16 v[0:15], v[118:121], v[114:117], v[0:15]
	s_and_saveexec_b64 s[6:7], s[0:1]
	s_cbranch_execz .LBB0_1024
	v_add_u32_e32 v103, s31, v93
	s_waitcnt vmcnt(1)
	ds_write_b128 v103, v[80:83]
.LBB0_1024:
	s_or_b64 exec, exec, s[6:7]
	v_add_f32_e32 v48, 0, v48
	v_add_f32_e32 v48, v49, v48
	v_add_f32_e32 v48, v50, v48
	v_add_f32_e32 v48, v51, v48
	v_add_f32_e32 v48, v52, v48
	v_add_f32_e32 v48, v53, v48
	v_add_f32_e32 v48, v54, v48
	v_add_f32_e32 v48, v55, v48
	v_add_f32_e32 v48, v56, v48
	v_add_f32_e32 v48, v57, v48
	v_add_f32_e32 v48, v58, v48
	v_add_f32_e32 v48, v59, v48
	v_add_f32_e32 v48, v60, v48
	v_add_f32_e32 v48, v61, v48
	v_add_f32_e32 v48, v62, v48
	v_add_f32_e32 v48, v63, v48
	v_add_f32_e32 v48, v97, v48
	v_add_f32_e32 v48, v99, v48
	v_add_f32_e32 v48, v100, v48
	v_add_f32_e32 v48, v101, v48
	v_add_f32_e32 v48, v102, v48
	v_add_f32_e32 v37, v37, v48
	v_add_f32_e32 v37, v38, v37
	v_add_f32_e32 v37, v39, v37
	v_add_f32_e32 v37, v40, v37
	v_add_f32_e32 v37, v41, v37
	v_add_f32_e32 v37, v42, v37
	v_add_f32_e32 v37, v43, v37
	v_add_f32_e32 v37, v44, v37
	v_add_f32_e32 v37, v45, v37
	v_add_f32_e32 v37, v46, v37
	v_add_f32_e32 v97, v47, v37
	s_add_i32 s16, s16, 1
	s_mov_b64 s[6:7], 0x4000
	v_fmac_f32_e32 v97, v94, v36
	v_add_u32_e32 v36, s31, v91
	v_lshl_add_u64 v[86:87], v[86:87], 0, s[6:7]
	s_cmp_eq_u32 s17, s16
	v_lshl_add_u64 v[88:89], v[88:89], 0, s[34:35]
	s_waitcnt vmcnt(0)
	ds_write_b128 v36, v[32:35] offset:18432
	s_waitcnt lgkmcnt(0)
	s_barrier
	s_cbranch_scc0 .LBB0_1020
	s_bitcmp1_b32 s17, 0
	s_cselect_b32 s0, 0x2400, 0
	v_add_u32_e32 v80, s0, v92
	ds_read_b128 v[32:35], v80
	s_lshl_b32 s60, s9, 1
	v_lshlrev_b32_e32 v128, 3, v108
	s_waitcnt lgkmcnt(0)
	v_mfma_f32_32x32x16_bf16 v[48:63], v[32:35], v[76:79], 0
	ds_read_b128 v[32:35], v80 offset:32
	s_waitcnt lgkmcnt(0)
	v_mfma_f32_32x32x16_bf16 v[48:63], v[32:35], v[72:75], v[48:63]
	ds_read_b128 v[32:35], v80 offset:64
	s_waitcnt lgkmcnt(0)
	v_mfma_f32_32x32x16_bf16 v[48:63], v[32:35], v[68:71], v[48:63]
	ds_read_b128 v[32:35], v80 offset:96
	s_waitcnt lgkmcnt(0)
	v_mfma_f32_32x32x16_bf16 v[48:63], v[32:35], v[64:67], v[48:63]
	ds_read_b128 v[32:35], v80 offset:4608
	s_waitcnt lgkmcnt(0)
	v_mfma_f32_32x32x16_bf16 v[32:47], v[32:35], v[76:79], 0
	ds_read_b128 v[76:79], v80 offset:4640
	s_nop 7
	v_max_f32_e32 v81, v49, v49
	v_max_f32_e32 v82, v48, v48
	v_max_f32_e32 v81, v82, v81
	s_waitcnt lgkmcnt(0)
	v_mfma_f32_32x32x16_bf16 v[32:47], v[76:79], v[72:75], v[32:47]
	ds_read_b128 v[72:75], v80 offset:4672
	ds_read_b128 v[76:79], v80 offset:4704
	s_waitcnt lgkmcnt(1)
	v_mfma_f32_32x32x16_bf16 v[32:47], v[72:75], v[68:71], v[32:47]
	v_max3_f32 v68, v81, v50, v51
	v_max3_f32 v68, v68, v52, v53
	v_max3_f32 v68, v68, v54, v55
	v_max3_f32 v68, v68, v56, v57
	v_max3_f32 v68, v68, v58, v59
	v_max3_f32 v68, v68, v60, v61
	v_max3_f32 v68, v68, v62, v63
	s_waitcnt lgkmcnt(0)
	v_mfma_f32_32x32x16_bf16 v[32:47], v[76:79], v[64:67], v[32:47]
	s_nop 11
	v_max3_f32 v64, v68, v32, v33
	v_max3_f32 v64, v64, v34, v35
	v_max3_f32 v64, v64, v36, v37
	v_max3_f32 v64, v64, v38, v39
	v_max3_f32 v64, v64, v40, v41
	v_max3_f32 v64, v64, v42, v43
	v_max3_f32 v64, v64, v44, v45
	v_max3_f32 v64, v64, v46, v47
	ds_bpermute_b32 v65, v90, v64
	s_waitcnt lgkmcnt(0)
	v_max3_f32 v64, v95, v64, v65
	v_sub_f32_e32 v48, v48, v64
	v_sub_f32_e32 v49, v49, v64
	v_exp_f32_e32 v48, v48
	v_sub_f32_e32 v50, v50, v64
	v_exp_f32_e32 v49, v49
	v_sub_f32_e32 v51, v51, v64
	v_exp_f32_e32 v50, v50
	v_sub_f32_e32 v52, v52, v64
	v_sub_f32_e32 v56, v56, v64
	v_exp_f32_e32 v51, v51
	v_sub_f32_e32 v53, v53, v64
	v_exp_f32_e32 v52, v52
	v_exp_f32_e32 v66, v56
	v_add_f32_e32 v56, 0, v48
	v_sub_f32_e32 v54, v54, v64
	v_exp_f32_e32 v53, v53
	v_add_f32_e32 v56, v49, v56
	v_sub_f32_e32 v55, v55, v64
	v_exp_f32_e32 v54, v54
	v_add_f32_e32 v56, v50, v56
	v_exp_f32_e32 v55, v55
	v_add_f32_e32 v56, v51, v56
	v_sub_f32_e32 v57, v57, v64
	v_add_f32_e32 v56, v52, v56
	v_sub_f32_e32 v58, v58, v64
	v_exp_f32_e32 v57, v57
	v_add_f32_e32 v56, v53, v56
	v_sub_f32_e32 v59, v59, v64
	v_exp_f32_e32 v58, v58
	v_add_f32_e32 v56, v54, v56
	v_sub_f32_e32 v60, v60, v64
	v_exp_f32_e32 v59, v59
	v_add_f32_e32 v56, v55, v56
	v_sub_f32_e32 v61, v61, v64
	v_exp_f32_e32 v60, v60
	v_add_f32_e32 v56, v66, v56
	v_sub_f32_e32 v62, v62, v64
	v_exp_f32_e32 v61, v61
	v_add_f32_e32 v56, v57, v56
	v_sub_f32_e32 v63, v63, v64
	v_exp_f32_e32 v62, v62
	v_add_f32_e32 v56, v58, v56
	v_exp_f32_e32 v63, v63
	v_add_f32_e32 v56, v59, v56
	v_sub_f32_e32 v32, v32, v64
	v_add_f32_e32 v56, v60, v56
	v_exp_f32_e32 v67, v32
	v_sub_f32_e32 v32, v33, v64
	v_add_f32_e32 v56, v61, v56
	v_exp_f32_e32 v68, v32
	v_sub_f32_e32 v32, v34, v64
	v_add_f32_e32 v56, v62, v56
	v_exp_f32_e32 v69, v32
	v_sub_f32_e32 v33, v35, v64
	v_add_f32_e32 v32, v63, v56
	v_exp_f32_e32 v70, v33
	v_sub_f32_e32 v33, v36, v64
	v_add_f32_e32 v32, v67, v32
	v_exp_f32_e32 v71, v33
	v_sub_f32_e32 v33, v37, v64
	v_add_f32_e32 v32, v68, v32
	v_exp_f32_e32 v72, v33
	v_sub_f32_e32 v33, v38, v64
	v_add_f32_e32 v32, v69, v32
	v_exp_f32_e32 v73, v33
	v_add_f32_e32 v32, v70, v32
	v_add_f32_e32 v32, v71, v32
	v_add_f32_e32 v32, v72, v32
	v_sub_f32_e32 v65, v95, v64
	v_add_f32_e32 v74, v73, v32
	v_sub_f32_e32 v32, v39, v64
	v_exp_f32_e32 v56, v65
	v_exp_f32_e32 v65, v32
	ds_read_b128 v[32:35], v80 offset:18432
	v_cvt_pk_bf16_f32 v36, v48, v49
	v_cvt_pk_bf16_f32 v37, v50, v51
	v_cvt_pk_bf16_f32 v38, v52, v53
	v_cvt_pk_bf16_f32 v39, v54, v55
	ds_read_b128 v[48:51], v80 offset:23040
	ds_read_b128 v[52:55], v80 offset:18464
	v_mul_f32_e32 v30, v30, v56
	v_mul_f32_e32 v31, v31, v56
	v_mul_f32_e32 v28, v28, v56
	v_mul_f32_e32 v29, v29, v56
	v_mul_f32_e32 v26, v26, v56
	v_mul_f32_e32 v27, v27, v56
	v_mul_f32_e32 v24, v24, v56
	v_mul_f32_e32 v25, v25, v56
	v_mul_f32_e32 v22, v22, v56
	v_mul_f32_e32 v23, v23, v56
	v_mul_f32_e32 v20, v20, v56
	v_mul_f32_e32 v21, v21, v56
	v_mul_f32_e32 v18, v18, v56
	v_mul_f32_e32 v19, v19, v56
	v_mul_f32_e32 v16, v16, v56
	v_mul_f32_e32 v17, v17, v56
	v_mul_f32_e32 v14, v14, v56
	v_mul_f32_e32 v15, v15, v56
	v_mul_f32_e32 v12, v12, v56
	v_mul_f32_e32 v13, v13, v56
	s_waitcnt lgkmcnt(2)
	v_mfma_f32_32x32x16_bf16 v[16:31], v[32:35], v[36:39], v[16:31]
	v_mul_f32_e64 v10, v10, v56
	v_mul_f32_e64 v11, v11, v56
	v_mul_f32_e64 v8, v8, v56
	v_mul_f32_e64 v9, v9, v56
	v_mul_f32_e64 v6, v6, v56
	v_mul_f32_e64 v7, v7, v56
	v_mul_f32_e32 v4, v4, v56
	v_mul_f32_e32 v5, v5, v56
	v_mul_f32_e32 v2, v2, v56
	v_mul_f32_e32 v3, v3, v56
	v_mul_f32_e32 v0, v0, v56
	v_mul_f32_e32 v1, v1, v56
	ds_read_b128 v[32:35], v80 offset:23072
	v_sub_f32_e32 v40, v40, v64
	s_waitcnt lgkmcnt(2)
	v_mfma_f32_32x32x16_bf16 v[0:15], v[48:51], v[36:39], v[0:15]
	v_exp_f32_e32 v75, v40
	v_sub_f32_e32 v36, v41, v64
	v_exp_f32_e32 v76, v36
	v_cvt_pk_bf16_f32 v36, v66, v57
	v_cvt_pk_bf16_f32 v37, v58, v59
	v_cvt_pk_bf16_f32 v38, v60, v61
	v_cvt_pk_bf16_f32 v39, v62, v63
	v_sub_f32_e32 v40, v42, v64
	ds_read_b128 v[48:51], v80 offset:18496
	s_waitcnt lgkmcnt(2)
	v_mfma_f32_32x32x16_bf16 v[16:31], v[52:55], v[36:39], v[16:31]
	v_exp_f32_e32 v52, v40
	v_add_f32_e32 v40, v65, v74
	v_add_f32_e32 v40, v75, v40
	v_add_f32_e32 v40, v76, v40
	v_add_f32_e32 v53, v52, v40
	v_sub_f32_e32 v54, v43, v64
	v_exp_f32_e32 v54, v54
	s_waitcnt lgkmcnt(1)
	v_mfma_f32_32x32x16_bf16 v[0:15], v[32:35], v[36:39], v[0:15]
	ds_read_b128 v[36:39], v80 offset:23104
	ds_read_b128 v[40:43], v80 offset:18528
	v_sub_f32_e32 v44, v44, v64
	v_cvt_pk_bf16_f32 v32, v67, v68
	v_cvt_pk_bf16_f32 v33, v69, v70
	v_cvt_pk_bf16_f32 v34, v71, v72
	v_cvt_pk_bf16_f32 v35, v73, v65
	v_exp_f32_e32 v44, v44
	v_sub_f32_e32 v45, v45, v64
	s_waitcnt lgkmcnt(2)
	v_mfma_f32_32x32x16_bf16 v[16:31], v[48:51], v[32:35], v[16:31]
	v_exp_f32_e32 v45, v45
	v_sub_f32_e32 v46, v46, v64
	ds_read_b128 v[48:51], v80 offset:23136
	s_waitcnt lgkmcnt(0)
	s_barrier
	v_mfma_f32_32x32x16_bf16 v[0:15], v[36:39], v[32:35], v[0:15]
	v_sub_f32_e32 v32, v47, v64
	v_exp_f32_e32 v36, v46
	v_exp_f32_e32 v37, v32
	v_add_f32_e32 v38, v54, v53
	v_add_f32_e32 v38, v44, v38
	v_add_f32_e32 v38, v45, v38
	v_cvt_pk_bf16_f32 v35, v36, v37
	v_add_f32_e32 v36, v36, v38
	v_add_f32_e32 v36, v37, v36
	v_fmac_f32_e32 v36, v97, v56
	ds_bpermute_b32 v37, v90, v36
	v_cvt_pk_bf16_f32 v32, v75, v76
	v_cvt_pk_bf16_f32 v33, v52, v54
	v_cvt_pk_bf16_f32 v34, v44, v45
	s_nop 1
	v_mfma_f32_32x32x16_bf16 v[16:31], v[40:43], v[32:35], v[16:31]
	v_mfma_f32_32x32x16_bf16 v[0:15], v[48:51], v[32:35], v[0:15]
	s_waitcnt lgkmcnt(0)
	v_add_f32_e32 v34, v36, v37
	v_div_scale_f32 v35, s[0:1], v34, v34, 1.0
	v_rcp_f32_e32 v36, v35
	v_lshlrev_b64 v[32:33], 11, v[84:85]
	v_lshl_add_u64 v[32:33], s[66:67], 0, v[32:33]
	v_lshl_add_u64 v[32:33], v[32:33], 0, s[60:61]
	v_fma_f32 v37, -v35, v36, 1.0
	v_fmac_f32_e32 v36, v37, v36
	v_div_scale_f32 v37, vcc, 1.0, v34, 1.0
	v_mul_f32_e32 v38, v37, v36
	v_fma_f32 v39, -v35, v38, v37
	v_fmac_f32_e32 v38, v39, v36
	v_fma_f32 v35, -v35, v38, v37
	v_div_fmas_f32 v35, v35, v36, v38
	v_div_fixup_f32 v34, v35, v34, 1.0
	v_mul_f32_e32 v16, v16, v34
	v_mul_f32_e32 v17, v17, v34
	v_mul_f32_e32 v18, v18, v34
	v_mul_f32_e32 v19, v19, v34
	v_cvt_pk_bf16_f32 v16, v16, v17
	v_cvt_pk_bf16_f32 v17, v18, v19
	v_lshl_add_u64 v[18:19], v[32:33], 0, v[128:129]
	s_mov_b64 s[0:1], 0x2d53900
	v_lshl_add_u64 v[32:33], v[18:19], 0, s[0:1]
	s_mov_b32 s0, 0x2d53000
	v_add_co_u32_e32 v18, vcc, s0, v18
	v_mul_f32_e32 v0, v0, v34
	v_mul_f32_e32 v1, v1, v34
	v_mul_f32_e32 v2, v2, v34
	v_mul_f32_e32 v3, v3, v34
	v_addc_co_u32_e32 v19, vcc, 0, v19, vcc
	v_cvt_pk_bf16_f32 v0, v0, v1
	v_cvt_pk_bf16_f32 v1, v2, v3
	global_store_dwordx2 v[18:19], v[16:17], off offset:2304
	v_mul_f32_e32 v16, v20, v34
	v_mul_f32_e32 v17, v21, v34
	v_mul_f32_e32 v18, v22, v34
	v_mul_f32_e32 v19, v23, v34
	global_store_dwordx2 v[32:33], v[0:1], off offset:64
	v_mul_f32_e32 v0, v4, v34
	v_mul_f32_e32 v1, v5, v34
	v_mul_f32_e32 v2, v6, v34
	v_mul_f32_e32 v3, v7, v34
	v_cvt_pk_bf16_f32 v16, v16, v17
	v_cvt_pk_bf16_f32 v17, v18, v19
	v_cvt_pk_bf16_f32 v0, v0, v1
	v_cvt_pk_bf16_f32 v1, v2, v3
	global_store_dwordx2 v[32:33], v[16:17], off offset:16
	v_mul_f32_e32 v16, v24, v34
	v_mul_f32_e32 v17, v25, v34
	v_mul_f32_e32 v18, v26, v34
	v_mul_f32_e32 v19, v27, v34
	global_store_dwordx2 v[32:33], v[0:1], off offset:80
	v_mul_f32_e32 v0, v8, v34
	v_mul_f32_e32 v1, v9, v34
	v_mul_f32_e32 v2, v10, v34
	v_mul_f32_e32 v3, v11, v34
	v_cvt_pk_bf16_f32 v16, v16, v17
	v_cvt_pk_bf16_f32 v17, v18, v19
	v_cvt_pk_bf16_f32 v0, v0, v1
	v_cvt_pk_bf16_f32 v1, v2, v3
	global_store_dwordx2 v[32:33], v[16:17], off offset:32
	v_mul_f32_e32 v16, v28, v34
	v_mul_f32_e32 v17, v29, v34
	v_mul_f32_e32 v18, v30, v34
	v_mul_f32_e32 v19, v31, v34
	global_store_dwordx2 v[32:33], v[0:1], off offset:96
	v_mul_f32_e32 v0, v12, v34
	v_mul_f32_e32 v1, v13, v34
	v_mul_f32_e32 v2, v14, v34
	v_mul_f32_e32 v3, v15, v34
	v_cvt_pk_bf16_f32 v16, v16, v17
	v_cvt_pk_bf16_f32 v17, v18, v19
	v_cvt_pk_bf16_f32 v0, v0, v1
	v_cvt_pk_bf16_f32 v1, v2, v3
	s_mov_b64 s[0:1], 0
	global_store_dwordx2 v[32:33], v[16:17], off offset:48
	global_store_dwordx2 v[32:33], v[0:1], off offset:112

.LBB0_1050:
	s_or_b64 exec, exec, s[4:5]
	s_and_b32 s4, s6, 1
	s_mul_i32 s5, s4, 0x3400
	v_add_u32_e32 v122, s5, v118
	ds_read_b128 v[32:35], v122
	ds_read_b128 v[36:39], v122 offset:32
	s_mul_i32 s5, s4, 0x2400
	s_xor_b32 s8, s4, 1
	s_mul_i32 s4, s8, 0x3400
	s_waitcnt lgkmcnt(1)
	v_mfma_f32_32x32x16_bf16 v[48:63], v[32:35], v[84:87], 0
	s_add_i32 s9, s4, 0
	s_waitcnt lgkmcnt(0)
	v_mfma_f32_32x32x16_bf16 v[48:63], v[36:39], v[80:83], v[48:63]
	ds_read_b128 v[32:35], v122 offset:64
	ds_read_b128 v[36:39], v122 offset:96
	s_waitcnt lgkmcnt(1)
	v_mfma_f32_32x32x16_bf16 v[48:63], v[32:35], v[76:79], v[48:63]
	s_waitcnt lgkmcnt(0)
	v_mfma_f32_32x32x16_bf16 v[48:63], v[36:39], v[72:75], v[48:63]
	ds_read_b128 v[32:35], v122 offset:128
	ds_read_b128 v[36:39], v122 offset:160
	s_waitcnt lgkmcnt(1)
	v_mfma_f32_32x32x16_bf16 v[48:63], v[32:35], v[68:71], v[48:63]
	ds_read_b128 v[32:35], v122 offset:6656
	ds_read_b128 v[124:127], v122 offset:6688
	s_waitcnt lgkmcnt(2)
	v_mfma_f32_32x32x16_bf16 v[48:63], v[36:39], v[64:67], v[48:63]
	s_waitcnt lgkmcnt(1)
	v_mfma_f32_32x32x16_bf16 v[32:47], v[32:35], v[84:87], 0
	s_nop 9
	v_max_f32_e32 v128, v48, v48
	s_waitcnt lgkmcnt(0)
	v_mfma_f32_32x32x16_bf16 v[32:47], v[124:127], v[80:83], v[32:47]
	ds_read_b128 v[124:127], v122 offset:6720
	ds_read_b128 v[130:133], v122 offset:6752
	s_waitcnt lgkmcnt(1)
	v_mfma_f32_32x32x16_bf16 v[32:47], v[124:127], v[76:79], v[32:47]
	s_waitcnt lgkmcnt(0)
	v_mfma_f32_32x32x16_bf16 v[32:47], v[130:133], v[72:75], v[32:47]
	ds_read_b128 v[124:127], v122 offset:6784
	ds_read_b128 v[130:133], v122 offset:6816
	v_max_f32_e32 v122, v49, v49
	v_max_f32_e32 v122, v128, v122
	v_max3_f32 v122, v122, v50, v51
	v_max3_f32 v122, v122, v52, v53
	v_max3_f32 v122, v122, v54, v55
	v_max3_f32 v122, v122, v56, v57
	s_waitcnt lgkmcnt(1)
	v_mfma_f32_32x32x16_bf16 v[32:47], v[124:127], v[68:71], v[32:47]
	v_max3_f32 v122, v122, v58, v59
	v_max3_f32 v122, v122, v60, v61
	v_max3_f32 v122, v122, v62, v63
	s_waitcnt lgkmcnt(0)
	v_mfma_f32_32x32x16_bf16 v[32:47], v[130:133], v[64:67], v[32:47]
	s_nop 11
	v_max3_f32 v122, v122, v32, v33
	v_max3_f32 v122, v122, v34, v35
	v_max3_f32 v122, v122, v36, v37
	v_max3_f32 v122, v122, v38, v39
	v_max3_f32 v122, v122, v40, v41
	v_max3_f32 v122, v122, v42, v43
	v_max3_f32 v122, v122, v44, v45
	v_max3_f32 v122, v122, v46, v47
	ds_bpermute_b32 v124, v97, v122
	s_waitcnt lgkmcnt(0)
	v_max3_f32 v122, v123, v122, v124
	v_sub_f32_e32 v32, v32, v122
	v_sub_f32_e32 v128, v123, v122
	v_exp_f32_e32 v123, v32
	v_sub_f32_e32 v32, v33, v122
	v_exp_f32_e32 v124, v32
	v_sub_f32_e32 v32, v34, v122
	v_exp_f32_e32 v125, v32
	v_sub_f32_e32 v32, v35, v122
	v_exp_f32_e32 v126, v32
	v_sub_f32_e32 v32, v36, v122
	v_exp_f32_e32 v127, v32
	v_exp_f32_e32 v36, v128
	v_sub_f32_e32 v32, v37, v122
	v_add_u32_e32 v128, s5, v99
	v_exp_f32_e32 v37, v32
	ds_read_b128 v[32:35], v128 offset:26624
	v_sub_f32_e32 v48, v48, v122
	v_sub_f32_e32 v49, v49, v122
	v_sub_f32_e32 v50, v50, v122
	v_sub_f32_e32 v51, v51, v122
	v_sub_f32_e32 v52, v52, v122
	v_sub_f32_e32 v53, v53, v122
	v_sub_f32_e32 v54, v54, v122
	v_sub_f32_e32 v55, v55, v122
	v_exp_f32_e32 v48, v48
	v_exp_f32_e32 v49, v49
	v_exp_f32_e32 v50, v50
	v_exp_f32_e32 v51, v51
	v_exp_f32_e32 v52, v52
	v_exp_f32_e32 v53, v53
	v_exp_f32_e32 v54, v54
	v_exp_f32_e32 v55, v55
	ds_read_b128 v[134:137], v128 offset:31232
	ds_read_b128 v[138:141], v128 offset:26656
	v_mul_f32_e32 v16, v16, v36
	v_mul_f32_e32 v17, v17, v36
	v_mul_f32_e32 v18, v18, v36
	v_mul_f32_e32 v19, v19, v36
	v_mul_f32_e32 v20, v20, v36
	v_mul_f32_e32 v21, v21, v36
	v_mul_f32_e32 v22, v22, v36
	v_mul_f32_e32 v23, v23, v36
	v_mul_f32_e32 v24, v24, v36
	v_mul_f32_e32 v25, v25, v36
	v_mul_f32_e32 v26, v26, v36
	v_mul_f32_e32 v27, v27, v36
	v_mul_f32_e32 v28, v28, v36
	v_mul_f32_e32 v29, v29, v36
	v_mul_f32_e32 v30, v30, v36
	v_mul_f32_e32 v31, v31, v36
	v_cvt_pk_bf16_f32 v130, v48, v49
	v_cvt_pk_bf16_f32 v131, v50, v51
	v_cvt_pk_bf16_f32 v132, v52, v53
	v_cvt_pk_bf16_f32 v133, v54, v55
	v_mul_f32_e32 v0, v0, v36
	v_mul_f32_e32 v1, v1, v36
	v_mul_f32_e32 v2, v2, v36
	v_mul_f32_e32 v3, v3, v36
	s_waitcnt lgkmcnt(2)
	v_mfma_f32_32x32x16_bf16 v[16:31], v[32:35], v[130:133], v[16:31]
	v_mul_f32_e64 v4, v4, v36
	v_mul_f32_e64 v5, v5, v36
	v_mul_f32_e64 v6, v6, v36
	v_mul_f32_e64 v7, v7, v36
	v_mul_f32_e64 v8, v8, v36
	v_mul_f32_e64 v9, v9, v36
	v_mul_f32_e32 v10, v10, v36
	v_mul_f32_e32 v11, v11, v36
	v_mul_f32_e32 v12, v12, v36
	v_mul_f32_e32 v13, v13, v36
	v_mul_f32_e32 v14, v14, v36
	v_mul_f32_e32 v15, v15, v36
	ds_read_b128 v[32:35], v128 offset:31264
	v_sub_f32_e32 v56, v56, v122
	s_waitcnt lgkmcnt(2)
	v_mfma_f32_32x32x16_bf16 v[0:15], v[134:137], v[130:133], v[0:15]
	v_sub_f32_e32 v57, v57, v122
	v_sub_f32_e32 v58, v58, v122
	v_sub_f32_e32 v59, v59, v122
	v_sub_f32_e32 v60, v60, v122
	v_sub_f32_e32 v61, v61, v122
	v_sub_f32_e32 v62, v62, v122
	v_sub_f32_e32 v63, v63, v122
	v_exp_f32_e32 v56, v56
	v_exp_f32_e32 v57, v57
	v_exp_f32_e32 v58, v58
	v_exp_f32_e32 v59, v59
	v_exp_f32_e32 v60, v60
	v_exp_f32_e32 v61, v61
	v_exp_f32_e32 v62, v62
	v_exp_f32_e32 v63, v63
	v_cvt_pk_bf16_f32 v130, v56, v57
	v_cvt_pk_bf16_f32 v131, v58, v59
	v_cvt_pk_bf16_f32 v132, v60, v61
	v_cvt_pk_bf16_f32 v133, v62, v63
	ds_read_b128 v[134:137], v128 offset:26688
	v_sub_f32_e32 v38, v38, v122
	s_waitcnt lgkmcnt(2)
	v_mfma_f32_32x32x16_bf16 v[16:31], v[138:141], v[130:133], v[16:31]
	v_sub_f32_e32 v39, v39, v122
	v_exp_f32_e32 v38, v38
	v_exp_f32_e32 v39, v39
	v_sub_f32_e32 v40, v40, v122
	v_sub_f32_e32 v41, v41, v122
	v_sub_f32_e32 v42, v42, v122
	v_sub_f32_e32 v43, v43, v122
	s_waitcnt lgkmcnt(1)
	v_mfma_f32_32x32x16_bf16 v[0:15], v[32:35], v[130:133], v[0:15]
	ds_read_b128 v[130:133], v128 offset:31296
	ds_read_b128 v[138:141], v128 offset:26720
	v_cvt_pk_bf16_f32 v32, v123, v124
	v_cvt_pk_bf16_f32 v33, v125, v126
	v_cvt_pk_bf16_f32 v34, v127, v37
	v_cvt_pk_bf16_f32 v35, v38, v39
	v_sub_f32_e32 v44, v44, v122
	v_sub_f32_e32 v45, v45, v122
	s_waitcnt lgkmcnt(2)
	v_mfma_f32_32x32x16_bf16 v[16:31], v[134:137], v[32:35], v[16:31]
	ds_read_b128 v[134:137], v128 offset:31328
	v_sub_f32_e32 v46, v46, v122
	v_exp_f32_e32 v40, v40
	v_exp_f32_e32 v41, v41
	v_exp_f32_e32 v42, v42
	v_exp_f32_e32 v43, v43
	v_exp_f32_e32 v44, v44
	s_waitcnt lgkmcnt(2)
	v_mfma_f32_32x32x16_bf16 v[0:15], v[130:133], v[32:35], v[0:15]
	v_sub_f32_e32 v32, v47, v122
	v_exp_f32_e32 v47, v32
	global_load_dwordx4 v[32:35], v[106:107], off
	v_exp_f32_e32 v45, v45
	v_exp_f32_e32 v46, v46
	v_cvt_pk_bf16_f32 v130, v40, v41
	v_cvt_pk_bf16_f32 v131, v42, v43
	v_cvt_pk_bf16_f32 v132, v44, v45
	v_cvt_pk_bf16_f32 v133, v46, v47
	s_waitcnt lgkmcnt(1)
	s_nop 0
	v_mfma_f32_32x32x16_bf16 v[16:31], v[138:141], v[130:133], v[16:31]
	s_waitcnt lgkmcnt(0)
	v_mfma_f32_32x32x16_bf16 v[0:15], v[134:137], v[130:133], v[0:15]
	s_and_saveexec_b64 s[4:5], s[0:1]
	s_cbranch_execz .LBB0_1052
	v_add3_u32 v128, s9, v119, v120
	s_waitcnt vmcnt(1)
	ds_write_b128 v128, v[88:91]

.LBB0_1054:
	s_or_b64 exec, exec, s[4:5]
	v_add_f32_e32 v48, 0, v48
	v_add_f32_e32 v48, v49, v48
	v_add_f32_e32 v48, v50, v48
	v_add_f32_e32 v48, v51, v48
	v_add_f32_e32 v48, v52, v48
	v_add_f32_e32 v48, v53, v48
	v_add_f32_e32 v48, v54, v48
	v_add_f32_e32 v48, v55, v48
	v_add_f32_e32 v48, v56, v48
	v_add_f32_e32 v48, v57, v48
	v_add_f32_e32 v48, v58, v48
	v_add_f32_e32 v48, v59, v48
	v_add_f32_e32 v48, v60, v48
	v_add_f32_e32 v48, v61, v48
	v_add_f32_e32 v48, v62, v48
	v_add_f32_e32 v48, v63, v48
	v_add_f32_e32 v48, v123, v48
	v_add_f32_e32 v48, v124, v48
	v_add_f32_e32 v48, v125, v48
	v_add_f32_e32 v48, v126, v48
	v_add_f32_e32 v48, v127, v48
	v_add_f32_e32 v37, v37, v48
	v_add_f32_e32 v37, v38, v37
	v_add_f32_e32 v37, v39, v37
	v_add_f32_e32 v37, v40, v37
	v_add_f32_e32 v37, v41, v37
	v_add_f32_e32 v37, v42, v37
	v_add_f32_e32 v37, v43, v37
	v_add_f32_e32 v37, v44, v37
	v_add_f32_e32 v37, v45, v37
	v_add_f32_e32 v37, v46, v37
	v_add_f32_e32 v123, v47, v37
	s_add_i32 s6, s6, 1
	s_mulk_i32 s8, 0x2400
	v_fmac_f32_e32 v123, v121, v36
	v_add_u32_e32 v36, s8, v117
	v_lshl_add_u64 v[102:103], v[102:103], 0, s[2:3]
	v_lshl_add_u64 v[104:105], v[104:105], 0, s[2:3]
	s_cmp_eq_u32 s7, s6
	v_lshl_add_u64 v[106:107], v[106:107], 0, s[34:35]
	s_waitcnt vmcnt(0)
	ds_write_b128 v36, v[32:35] offset:26624
	s_waitcnt lgkmcnt(0)
	s_barrier
	s_cbranch_scc0 .LBB0_1046
	s_and_b32 s0, s7, 1
	s_mul_i32 s1, s0, 0x3400
	v_add_u32_e32 v88, s1, v118
	ds_read_b128 v[32:35], v88
	s_mulk_i32 s0, 0x2400
	s_lshl_b32 s60, s15, 7
	v_lshlrev_b32_e32 v128, 3, v108
	s_waitcnt lgkmcnt(0)
	v_mfma_f32_32x32x16_bf16 v[48:63], v[32:35], v[84:87], 0
	ds_read_b128 v[32:35], v88 offset:32
	s_waitcnt lgkmcnt(0)
	v_mfma_f32_32x32x16_bf16 v[48:63], v[32:35], v[80:83], v[48:63]
	ds_read_b128 v[32:35], v88 offset:64
	s_waitcnt lgkmcnt(0)
	v_mfma_f32_32x32x16_bf16 v[48:63], v[32:35], v[76:79], v[48:63]
	ds_read_b128 v[32:35], v88 offset:96
	s_waitcnt lgkmcnt(0)
	v_mfma_f32_32x32x16_bf16 v[48:63], v[32:35], v[72:75], v[48:63]
	ds_read_b128 v[32:35], v88 offset:128
	s_waitcnt lgkmcnt(0)
	v_mfma_f32_32x32x16_bf16 v[48:63], v[32:35], v[68:71], v[48:63]
	ds_read_b128 v[32:35], v88 offset:160
	s_waitcnt lgkmcnt(0)
	v_mfma_f32_32x32x16_bf16 v[48:63], v[32:35], v[64:67], v[48:63]
	ds_read_b128 v[32:35], v88 offset:6656
	s_waitcnt lgkmcnt(0)
	v_mfma_f32_32x32x16_bf16 v[32:47], v[32:35], v[84:87], 0
	ds_read_b128 v[84:87], v88 offset:6688
	s_waitcnt lgkmcnt(0)
	v_mfma_f32_32x32x16_bf16 v[32:47], v[84:87], v[80:83], v[32:47]
	ds_read_b128 v[80:83], v88 offset:6720
	s_waitcnt lgkmcnt(0)
	v_mfma_f32_32x32x16_bf16 v[32:47], v[80:83], v[76:79], v[32:47]
	ds_read_b128 v[76:79], v88 offset:6752
	s_nop 1
	v_max_f32_e32 v80, v49, v49
	v_max_f32_e32 v81, v48, v48
	v_max_f32_e32 v80, v81, v80
	s_waitcnt lgkmcnt(0)
	v_mfma_f32_32x32x16_bf16 v[32:47], v[76:79], v[72:75], v[32:47]
	ds_read_b128 v[72:75], v88 offset:6784
	ds_read_b128 v[76:79], v88 offset:6816
	s_waitcnt lgkmcnt(1)
	v_mfma_f32_32x32x16_bf16 v[32:47], v[72:75], v[68:71], v[32:47]
	v_max3_f32 v68, v80, v50, v51
	v_max3_f32 v68, v68, v52, v53
	v_max3_f32 v68, v68, v54, v55
	v_max3_f32 v68, v68, v56, v57
	v_max3_f32 v68, v68, v58, v59
	v_max3_f32 v68, v68, v60, v61
	v_max3_f32 v68, v68, v62, v63
	s_waitcnt lgkmcnt(0)
	v_mfma_f32_32x32x16_bf16 v[32:47], v[76:79], v[64:67], v[32:47]
	v_add_u32_e32 v75, s0, v99
	s_nop 10
	v_max3_f32 v64, v68, v32, v33
	v_max3_f32 v64, v64, v34, v35
	v_max3_f32 v64, v64, v36, v37
	v_max3_f32 v64, v64, v38, v39
	v_max3_f32 v64, v64, v40, v41
	v_max3_f32 v64, v64, v42, v43
	v_max3_f32 v64, v64, v44, v45
	v_max3_f32 v64, v64, v46, v47
	ds_bpermute_b32 v65, v97, v64
	s_waitcnt lgkmcnt(0)
	v_max3_f32 v64, v122, v64, v65
	v_sub_f32_e32 v48, v48, v64
	v_exp_f32_e32 v48, v48
	v_sub_f32_e32 v49, v49, v64
	v_exp_f32_e32 v49, v49
	v_sub_f32_e32 v50, v50, v64
	v_exp_f32_e32 v50, v50
	v_sub_f32_e32 v51, v51, v64
	v_exp_f32_e32 v51, v51
	v_sub_f32_e32 v52, v52, v64
	v_add_f32_e32 v66, 0, v48
	v_exp_f32_e32 v52, v52
	v_sub_f32_e32 v53, v53, v64
	v_add_f32_e32 v66, v49, v66
	v_exp_f32_e32 v53, v53
	v_sub_f32_e32 v54, v54, v64
	v_add_f32_e32 v66, v50, v66
	v_exp_f32_e32 v54, v54
	v_sub_f32_e32 v55, v55, v64
	v_add_f32_e32 v66, v51, v66
	v_exp_f32_e32 v55, v55
	v_sub_f32_e32 v56, v56, v64
	v_add_f32_e32 v66, v52, v66
	v_exp_f32_e32 v67, v56
	v_sub_f32_e32 v56, v57, v64
	v_add_f32_e32 v66, v53, v66
	v_exp_f32_e32 v57, v56
	v_sub_f32_e32 v56, v58, v64
	v_add_f32_e32 v66, v54, v66
	v_exp_f32_e32 v58, v56
	v_sub_f32_e32 v56, v59, v64
	v_sub_f32_e32 v32, v32, v64
	v_exp_f32_e32 v59, v56
	v_sub_f32_e32 v56, v60, v64
	v_exp_f32_e32 v68, v32
	v_sub_f32_e32 v32, v33, v64
	v_add_f32_e32 v33, v55, v66
	v_exp_f32_e32 v60, v56
	v_sub_f32_e32 v56, v61, v64
	v_add_f32_e32 v33, v67, v33
	v_exp_f32_e32 v61, v56
	v_sub_f32_e32 v56, v62, v64
	v_add_f32_e32 v33, v57, v33
	v_exp_f32_e32 v62, v56
	v_sub_f32_e32 v56, v63, v64
	v_add_f32_e32 v33, v58, v33
	v_exp_f32_e32 v63, v56
	v_add_f32_e32 v33, v59, v33
	v_add_f32_e32 v33, v60, v33
	v_exp_f32_e32 v69, v32
	v_sub_f32_e32 v32, v34, v64
	v_add_f32_e32 v33, v61, v33
	v_exp_f32_e32 v70, v32
	v_sub_f32_e32 v32, v35, v64
	v_add_f32_e32 v33, v62, v33
	v_add_f32_e32 v33, v63, v33
	v_exp_f32_e32 v66, v32
	v_sub_f32_e32 v32, v36, v64
	v_add_f32_e32 v33, v68, v33
	v_exp_f32_e32 v71, v32
	v_sub_f32_e32 v32, v37, v64
	v_add_f32_e32 v33, v69, v33
	v_exp_f32_e32 v72, v32
	v_sub_f32_e32 v32, v38, v64
	v_add_f32_e32 v33, v70, v33
	v_exp_f32_e32 v73, v32
	v_add_f32_e32 v32, v66, v33
	v_add_f32_e32 v32, v71, v32
	v_add_f32_e32 v32, v72, v32
	v_sub_f32_e32 v65, v122, v64
	v_add_f32_e32 v74, v73, v32
	v_sub_f32_e32 v32, v39, v64
	v_exp_f32_e32 v56, v65
	v_exp_f32_e32 v65, v32
	ds_read_b128 v[32:35], v75 offset:26624
	v_cvt_pk_bf16_f32 v36, v48, v49
	v_cvt_pk_bf16_f32 v37, v50, v51
	v_cvt_pk_bf16_f32 v38, v52, v53
	v_cvt_pk_bf16_f32 v39, v54, v55
	ds_read_b128 v[48:51], v75 offset:31232
	ds_read_b128 v[52:55], v75 offset:26656
	v_mul_f32_e32 v30, v30, v56
	v_mul_f32_e32 v31, v31, v56
	v_mul_f32_e32 v28, v28, v56
	v_mul_f32_e32 v29, v29, v56
	v_mul_f32_e32 v26, v26, v56
	v_mul_f32_e32 v27, v27, v56
	v_mul_f32_e32 v24, v24, v56
	v_mul_f32_e32 v25, v25, v56
	v_mul_f32_e32 v22, v22, v56
	v_mul_f32_e32 v23, v23, v56
	v_mul_f32_e32 v20, v20, v56
	v_mul_f32_e32 v21, v21, v56
	v_mul_f32_e32 v18, v18, v56
	v_mul_f32_e32 v19, v19, v56
	v_mul_f32_e32 v16, v16, v56
	v_mul_f32_e32 v17, v17, v56
	v_mul_f32_e32 v14, v14, v56
	v_mul_f32_e32 v15, v15, v56
	v_mul_f32_e32 v12, v12, v56
	v_mul_f32_e32 v13, v13, v56
	s_waitcnt lgkmcnt(2)
	v_mfma_f32_32x32x16_bf16 v[16:31], v[32:35], v[36:39], v[16:31]
	v_mul_f32_e64 v10, v10, v56
	v_mul_f32_e64 v11, v11, v56
	v_mul_f32_e64 v8, v8, v56
	v_mul_f32_e64 v9, v9, v56
	v_mul_f32_e64 v6, v6, v56
	v_mul_f32_e64 v7, v7, v56
	v_mul_f32_e32 v4, v4, v56
	v_mul_f32_e32 v5, v5, v56
	v_mul_f32_e32 v2, v2, v56
	v_mul_f32_e32 v3, v3, v56
	v_mul_f32_e32 v0, v0, v56
	v_mul_f32_e32 v1, v1, v56
	ds_read_b128 v[32:35], v75 offset:31264
	v_sub_f32_e32 v40, v40, v64
	s_waitcnt lgkmcnt(2)
	v_mfma_f32_32x32x16_bf16 v[0:15], v[48:51], v[36:39], v[0:15]
	v_exp_f32_e32 v76, v40
	v_sub_f32_e32 v36, v41, v64
	v_exp_f32_e32 v77, v36
	v_cvt_pk_bf16_f32 v36, v67, v57
	v_cvt_pk_bf16_f32 v37, v58, v59
	v_cvt_pk_bf16_f32 v38, v60, v61
	v_cvt_pk_bf16_f32 v39, v62, v63
	v_sub_f32_e32 v40, v42, v64
	ds_read_b128 v[48:51], v75 offset:26688
	s_waitcnt lgkmcnt(2)
	v_mfma_f32_32x32x16_bf16 v[16:31], v[52:55], v[36:39], v[16:31]
	v_exp_f32_e32 v52, v40
	v_add_f32_e32 v40, v65, v74
	v_add_f32_e32 v40, v76, v40
	v_add_f32_e32 v40, v77, v40
	v_add_f32_e32 v53, v52, v40
	v_sub_f32_e32 v54, v43, v64
	v_exp_f32_e32 v54, v54
	s_waitcnt lgkmcnt(1)
	v_mfma_f32_32x32x16_bf16 v[0:15], v[32:35], v[36:39], v[0:15]
	ds_read_b128 v[36:39], v75 offset:31296
	ds_read_b128 v[40:43], v75 offset:26720
	v_sub_f32_e32 v44, v44, v64
	v_cvt_pk_bf16_f32 v32, v68, v69
	v_cvt_pk_bf16_f32 v33, v70, v66
	v_cvt_pk_bf16_f32 v34, v71, v72
	v_cvt_pk_bf16_f32 v35, v73, v65
	v_exp_f32_e32 v44, v44
	v_sub_f32_e32 v45, v45, v64
	s_waitcnt lgkmcnt(2)
	v_mfma_f32_32x32x16_bf16 v[16:31], v[48:51], v[32:35], v[16:31]
	v_exp_f32_e32 v45, v45
	v_sub_f32_e32 v46, v46, v64
	ds_read_b128 v[48:51], v75 offset:31328
	s_waitcnt lgkmcnt(0)
	s_barrier
	v_mfma_f32_32x32x16_bf16 v[0:15], v[36:39], v[32:35], v[0:15]
	v_sub_f32_e32 v32, v47, v64
	v_exp_f32_e32 v36, v46
	v_exp_f32_e32 v37, v32
	v_add_f32_e32 v38, v54, v53
	v_add_f32_e32 v38, v44, v38
	v_add_f32_e32 v38, v45, v38
	v_cvt_pk_bf16_f32 v35, v36, v37
	v_add_f32_e32 v36, v36, v38
	v_add_f32_e32 v36, v37, v36
	v_fmac_f32_e32 v36, v123, v56
	ds_bpermute_b32 v37, v97, v36
	v_cvt_pk_bf16_f32 v32, v76, v77
	v_cvt_pk_bf16_f32 v33, v52, v54
	v_cvt_pk_bf16_f32 v34, v44, v45
	s_nop 1
	v_mfma_f32_32x32x16_bf16 v[16:31], v[40:43], v[32:35], v[16:31]
	v_mfma_f32_32x32x16_bf16 v[0:15], v[48:51], v[32:35], v[0:15]
	s_waitcnt lgkmcnt(0)
	v_add_f32_e32 v34, v36, v37
	v_div_scale_f32 v35, s[0:1], v34, v34, 1.0
	v_rcp_f32_e32 v36, v35
	v_lshlrev_b64 v[32:33], 11, v[100:101]
	v_lshl_add_u64 v[32:33], s[66:67], 0, v[32:33]
	v_lshl_add_u64 v[32:33], v[32:33], 0, s[60:61]
	v_fma_f32 v37, -v35, v36, 1.0
	v_fmac_f32_e32 v36, v37, v36
	v_div_scale_f32 v37, vcc, 1.0, v34, 1.0
	v_mul_f32_e32 v38, v37, v36
	v_fma_f32 v39, -v35, v38, v37
	v_fmac_f32_e32 v38, v39, v36
	v_fma_f32 v35, -v35, v38, v37
	v_div_fmas_f32 v35, v35, v36, v38
	v_div_fixup_f32 v34, v35, v34, 1.0
	v_mul_f32_e32 v16, v16, v34
	v_mul_f32_e32 v17, v17, v34
	v_mul_f32_e32 v18, v18, v34
	v_mul_f32_e32 v19, v19, v34
	v_cvt_pk_bf16_f32 v16, v16, v17
	v_cvt_pk_bf16_f32 v17, v18, v19
	v_lshl_add_u64 v[18:19], v[32:33], 0, v[128:129]
	s_mov_b64 s[0:1], 0x2d53d00
	v_lshl_add_u64 v[32:33], v[18:19], 0, s[0:1]
	s_mov_b32 s0, 0x2d53000
	v_add_co_u32_e32 v18, vcc, s0, v18
	v_mul_f32_e32 v0, v0, v34
	v_mul_f32_e32 v1, v1, v34
	v_mul_f32_e32 v2, v2, v34
	v_mul_f32_e32 v3, v3, v34
	v_addc_co_u32_e32 v19, vcc, 0, v19, vcc
	v_cvt_pk_bf16_f32 v0, v0, v1
	v_cvt_pk_bf16_f32 v1, v2, v3
	global_store_dwordx2 v[18:19], v[16:17], off offset:3328
	v_mul_f32_e32 v16, v20, v34
	v_mul_f32_e32 v17, v21, v34
	v_mul_f32_e32 v18, v22, v34
	v_mul_f32_e32 v19, v23, v34
	global_store_dwordx2 v[32:33], v[0:1], off offset:64
	v_mul_f32_e32 v0, v4, v34
	v_mul_f32_e32 v1, v5, v34
	v_mul_f32_e32 v2, v6, v34
	v_mul_f32_e32 v3, v7, v34
	v_cvt_pk_bf16_f32 v16, v16, v17
	v_cvt_pk_bf16_f32 v17, v18, v19
	v_cvt_pk_bf16_f32 v0, v0, v1
	v_cvt_pk_bf16_f32 v1, v2, v3
	global_store_dwordx2 v[32:33], v[16:17], off offset:16
	v_mul_f32_e32 v16, v24, v34
	v_mul_f32_e32 v17, v25, v34
	v_mul_f32_e32 v18, v26, v34
	v_mul_f32_e32 v19, v27, v34
	global_store_dwordx2 v[32:33], v[0:1], off offset:80
	v_mul_f32_e32 v0, v8, v34
	v_mul_f32_e32 v1, v9, v34
	v_mul_f32_e32 v2, v10, v34
	v_mul_f32_e32 v3, v11, v34
	v_cvt_pk_bf16_f32 v16, v16, v17
	v_cvt_pk_bf16_f32 v17, v18, v19
	v_cvt_pk_bf16_f32 v0, v0, v1
	v_cvt_pk_bf16_f32 v1, v2, v3
	global_store_dwordx2 v[32:33], v[16:17], off offset:32
	v_mul_f32_e32 v16, v28, v34
	v_mul_f32_e32 v17, v29, v34
	v_mul_f32_e32 v18, v30, v34
	v_mul_f32_e32 v19, v31, v34
	global_store_dwordx2 v[32:33], v[0:1], off offset:96
	v_mul_f32_e32 v0, v12, v34
	v_mul_f32_e32 v1, v13, v34
	v_mul_f32_e32 v2, v14, v34
	v_mul_f32_e32 v3, v15, v34
	v_cvt_pk_bf16_f32 v16, v16, v17
	v_cvt_pk_bf16_f32 v17, v18, v19
	v_cvt_pk_bf16_f32 v0, v0, v1
	v_cvt_pk_bf16_f32 v1, v2, v3
	global_store_dwordx2 v[32:33], v[16:17], off offset:48
	global_store_dwordx2 v[32:33], v[0:1], off offset:112
	s_branch .LBB0_1079

.LBB0_1069:
	s_or_b64 exec, exec, s[4:5]
	s_and_b32 s4, s6, 1
	s_mul_i32 s5, s4, 0x2400
	v_add_u32_e32 v94, s5, v87
	ds_read_b128 v[32:35], v94
	ds_read_b128 v[90:93], v94 offset:32
	s_xor_b32 s9, s4, 1
	s_mulk_i32 s9, 0x2400
	s_waitcnt lgkmcnt(1)
	v_mfma_f32_32x32x16_bf16 v[48:63], v[32:35], v[68:71], 0
	ds_read_b128 v[32:35], v94 offset:4608
	s_waitcnt lgkmcnt(1)
	v_mfma_f32_32x32x16_bf16 v[48:63], v[90:93], v[64:67], v[48:63]
	ds_read_b128 v[90:93], v94 offset:4640
	s_waitcnt lgkmcnt(1)
	v_mfma_f32_32x32x16_bf16 v[32:47], v[32:35], v[68:71], 0
	s_nop 8
	v_max_f32_e32 v94, v49, v49
	v_max_f32_e32 v95, v48, v48
	v_max_f32_e32 v94, v95, v94
	v_max3_f32 v94, v94, v50, v51
	s_waitcnt lgkmcnt(0)
	v_mfma_f32_32x32x16_bf16 v[32:47], v[90:93], v[64:67], v[32:47]
	v_max3_f32 v90, v94, v52, v53
	v_max3_f32 v90, v90, v54, v55
	v_max3_f32 v90, v90, v56, v57
	v_max3_f32 v90, v90, v58, v59
	v_max3_f32 v90, v90, v60, v61
	v_max3_f32 v90, v90, v62, v63
	s_nop 5
	v_max3_f32 v90, v90, v32, v33
	v_max3_f32 v90, v90, v34, v35
	v_max3_f32 v90, v90, v36, v37
	v_max3_f32 v90, v90, v38, v39
	v_max3_f32 v90, v90, v40, v41
	v_max3_f32 v90, v90, v42, v43
	v_max3_f32 v90, v90, v44, v45
	v_max3_f32 v90, v90, v46, v47
	ds_bpermute_b32 v91, v82, v90
	s_waitcnt lgkmcnt(0)
	v_max3_f32 v90, v86, v90, v91
	v_sub_f32_e32 v32, v32, v90
	v_sub_f32_e32 v95, v86, v90
	v_exp_f32_e32 v86, v32
	v_sub_f32_e32 v32, v33, v90
	v_exp_f32_e32 v91, v32
	v_sub_f32_e32 v32, v34, v90
	v_exp_f32_e32 v92, v32
	v_sub_f32_e32 v32, v35, v90
	v_exp_f32_e32 v93, v32
	v_sub_f32_e32 v32, v36, v90
	v_exp_f32_e32 v94, v32
	v_sub_f32_e32 v32, v37, v90
	v_exp_f32_e32 v37, v32
	global_load_dwordx4 v[32:35], v[80:81], off
	v_exp_f32_e32 v36, v95
	v_add_u32_e32 v95, s5, v84
	ds_read_b128 v[100:103], v95 offset:18432
	ds_read_b128 v[116:119], v95 offset:23040
	v_sub_f32_e32 v48, v48, v90
	v_sub_f32_e32 v49, v49, v90
	v_sub_f32_e32 v50, v50, v90
	v_sub_f32_e32 v51, v51, v90
	v_sub_f32_e32 v52, v52, v90
	v_sub_f32_e32 v53, v53, v90
	v_sub_f32_e32 v54, v54, v90
	v_sub_f32_e32 v55, v55, v90
	v_exp_f32_e32 v48, v48
	v_exp_f32_e32 v49, v49
	v_exp_f32_e32 v50, v50
	v_exp_f32_e32 v51, v51
	v_exp_f32_e32 v52, v52
	v_exp_f32_e32 v53, v53
	v_exp_f32_e32 v54, v54
	v_exp_f32_e32 v55, v55
	v_mul_f32_e32 v0, v0, v36
	v_mul_f32_e32 v1, v1, v36
	v_mul_f32_e32 v2, v2, v36
	v_mul_f32_e32 v3, v3, v36
	v_mul_f32_e32 v4, v4, v36
	v_mul_f32_e32 v5, v5, v36
	v_mul_f32_e32 v6, v6, v36
	v_mul_f32_e32 v7, v7, v36
	v_mul_f32_e32 v8, v8, v36
	v_mul_f32_e32 v9, v9, v36
	v_mul_f32_e32 v10, v10, v36
	v_mul_f32_e32 v11, v11, v36
	v_mul_f32_e32 v12, v12, v36
	v_mul_f32_e32 v13, v13, v36
	v_mul_f32_e32 v14, v14, v36
	v_mul_f32_e32 v15, v15, v36
	v_cvt_pk_bf16_f32 v104, v48, v49
	v_cvt_pk_bf16_f32 v105, v50, v51
	v_cvt_pk_bf16_f32 v106, v52, v53
	v_cvt_pk_bf16_f32 v107, v54, v55
	v_sub_f32_e32 v56, v56, v90
	v_sub_f32_e32 v57, v57, v90
	s_waitcnt lgkmcnt(1)
	v_mfma_f32_32x32x16_bf16 v[0:15], v[100:103], v[104:107], v[0:15]
	ds_read_b128 v[100:103], v95 offset:18464
	v_sub_f32_e32 v58, v58, v90
	v_sub_f32_e32 v59, v59, v90
	v_sub_f32_e32 v60, v60, v90
	v_sub_f32_e32 v61, v61, v90
	v_sub_f32_e32 v62, v62, v90
	v_sub_f32_e32 v63, v63, v90
	v_exp_f32_e32 v56, v56
	v_exp_f32_e32 v57, v57
	v_exp_f32_e32 v58, v58
	v_exp_f32_e32 v59, v59
	v_exp_f32_e32 v60, v60
	v_exp_f32_e32 v61, v61
	v_exp_f32_e32 v62, v62
	v_exp_f32_e32 v63, v63
	v_mul_f32_e32 v16, v16, v36
	v_mul_f32_e32 v17, v17, v36
	v_mul_f32_e32 v18, v18, v36
	v_mul_f32_e32 v19, v19, v36
	v_mul_f32_e32 v20, v20, v36
	v_mul_f32_e32 v21, v21, v36
	v_mul_f32_e32 v22, v22, v36
	v_mul_f32_e32 v23, v23, v36
	v_mul_f32_e32 v24, v24, v36
	v_mul_f32_e32 v25, v25, v36
	v_mul_f32_e32 v26, v26, v36
	v_mul_f32_e32 v27, v27, v36
	v_mul_f32_e32 v28, v28, v36
	v_mul_f32_e32 v29, v29, v36
	v_mul_f32_e32 v30, v30, v36
	v_mul_f32_e32 v31, v31, v36
	v_sub_f32_e32 v38, v38, v90
	v_sub_f32_e32 v39, v39, v90
	s_waitcnt lgkmcnt(1)
	v_mfma_f32_32x32x16_bf16 v[16:31], v[116:119], v[104:107], v[16:31]
	ds_read_b128 v[104:107], v95 offset:23072
	v_cvt_pk_bf16_f32 v116, v56, v57
	v_cvt_pk_bf16_f32 v117, v58, v59
	v_cvt_pk_bf16_f32 v118, v60, v61
	v_cvt_pk_bf16_f32 v119, v62, v63
	v_exp_f32_e32 v38, v38
	v_exp_f32_e32 v39, v39
	s_waitcnt lgkmcnt(1)
	v_mfma_f32_32x32x16_bf16 v[0:15], v[100:103], v[116:119], v[0:15]
	ds_read_b128 v[100:103], v95 offset:18496
	v_sub_f32_e32 v40, v40, v90
	v_sub_f32_e32 v41, v41, v90
	v_sub_f32_e32 v42, v42, v90
	v_sub_f32_e32 v43, v43, v90
	v_sub_f32_e32 v44, v44, v90
	v_sub_f32_e32 v45, v45, v90
	s_waitcnt lgkmcnt(1)
	v_mfma_f32_32x32x16_bf16 v[16:31], v[104:107], v[116:119], v[16:31]
	v_cvt_pk_bf16_f32 v104, v86, v91
	v_cvt_pk_bf16_f32 v105, v92, v93
	v_cvt_pk_bf16_f32 v106, v94, v37
	v_cvt_pk_bf16_f32 v107, v38, v39
	ds_read_b128 v[116:119], v95 offset:23104
	v_sub_f32_e32 v46, v46, v90
	v_sub_f32_e32 v47, v47, v90
	s_waitcnt lgkmcnt(1)
	v_mfma_f32_32x32x16_bf16 v[0:15], v[100:103], v[104:107], v[0:15]
	ds_read_b128 v[100:103], v95 offset:18528
	v_exp_f32_e32 v40, v40
	v_exp_f32_e32 v41, v41
	v_exp_f32_e32 v42, v42
	v_exp_f32_e32 v43, v43
	v_exp_f32_e32 v44, v44
	v_exp_f32_e32 v45, v45
	v_exp_f32_e32 v46, v46
	v_exp_f32_e32 v47, v47
	s_waitcnt lgkmcnt(1)
	v_mfma_f32_32x32x16_bf16 v[16:31], v[116:119], v[104:107], v[16:31]
	v_cvt_pk_bf16_f32 v104, v40, v41
	v_cvt_pk_bf16_f32 v105, v42, v43
	v_cvt_pk_bf16_f32 v106, v44, v45
	v_cvt_pk_bf16_f32 v107, v46, v47
	s_waitcnt lgkmcnt(0)
	s_nop 0
	v_mfma_f32_32x32x16_bf16 v[0:15], v[100:103], v[104:107], v[0:15]
	ds_read_b128 v[100:103], v95 offset:23136
	s_waitcnt lgkmcnt(0)
	v_mfma_f32_32x32x16_bf16 v[16:31], v[100:103], v[104:107], v[16:31]
	s_and_saveexec_b64 s[4:5], s[0:1]
	s_cbranch_execz .LBB0_1071
	v_add_u32_e32 v95, s9, v88
	s_waitcnt vmcnt(1)
	ds_write_b128 v95, v[72:75]
.LBB0_1071:
	s_or_b64 exec, exec, s[4:5]
	v_add_f32_e32 v48, 0, v48
	v_add_f32_e32 v48, v49, v48
	v_add_f32_e32 v48, v50, v48
	v_add_f32_e32 v48, v51, v48
	v_add_f32_e32 v48, v52, v48
	v_add_f32_e32 v48, v53, v48
	v_add_f32_e32 v48, v54, v48
	v_add_f32_e32 v48, v55, v48
	v_add_f32_e32 v48, v56, v48
	v_add_f32_e32 v48, v57, v48
	v_add_f32_e32 v48, v58, v48
	v_add_f32_e32 v48, v59, v48
	v_add_f32_e32 v48, v60, v48
	v_add_f32_e32 v48, v61, v48
	v_add_f32_e32 v48, v62, v48
	v_add_f32_e32 v48, v63, v48
	v_add_f32_e32 v48, v86, v48
	v_add_f32_e32 v48, v91, v48
	v_add_f32_e32 v48, v92, v48
	v_add_f32_e32 v48, v93, v48
	v_add_f32_e32 v48, v94, v48
	v_add_f32_e32 v37, v37, v48
	v_add_f32_e32 v37, v38, v37
	v_add_f32_e32 v37, v39, v37
	v_add_f32_e32 v37, v40, v37
	v_add_f32_e32 v37, v41, v37
	v_add_f32_e32 v37, v42, v37
	v_add_f32_e32 v37, v43, v37
	v_add_f32_e32 v37, v44, v37
	v_add_f32_e32 v37, v45, v37
	v_add_f32_e32 v37, v46, v37
	v_add_f32_e32 v86, v47, v37
	s_add_i32 s6, s6, 1
	v_fmac_f32_e32 v86, v89, v36
	v_add_u32_e32 v36, s9, v85
	v_lshl_add_u64 v[78:79], v[78:79], 0, s[62:63]
	s_cmp_eq_u32 s7, s6
	v_lshl_add_u64 v[80:81], v[80:81], 0, s[34:35]
	s_waitcnt vmcnt(0)
	ds_write_b128 v36, v[32:35] offset:18432
	s_waitcnt lgkmcnt(0)
	s_barrier
	s_cbranch_scc0 .LBB0_1067
	s_bitcmp1_b32 s7, 0
	s_cselect_b32 s0, 0x2400, 0
	v_add_u32_e32 v72, s0, v87
	ds_read_b128 v[32:35], v72
	v_add_u32_e32 v74, s0, v84
	v_cmp_gt_u32_e32 vcc, 32, v112
	s_waitcnt lgkmcnt(0)
	v_mfma_f32_32x32x16_bf16 v[48:63], v[32:35], v[68:71], 0
	ds_read_b128 v[32:35], v72 offset:32
	s_waitcnt lgkmcnt(0)
	v_mfma_f32_32x32x16_bf16 v[48:63], v[32:35], v[64:67], v[48:63]
	ds_read_b128 v[32:35], v72 offset:4608
	s_waitcnt lgkmcnt(0)
	v_mfma_f32_32x32x16_bf16 v[32:47], v[32:35], v[68:71], 0
	ds_read_b128 v[68:71], v72 offset:4640
	s_nop 7
	v_max_f32_e32 v72, v49, v49
	v_max_f32_e32 v73, v48, v48
	v_max_f32_e32 v72, v73, v72
	v_max3_f32 v72, v72, v50, v51
	s_waitcnt lgkmcnt(0)
	v_mfma_f32_32x32x16_bf16 v[32:47], v[68:71], v[64:67], v[32:47]
	v_max3_f32 v64, v72, v52, v53
	v_max3_f32 v64, v64, v54, v55
	v_max3_f32 v64, v64, v56, v57
	v_max3_f32 v64, v64, v58, v59
	v_max3_f32 v64, v64, v60, v61
	v_max3_f32 v64, v64, v62, v63
	s_nop 5
	v_max3_f32 v64, v64, v32, v33
	v_max3_f32 v64, v64, v34, v35
	v_max3_f32 v64, v64, v36, v37
	v_max3_f32 v64, v64, v38, v39
	v_max3_f32 v64, v64, v40, v41
	v_max3_f32 v64, v64, v42, v43
	v_max3_f32 v64, v64, v44, v45
	v_max3_f32 v64, v64, v46, v47
	ds_bpermute_b32 v65, v82, v64
	s_waitcnt lgkmcnt(0)
	v_max3_f32 v64, v90, v64, v65
	v_sub_f32_e32 v48, v48, v64
	v_sub_f32_e32 v49, v49, v64
	v_exp_f32_e32 v48, v48
	v_sub_f32_e32 v50, v50, v64
	v_exp_f32_e32 v49, v49
	v_sub_f32_e32 v51, v51, v64
	v_exp_f32_e32 v50, v50
	v_sub_f32_e32 v52, v52, v64
	v_exp_f32_e32 v51, v51
	v_sub_f32_e32 v53, v53, v64
	v_exp_f32_e32 v52, v52
	v_add_f32_e32 v66, 0, v48
	v_sub_f32_e32 v54, v54, v64
	v_exp_f32_e32 v53, v53
	v_add_f32_e32 v66, v49, v66
	v_sub_f32_e32 v55, v55, v64
	v_exp_f32_e32 v54, v54
	v_add_f32_e32 v66, v50, v66
	v_sub_f32_e32 v56, v56, v64
	v_exp_f32_e32 v55, v55
	v_add_f32_e32 v66, v51, v66
	v_sub_f32_e32 v57, v57, v64
	v_exp_f32_e32 v56, v56
	v_add_f32_e32 v66, v52, v66
	v_sub_f32_e32 v58, v58, v64
	v_exp_f32_e32 v57, v57
	v_add_f32_e32 v66, v53, v66
	v_sub_f32_e32 v59, v59, v64
	v_exp_f32_e32 v58, v58
	v_add_f32_e32 v66, v54, v66
	v_exp_f32_e32 v59, v59
	v_add_f32_e32 v66, v55, v66
	v_sub_f32_e32 v60, v60, v64
	v_add_f32_e32 v66, v56, v66
	v_exp_f32_e32 v60, v60
	v_sub_f32_e32 v61, v61, v64
	v_add_f32_e32 v66, v57, v66
	v_exp_f32_e32 v61, v61
	v_sub_f32_e32 v62, v62, v64
	v_add_f32_e32 v66, v58, v66
	v_exp_f32_e32 v62, v62
	v_sub_f32_e32 v63, v63, v64
	v_add_f32_e32 v66, v59, v66
	v_exp_f32_e32 v63, v63
	v_sub_f32_e32 v32, v32, v64
	v_add_f32_e32 v66, v60, v66
	v_exp_f32_e32 v67, v32
	v_sub_f32_e32 v32, v33, v64
	v_add_f32_e32 v66, v61, v66
	v_exp_f32_e32 v33, v32
	v_sub_f32_e32 v34, v34, v64
	v_add_f32_e32 v32, v62, v66
	v_exp_f32_e32 v66, v34
	v_sub_f32_e32 v34, v35, v64
	v_add_f32_e32 v32, v63, v32
	v_exp_f32_e32 v68, v34
	v_sub_f32_e32 v34, v36, v64
	v_add_f32_e32 v32, v67, v32
	v_exp_f32_e32 v69, v34
	v_sub_f32_e32 v34, v37, v64
	v_add_f32_e32 v32, v33, v32
	v_exp_f32_e32 v70, v34
	v_add_f32_e32 v32, v66, v32
	v_add_f32_e32 v32, v68, v32
	v_add_f32_e32 v32, v69, v32
	v_sub_f32_e32 v65, v90, v64
	v_add_f32_e32 v71, v70, v32
	v_sub_f32_e32 v32, v38, v64
	v_sub_f32_e32 v34, v39, v64
	v_exp_f32_e32 v72, v32
	v_exp_f32_e32 v32, v65
	v_exp_f32_e32 v65, v34
	v_sub_f32_e32 v34, v40, v64
	v_exp_f32_e32 v73, v34
	ds_read_b128 v[34:37], v74 offset:18432
	v_mul_f32_e32 v14, v14, v32
	v_mul_f32_e32 v15, v15, v32
	v_mul_f32_e32 v12, v12, v32
	v_mul_f32_e32 v13, v13, v32
	v_mul_f32_e32 v10, v10, v32
	v_mul_f32_e32 v11, v11, v32
	v_mul_f32_e32 v8, v8, v32
	v_mul_f32_e32 v9, v9, v32
	v_mul_f32_e32 v6, v6, v32
	v_mul_f32_e32 v7, v7, v32
	v_mul_f32_e32 v4, v4, v32
	v_mul_f32_e32 v5, v5, v32
	v_mul_f32_e32 v2, v2, v32
	v_mul_f32_e32 v3, v3, v32
	v_mul_f32_e32 v0, v0, v32
	v_mul_f32_e32 v1, v1, v32
	v_cvt_pk_bf16_f32 v48, v48, v49
	v_cvt_pk_bf16_f32 v49, v50, v51
	v_cvt_pk_bf16_f32 v50, v52, v53
	v_cvt_pk_bf16_f32 v51, v54, v55
	ds_read_b128 v[52:55], v74 offset:23040
	v_mul_f32_e32 v30, v30, v32
	v_mul_f32_e32 v31, v31, v32
	s_waitcnt lgkmcnt(1)
	v_mfma_f32_32x32x16_bf16 v[0:15], v[34:37], v[48:51], v[0:15]
	ds_read_b128 v[34:37], v74 offset:18464
	v_mul_f32_e64 v28, v28, v32
	v_mul_f32_e64 v29, v29, v32
	v_mul_f32_e64 v26, v26, v32
	v_mul_f32_e64 v27, v27, v32
	v_mul_f32_e32 v24, v24, v32
	v_mul_f32_e32 v25, v25, v32
	v_mul_f32_e32 v22, v22, v32
	v_mul_f32_e32 v23, v23, v32
	v_mul_f32_e32 v20, v20, v32
	v_mul_f32_e32 v21, v21, v32
	v_mul_f32_e32 v18, v18, v32
	v_mul_f32_e32 v19, v19, v32
	v_mul_f32_e32 v16, v16, v32
	v_mul_f32_e32 v17, v17, v32
	v_sub_f32_e32 v38, v41, v64
	v_cvt_pk_bf16_f32 v39, v58, v59
	s_waitcnt lgkmcnt(1)
	v_mfma_f32_32x32x16_bf16 v[16:31], v[52:55], v[48:51], v[16:31]
	v_exp_f32_e32 v52, v38
	v_cvt_pk_bf16_f32 v38, v56, v57
	v_cvt_pk_bf16_f32 v40, v60, v61
	v_cvt_pk_bf16_f32 v41, v62, v63
	ds_read_b128 v[48:51], v74 offset:23072
	s_waitcnt lgkmcnt(1)
	v_mfma_f32_32x32x16_bf16 v[0:15], v[34:37], v[38:41], v[0:15]
	v_add_f32_e32 v34, v72, v71
	v_add_f32_e32 v34, v65, v34
	v_add_f32_e32 v34, v73, v34
	v_add_f32_e32 v53, v52, v34
	v_sub_f32_e32 v34, v42, v64
	v_exp_f32_e32 v54, v34
	ds_read_b128 v[34:37], v74 offset:18496
	s_waitcnt lgkmcnt(1)
	v_mfma_f32_32x32x16_bf16 v[16:31], v[48:51], v[38:41], v[16:31]
	ds_read_b128 v[48:51], v74 offset:23104
	v_sub_f32_e32 v38, v43, v64
	v_exp_f32_e32 v55, v38
	v_cvt_pk_bf16_f32 v38, v67, v33
	v_cvt_pk_bf16_f32 v39, v66, v68
	v_cvt_pk_bf16_f32 v40, v69, v70
	v_cvt_pk_bf16_f32 v41, v72, v65
	v_sub_f32_e32 v33, v44, v64
	v_exp_f32_e32 v33, v33
	s_waitcnt lgkmcnt(1)
	v_mfma_f32_32x32x16_bf16 v[0:15], v[34:37], v[38:41], v[0:15]
	v_sub_f32_e32 v34, v45, v64
	v_exp_f32_e32 v56, v34
	v_sub_f32_e32 v34, v46, v64
	v_exp_f32_e32 v46, v34
	ds_read_b128 v[34:37], v74 offset:18528
	ds_read_b128 v[42:45], v74 offset:23136
	s_waitcnt lgkmcnt(0)
	v_mfma_f32_32x32x16_bf16 v[16:31], v[48:51], v[38:41], v[16:31]
	v_sub_f32_e32 v38, v47, v64
	v_exp_f32_e32 v47, v38
	v_cvt_pk_bf16_f32 v38, v73, v52
	v_cvt_pk_bf16_f32 v39, v54, v55
	v_cvt_pk_bf16_f32 v40, v33, v56
	v_cvt_pk_bf16_f32 v41, v46, v47
	s_barrier
	s_nop 0
	v_mfma_f32_32x32x16_bf16 v[0:15], v[34:37], v[38:41], v[0:15]
	v_add_f32_e32 v34, v54, v53
	v_add_f32_e32 v34, v55, v34
	v_add_f32_e32 v33, v33, v34
	v_add_f32_e32 v33, v56, v33
	v_add_f32_e32 v33, v46, v33
	v_add_f32_e32 v34, v47, v33
	v_fmac_f32_e32 v34, v86, v32
	v_mfma_f32_32x32x16_bf16 v[16:31], v[42:45], v[38:41], v[16:31]
	ds_bpermute_b32 v35, v82, v34
	v_mov_b32_e32 v32, 0
	v_mov_b32_e32 v33, 0
	s_and_saveexec_b64 s[0:1], vcc
	s_cbranch_execz .LBB0_1074
	v_or_b32_e32 v128, s27, v112
	v_readlane_b32 s36, v250, 21
	v_lshlrev_b64 v[32:33], 2, v[128:129]
	v_readlane_b32 s40, v250, 25
	v_readlane_b32 s41, v250, 26
	v_readlane_b32 s42, v250, 27
	v_readlane_b32 s43, v250, 28
	v_readlane_b32 s44, v250, 29
	v_readlane_b32 s45, v250, 30
	v_readlane_b32 s46, v250, 31
	v_readlane_b32 s47, v250, 32
	v_lshl_add_u64 v[36:37], s[40:41], 0, v[32:33]
	v_lshl_add_u64 v[38:39], s[42:43], 0, v[32:33]
	v_lshl_add_u64 v[40:41], s[44:45], 0, v[32:33]
	v_lshl_add_u64 v[32:33], s[46:47], 0, v[32:33]
	global_load_dword v37, v[36:37], off
	v_readlane_b32 s37, v250, 22
	global_load_dword v39, v[38:39], off
	v_readlane_b32 s38, v250, 23
	global_load_dword v36, v[40:41], off
	global_load_dword v38, v[32:33], off
	v_readlane_b32 s39, v250, 24
	v_readlane_b32 s48, v250, 33
	v_readlane_b32 s49, v250, 34
	v_readlane_b32 s50, v250, 35
	v_readlane_b32 s51, v250, 36
	s_waitcnt vmcnt(0)
	v_pk_mul_f32 v[32:33], v[36:37], v[38:39]

.LBB0_1076:
	s_or_b64 exec, exec, s[4:5]
	s_waitcnt lgkmcnt(0)
	s_barrier
	s_and_saveexec_b64 s[4:5], s[0:1]
	s_cbranch_execz .LBB0_1078
	v_div_scale_f32 v35, s[0:1], v33, v33, 1.0
	v_rcp_f32_e32 v36, v35
	v_div_scale_f32 v37, vcc, 1.0, v33, 1.0
	s_movk_i32 s0, 0x210
	v_fma_f32 v38, -v35, v36, 1.0
	v_fmac_f32_e32 v36, v38, v36
	v_mul_f32_e32 v38, v37, v36
	v_fma_f32 v39, -v35, v38, v37
	v_fmac_f32_e32 v38, v39, v36
	v_fma_f32 v35, -v35, v38, v37
	v_div_fmas_f32 v35, v35, v36, v38
	v_div_fixup_f32 v38, v35, v33, 1.0
	v_lshl_add_u32 v33, v162, 2, v34
	v_mad_u32_u24 v37, v108, s0, v33
	v_add_u32_e32 v34, 0x400, v37
	ds_read2_b32 v[40:41], v37 offset1:33
	ds_read2_b32 v[42:43], v37 offset0:66 offset1:99
	ds_read2_b32 v[44:45], v34 offset0:8 offset1:41
	ds_read2_b32 v[46:47], v34 offset0:74 offset1:107
	v_add_u32_e32 v34, 0x800, v37
	ds_read2_b32 v[48:49], v34 offset0:16 offset1:49
	ds_read2_b32 v[50:51], v34 offset0:82 offset1:115
	v_add_u32_e32 v34, 0xc00, v37
	ds_read2_b32 v[52:53], v34 offset0:24 offset1:57
	ds_read2_b32 v[54:55], v34 offset0:90 offset1:123
	v_lshl_or_b32 v34, v108, 2, 32
	s_movk_i32 s0, 0x84
	v_mad_u32_u24 v33, v34, s0, v33
	v_add_u32_e32 v34, 0x1000, v37
	ds_read2_b32 v[56:57], v34 offset0:65 offset1:98
	v_add_u32_e32 v34, 0x1200, v37
	ds_read2_b32 v[58:59], v34 offset0:3 offset1:168
	v_add_u32_e32 v34, 0x1400, v37
	ds_read2_b32 v[60:61], v34 offset0:73 offset1:106
	v_add_u32_e32 v34, 0x1600, v37
	ds_read2_b32 v[62:63], v34 offset0:11 offset1:176
	v_add_u32_e32 v34, 0x1a00, v37
	ds_read2_b32 v[64:65], v34 offset0:19 offset1:184
	v_add_u32_e32 v34, 0x1c00, v37
	v_add_u32_e32 v36, 0x1800, v37
	ds_read2_b32 v[34:35], v34 offset0:89 offset1:122
	ds_read2_b32 v[66:67], v36 offset0:81 offset1:114
	v_readlane_b32 s6, v254, 29
	s_waitcnt lgkmcnt(2)
	v_mov_b32_e32 v36, v65
	ds_read_b32 v68, v33
	ds_read_b32 v71, v37 offset:7788
	s_waitcnt lgkmcnt(3)
	v_mov_b32_e32 v37, v34
	v_readlane_b32 s7, v254, 30
	v_pk_fma_f32 v[28:29], v[28:29], v[38:39], v[36:37] op_sel_hi:[1,0,1] neg_lo:[0,0,1] neg_hi:[0,0,1]
	v_mov_b32_e32 v70, v35
	v_pk_fma_f32 v[0:1], v[0:1], v[38:39], v[40:41] op_sel_hi:[1,0,1] neg_lo:[0,0,1] neg_hi:[0,0,1]
	v_pk_fma_f32 v[2:3], v[2:3], v[38:39], v[42:43] op_sel_hi:[1,0,1] neg_lo:[0,0,1] neg_hi:[0,0,1]
	v_pk_mul_f32 v[40:41], v[0:1], v[0:1]
	global_load_dwordx4 v[34:37], v96, s[6:7]
	v_pk_mul_f32 v[42:43], v[2:3], v[2:3]
	v_add_f32_e32 v33, v40, v41
	v_pk_fma_f32 v[4:5], v[4:5], v[38:39], v[44:45] op_sel_hi:[1,0,1] neg_lo:[0,0,1] neg_hi:[0,0,1]
	v_add_f32_e32 v33, v33, v42
	v_pk_mul_f32 v[44:45], v[4:5], v[4:5]
	v_add_f32_e32 v33, v33, v43
	v_pk_fma_f32 v[6:7], v[6:7], v[38:39], v[46:47] op_sel_hi:[1,0,1] neg_lo:[0,0,1] neg_hi:[0,0,1]
	v_add_f32_e32 v33, v33, v44
	v_pk_mul_f32 v[46:47], v[6:7], v[6:7]
	v_add_f32_e32 v33, v33, v45
	v_pk_fma_f32 v[8:9], v[8:9], v[38:39], v[48:49] op_sel_hi:[1,0,1] neg_lo:[0,0,1] neg_hi:[0,0,1]
	v_add_f32_e32 v33, v33, v46
	v_pk_mul_f32 v[48:49], v[8:9], v[8:9]
	v_add_f32_e32 v33, v33, v47
	v_pk_fma_f32 v[10:11], v[10:11], v[38:39], v[50:51] op_sel_hi:[1,0,1] neg_lo:[0,0,1] neg_hi:[0,0,1]
	v_add_f32_e32 v33, v33, v48
	v_pk_mul_f32 v[50:51], v[10:11], v[10:11]
	v_add_f32_e32 v33, v33, v49
	v_pk_fma_f32 v[12:13], v[12:13], v[38:39], v[52:53] op_sel_hi:[1,0,1] neg_lo:[0,0,1] neg_hi:[0,0,1]
	v_add_f32_e32 v33, v33, v50
	v_pk_mul_f32 v[52:53], v[12:13], v[12:13]
	v_add_f32_e32 v33, v33, v51
	v_pk_fma_f32 v[14:15], v[14:15], v[38:39], v[54:55] op_sel_hi:[1,0,1] neg_lo:[0,0,1] neg_hi:[0,0,1]
	v_add_f32_e32 v33, v33, v52
	v_pk_mul_f32 v[54:55], v[14:15], v[14:15]
	v_mov_b32_e32 v69, v56
	v_add_f32_e32 v33, v33, v53
	s_waitcnt lgkmcnt(1)
	v_pk_fma_f32 v[16:17], v[16:17], v[38:39], v[68:69] op_sel_hi:[1,0,1] neg_lo:[0,0,1] neg_hi:[0,0,1]
	v_add_f32_e32 v33, v33, v54
	v_mov_b32_e32 v74, v57
	v_mov_b32_e32 v75, v58
	v_pk_mul_f32 v[56:57], v[16:17], v[16:17]
	v_add_f32_e32 v33, v33, v55
	v_pk_fma_f32 v[18:19], v[18:19], v[38:39], v[74:75] op_sel_hi:[1,0,1] neg_lo:[0,0,1] neg_hi:[0,0,1]
	v_add_f32_e32 v33, v33, v56
	v_pk_mul_f32 v[74:75], v[18:19], v[18:19]
	v_mov_b32_e32 v58, v59
	v_mov_b32_e32 v59, v60
	v_add_f32_e32 v33, v33, v57
	v_pk_fma_f32 v[20:21], v[20:21], v[38:39], v[58:59] op_sel_hi:[1,0,1] neg_lo:[0,0,1] neg_hi:[0,0,1]
	v_add_f32_e32 v33, v33, v74
	v_mov_b32_e32 v68, v61
	v_mov_b32_e32 v69, v62
	v_pk_mul_f32 v[58:59], v[20:21], v[20:21]
	v_add_f32_e32 v33, v33, v75
	v_pk_fma_f32 v[22:23], v[22:23], v[38:39], v[68:69] op_sel_hi:[1,0,1] neg_lo:[0,0,1] neg_hi:[0,0,1]
	v_add_f32_e32 v33, v33, v58
	v_pk_mul_f32 v[68:69], v[22:23], v[22:23]
	v_mov_b32_e32 v62, v63
	v_mov_b32_e32 v63, v66
	v_add_f32_e32 v33, v33, v59
	v_mov_b32_e32 v60, v67
	v_mov_b32_e32 v61, v64
	v_pk_fma_f32 v[24:25], v[24:25], v[38:39], v[62:63] op_sel_hi:[1,0,1] neg_lo:[0,0,1] neg_hi:[0,0,1]
	v_add_f32_e32 v33, v33, v68
	s_waitcnt lgkmcnt(0)
	v_pk_fma_f32 v[30:31], v[30:31], v[38:39], v[70:71] op_sel_hi:[1,0,1] neg_lo:[0,0,1] neg_hi:[0,0,1]
	v_pk_fma_f32 v[26:27], v[26:27], v[38:39], v[60:61] op_sel_hi:[1,0,1] neg_lo:[0,0,1] neg_hi:[0,0,1]
	v_pk_mul_f32 v[38:39], v[24:25], v[24:25]
	v_add_f32_e32 v33, v33, v69
	v_add_f32_e32 v33, v33, v38
	v_pk_mul_f32 v[60:61], v[26:27], v[26:27]
	v_add_f32_e32 v33, v33, v39
	v_add_f32_e32 v33, v33, v60
	v_pk_mul_f32 v[72:73], v[28:29], v[28:29]
	v_add_f32_e32 v33, v33, v61
	v_add_f32_e32 v33, v33, v72
	v_pk_mul_f32 v[70:71], v[30:31], v[30:31]
	v_add_f32_e32 v33, v33, v73
	v_add_f32_e32 v33, v33, v70
	v_add_f32_e32 v38, v33, v71
	ds_bpermute_b32 v39, v82, v38
	s_mov_b32 s0, 0x800000
	v_sub_f32_e32 v40, 1.0, v32
	v_lshlrev_b64 v[32:33], 11, v[76:77]
	v_lshl_add_u64 v[32:33], s[66:67], 0, v[32:33]
	s_waitcnt lgkmcnt(0)
	v_add_f32_e32 v38, v38, v39
	v_fmamk_f32 v38, v38, 0x3c800000, v225
	v_mul_f32_e32 v39, 0x4b800000, v38
	v_cmp_gt_f32_e32 vcc, s0, v38
	s_lshl_b32 s60, s8, 1
	v_lshl_add_u64 v[32:33], v[32:33], 0, s[60:61]
	v_cndmask_b32_e32 v38, v38, v39, vcc
	v_rsq_f32_e32 v38, v38
	v_lshlrev_b32_e32 v128, 3, v108
	v_lshl_add_u64 v[32:33], v[32:33], 0, v[128:129]
	s_mov_b32 s0, 0x2d53000
	v_mul_f32_e32 v39, 0x45800000, v38
	v_cndmask_b32_e32 v38, v38, v39, vcc
	v_mul_f32_e32 v38, v40, v38
	v_mul_f32_e32 v0, v0, v38
	v_mul_f32_e32 v1, v1, v38
	v_mul_f32_e32 v2, v2, v38
	v_mul_f32_e32 v3, v3, v38
	s_waitcnt vmcnt(0)
	v_pk_mul_f32 v[0:1], v[34:35], v[0:1]
	v_pk_mul_f32 v[2:3], v[36:37], v[2:3]
	v_cvt_pk_bf16_f32 v0, v0, v1
	v_cvt_pk_bf16_f32 v1, v2, v3
	v_add_co_u32_e32 v2, vcc, s0, v32
	v_mul_f32_e32 v4, v4, v38
	v_mul_f32_e32 v5, v5, v38
	s_nop 0
	v_addc_co_u32_e32 v3, vcc, 0, v33, vcc
	global_store_dwordx2 v[2:3], v[0:1], off offset:1792
	global_load_dwordx4 v[0:3], v96, s[6:7] offset:32
	v_mul_f32_e32 v6, v6, v38
	v_mul_f32_e32 v7, v7, v38
	s_mov_b64 s[0:1], 0x2d53700
	v_lshl_add_u64 v[32:33], v[32:33], 0, s[0:1]
	s_waitcnt vmcnt(0)
	v_pk_mul_f32 v[0:1], v[0:1], v[4:5]
	v_pk_mul_f32 v[2:3], v[2:3], v[6:7]
	v_cvt_pk_bf16_f32 v0, v0, v1
	v_cvt_pk_bf16_f32 v1, v2, v3
	global_store_dwordx2 v[32:33], v[0:1], off offset:16
	global_load_dwordx4 v[0:3], v96, s[6:7] offset:64
	v_mul_f32_e32 v4, v8, v38
	v_mul_f32_e32 v5, v9, v38
	v_mul_f32_e32 v6, v10, v38
	v_mul_f32_e32 v7, v11, v38
	s_waitcnt vmcnt(0)
	v_pk_mul_f32 v[0:1], v[0:1], v[4:5]
	v_pk_mul_f32 v[2:3], v[2:3], v[6:7]
	v_cvt_pk_bf16_f32 v0, v0, v1
	v_cvt_pk_bf16_f32 v1, v2, v3
	global_store_dwordx2 v[32:33], v[0:1], off offset:32
	global_load_dwordx4 v[0:3], v96, s[6:7] offset:96
	v_mul_f32_e32 v4, v12, v38
	v_mul_f32_e32 v5, v13, v38
	v_mul_f32_e32 v6, v14, v38
	v_mul_f32_e32 v7, v15, v38
	s_waitcnt vmcnt(0)
	v_pk_mul_f32 v[0:1], v[0:1], v[4:5]
	v_pk_mul_f32 v[2:3], v[2:3], v[6:7]
	v_cvt_pk_bf16_f32 v0, v0, v1
	v_cvt_pk_bf16_f32 v1, v2, v3
	global_store_dwordx2 v[32:33], v[0:1], off offset:48
	global_load_dwordx4 v[0:3], v96, s[6:7] offset:128
	v_mul_f32_e32 v4, v16, v38
	v_mul_f32_e32 v5, v17, v38
	v_mul_f32_e32 v6, v18, v38
	v_mul_f32_e32 v7, v19, v38
	s_waitcnt vmcnt(0)
	v_pk_mul_f32 v[0:1], v[0:1], v[4:5]
	v_pk_mul_f32 v[2:3], v[2:3], v[6:7]
	v_cvt_pk_bf16_f32 v0, v0, v1
	v_cvt_pk_bf16_f32 v1, v2, v3
	global_store_dwordx2 v[32:33], v[0:1], off offset:64
	global_load_dwordx4 v[0:3], v96, s[6:7] offset:160
	v_mul_f32_e32 v4, v20, v38
	v_mul_f32_e32 v5, v21, v38
	v_mul_f32_e32 v6, v22, v38
	v_mul_f32_e32 v7, v23, v38
	s_waitcnt vmcnt(0)
	v_pk_mul_f32 v[0:1], v[0:1], v[4:5]
	v_pk_mul_f32 v[2:3], v[2:3], v[6:7]
	v_cvt_pk_bf16_f32 v0, v0, v1
	v_cvt_pk_bf16_f32 v1, v2, v3
	global_store_dwordx2 v[32:33], v[0:1], off offset:80
	global_load_dwordx4 v[0:3], v96, s[6:7] offset:192
	v_mul_f32_e32 v4, v24, v38
	v_mul_f32_e32 v5, v25, v38
	v_mul_f32_e32 v6, v26, v38
	v_mul_f32_e32 v7, v27, v38
	s_waitcnt vmcnt(0)
	v_pk_mul_f32 v[0:1], v[4:5], v[0:1]
	v_pk_mul_f32 v[2:3], v[6:7], v[2:3]
	v_cvt_pk_bf16_f32 v0, v0, v1
	v_cvt_pk_bf16_f32 v1, v2, v3
	global_store_dwordx2 v[32:33], v[0:1], off offset:96
	global_load_dwordx4 v[0:3], v96, s[6:7] offset:224
	v_mul_f32_e32 v4, v28, v38
	v_mul_f32_e32 v5, v29, v38
	v_mul_f32_e32 v6, v30, v38
	v_mul_f32_e32 v7, v31, v38
	s_waitcnt vmcnt(0)
	v_pk_mul_f32 v[0:1], v[4:5], v[0:1]
	v_pk_mul_f32 v[2:3], v[6:7], v[2:3]
	v_cvt_pk_bf16_f32 v0, v0, v1
	v_cvt_pk_bf16_f32 v1, v2, v3
	global_store_dwordx2 v[32:33], v[0:1], off offset:112

.LBB0_1096:
	s_or_b64 exec, exec, s[4:5]
	s_and_b32 s4, s6, 1
	s_mul_i32 s5, s4, 0x3400
	v_add_u32_e32 v124, s5, v119
	ds_read_b128 v[32:35], v124
	ds_read_b128 v[130:133], v124 offset:6688
	s_mul_i32 s5, s4, 0x2400
	s_xor_b32 s7, s4, 1
	s_mul_i32 s4, s7, 0x3400
	s_add_i32 s8, s4, 0
	s_waitcnt lgkmcnt(1)
	v_mfma_f32_32x32x16_bf16 v[48:63], v[32:35], v[84:87], 0
	ds_read_b128 v[32:35], v124 offset:32
	s_waitcnt lgkmcnt(0)
	v_mfma_f32_32x32x16_bf16 v[48:63], v[32:35], v[80:83], v[48:63]
	ds_read_b128 v[32:35], v124 offset:64
	s_waitcnt lgkmcnt(0)
	v_mfma_f32_32x32x16_bf16 v[48:63], v[32:35], v[76:79], v[48:63]
	ds_read_b128 v[32:35], v124 offset:96
	s_waitcnt lgkmcnt(0)
	v_mfma_f32_32x32x16_bf16 v[48:63], v[32:35], v[72:75], v[48:63]
	ds_read_b128 v[32:35], v124 offset:128
	s_waitcnt lgkmcnt(0)
	v_mfma_f32_32x32x16_bf16 v[48:63], v[32:35], v[68:71], v[48:63]
	ds_read_b128 v[32:35], v124 offset:160
	s_waitcnt lgkmcnt(0)
	v_mfma_f32_32x32x16_bf16 v[48:63], v[32:35], v[64:67], v[48:63]
	ds_read_b128 v[32:35], v124 offset:6656
	s_waitcnt lgkmcnt(0)
	v_mfma_f32_32x32x16_bf16 v[32:47], v[32:35], v[84:87], 0
	s_nop 8
	v_max_f32_e32 v126, v48, v48
	v_mfma_f32_32x32x16_bf16 v[32:47], v[130:133], v[80:83], v[32:47]
	ds_read_b128 v[130:133], v124 offset:6720
	s_waitcnt lgkmcnt(0)
	v_mfma_f32_32x32x16_bf16 v[32:47], v[130:133], v[76:79], v[32:47]
	ds_read_b128 v[130:133], v124 offset:6752
	s_waitcnt lgkmcnt(0)
	v_mfma_f32_32x32x16_bf16 v[32:47], v[130:133], v[72:75], v[32:47]
	ds_read_b128 v[130:133], v124 offset:6784
	ds_read_b128 v[134:137], v124 offset:6816
	v_max_f32_e32 v124, v49, v49
	v_max_f32_e32 v124, v126, v124
	v_max3_f32 v124, v124, v50, v51
	v_max3_f32 v124, v124, v52, v53
	v_max3_f32 v124, v124, v54, v55
	v_max3_f32 v124, v124, v56, v57
	s_waitcnt lgkmcnt(1)
	v_mfma_f32_32x32x16_bf16 v[32:47], v[130:133], v[68:71], v[32:47]
	v_max3_f32 v124, v124, v58, v59
	v_max3_f32 v124, v124, v60, v61
	v_max3_f32 v124, v124, v62, v63
	v_lshl_add_u64 v[130:131], s[60:61], 1, v[102:103]
	s_waitcnt lgkmcnt(0)
	v_mfma_f32_32x32x16_bf16 v[32:47], v[134:137], v[64:67], v[32:47]
	s_nop 11
	v_max3_f32 v124, v124, v32, v33
	v_max3_f32 v124, v124, v34, v35
	v_max3_f32 v124, v124, v36, v37
	v_max3_f32 v124, v124, v38, v39
	v_max3_f32 v124, v124, v40, v41
	v_max3_f32 v124, v124, v42, v43
	v_max3_f32 v124, v124, v44, v45
	v_max3_f32 v124, v124, v46, v47
	ds_bpermute_b32 v126, v97, v124
	s_waitcnt lgkmcnt(0)
	v_max3_f32 v124, v125, v124, v126
	v_sub_f32_e32 v32, v32, v124
	v_sub_f32_e32 v133, v125, v124
	v_exp_f32_e32 v125, v32
	v_sub_f32_e32 v32, v33, v124
	v_exp_f32_e32 v126, v32
	v_sub_f32_e32 v32, v34, v124
	v_exp_f32_e32 v127, v32
	v_sub_f32_e32 v32, v35, v124
	v_exp_f32_e32 v128, v32
	v_sub_f32_e32 v32, v36, v124
	v_exp_f32_e32 v132, v32
	v_sub_f32_e32 v32, v37, v124
	v_exp_f32_e32 v37, v32
	global_load_dwordx4 v[32:35], v[130:131], off
	v_add_u32_e32 v130, s5, v99
	ds_read_b128 v[134:137], v130 offset:26624
	ds_read_b128 v[142:145], v130 offset:31232
	v_sub_f32_e32 v48, v48, v124
	v_sub_f32_e32 v49, v49, v124
	v_sub_f32_e32 v50, v50, v124
	v_sub_f32_e32 v51, v51, v124
	v_sub_f32_e32 v52, v52, v124
	v_sub_f32_e32 v53, v53, v124
	v_sub_f32_e32 v54, v54, v124
	v_sub_f32_e32 v55, v55, v124
	v_exp_f32_e32 v48, v48
	v_exp_f32_e32 v49, v49
	v_exp_f32_e32 v50, v50
	v_exp_f32_e32 v51, v51
	v_exp_f32_e32 v52, v52
	v_exp_f32_e32 v53, v53
	v_exp_f32_e32 v54, v54
	v_exp_f32_e32 v55, v55
	v_exp_f32_e32 v36, v133
	v_cvt_pk_bf16_f32 v138, v48, v49
	v_cvt_pk_bf16_f32 v139, v50, v51
	v_cvt_pk_bf16_f32 v140, v52, v53
	v_mul_f32_e32 v16, v16, v36
	v_mul_f32_e32 v17, v17, v36
	v_mul_f32_e32 v18, v18, v36
	v_mul_f32_e32 v19, v19, v36
	v_mul_f32_e32 v20, v20, v36
	v_mul_f32_e32 v21, v21, v36
	v_mul_f32_e32 v22, v22, v36
	v_mul_f32_e32 v23, v23, v36
	v_mul_f32_e32 v24, v24, v36
	v_mul_f32_e32 v25, v25, v36
	v_mul_f32_e32 v26, v26, v36
	v_mul_f32_e32 v27, v27, v36
	v_mul_f32_e32 v28, v28, v36
	v_mul_f32_e32 v29, v29, v36
	v_mul_f32_e32 v30, v30, v36
	v_mul_f32_e32 v31, v31, v36
	v_cvt_pk_bf16_f32 v141, v54, v55
	v_sub_f32_e32 v56, v56, v124
	v_sub_f32_e32 v57, v57, v124
	s_waitcnt lgkmcnt(1)
	v_mfma_f32_32x32x16_bf16 v[16:31], v[134:137], v[138:141], v[16:31]
	ds_read_b128 v[134:137], v130 offset:26656
	v_sub_f32_e32 v58, v58, v124
	v_sub_f32_e32 v59, v59, v124
	v_sub_f32_e32 v60, v60, v124
	v_sub_f32_e32 v61, v61, v124
	v_sub_f32_e32 v62, v62, v124
	v_sub_f32_e32 v63, v63, v124
	v_exp_f32_e32 v56, v56
	v_exp_f32_e32 v57, v57
	v_exp_f32_e32 v58, v58
	v_exp_f32_e32 v59, v59
	v_exp_f32_e32 v60, v60
	v_exp_f32_e32 v61, v61
	v_exp_f32_e32 v62, v62
	v_exp_f32_e32 v63, v63
	v_mul_f32_e32 v0, v0, v36
	v_mul_f32_e32 v1, v1, v36
	v_mul_f32_e32 v2, v2, v36
	v_mul_f32_e32 v3, v3, v36
	v_mul_f32_e32 v4, v4, v36
	v_mul_f32_e32 v5, v5, v36
	v_mul_f32_e32 v6, v6, v36
	v_mul_f32_e32 v7, v7, v36
	v_mul_f32_e32 v8, v8, v36
	v_mul_f32_e32 v9, v9, v36
	v_mul_f32_e32 v10, v10, v36
	v_mul_f32_e32 v11, v11, v36
	v_mul_f32_e32 v12, v12, v36
	v_mul_f32_e32 v13, v13, v36
	v_mul_f32_e32 v14, v14, v36
	v_mul_f32_e32 v15, v15, v36
	v_sub_f32_e32 v38, v38, v124
	v_sub_f32_e32 v39, v39, v124
	s_waitcnt lgkmcnt(1)
	v_mfma_f32_32x32x16_bf16 v[0:15], v[142:145], v[138:141], v[0:15]
	ds_read_b128 v[138:141], v130 offset:31264
	v_cvt_pk_bf16_f32 v142, v56, v57
	v_cvt_pk_bf16_f32 v143, v58, v59
	v_cvt_pk_bf16_f32 v144, v60, v61
	v_cvt_pk_bf16_f32 v145, v62, v63
	v_exp_f32_e32 v38, v38
	v_exp_f32_e32 v39, v39
	s_waitcnt lgkmcnt(1)
	v_mfma_f32_32x32x16_bf16 v[16:31], v[134:137], v[142:145], v[16:31]
	ds_read_b128 v[134:137], v130 offset:26688
	v_sub_f32_e32 v40, v40, v124
	v_sub_f32_e32 v41, v41, v124
	v_sub_f32_e32 v42, v42, v124
	v_sub_f32_e32 v43, v43, v124
	v_sub_f32_e32 v44, v44, v124
	v_sub_f32_e32 v45, v45, v124
	s_waitcnt lgkmcnt(1)
	v_mfma_f32_32x32x16_bf16 v[0:15], v[138:141], v[142:145], v[0:15]
	v_cvt_pk_bf16_f32 v138, v125, v126
	v_cvt_pk_bf16_f32 v139, v127, v128
	v_cvt_pk_bf16_f32 v140, v132, v37
	v_cvt_pk_bf16_f32 v141, v38, v39
	ds_read_b128 v[142:145], v130 offset:31296
	v_sub_f32_e32 v46, v46, v124
	v_sub_f32_e32 v47, v47, v124
	s_waitcnt lgkmcnt(1)
	v_mfma_f32_32x32x16_bf16 v[16:31], v[134:137], v[138:141], v[16:31]
	ds_read_b128 v[134:137], v130 offset:26720
	v_exp_f32_e32 v40, v40
	v_exp_f32_e32 v41, v41
	v_exp_f32_e32 v42, v42
	v_exp_f32_e32 v43, v43
	v_exp_f32_e32 v44, v44
	v_exp_f32_e32 v45, v45
	v_exp_f32_e32 v46, v46
	v_exp_f32_e32 v47, v47
	s_waitcnt lgkmcnt(1)
	v_mfma_f32_32x32x16_bf16 v[0:15], v[142:145], v[138:141], v[0:15]
	v_cvt_pk_bf16_f32 v138, v40, v41
	v_cvt_pk_bf16_f32 v139, v42, v43
	v_cvt_pk_bf16_f32 v140, v44, v45
	v_cvt_pk_bf16_f32 v141, v46, v47
	s_waitcnt lgkmcnt(0)
	s_nop 0
	v_mfma_f32_32x32x16_bf16 v[16:31], v[134:137], v[138:141], v[16:31]
	ds_read_b128 v[134:137], v130 offset:31328
	s_waitcnt lgkmcnt(0)
	v_mfma_f32_32x32x16_bf16 v[0:15], v[134:137], v[138:141], v[0:15]
	s_and_saveexec_b64 s[4:5], s[0:1]
	s_cbranch_execz .LBB0_1098
	v_add3_u32 v130, s8, v121, v122
	s_waitcnt vmcnt(1)
	ds_write_b128 v130, v[88:91]

.LBB0_1100:
	s_or_b64 exec, exec, s[4:5]
	v_add_f32_e32 v48, 0, v48
	v_add_f32_e32 v48, v49, v48
	v_add_f32_e32 v48, v50, v48
	v_add_f32_e32 v48, v51, v48
	v_add_f32_e32 v48, v52, v48
	v_add_f32_e32 v48, v53, v48
	v_add_f32_e32 v48, v54, v48
	v_add_f32_e32 v48, v55, v48
	v_add_f32_e32 v48, v56, v48
	v_add_f32_e32 v48, v57, v48
	v_add_f32_e32 v48, v58, v48
	v_add_f32_e32 v48, v59, v48
	v_add_f32_e32 v48, v60, v48
	v_add_f32_e32 v48, v61, v48
	v_add_f32_e32 v48, v62, v48
	v_add_f32_e32 v48, v63, v48
	v_add_f32_e32 v48, v125, v48
	v_add_f32_e32 v48, v126, v48
	v_add_f32_e32 v48, v127, v48
	v_add_f32_e32 v48, v128, v48
	v_add_f32_e32 v48, v132, v48
	v_add_f32_e32 v37, v37, v48
	v_add_f32_e32 v37, v38, v37
	v_add_f32_e32 v37, v39, v37
	v_add_f32_e32 v37, v40, v37
	v_add_f32_e32 v37, v41, v37
	v_add_f32_e32 v37, v42, v37
	v_add_f32_e32 v37, v43, v37
	v_add_f32_e32 v37, v44, v37
	v_add_f32_e32 v37, v45, v37
	v_add_f32_e32 v37, v46, v37
	v_add_f32_e32 v125, v47, v37
	s_add_i32 s6, s6, 1
	s_mulk_i32 s7, 0x2400
	s_add_i32 s60, s60, 64
	v_readlane_b32 s4, v253, 48
	v_fmac_f32_e32 v125, v123, v36
	v_add_u32_e32 v36, s7, v118
	s_cmp_eq_u32 s4, s6
	s_waitcnt vmcnt(0)
	ds_write_b128 v36, v[32:35] offset:26624
	s_waitcnt lgkmcnt(0)
	s_barrier
	s_cbranch_scc0 .LBB0_1092
	v_readlane_b32 s0, v253, 48
	s_and_b32 s0, s0, 1
	s_mul_i32 s1, s0, 0x3400
	v_add_u32_e32 v88, s1, v119
	ds_read_b128 v[32:35], v88
	s_mulk_i32 s0, 0x2400
	v_lshlrev_b32_e32 v128, 3, v108
	s_waitcnt lgkmcnt(0)
	v_mfma_f32_32x32x16_bf16 v[48:63], v[32:35], v[84:87], 0
	ds_read_b128 v[32:35], v88 offset:32
	s_waitcnt lgkmcnt(0)
	v_mfma_f32_32x32x16_bf16 v[48:63], v[32:35], v[80:83], v[48:63]
	ds_read_b128 v[32:35], v88 offset:64
	s_waitcnt lgkmcnt(0)
	v_mfma_f32_32x32x16_bf16 v[48:63], v[32:35], v[76:79], v[48:63]
	ds_read_b128 v[32:35], v88 offset:96
	s_waitcnt lgkmcnt(0)
	v_mfma_f32_32x32x16_bf16 v[48:63], v[32:35], v[72:75], v[48:63]
	ds_read_b128 v[32:35], v88 offset:128
	s_waitcnt lgkmcnt(0)
	v_mfma_f32_32x32x16_bf16 v[48:63], v[32:35], v[68:71], v[48:63]
	ds_read_b128 v[32:35], v88 offset:160
	s_waitcnt lgkmcnt(0)
	v_mfma_f32_32x32x16_bf16 v[48:63], v[32:35], v[64:67], v[48:63]
	ds_read_b128 v[32:35], v88 offset:6656
	s_waitcnt lgkmcnt(0)
	v_mfma_f32_32x32x16_bf16 v[32:47], v[32:35], v[84:87], 0
	ds_read_b128 v[84:87], v88 offset:6688
	s_waitcnt lgkmcnt(0)
	v_mfma_f32_32x32x16_bf16 v[32:47], v[84:87], v[80:83], v[32:47]
	ds_read_b128 v[80:83], v88 offset:6720
	s_waitcnt lgkmcnt(0)
	v_mfma_f32_32x32x16_bf16 v[32:47], v[80:83], v[76:79], v[32:47]
	ds_read_b128 v[76:79], v88 offset:6752
	s_nop 1
	v_max_f32_e32 v80, v49, v49
	v_max_f32_e32 v81, v48, v48
	v_max_f32_e32 v80, v81, v80
	s_waitcnt lgkmcnt(0)
	v_mfma_f32_32x32x16_bf16 v[32:47], v[76:79], v[72:75], v[32:47]
	ds_read_b128 v[72:75], v88 offset:6784
	ds_read_b128 v[76:79], v88 offset:6816
	s_waitcnt lgkmcnt(1)
	v_mfma_f32_32x32x16_bf16 v[32:47], v[72:75], v[68:71], v[32:47]
	v_max3_f32 v68, v80, v50, v51
	v_max3_f32 v68, v68, v52, v53
	v_max3_f32 v68, v68, v54, v55
	v_max3_f32 v68, v68, v56, v57
	v_max3_f32 v68, v68, v58, v59
	v_max3_f32 v68, v68, v60, v61
	v_max3_f32 v68, v68, v62, v63
	s_waitcnt lgkmcnt(0)
	v_mfma_f32_32x32x16_bf16 v[32:47], v[76:79], v[64:67], v[32:47]
	v_add_u32_e32 v75, s0, v99
	s_nop 10
	v_max3_f32 v64, v68, v32, v33
	v_max3_f32 v64, v64, v34, v35
	v_max3_f32 v64, v64, v36, v37
	v_max3_f32 v64, v64, v38, v39
	v_max3_f32 v64, v64, v40, v41
	v_max3_f32 v64, v64, v42, v43
	v_max3_f32 v64, v64, v44, v45
	v_max3_f32 v64, v64, v46, v47
	ds_bpermute_b32 v65, v97, v64
	s_waitcnt lgkmcnt(0)
	v_max3_f32 v64, v124, v64, v65
	v_sub_f32_e32 v48, v48, v64
	v_exp_f32_e32 v48, v48
	v_sub_f32_e32 v49, v49, v64
	v_exp_f32_e32 v49, v49
	v_sub_f32_e32 v50, v50, v64
	v_exp_f32_e32 v50, v50
	v_sub_f32_e32 v51, v51, v64
	v_exp_f32_e32 v51, v51
	v_sub_f32_e32 v52, v52, v64
	v_add_f32_e32 v66, 0, v48
	v_exp_f32_e32 v52, v52
	v_sub_f32_e32 v53, v53, v64
	v_add_f32_e32 v66, v49, v66
	v_exp_f32_e32 v53, v53
	v_sub_f32_e32 v54, v54, v64
	v_add_f32_e32 v66, v50, v66
	v_exp_f32_e32 v54, v54
	v_sub_f32_e32 v55, v55, v64
	v_add_f32_e32 v66, v51, v66
	v_exp_f32_e32 v55, v55
	v_sub_f32_e32 v56, v56, v64
	v_add_f32_e32 v66, v52, v66
	v_exp_f32_e32 v67, v56
	v_sub_f32_e32 v56, v57, v64
	v_add_f32_e32 v66, v53, v66
	v_exp_f32_e32 v57, v56
	v_sub_f32_e32 v56, v58, v64
	v_add_f32_e32 v66, v54, v66
	v_exp_f32_e32 v58, v56
	v_sub_f32_e32 v56, v59, v64
	v_sub_f32_e32 v32, v32, v64
	v_exp_f32_e32 v59, v56
	v_sub_f32_e32 v56, v60, v64
	v_exp_f32_e32 v68, v32
	v_sub_f32_e32 v32, v33, v64
	v_add_f32_e32 v33, v55, v66
	v_exp_f32_e32 v60, v56
	v_sub_f32_e32 v56, v61, v64
	v_add_f32_e32 v33, v67, v33
	v_exp_f32_e32 v61, v56
	v_sub_f32_e32 v56, v62, v64
	v_add_f32_e32 v33, v57, v33
	v_exp_f32_e32 v62, v56
	v_sub_f32_e32 v56, v63, v64
	v_add_f32_e32 v33, v58, v33
	v_exp_f32_e32 v63, v56
	v_add_f32_e32 v33, v59, v33
	v_add_f32_e32 v33, v60, v33
	v_exp_f32_e32 v69, v32
	v_sub_f32_e32 v32, v34, v64
	v_add_f32_e32 v33, v61, v33
	v_exp_f32_e32 v70, v32
	v_sub_f32_e32 v32, v35, v64
	v_add_f32_e32 v33, v62, v33
	v_add_f32_e32 v33, v63, v33
	v_exp_f32_e32 v66, v32
	v_sub_f32_e32 v32, v36, v64
	v_add_f32_e32 v33, v68, v33
	v_exp_f32_e32 v71, v32
	v_sub_f32_e32 v32, v37, v64
	v_add_f32_e32 v33, v69, v33
	v_exp_f32_e32 v72, v32
	v_sub_f32_e32 v32, v38, v64
	v_add_f32_e32 v33, v70, v33
	v_exp_f32_e32 v73, v32
	v_add_f32_e32 v32, v66, v33
	v_add_f32_e32 v32, v71, v32
	v_add_f32_e32 v32, v72, v32
	v_sub_f32_e32 v65, v124, v64
	v_add_f32_e32 v74, v73, v32
	v_sub_f32_e32 v32, v39, v64
	v_exp_f32_e32 v56, v65
	v_exp_f32_e32 v65, v32
	ds_read_b128 v[32:35], v75 offset:26624
	v_cvt_pk_bf16_f32 v36, v48, v49
	v_cvt_pk_bf16_f32 v37, v50, v51
	v_cvt_pk_bf16_f32 v38, v52, v53
	v_cvt_pk_bf16_f32 v39, v54, v55
	ds_read_b128 v[48:51], v75 offset:31232
	ds_read_b128 v[52:55], v75 offset:26656
	v_mul_f32_e32 v30, v30, v56
	v_mul_f32_e32 v31, v31, v56
	v_mul_f32_e32 v28, v28, v56
	v_mul_f32_e32 v29, v29, v56
	v_mul_f32_e32 v26, v26, v56
	v_mul_f32_e32 v27, v27, v56
	v_mul_f32_e32 v24, v24, v56
	v_mul_f32_e32 v25, v25, v56
	v_mul_f32_e32 v22, v22, v56
	v_mul_f32_e32 v23, v23, v56
	v_mul_f32_e32 v20, v20, v56
	v_mul_f32_e32 v21, v21, v56
	v_mul_f32_e32 v18, v18, v56
	v_mul_f32_e32 v19, v19, v56
	v_mul_f32_e32 v16, v16, v56
	v_mul_f32_e32 v17, v17, v56
	v_mul_f32_e32 v14, v14, v56
	v_mul_f32_e32 v15, v15, v56
	v_mul_f32_e32 v12, v12, v56
	v_mul_f32_e32 v13, v13, v56
	s_waitcnt lgkmcnt(2)
	v_mfma_f32_32x32x16_bf16 v[16:31], v[32:35], v[36:39], v[16:31]
	v_mul_f32_e64 v10, v10, v56
	v_mul_f32_e64 v11, v11, v56
	v_mul_f32_e64 v8, v8, v56
	v_mul_f32_e64 v9, v9, v56
	v_mul_f32_e64 v6, v6, v56
	v_mul_f32_e64 v7, v7, v56
	v_mul_f32_e32 v4, v4, v56
	v_mul_f32_e32 v5, v5, v56
	v_mul_f32_e32 v2, v2, v56
	v_mul_f32_e32 v3, v3, v56
	v_mul_f32_e32 v0, v0, v56
	v_mul_f32_e32 v1, v1, v56
	ds_read_b128 v[32:35], v75 offset:31264
	v_sub_f32_e32 v40, v40, v64
	s_waitcnt lgkmcnt(2)
	v_mfma_f32_32x32x16_bf16 v[0:15], v[48:51], v[36:39], v[0:15]
	v_exp_f32_e32 v76, v40
	v_sub_f32_e32 v36, v41, v64
	v_exp_f32_e32 v77, v36
	v_cvt_pk_bf16_f32 v36, v67, v57
	v_cvt_pk_bf16_f32 v37, v58, v59
	v_cvt_pk_bf16_f32 v38, v60, v61
	v_cvt_pk_bf16_f32 v39, v62, v63
	v_sub_f32_e32 v40, v42, v64
	ds_read_b128 v[48:51], v75 offset:26688
	s_waitcnt lgkmcnt(2)
	v_mfma_f32_32x32x16_bf16 v[16:31], v[52:55], v[36:39], v[16:31]
	v_exp_f32_e32 v52, v40
	v_add_f32_e32 v40, v65, v74
	v_add_f32_e32 v40, v76, v40
	v_add_f32_e32 v40, v77, v40
	v_add_f32_e32 v53, v52, v40
	v_sub_f32_e32 v54, v43, v64
	v_exp_f32_e32 v54, v54
	s_waitcnt lgkmcnt(1)
	v_mfma_f32_32x32x16_bf16 v[0:15], v[32:35], v[36:39], v[0:15]
	ds_read_b128 v[36:39], v75 offset:31296
	ds_read_b128 v[40:43], v75 offset:26720
	v_sub_f32_e32 v44, v44, v64
	v_cvt_pk_bf16_f32 v32, v68, v69
	v_cvt_pk_bf16_f32 v33, v70, v66
	v_cvt_pk_bf16_f32 v34, v71, v72
	v_cvt_pk_bf16_f32 v35, v73, v65
	v_exp_f32_e32 v44, v44
	v_sub_f32_e32 v45, v45, v64
	s_waitcnt lgkmcnt(2)
	v_mfma_f32_32x32x16_bf16 v[16:31], v[48:51], v[32:35], v[16:31]
	v_exp_f32_e32 v45, v45
	v_sub_f32_e32 v46, v46, v64
	ds_read_b128 v[48:51], v75 offset:31328
	s_waitcnt lgkmcnt(0)
	s_barrier
	v_mfma_f32_32x32x16_bf16 v[0:15], v[36:39], v[32:35], v[0:15]
	v_sub_f32_e32 v32, v47, v64
	v_exp_f32_e32 v36, v46
	v_exp_f32_e32 v37, v32
	v_add_f32_e32 v38, v54, v53
	v_add_f32_e32 v38, v44, v38
	v_add_f32_e32 v38, v45, v38
	v_cvt_pk_bf16_f32 v35, v36, v37
	v_add_f32_e32 v36, v36, v38
	v_add_f32_e32 v36, v37, v36
	v_fmac_f32_e32 v36, v125, v56
	ds_bpermute_b32 v37, v97, v36
	v_cvt_pk_bf16_f32 v32, v76, v77
	v_cvt_pk_bf16_f32 v33, v52, v54
	v_cvt_pk_bf16_f32 v34, v44, v45
	s_nop 1
	v_mfma_f32_32x32x16_bf16 v[16:31], v[40:43], v[32:35], v[16:31]
	v_mfma_f32_32x32x16_bf16 v[0:15], v[48:51], v[32:35], v[0:15]
	s_waitcnt lgkmcnt(0)
	v_add_f32_e32 v34, v36, v37
	v_div_scale_f32 v35, s[0:1], v34, v34, 1.0
	v_rcp_f32_e32 v36, v35
	v_lshlrev_b64 v[32:33], 11, v[100:101]
	v_readlane_b32 s0, v252, 48
	v_lshl_add_u64 v[32:33], s[66:67], 0, v[32:33]
	v_fma_f32 v37, -v35, v36, 1.0
	v_fmac_f32_e32 v36, v37, v36
	v_div_scale_f32 v37, vcc, 1.0, v34, 1.0
	v_mul_f32_e32 v38, v37, v36
	v_fma_f32 v39, -v35, v38, v37
	v_fmac_f32_e32 v38, v39, v36
	v_fma_f32 v35, -v35, v38, v37
	v_div_fmas_f32 v35, v35, v36, v38
	s_lshl_b32 s60, s0, 1
	v_div_fixup_f32 v34, v35, v34, 1.0
	v_lshl_add_u64 v[32:33], v[32:33], 0, s[60:61]
	v_mul_f32_e32 v16, v16, v34
	v_mul_f32_e32 v17, v17, v34
	v_mul_f32_e32 v18, v18, v34
	v_mul_f32_e32 v19, v19, v34
	v_cvt_pk_bf16_f32 v16, v16, v17
	v_cvt_pk_bf16_f32 v17, v18, v19
	v_lshl_add_u64 v[18:19], v[32:33], 0, v[128:129]
	s_mov_b64 s[0:1], 0x2d53d00
	v_lshl_add_u64 v[32:33], v[18:19], 0, s[0:1]
	s_mov_b32 s0, 0x2d53000
	v_add_co_u32_e32 v18, vcc, s0, v18
	v_mul_f32_e32 v0, v0, v34
	v_mul_f32_e32 v1, v1, v34
	v_mul_f32_e32 v2, v2, v34
	v_mul_f32_e32 v3, v3, v34
	v_addc_co_u32_e32 v19, vcc, 0, v19, vcc
	v_cvt_pk_bf16_f32 v0, v0, v1
	v_cvt_pk_bf16_f32 v1, v2, v3
	global_store_dwordx2 v[18:19], v[16:17], off offset:3328
	v_mul_f32_e32 v16, v20, v34
	v_mul_f32_e32 v17, v21, v34
	v_mul_f32_e32 v18, v22, v34
	v_mul_f32_e32 v19, v23, v34
	global_store_dwordx2 v[32:33], v[0:1], off offset:64
	v_mul_f32_e32 v0, v4, v34
	v_mul_f32_e32 v1, v5, v34
	v_mul_f32_e32 v2, v6, v34
	v_mul_f32_e32 v3, v7, v34
	v_cvt_pk_bf16_f32 v16, v16, v17
	v_cvt_pk_bf16_f32 v17, v18, v19
	v_cvt_pk_bf16_f32 v0, v0, v1
	v_cvt_pk_bf16_f32 v1, v2, v3
	global_store_dwordx2 v[32:33], v[16:17], off offset:16
	v_mul_f32_e32 v16, v24, v34
	v_mul_f32_e32 v17, v25, v34
	v_mul_f32_e32 v18, v26, v34
	v_mul_f32_e32 v19, v27, v34
	global_store_dwordx2 v[32:33], v[0:1], off offset:80
	v_mul_f32_e32 v0, v8, v34
	v_mul_f32_e32 v1, v9, v34
	v_mul_f32_e32 v2, v10, v34
	v_mul_f32_e32 v3, v11, v34
	v_cvt_pk_bf16_f32 v16, v16, v17
	v_cvt_pk_bf16_f32 v17, v18, v19
	v_cvt_pk_bf16_f32 v0, v0, v1
	v_cvt_pk_bf16_f32 v1, v2, v3
	global_store_dwordx2 v[32:33], v[16:17], off offset:32
	v_mul_f32_e32 v16, v28, v34
	v_mul_f32_e32 v17, v29, v34
	v_mul_f32_e32 v18, v30, v34
	v_mul_f32_e32 v19, v31, v34
	global_store_dwordx2 v[32:33], v[0:1], off offset:96
	v_mul_f32_e32 v0, v12, v34
	v_mul_f32_e32 v1, v13, v34
	v_mul_f32_e32 v2, v14, v34
	v_mul_f32_e32 v3, v15, v34
	v_cvt_pk_bf16_f32 v16, v16, v17
	v_cvt_pk_bf16_f32 v17, v18, v19
	v_cvt_pk_bf16_f32 v0, v0, v1
	v_cvt_pk_bf16_f32 v1, v2, v3
	s_mov_b64 s[0:1], 0
	global_store_dwordx2 v[32:33], v[16:17], off offset:48
	global_store_dwordx2 v[32:33], v[0:1], off offset:112

.LBB0_1112:
	s_or_b64 exec, exec, s[6:7]
	s_and_b32 s6, s5, 1
	s_mul_i32 s7, s6, 0x2400
	v_add_u32_e32 v115, s7, v91
	ds_read_b128 v[32:35], v115
	ds_read_b128 v[102:105], v115 offset:4640
	s_xor_b32 s8, s6, 1
	s_mulk_i32 s8, 0x2400
	s_waitcnt lgkmcnt(1)
	v_mfma_f32_32x32x16_bf16 v[48:63], v[32:35], v[76:79], 0
	ds_read_b128 v[32:35], v115 offset:32
	s_waitcnt lgkmcnt(0)
	v_mfma_f32_32x32x16_bf16 v[48:63], v[32:35], v[72:75], v[48:63]
	ds_read_b128 v[32:35], v115 offset:64
	s_waitcnt lgkmcnt(0)
	v_mfma_f32_32x32x16_bf16 v[48:63], v[32:35], v[68:71], v[48:63]
	ds_read_b128 v[32:35], v115 offset:96
	s_waitcnt lgkmcnt(0)
	v_mfma_f32_32x32x16_bf16 v[48:63], v[32:35], v[64:67], v[48:63]
	ds_read_b128 v[32:35], v115 offset:4608
	s_waitcnt lgkmcnt(0)
	v_mfma_f32_32x32x16_bf16 v[32:47], v[32:35], v[76:79], 0
	s_nop 8
	v_max_f32_e32 v94, v49, v49
	v_max_f32_e32 v97, v48, v48
	v_max_f32_e32 v94, v97, v94
	v_max3_f32 v94, v94, v50, v51
	v_max3_f32 v94, v94, v52, v53
	v_max3_f32 v94, v94, v54, v55
	v_max3_f32 v94, v94, v56, v57
	v_mfma_f32_32x32x16_bf16 v[32:47], v[102:105], v[72:75], v[32:47]
	ds_read_b128 v[102:105], v115 offset:4672
	ds_read_b128 v[116:119], v115 offset:4704
	v_max3_f32 v94, v94, v58, v59
	v_max3_f32 v94, v94, v60, v61
	v_max3_f32 v94, v94, v62, v63
	ds_read_b128 v[120:123], v115 offset:23040
	s_waitcnt lgkmcnt(2)
	v_mfma_f32_32x32x16_bf16 v[32:47], v[102:105], v[68:71], v[32:47]
	v_lshl_add_u64 v[104:105], s[60:61], 1, v[84:85]
	s_waitcnt lgkmcnt(1)
	v_mfma_f32_32x32x16_bf16 v[32:47], v[116:119], v[64:67], v[32:47]
	s_nop 11
	v_max3_f32 v94, v94, v32, v33
	v_max3_f32 v94, v94, v34, v35
	v_max3_f32 v94, v94, v36, v37
	v_max3_f32 v94, v94, v38, v39
	v_max3_f32 v94, v94, v40, v41
	v_max3_f32 v94, v94, v42, v43
	v_max3_f32 v94, v94, v44, v45
	v_max3_f32 v94, v94, v46, v47
	ds_bpermute_b32 v97, v88, v94
	s_waitcnt lgkmcnt(0)
	v_max3_f32 v94, v95, v94, v97
	v_sub_f32_e32 v32, v32, v94
	v_sub_f32_e32 v106, v95, v94
	v_exp_f32_e32 v95, v32
	v_sub_f32_e32 v32, v33, v94
	v_exp_f32_e32 v97, v32
	v_sub_f32_e32 v32, v34, v94
	v_exp_f32_e32 v99, v32
	v_sub_f32_e32 v32, v35, v94
	v_exp_f32_e32 v102, v32
	v_sub_f32_e32 v32, v36, v94
	v_exp_f32_e32 v103, v32
	v_sub_f32_e32 v32, v37, v94
	v_exp_f32_e32 v37, v32
	global_load_dwordx4 v[32:35], v[104:105], off
	v_exp_f32_e32 v36, v106
	ds_read_b128 v[104:107], v115 offset:18432
	v_sub_f32_e32 v48, v48, v94
	v_sub_f32_e32 v49, v49, v94
	v_sub_f32_e32 v50, v50, v94
	v_sub_f32_e32 v51, v51, v94
	v_sub_f32_e32 v52, v52, v94
	v_sub_f32_e32 v53, v53, v94
	v_sub_f32_e32 v54, v54, v94
	v_sub_f32_e32 v55, v55, v94
	v_exp_f32_e32 v48, v48
	v_exp_f32_e32 v49, v49
	v_exp_f32_e32 v50, v50
	v_exp_f32_e32 v51, v51
	v_exp_f32_e32 v52, v52
	v_exp_f32_e32 v53, v53
	v_exp_f32_e32 v54, v54
	v_exp_f32_e32 v55, v55
	v_mul_f32_e32 v16, v16, v36
	v_mul_f32_e32 v17, v17, v36
	v_mul_f32_e32 v18, v18, v36
	v_mul_f32_e32 v19, v19, v36
	v_mul_f32_e32 v20, v20, v36
	v_mul_f32_e32 v21, v21, v36
	v_mul_f32_e32 v22, v22, v36
	v_mul_f32_e32 v23, v23, v36
	v_mul_f32_e32 v24, v24, v36
	v_mul_f32_e32 v25, v25, v36
	v_mul_f32_e32 v26, v26, v36
	v_mul_f32_e32 v27, v27, v36
	v_mul_f32_e32 v28, v28, v36
	v_mul_f32_e32 v29, v29, v36
	v_mul_f32_e32 v30, v30, v36
	v_mul_f32_e32 v31, v31, v36
	v_cvt_pk_bf16_f32 v116, v48, v49
	v_cvt_pk_bf16_f32 v117, v50, v51
	v_cvt_pk_bf16_f32 v118, v52, v53
	v_cvt_pk_bf16_f32 v119, v54, v55
	v_sub_f32_e32 v56, v56, v94
	v_sub_f32_e32 v57, v57, v94
	s_waitcnt lgkmcnt(0)
	v_mfma_f32_32x32x16_bf16 v[16:31], v[104:107], v[116:119], v[16:31]
	ds_read_b128 v[104:107], v115 offset:18464
	v_sub_f32_e32 v58, v58, v94
	v_sub_f32_e32 v59, v59, v94
	v_sub_f32_e32 v60, v60, v94
	v_sub_f32_e32 v61, v61, v94
	v_sub_f32_e32 v62, v62, v94
	v_sub_f32_e32 v63, v63, v94
	v_exp_f32_e32 v56, v56
	v_exp_f32_e32 v57, v57
	v_exp_f32_e32 v58, v58
	v_exp_f32_e32 v59, v59
	v_exp_f32_e32 v60, v60
	v_exp_f32_e32 v61, v61
	v_exp_f32_e32 v62, v62
	v_exp_f32_e32 v63, v63
	v_mul_f32_e32 v0, v0, v36
	v_mul_f32_e32 v1, v1, v36
	v_mul_f32_e32 v2, v2, v36
	v_mul_f32_e32 v3, v3, v36
	v_mul_f32_e32 v4, v4, v36
	v_mul_f32_e32 v5, v5, v36
	v_mul_f32_e32 v6, v6, v36
	v_mul_f32_e32 v7, v7, v36
	v_mul_f32_e32 v8, v8, v36
	v_mul_f32_e32 v9, v9, v36
	v_mul_f32_e32 v10, v10, v36
	v_mul_f32_e32 v11, v11, v36
	v_mul_f32_e32 v12, v12, v36
	v_mul_f32_e32 v13, v13, v36
	v_mul_f32_e32 v14, v14, v36
	v_mul_f32_e32 v15, v15, v36
	v_sub_f32_e32 v38, v38, v94
	v_sub_f32_e32 v39, v39, v94
	v_mfma_f32_32x32x16_bf16 v[0:15], v[120:123], v[116:119], v[0:15]
	ds_read_b128 v[116:119], v115 offset:23072
	v_cvt_pk_bf16_f32 v120, v56, v57
	v_cvt_pk_bf16_f32 v121, v58, v59
	v_cvt_pk_bf16_f32 v122, v60, v61
	v_cvt_pk_bf16_f32 v123, v62, v63
	v_exp_f32_e32 v38, v38
	v_exp_f32_e32 v39, v39
	s_waitcnt lgkmcnt(1)
	v_mfma_f32_32x32x16_bf16 v[16:31], v[104:107], v[120:123], v[16:31]
	ds_read_b128 v[104:107], v115 offset:18496
	v_sub_f32_e32 v40, v40, v94
	v_sub_f32_e32 v41, v41, v94
	v_sub_f32_e32 v42, v42, v94
	v_sub_f32_e32 v43, v43, v94
	v_sub_f32_e32 v44, v44, v94
	v_sub_f32_e32 v45, v45, v94
	s_waitcnt lgkmcnt(1)
	v_mfma_f32_32x32x16_bf16 v[0:15], v[116:119], v[120:123], v[0:15]
	v_cvt_pk_bf16_f32 v116, v95, v97
	v_cvt_pk_bf16_f32 v117, v99, v102
	v_cvt_pk_bf16_f32 v118, v103, v37
	v_cvt_pk_bf16_f32 v119, v38, v39
	ds_read_b128 v[120:123], v115 offset:23104
	v_sub_f32_e32 v46, v46, v94
	v_sub_f32_e32 v47, v47, v94
	s_waitcnt lgkmcnt(1)
	v_mfma_f32_32x32x16_bf16 v[16:31], v[104:107], v[116:119], v[16:31]
	ds_read_b128 v[104:107], v115 offset:18528
	v_exp_f32_e32 v40, v40
	v_exp_f32_e32 v41, v41
	v_exp_f32_e32 v42, v42
	v_exp_f32_e32 v43, v43
	v_exp_f32_e32 v44, v44
	v_exp_f32_e32 v45, v45
	v_exp_f32_e32 v46, v46
	v_exp_f32_e32 v47, v47
	s_waitcnt lgkmcnt(1)
	v_mfma_f32_32x32x16_bf16 v[0:15], v[120:123], v[116:119], v[0:15]
	v_cvt_pk_bf16_f32 v116, v40, v41
	v_cvt_pk_bf16_f32 v117, v42, v43
	v_cvt_pk_bf16_f32 v118, v44, v45
	v_cvt_pk_bf16_f32 v119, v46, v47
	s_waitcnt lgkmcnt(0)
	s_nop 0
	v_mfma_f32_32x32x16_bf16 v[16:31], v[104:107], v[116:119], v[16:31]
	ds_read_b128 v[104:107], v115 offset:23136
	s_waitcnt lgkmcnt(0)
	v_mfma_f32_32x32x16_bf16 v[0:15], v[104:107], v[116:119], v[0:15]
	s_and_saveexec_b64 s[6:7], s[0:1]
	s_cbranch_execz .LBB0_1114
	v_add_u32_e32 v104, s8, v92
	s_waitcnt vmcnt(1)
	ds_write_b128 v104, v[80:83]
.LBB0_1114:
	s_or_b64 exec, exec, s[6:7]
	v_add_f32_e32 v48, 0, v48
	v_add_f32_e32 v48, v49, v48
	v_add_f32_e32 v48, v50, v48
	v_add_f32_e32 v48, v51, v48
	v_add_f32_e32 v48, v52, v48
	v_add_f32_e32 v48, v53, v48
	v_add_f32_e32 v48, v54, v48
	v_add_f32_e32 v48, v55, v48
	v_add_f32_e32 v48, v56, v48
	v_add_f32_e32 v48, v57, v48
	v_add_f32_e32 v48, v58, v48
	v_add_f32_e32 v48, v59, v48
	v_add_f32_e32 v48, v60, v48
	v_add_f32_e32 v48, v61, v48
	v_add_f32_e32 v48, v62, v48
	v_add_f32_e32 v48, v63, v48
	v_add_f32_e32 v48, v95, v48
	v_add_f32_e32 v48, v97, v48
	v_add_f32_e32 v48, v99, v48
	v_add_f32_e32 v48, v102, v48
	v_add_f32_e32 v48, v103, v48
	v_add_f32_e32 v37, v37, v48
	v_add_f32_e32 v37, v38, v37
	v_add_f32_e32 v37, v39, v37
	v_add_f32_e32 v37, v40, v37
	v_add_f32_e32 v37, v41, v37
	v_add_f32_e32 v37, v42, v37
	v_add_f32_e32 v37, v43, v37
	v_add_f32_e32 v37, v44, v37
	v_add_f32_e32 v37, v45, v37
	v_add_f32_e32 v37, v46, v37
	v_add_f32_e32 v95, v47, v37
	s_add_i32 s5, s5, 1
	s_add_i32 s60, s60, 64
	v_readlane_b32 s6, v253, 48
	v_fmac_f32_e32 v95, v93, v36
	v_add_u32_e32 v36, s8, v90
	s_cmp_eq_u32 s6, s5
	s_waitcnt vmcnt(0)
	ds_write_b128 v36, v[32:35] offset:18432
	s_waitcnt lgkmcnt(0)
	s_barrier
	s_cbranch_scc0 .LBB0_1110
	v_readlane_b32 s0, v253, 48
	s_bitcmp1_b32 s0, 0
	s_cselect_b32 s0, 0x2400, 0
	v_add_u32_e32 v80, s0, v91
	ds_read_b128 v[32:35], v80
	s_mov_b32 s5, s61
	v_lshlrev_b32_e32 v128, 3, v108
	s_waitcnt lgkmcnt(0)
	v_mfma_f32_32x32x16_bf16 v[48:63], v[32:35], v[76:79], 0
	ds_read_b128 v[32:35], v80 offset:32
	s_waitcnt lgkmcnt(0)
	v_mfma_f32_32x32x16_bf16 v[48:63], v[32:35], v[72:75], v[48:63]
	ds_read_b128 v[32:35], v80 offset:64
	s_waitcnt lgkmcnt(0)
	v_mfma_f32_32x32x16_bf16 v[48:63], v[32:35], v[68:71], v[48:63]
	ds_read_b128 v[32:35], v80 offset:96
	s_waitcnt lgkmcnt(0)
	v_mfma_f32_32x32x16_bf16 v[48:63], v[32:35], v[64:67], v[48:63]
	ds_read_b128 v[32:35], v80 offset:4608
	s_waitcnt lgkmcnt(0)
	v_mfma_f32_32x32x16_bf16 v[32:47], v[32:35], v[76:79], 0
	ds_read_b128 v[76:79], v80 offset:4640
	s_nop 7
	v_max_f32_e32 v81, v49, v49
	v_max_f32_e32 v82, v48, v48
	v_max_f32_e32 v81, v82, v81
	s_waitcnt lgkmcnt(0)
	v_mfma_f32_32x32x16_bf16 v[32:47], v[76:79], v[72:75], v[32:47]
	ds_read_b128 v[72:75], v80 offset:4672
	ds_read_b128 v[76:79], v80 offset:4704
	s_waitcnt lgkmcnt(1)
	v_mfma_f32_32x32x16_bf16 v[32:47], v[72:75], v[68:71], v[32:47]
	v_max3_f32 v68, v81, v50, v51
	v_max3_f32 v68, v68, v52, v53
	v_max3_f32 v68, v68, v54, v55
	v_max3_f32 v68, v68, v56, v57
	v_max3_f32 v68, v68, v58, v59
	v_max3_f32 v68, v68, v60, v61
	v_max3_f32 v68, v68, v62, v63
	s_waitcnt lgkmcnt(0)
	v_mfma_f32_32x32x16_bf16 v[32:47], v[76:79], v[64:67], v[32:47]
	s_nop 11
	v_max3_f32 v64, v68, v32, v33
	v_max3_f32 v64, v64, v34, v35
	v_max3_f32 v64, v64, v36, v37
	v_max3_f32 v64, v64, v38, v39
	v_max3_f32 v64, v64, v40, v41
	v_max3_f32 v64, v64, v42, v43
	v_max3_f32 v64, v64, v44, v45
	v_max3_f32 v64, v64, v46, v47
	ds_bpermute_b32 v65, v88, v64
	s_waitcnt lgkmcnt(0)
	v_max3_f32 v64, v94, v64, v65
	v_sub_f32_e32 v48, v48, v64
	v_sub_f32_e32 v49, v49, v64
	v_exp_f32_e32 v48, v48
	v_sub_f32_e32 v50, v50, v64
	v_exp_f32_e32 v49, v49
	v_sub_f32_e32 v51, v51, v64
	v_exp_f32_e32 v50, v50
	v_sub_f32_e32 v52, v52, v64
	v_sub_f32_e32 v56, v56, v64
	v_exp_f32_e32 v51, v51
	v_sub_f32_e32 v53, v53, v64
	v_exp_f32_e32 v52, v52
	v_exp_f32_e32 v66, v56
	v_add_f32_e32 v56, 0, v48
	v_sub_f32_e32 v54, v54, v64
	v_exp_f32_e32 v53, v53
	v_add_f32_e32 v56, v49, v56
	v_sub_f32_e32 v55, v55, v64
	v_exp_f32_e32 v54, v54
	v_add_f32_e32 v56, v50, v56
	v_exp_f32_e32 v55, v55
	v_add_f32_e32 v56, v51, v56
	v_sub_f32_e32 v57, v57, v64
	v_add_f32_e32 v56, v52, v56
	v_sub_f32_e32 v58, v58, v64
	v_exp_f32_e32 v57, v57
	v_add_f32_e32 v56, v53, v56
	v_sub_f32_e32 v59, v59, v64
	v_exp_f32_e32 v58, v58
	v_add_f32_e32 v56, v54, v56
	v_sub_f32_e32 v60, v60, v64
	v_exp_f32_e32 v59, v59
	v_add_f32_e32 v56, v55, v56
	v_sub_f32_e32 v61, v61, v64
	v_exp_f32_e32 v60, v60
	v_add_f32_e32 v56, v66, v56
	v_sub_f32_e32 v62, v62, v64
	v_exp_f32_e32 v61, v61
	v_add_f32_e32 v56, v57, v56
	v_sub_f32_e32 v63, v63, v64
	v_exp_f32_e32 v62, v62
	v_add_f32_e32 v56, v58, v56
	v_exp_f32_e32 v63, v63
	v_add_f32_e32 v56, v59, v56
	v_sub_f32_e32 v32, v32, v64
	v_add_f32_e32 v56, v60, v56
	v_exp_f32_e32 v67, v32
	v_sub_f32_e32 v32, v33, v64
	v_add_f32_e32 v56, v61, v56
	v_exp_f32_e32 v68, v32
	v_sub_f32_e32 v32, v34, v64
	v_add_f32_e32 v56, v62, v56
	v_exp_f32_e32 v69, v32
	v_sub_f32_e32 v33, v35, v64
	v_add_f32_e32 v32, v63, v56
	v_exp_f32_e32 v70, v33
	v_sub_f32_e32 v33, v36, v64
	v_add_f32_e32 v32, v67, v32
	v_exp_f32_e32 v71, v33
	v_sub_f32_e32 v33, v37, v64
	v_add_f32_e32 v32, v68, v32
	v_exp_f32_e32 v72, v33
	v_sub_f32_e32 v33, v38, v64
	v_add_f32_e32 v32, v69, v32
	v_exp_f32_e32 v73, v33
	v_add_f32_e32 v32, v70, v32
	v_add_f32_e32 v32, v71, v32
	v_add_f32_e32 v32, v72, v32
	v_sub_f32_e32 v65, v94, v64
	v_add_f32_e32 v74, v73, v32
	v_sub_f32_e32 v32, v39, v64
	v_exp_f32_e32 v56, v65
	v_exp_f32_e32 v65, v32
	ds_read_b128 v[32:35], v80 offset:18432
	v_cvt_pk_bf16_f32 v36, v48, v49
	v_cvt_pk_bf16_f32 v37, v50, v51
	v_cvt_pk_bf16_f32 v38, v52, v53
	v_cvt_pk_bf16_f32 v39, v54, v55
	ds_read_b128 v[48:51], v80 offset:23040
	ds_read_b128 v[52:55], v80 offset:18464
	v_mul_f32_e32 v30, v30, v56
	v_mul_f32_e32 v31, v31, v56
	v_mul_f32_e32 v28, v28, v56
	v_mul_f32_e32 v29, v29, v56
	v_mul_f32_e32 v26, v26, v56
	v_mul_f32_e32 v27, v27, v56
	v_mul_f32_e32 v24, v24, v56
	v_mul_f32_e32 v25, v25, v56
	v_mul_f32_e32 v22, v22, v56
	v_mul_f32_e32 v23, v23, v56
	v_mul_f32_e32 v20, v20, v56
	v_mul_f32_e32 v21, v21, v56
	v_mul_f32_e32 v18, v18, v56
	v_mul_f32_e32 v19, v19, v56
	v_mul_f32_e32 v16, v16, v56
	v_mul_f32_e32 v17, v17, v56
	v_mul_f32_e32 v14, v14, v56
	v_mul_f32_e32 v15, v15, v56
	v_mul_f32_e32 v12, v12, v56
	v_mul_f32_e32 v13, v13, v56
	s_waitcnt lgkmcnt(2)
	v_mfma_f32_32x32x16_bf16 v[16:31], v[32:35], v[36:39], v[16:31]
	v_mul_f32_e64 v10, v10, v56
	v_mul_f32_e64 v11, v11, v56
	v_mul_f32_e64 v8, v8, v56
	v_mul_f32_e64 v9, v9, v56
	v_mul_f32_e64 v6, v6, v56
	v_mul_f32_e64 v7, v7, v56
	v_mul_f32_e32 v4, v4, v56
	v_mul_f32_e32 v5, v5, v56
	v_mul_f32_e32 v2, v2, v56
	v_mul_f32_e32 v3, v3, v56
	v_mul_f32_e32 v0, v0, v56
	v_mul_f32_e32 v1, v1, v56
	ds_read_b128 v[32:35], v80 offset:23072
	v_sub_f32_e32 v40, v40, v64
	s_waitcnt lgkmcnt(2)
	v_mfma_f32_32x32x16_bf16 v[0:15], v[48:51], v[36:39], v[0:15]
	v_exp_f32_e32 v75, v40
	v_sub_f32_e32 v36, v41, v64
	v_exp_f32_e32 v76, v36
	v_cvt_pk_bf16_f32 v36, v66, v57
	v_cvt_pk_bf16_f32 v37, v58, v59
	v_cvt_pk_bf16_f32 v38, v60, v61
	v_cvt_pk_bf16_f32 v39, v62, v63
	v_sub_f32_e32 v40, v42, v64
	ds_read_b128 v[48:51], v80 offset:18496
	s_waitcnt lgkmcnt(2)
	v_mfma_f32_32x32x16_bf16 v[16:31], v[52:55], v[36:39], v[16:31]
	v_exp_f32_e32 v52, v40
	v_add_f32_e32 v40, v65, v74
	v_add_f32_e32 v40, v75, v40
	v_add_f32_e32 v40, v76, v40
	v_add_f32_e32 v53, v52, v40
	v_sub_f32_e32 v54, v43, v64
	v_exp_f32_e32 v54, v54
	s_waitcnt lgkmcnt(1)
	v_mfma_f32_32x32x16_bf16 v[0:15], v[32:35], v[36:39], v[0:15]
	ds_read_b128 v[36:39], v80 offset:23104
	ds_read_b128 v[40:43], v80 offset:18528
	v_sub_f32_e32 v44, v44, v64
	v_cvt_pk_bf16_f32 v32, v67, v68
	v_cvt_pk_bf16_f32 v33, v69, v70
	v_cvt_pk_bf16_f32 v34, v71, v72
	v_cvt_pk_bf16_f32 v35, v73, v65
	v_exp_f32_e32 v44, v44
	v_sub_f32_e32 v45, v45, v64
	s_waitcnt lgkmcnt(2)
	v_mfma_f32_32x32x16_bf16 v[16:31], v[48:51], v[32:35], v[16:31]
	v_exp_f32_e32 v45, v45
	v_sub_f32_e32 v46, v46, v64
	ds_read_b128 v[48:51], v80 offset:23136
	s_waitcnt lgkmcnt(0)
	s_barrier
	v_mfma_f32_32x32x16_bf16 v[0:15], v[36:39], v[32:35], v[0:15]
	v_sub_f32_e32 v32, v47, v64
	v_exp_f32_e32 v36, v46
	v_exp_f32_e32 v37, v32
	v_add_f32_e32 v38, v54, v53
	v_add_f32_e32 v38, v44, v38
	v_add_f32_e32 v38, v45, v38
	v_cvt_pk_bf16_f32 v35, v36, v37
	v_add_f32_e32 v36, v36, v38
	v_add_f32_e32 v36, v37, v36
	v_fmac_f32_e32 v36, v95, v56
	ds_bpermute_b32 v37, v88, v36
	v_cvt_pk_bf16_f32 v32, v75, v76
	v_cvt_pk_bf16_f32 v33, v52, v54
	v_cvt_pk_bf16_f32 v34, v44, v45
	s_nop 1
	v_mfma_f32_32x32x16_bf16 v[16:31], v[40:43], v[32:35], v[16:31]
	v_mfma_f32_32x32x16_bf16 v[0:15], v[48:51], v[32:35], v[0:15]
	s_waitcnt lgkmcnt(0)
	v_add_f32_e32 v34, v36, v37
	v_div_scale_f32 v35, s[0:1], v34, v34, 1.0
	v_rcp_f32_e32 v36, v35
	v_lshlrev_b64 v[32:33], 11, v[100:101]
	v_lshl_add_u64 v[32:33], s[66:67], 0, v[32:33]
	v_lshl_add_u64 v[32:33], v[32:33], 0, s[4:5]
	v_fma_f32 v37, -v35, v36, 1.0
	v_fmac_f32_e32 v36, v37, v36
	v_div_scale_f32 v37, vcc, 1.0, v34, 1.0
	v_mul_f32_e32 v38, v37, v36
	v_fma_f32 v39, -v35, v38, v37
	v_fmac_f32_e32 v38, v39, v36
	v_fma_f32 v35, -v35, v38, v37
	v_div_fmas_f32 v35, v35, v36, v38
	v_div_fixup_f32 v34, v35, v34, 1.0
	v_mul_f32_e32 v16, v16, v34
	v_mul_f32_e32 v17, v17, v34
	v_mul_f32_e32 v18, v18, v34
	v_mul_f32_e32 v19, v19, v34
	v_cvt_pk_bf16_f32 v16, v16, v17
	v_cvt_pk_bf16_f32 v17, v18, v19
	v_lshl_add_u64 v[18:19], v[32:33], 0, v[128:129]
	s_mov_b64 s[0:1], 0x2d53900
	v_lshl_add_u64 v[32:33], v[18:19], 0, s[0:1]
	s_mov_b32 s0, 0x2d53000
	v_add_co_u32_e32 v18, vcc, s0, v18
	v_mul_f32_e32 v0, v0, v34
	v_mul_f32_e32 v1, v1, v34
	v_mul_f32_e32 v2, v2, v34
	v_mul_f32_e32 v3, v3, v34
	v_addc_co_u32_e32 v19, vcc, 0, v19, vcc
	v_cvt_pk_bf16_f32 v0, v0, v1
	v_cvt_pk_bf16_f32 v1, v2, v3
	global_store_dwordx2 v[18:19], v[16:17], off offset:2304
	v_mul_f32_e32 v16, v20, v34
	v_mul_f32_e32 v17, v21, v34
	v_mul_f32_e32 v18, v22, v34
	v_mul_f32_e32 v19, v23, v34
	global_store_dwordx2 v[32:33], v[0:1], off offset:64
	v_mul_f32_e32 v0, v4, v34
	v_mul_f32_e32 v1, v5, v34
	v_mul_f32_e32 v2, v6, v34
	v_mul_f32_e32 v3, v7, v34
	v_cvt_pk_bf16_f32 v16, v16, v17
	v_cvt_pk_bf16_f32 v17, v18, v19
	v_cvt_pk_bf16_f32 v0, v0, v1
	v_cvt_pk_bf16_f32 v1, v2, v3
	global_store_dwordx2 v[32:33], v[16:17], off offset:16
	v_mul_f32_e32 v16, v24, v34
	v_mul_f32_e32 v17, v25, v34
	v_mul_f32_e32 v18, v26, v34
	v_mul_f32_e32 v19, v27, v34
	global_store_dwordx2 v[32:33], v[0:1], off offset:80
	v_mul_f32_e32 v0, v8, v34
	v_mul_f32_e32 v1, v9, v34
	v_mul_f32_e32 v2, v10, v34
	v_mul_f32_e32 v3, v11, v34
	v_cvt_pk_bf16_f32 v16, v16, v17
	v_cvt_pk_bf16_f32 v17, v18, v19
	v_cvt_pk_bf16_f32 v0, v0, v1
	v_cvt_pk_bf16_f32 v1, v2, v3
	global_store_dwordx2 v[32:33], v[16:17], off offset:32
	v_mul_f32_e32 v16, v28, v34
	v_mul_f32_e32 v17, v29, v34
	v_mul_f32_e32 v18, v30, v34
	v_mul_f32_e32 v19, v31, v34
	global_store_dwordx2 v[32:33], v[0:1], off offset:96
	v_mul_f32_e32 v0, v12, v34
	v_mul_f32_e32 v1, v13, v34
	v_mul_f32_e32 v2, v14, v34
	v_mul_f32_e32 v3, v15, v34
	v_cvt_pk_bf16_f32 v16, v16, v17
	v_cvt_pk_bf16_f32 v17, v18, v19
	v_cvt_pk_bf16_f32 v0, v0, v1
	v_cvt_pk_bf16_f32 v1, v2, v3
	global_store_dwordx2 v[32:33], v[16:17], off offset:48
	global_store_dwordx2 v[32:33], v[0:1], off offset:112
	s_cbranch_execz .LBB0_1118
	s_branch .LBB0_1137

.LBB0_1127:
	s_or_b64 exec, exec, s[4:5]
	s_and_b32 s4, s6, 1
	s_mul_i32 s5, s4, 0x2400
	v_add_u32_e32 v91, s5, v88
	ds_read_b128 v[32:35], v91
	ds_read_b128 v[92:95], v91 offset:32
	v_lshl_add_u64 v[100:101], s[60:61], 1, v[78:79]
	s_xor_b32 s7, s4, 1
	s_mulk_i32 s7, 0x2400
	s_waitcnt lgkmcnt(1)
	v_mfma_f32_32x32x16_bf16 v[48:63], v[32:35], v[68:71], 0
	ds_read_b128 v[32:35], v91 offset:4608
	s_waitcnt lgkmcnt(1)
	v_mfma_f32_32x32x16_bf16 v[48:63], v[92:95], v[64:67], v[48:63]
	ds_read_b128 v[92:95], v91 offset:4640
	s_waitcnt lgkmcnt(1)
	v_mfma_f32_32x32x16_bf16 v[32:47], v[32:35], v[68:71], 0
	s_nop 8
	v_max_f32_e32 v91, v49, v49
	v_max_f32_e32 v97, v48, v48
	v_max_f32_e32 v91, v97, v91
	v_max3_f32 v91, v91, v50, v51
	v_max3_f32 v91, v91, v52, v53
	v_max3_f32 v91, v91, v54, v55
	v_max3_f32 v91, v91, v56, v57
	s_waitcnt lgkmcnt(0)
	v_mfma_f32_32x32x16_bf16 v[32:47], v[92:95], v[64:67], v[32:47]
	v_max3_f32 v91, v91, v58, v59
	v_max3_f32 v91, v91, v60, v61
	v_max3_f32 v91, v91, v62, v63
	s_nop 8
	v_max3_f32 v91, v91, v32, v33
	v_max3_f32 v91, v91, v34, v35
	v_max3_f32 v91, v91, v36, v37
	v_max3_f32 v91, v91, v38, v39
	v_max3_f32 v91, v91, v40, v41
	v_max3_f32 v91, v91, v42, v43
	v_max3_f32 v91, v91, v44, v45
	v_max3_f32 v91, v91, v46, v47
	ds_bpermute_b32 v92, v82, v91
	s_waitcnt lgkmcnt(0)
	v_max3_f32 v91, v86, v91, v92
	v_sub_f32_e32 v32, v32, v91
	v_sub_f32_e32 v97, v86, v91
	v_exp_f32_e32 v86, v32
	v_sub_f32_e32 v32, v33, v91
	v_exp_f32_e32 v92, v32
	v_sub_f32_e32 v32, v34, v91
	v_exp_f32_e32 v93, v32
	v_sub_f32_e32 v32, v35, v91
	v_exp_f32_e32 v94, v32
	v_sub_f32_e32 v32, v36, v91
	v_exp_f32_e32 v95, v32
	v_sub_f32_e32 v32, v37, v91
	v_exp_f32_e32 v37, v32
	global_load_dwordx4 v[32:35], v[100:101], off
	v_exp_f32_e32 v36, v97
	v_add_u32_e32 v97, s5, v84
	ds_read_b128 v[100:103], v97 offset:18432
	ds_read_b128 v[116:119], v97 offset:23040
	v_sub_f32_e32 v48, v48, v91
	v_sub_f32_e32 v49, v49, v91
	v_sub_f32_e32 v50, v50, v91
	v_sub_f32_e32 v51, v51, v91
	v_sub_f32_e32 v52, v52, v91
	v_sub_f32_e32 v53, v53, v91
	v_sub_f32_e32 v54, v54, v91
	v_sub_f32_e32 v55, v55, v91
	v_exp_f32_e32 v48, v48
	v_exp_f32_e32 v49, v49
	v_exp_f32_e32 v50, v50
	v_exp_f32_e32 v51, v51
	v_exp_f32_e32 v52, v52
	v_exp_f32_e32 v53, v53
	v_exp_f32_e32 v54, v54
	v_exp_f32_e32 v55, v55
	v_mul_f32_e32 v0, v0, v36
	v_mul_f32_e32 v1, v1, v36
	v_mul_f32_e32 v2, v2, v36
	v_mul_f32_e32 v3, v3, v36
	v_mul_f32_e32 v4, v4, v36
	v_mul_f32_e32 v5, v5, v36
	v_mul_f32_e32 v6, v6, v36
	v_mul_f32_e32 v7, v7, v36
	v_mul_f32_e32 v8, v8, v36
	v_mul_f32_e32 v9, v9, v36
	v_mul_f32_e32 v10, v10, v36
	v_mul_f32_e32 v11, v11, v36
	v_mul_f32_e32 v12, v12, v36
	v_mul_f32_e32 v13, v13, v36
	v_mul_f32_e32 v14, v14, v36
	v_mul_f32_e32 v15, v15, v36
	v_cvt_pk_bf16_f32 v104, v48, v49
	v_cvt_pk_bf16_f32 v105, v50, v51
	v_cvt_pk_bf16_f32 v106, v52, v53
	v_cvt_pk_bf16_f32 v107, v54, v55
	v_sub_f32_e32 v56, v56, v91
	v_sub_f32_e32 v57, v57, v91
	s_waitcnt lgkmcnt(1)
	v_mfma_f32_32x32x16_bf16 v[0:15], v[100:103], v[104:107], v[0:15]
	ds_read_b128 v[100:103], v97 offset:18464
	v_sub_f32_e32 v58, v58, v91
	v_sub_f32_e32 v59, v59, v91
	v_sub_f32_e32 v60, v60, v91
	v_sub_f32_e32 v61, v61, v91
	v_sub_f32_e32 v62, v62, v91
	v_sub_f32_e32 v63, v63, v91
	v_exp_f32_e32 v56, v56
	v_exp_f32_e32 v57, v57
	v_exp_f32_e32 v58, v58
	v_exp_f32_e32 v59, v59
	v_exp_f32_e32 v60, v60
	v_exp_f32_e32 v61, v61
	v_exp_f32_e32 v62, v62
	v_exp_f32_e32 v63, v63
	v_mul_f32_e32 v16, v16, v36
	v_mul_f32_e32 v17, v17, v36
	v_mul_f32_e32 v18, v18, v36
	v_mul_f32_e32 v19, v19, v36
	v_mul_f32_e32 v20, v20, v36
	v_mul_f32_e32 v21, v21, v36
	v_mul_f32_e32 v22, v22, v36
	v_mul_f32_e32 v23, v23, v36
	v_mul_f32_e32 v24, v24, v36
	v_mul_f32_e32 v25, v25, v36
	v_mul_f32_e32 v26, v26, v36
	v_mul_f32_e32 v27, v27, v36
	v_mul_f32_e32 v28, v28, v36
	v_mul_f32_e32 v29, v29, v36
	v_mul_f32_e32 v30, v30, v36
	v_mul_f32_e32 v31, v31, v36
	v_sub_f32_e32 v38, v38, v91
	v_sub_f32_e32 v39, v39, v91
	s_waitcnt lgkmcnt(1)
	v_mfma_f32_32x32x16_bf16 v[16:31], v[116:119], v[104:107], v[16:31]
	ds_read_b128 v[104:107], v97 offset:23072
	v_cvt_pk_bf16_f32 v116, v56, v57
	v_cvt_pk_bf16_f32 v117, v58, v59
	v_cvt_pk_bf16_f32 v118, v60, v61
	v_cvt_pk_bf16_f32 v119, v62, v63
	v_exp_f32_e32 v38, v38
	v_exp_f32_e32 v39, v39
	s_waitcnt lgkmcnt(1)
	v_mfma_f32_32x32x16_bf16 v[0:15], v[100:103], v[116:119], v[0:15]
	ds_read_b128 v[100:103], v97 offset:18496
	v_sub_f32_e32 v40, v40, v91
	v_sub_f32_e32 v41, v41, v91
	v_sub_f32_e32 v42, v42, v91
	v_sub_f32_e32 v43, v43, v91
	v_sub_f32_e32 v44, v44, v91
	v_sub_f32_e32 v45, v45, v91
	s_waitcnt lgkmcnt(1)
	v_mfma_f32_32x32x16_bf16 v[16:31], v[104:107], v[116:119], v[16:31]
	v_cvt_pk_bf16_f32 v104, v86, v92
	v_cvt_pk_bf16_f32 v105, v93, v94
	v_cvt_pk_bf16_f32 v106, v95, v37
	v_cvt_pk_bf16_f32 v107, v38, v39
	ds_read_b128 v[116:119], v97 offset:23104
	v_sub_f32_e32 v46, v46, v91
	v_sub_f32_e32 v47, v47, v91
	s_waitcnt lgkmcnt(1)
	v_mfma_f32_32x32x16_bf16 v[0:15], v[100:103], v[104:107], v[0:15]
	ds_read_b128 v[100:103], v97 offset:18528
	v_exp_f32_e32 v40, v40
	v_exp_f32_e32 v41, v41
	v_exp_f32_e32 v42, v42
	v_exp_f32_e32 v43, v43
	v_exp_f32_e32 v44, v44
	v_exp_f32_e32 v45, v45
	v_exp_f32_e32 v46, v46
	v_exp_f32_e32 v47, v47
	s_waitcnt lgkmcnt(1)
	v_mfma_f32_32x32x16_bf16 v[16:31], v[116:119], v[104:107], v[16:31]
	v_cvt_pk_bf16_f32 v104, v40, v41
	v_cvt_pk_bf16_f32 v105, v42, v43
	v_cvt_pk_bf16_f32 v106, v44, v45
	v_cvt_pk_bf16_f32 v107, v46, v47
	s_waitcnt lgkmcnt(0)
	s_nop 0
	v_mfma_f32_32x32x16_bf16 v[0:15], v[100:103], v[104:107], v[0:15]
	ds_read_b128 v[100:103], v97 offset:23136
	s_waitcnt lgkmcnt(0)
	v_mfma_f32_32x32x16_bf16 v[16:31], v[100:103], v[104:107], v[16:31]
	s_and_saveexec_b64 s[4:5], s[0:1]
	s_cbranch_execz .LBB0_1129
	v_add_u32_e32 v97, s7, v89
	s_waitcnt vmcnt(1)
	ds_write_b128 v97, v[72:75]
.LBB0_1129:
	s_or_b64 exec, exec, s[4:5]
	v_add_f32_e32 v48, 0, v48
	v_add_f32_e32 v48, v49, v48
	v_add_f32_e32 v48, v50, v48
	v_add_f32_e32 v48, v51, v48
	v_add_f32_e32 v48, v52, v48
	v_add_f32_e32 v48, v53, v48
	v_add_f32_e32 v48, v54, v48
	v_add_f32_e32 v48, v55, v48
	v_add_f32_e32 v48, v56, v48
	v_add_f32_e32 v48, v57, v48
	v_add_f32_e32 v48, v58, v48
	v_add_f32_e32 v48, v59, v48
	v_add_f32_e32 v48, v60, v48
	v_add_f32_e32 v48, v61, v48
	v_add_f32_e32 v48, v62, v48
	v_add_f32_e32 v48, v63, v48
	v_add_f32_e32 v48, v86, v48
	v_add_f32_e32 v48, v92, v48
	v_add_f32_e32 v48, v93, v48
	v_add_f32_e32 v48, v94, v48
	v_add_f32_e32 v48, v95, v48
	v_add_f32_e32 v37, v37, v48
	v_add_f32_e32 v37, v38, v37
	v_add_f32_e32 v37, v39, v37
	v_add_f32_e32 v37, v40, v37
	v_add_f32_e32 v37, v41, v37
	v_add_f32_e32 v37, v42, v37
	v_add_f32_e32 v37, v43, v37
	v_add_f32_e32 v37, v44, v37
	v_add_f32_e32 v37, v45, v37
	v_add_f32_e32 v37, v46, v37
	v_add_f32_e32 v86, v47, v37
	s_add_i32 s6, s6, 1
	s_add_i32 s60, s60, 64
	v_readlane_b32 s4, v253, 48
	v_fmac_f32_e32 v86, v90, v36
	v_add_u32_e32 v36, s7, v87
	s_cmp_eq_u32 s4, s6
	s_waitcnt vmcnt(0)
	ds_write_b128 v36, v[32:35] offset:18432
	s_waitcnt lgkmcnt(0)
	s_barrier
	s_cbranch_scc0 .LBB0_1125
	v_readlane_b32 s0, v253, 48
	s_bitcmp1_b32 s0, 0
	s_cselect_b32 s0, 0x2400, 0
	v_add_u32_e32 v72, s0, v88
	ds_read_b128 v[32:35], v72
	v_add_u32_e32 v74, s0, v84
	v_cmp_gt_u32_e32 vcc, 32, v112
	s_waitcnt lgkmcnt(0)
	v_mfma_f32_32x32x16_bf16 v[48:63], v[32:35], v[68:71], 0
	ds_read_b128 v[32:35], v72 offset:32
	s_waitcnt lgkmcnt(0)
	v_mfma_f32_32x32x16_bf16 v[48:63], v[32:35], v[64:67], v[48:63]
	ds_read_b128 v[32:35], v72 offset:4608
	s_waitcnt lgkmcnt(0)
	v_mfma_f32_32x32x16_bf16 v[32:47], v[32:35], v[68:71], 0
	ds_read_b128 v[68:71], v72 offset:4640
	s_nop 7
	v_max_f32_e32 v72, v49, v49
	v_max_f32_e32 v73, v48, v48
	v_max_f32_e32 v72, v73, v72
	v_max3_f32 v72, v72, v50, v51
	s_waitcnt lgkmcnt(0)
	v_mfma_f32_32x32x16_bf16 v[32:47], v[68:71], v[64:67], v[32:47]
	v_max3_f32 v64, v72, v52, v53
	v_max3_f32 v64, v64, v54, v55
	v_max3_f32 v64, v64, v56, v57
	v_max3_f32 v64, v64, v58, v59
	v_max3_f32 v64, v64, v60, v61
	v_max3_f32 v64, v64, v62, v63
	s_nop 5
	v_max3_f32 v64, v64, v32, v33
	v_max3_f32 v64, v64, v34, v35
	v_max3_f32 v64, v64, v36, v37
	v_max3_f32 v64, v64, v38, v39
	v_max3_f32 v64, v64, v40, v41
	v_max3_f32 v64, v64, v42, v43
	v_max3_f32 v64, v64, v44, v45
	v_max3_f32 v64, v64, v46, v47
	ds_bpermute_b32 v65, v82, v64
	s_waitcnt lgkmcnt(0)
	v_max3_f32 v64, v91, v64, v65
	v_sub_f32_e32 v48, v48, v64
	v_sub_f32_e32 v49, v49, v64
	v_exp_f32_e32 v48, v48
	v_sub_f32_e32 v50, v50, v64
	v_exp_f32_e32 v49, v49
	v_sub_f32_e32 v51, v51, v64
	v_exp_f32_e32 v50, v50
	v_sub_f32_e32 v52, v52, v64
	v_exp_f32_e32 v51, v51
	v_sub_f32_e32 v53, v53, v64
	v_exp_f32_e32 v52, v52
	v_add_f32_e32 v66, 0, v48
	v_sub_f32_e32 v54, v54, v64
	v_exp_f32_e32 v53, v53
	v_add_f32_e32 v66, v49, v66
	v_sub_f32_e32 v55, v55, v64
	v_exp_f32_e32 v54, v54
	v_add_f32_e32 v66, v50, v66
	v_sub_f32_e32 v56, v56, v64
	v_exp_f32_e32 v55, v55
	v_add_f32_e32 v66, v51, v66
	v_sub_f32_e32 v57, v57, v64
	v_exp_f32_e32 v56, v56
	v_add_f32_e32 v66, v52, v66
	v_sub_f32_e32 v58, v58, v64
	v_exp_f32_e32 v57, v57
	v_add_f32_e32 v66, v53, v66
	v_sub_f32_e32 v59, v59, v64
	v_exp_f32_e32 v58, v58
	v_add_f32_e32 v66, v54, v66
	v_exp_f32_e32 v59, v59
	v_add_f32_e32 v66, v55, v66
	v_sub_f32_e32 v60, v60, v64
	v_add_f32_e32 v66, v56, v66
	v_exp_f32_e32 v60, v60
	v_sub_f32_e32 v61, v61, v64
	v_add_f32_e32 v66, v57, v66
	v_exp_f32_e32 v61, v61
	v_sub_f32_e32 v62, v62, v64
	v_add_f32_e32 v66, v58, v66
	v_exp_f32_e32 v62, v62
	v_sub_f32_e32 v63, v63, v64
	v_add_f32_e32 v66, v59, v66
	v_exp_f32_e32 v63, v63
	v_sub_f32_e32 v32, v32, v64
	v_add_f32_e32 v66, v60, v66
	v_exp_f32_e32 v67, v32
	v_sub_f32_e32 v32, v33, v64
	v_add_f32_e32 v66, v61, v66
	v_exp_f32_e32 v33, v32
	v_sub_f32_e32 v34, v34, v64
	v_add_f32_e32 v32, v62, v66
	v_exp_f32_e32 v66, v34
	v_sub_f32_e32 v34, v35, v64
	v_add_f32_e32 v32, v63, v32
	v_exp_f32_e32 v68, v34
	v_sub_f32_e32 v34, v36, v64
	v_add_f32_e32 v32, v67, v32
	v_exp_f32_e32 v69, v34
	v_sub_f32_e32 v34, v37, v64
	v_add_f32_e32 v32, v33, v32
	v_exp_f32_e32 v70, v34
	v_add_f32_e32 v32, v66, v32
	v_add_f32_e32 v32, v68, v32
	v_add_f32_e32 v32, v69, v32
	v_sub_f32_e32 v65, v91, v64
	v_add_f32_e32 v71, v70, v32
	v_sub_f32_e32 v32, v38, v64
	v_sub_f32_e32 v34, v39, v64
	v_exp_f32_e32 v72, v32
	v_exp_f32_e32 v32, v65
	v_exp_f32_e32 v65, v34
	v_sub_f32_e32 v34, v40, v64
	v_exp_f32_e32 v73, v34
	ds_read_b128 v[34:37], v74 offset:18432
	v_mul_f32_e32 v14, v14, v32
	v_mul_f32_e32 v15, v15, v32
	v_mul_f32_e32 v12, v12, v32
	v_mul_f32_e32 v13, v13, v32
	v_mul_f32_e32 v10, v10, v32
	v_mul_f32_e32 v11, v11, v32
	v_mul_f32_e32 v8, v8, v32
	v_mul_f32_e32 v9, v9, v32
	v_mul_f32_e32 v6, v6, v32
	v_mul_f32_e32 v7, v7, v32
	v_mul_f32_e32 v4, v4, v32
	v_mul_f32_e32 v5, v5, v32
	v_mul_f32_e32 v2, v2, v32
	v_mul_f32_e32 v3, v3, v32
	v_mul_f32_e32 v0, v0, v32
	v_mul_f32_e32 v1, v1, v32
	v_cvt_pk_bf16_f32 v48, v48, v49
	v_cvt_pk_bf16_f32 v49, v50, v51
	v_cvt_pk_bf16_f32 v50, v52, v53
	v_cvt_pk_bf16_f32 v51, v54, v55
	ds_read_b128 v[52:55], v74 offset:23040
	v_mul_f32_e32 v30, v30, v32
	v_mul_f32_e32 v31, v31, v32
	s_waitcnt lgkmcnt(1)
	v_mfma_f32_32x32x16_bf16 v[0:15], v[34:37], v[48:51], v[0:15]
	ds_read_b128 v[34:37], v74 offset:18464
	v_mul_f32_e64 v28, v28, v32
	v_mul_f32_e64 v29, v29, v32
	v_mul_f32_e64 v26, v26, v32
	v_mul_f32_e64 v27, v27, v32
	v_mul_f32_e32 v24, v24, v32
	v_mul_f32_e32 v25, v25, v32
	v_mul_f32_e32 v22, v22, v32
	v_mul_f32_e32 v23, v23, v32
	v_mul_f32_e32 v20, v20, v32
	v_mul_f32_e32 v21, v21, v32
	v_mul_f32_e32 v18, v18, v32
	v_mul_f32_e32 v19, v19, v32
	v_mul_f32_e32 v16, v16, v32
	v_mul_f32_e32 v17, v17, v32
	v_sub_f32_e32 v38, v41, v64
	v_cvt_pk_bf16_f32 v39, v58, v59
	s_waitcnt lgkmcnt(1)
	v_mfma_f32_32x32x16_bf16 v[16:31], v[52:55], v[48:51], v[16:31]
	v_exp_f32_e32 v52, v38
	v_cvt_pk_bf16_f32 v38, v56, v57
	v_cvt_pk_bf16_f32 v40, v60, v61
	v_cvt_pk_bf16_f32 v41, v62, v63
	ds_read_b128 v[48:51], v74 offset:23072
	s_waitcnt lgkmcnt(1)
	v_mfma_f32_32x32x16_bf16 v[0:15], v[34:37], v[38:41], v[0:15]
	v_add_f32_e32 v34, v72, v71
	v_add_f32_e32 v34, v65, v34
	v_add_f32_e32 v34, v73, v34
	v_add_f32_e32 v53, v52, v34
	v_sub_f32_e32 v34, v42, v64
	v_exp_f32_e32 v54, v34
	ds_read_b128 v[34:37], v74 offset:18496
	s_waitcnt lgkmcnt(1)
	v_mfma_f32_32x32x16_bf16 v[16:31], v[48:51], v[38:41], v[16:31]
	ds_read_b128 v[48:51], v74 offset:23104
	v_sub_f32_e32 v38, v43, v64
	v_exp_f32_e32 v55, v38
	v_cvt_pk_bf16_f32 v38, v67, v33
	v_cvt_pk_bf16_f32 v39, v66, v68
	v_cvt_pk_bf16_f32 v40, v69, v70
	v_cvt_pk_bf16_f32 v41, v72, v65
	v_sub_f32_e32 v33, v44, v64
	v_exp_f32_e32 v33, v33
	s_waitcnt lgkmcnt(1)
	v_mfma_f32_32x32x16_bf16 v[0:15], v[34:37], v[38:41], v[0:15]
	v_sub_f32_e32 v34, v45, v64
	v_exp_f32_e32 v56, v34
	v_sub_f32_e32 v34, v46, v64
	v_exp_f32_e32 v46, v34
	ds_read_b128 v[34:37], v74 offset:18528
	ds_read_b128 v[42:45], v74 offset:23136
	s_waitcnt lgkmcnt(0)
	v_mfma_f32_32x32x16_bf16 v[16:31], v[48:51], v[38:41], v[16:31]
	v_sub_f32_e32 v38, v47, v64
	v_exp_f32_e32 v47, v38
	v_cvt_pk_bf16_f32 v38, v73, v52
	v_cvt_pk_bf16_f32 v39, v54, v55
	v_cvt_pk_bf16_f32 v40, v33, v56
	v_cvt_pk_bf16_f32 v41, v46, v47
	s_barrier
	s_nop 0
	v_mfma_f32_32x32x16_bf16 v[0:15], v[34:37], v[38:41], v[0:15]
	v_add_f32_e32 v34, v54, v53
	v_add_f32_e32 v34, v55, v34
	v_add_f32_e32 v33, v33, v34
	v_add_f32_e32 v33, v56, v33
	v_add_f32_e32 v33, v46, v33
	v_add_f32_e32 v34, v47, v33
	v_fmac_f32_e32 v34, v86, v32
	v_mfma_f32_32x32x16_bf16 v[16:31], v[42:45], v[38:41], v[16:31]
	ds_bpermute_b32 v35, v82, v34
	v_mov_b32_e32 v32, 0
	v_mov_b32_e32 v33, 0
	s_and_saveexec_b64 s[0:1], vcc
	s_cbranch_execz .LBB0_1132
	v_or_b32_e32 v128, s27, v112
	v_readlane_b32 s36, v250, 21
	v_lshlrev_b64 v[32:33], 2, v[128:129]
	v_readlane_b32 s40, v250, 25
	v_readlane_b32 s41, v250, 26
	v_readlane_b32 s42, v250, 27
	v_readlane_b32 s43, v250, 28
	v_readlane_b32 s44, v250, 29
	v_readlane_b32 s45, v250, 30
	v_readlane_b32 s46, v250, 31
	v_readlane_b32 s47, v250, 32
	v_lshl_add_u64 v[36:37], s[40:41], 0, v[32:33]
	v_lshl_add_u64 v[38:39], s[42:43], 0, v[32:33]
	v_lshl_add_u64 v[40:41], s[44:45], 0, v[32:33]
	v_lshl_add_u64 v[32:33], s[46:47], 0, v[32:33]
	global_load_dword v37, v[36:37], off
	v_readlane_b32 s37, v250, 22
	global_load_dword v39, v[38:39], off
	v_readlane_b32 s38, v250, 23
	global_load_dword v36, v[40:41], off
	global_load_dword v38, v[32:33], off
	v_readlane_b32 s39, v250, 24
	v_readlane_b32 s48, v250, 33
	v_readlane_b32 s49, v250, 34
	v_readlane_b32 s50, v250, 35
	v_readlane_b32 s51, v250, 36
	s_waitcnt vmcnt(0)
	v_pk_mul_f32 v[32:33], v[36:37], v[38:39]

.LBB0_1154:
	s_or_b64 exec, exec, s[4:5]
	s_and_b32 s4, s6, 1
	s_mul_i32 s5, s4, 0x3400
	v_add_u32_e32 v123, s5, v118
	ds_read_b128 v[32:35], v123
	ds_read_b128 v[130:133], v123 offset:6688
	s_mul_i32 s5, s4, 0x2400
	v_add_u32_e32 v142, s5, v99
	s_xor_b32 s7, s4, 1
	s_mul_i32 s4, s7, 0x3400
	s_add_i32 s8, s4, 0
	s_waitcnt lgkmcnt(1)
	v_mfma_f32_32x32x16_bf16 v[48:63], v[32:35], v[84:87], 0
	ds_read_b128 v[32:35], v123 offset:32
	s_waitcnt lgkmcnt(0)
	v_mfma_f32_32x32x16_bf16 v[48:63], v[32:35], v[80:83], v[48:63]
	ds_read_b128 v[32:35], v123 offset:64
	s_waitcnt lgkmcnt(0)
	v_mfma_f32_32x32x16_bf16 v[48:63], v[32:35], v[76:79], v[48:63]
	ds_read_b128 v[32:35], v123 offset:96
	s_waitcnt lgkmcnt(0)
	v_mfma_f32_32x32x16_bf16 v[48:63], v[32:35], v[72:75], v[48:63]
	ds_read_b128 v[32:35], v123 offset:128
	s_waitcnt lgkmcnt(0)
	v_mfma_f32_32x32x16_bf16 v[48:63], v[32:35], v[68:71], v[48:63]
	ds_read_b128 v[32:35], v123 offset:160
	s_waitcnt lgkmcnt(0)
	v_mfma_f32_32x32x16_bf16 v[48:63], v[32:35], v[64:67], v[48:63]
	ds_read_b128 v[32:35], v123 offset:6656
	s_waitcnt lgkmcnt(0)
	v_mfma_f32_32x32x16_bf16 v[32:47], v[32:35], v[84:87], 0
	s_nop 8
	v_max_f32_e32 v125, v48, v48
	v_mfma_f32_32x32x16_bf16 v[32:47], v[130:133], v[80:83], v[32:47]
	ds_read_b128 v[130:133], v123 offset:6720
	s_waitcnt lgkmcnt(0)
	v_mfma_f32_32x32x16_bf16 v[32:47], v[130:133], v[76:79], v[32:47]
	ds_read_b128 v[130:133], v123 offset:6752
	s_waitcnt lgkmcnt(0)
	v_mfma_f32_32x32x16_bf16 v[32:47], v[130:133], v[72:75], v[32:47]
	ds_read_b128 v[130:133], v123 offset:6784
	ds_read_b128 v[134:137], v123 offset:6816
	v_max_f32_e32 v123, v49, v49
	v_max_f32_e32 v123, v125, v123
	v_max3_f32 v123, v123, v50, v51
	v_max3_f32 v123, v123, v52, v53
	v_max3_f32 v123, v123, v54, v55
	v_max3_f32 v123, v123, v56, v57
	s_waitcnt lgkmcnt(1)
	v_mfma_f32_32x32x16_bf16 v[32:47], v[130:133], v[68:71], v[32:47]
	v_max3_f32 v123, v123, v58, v59
	v_max3_f32 v123, v123, v60, v61
	v_max3_f32 v123, v123, v62, v63
	v_lshl_add_u64 v[130:131], s[60:61], 1, v[102:103]
	ds_read_b128 v[138:141], v142 offset:31232
	s_waitcnt lgkmcnt(1)
	v_mfma_f32_32x32x16_bf16 v[32:47], v[134:137], v[64:67], v[32:47]
	s_nop 11
	v_max3_f32 v123, v123, v32, v33
	v_max3_f32 v123, v123, v34, v35
	v_max3_f32 v123, v123, v36, v37
	v_max3_f32 v123, v123, v38, v39
	v_max3_f32 v123, v123, v40, v41
	v_max3_f32 v123, v123, v42, v43
	v_max3_f32 v123, v123, v44, v45
	v_max3_f32 v123, v123, v46, v47
	ds_bpermute_b32 v125, v97, v123
	s_waitcnt lgkmcnt(0)
	v_max3_f32 v123, v124, v123, v125
	v_sub_f32_e32 v32, v32, v123
	v_sub_f32_e32 v132, v124, v123
	v_exp_f32_e32 v124, v32
	v_sub_f32_e32 v32, v33, v123
	v_exp_f32_e32 v125, v32
	v_sub_f32_e32 v32, v34, v123
	v_exp_f32_e32 v126, v32
	v_sub_f32_e32 v32, v35, v123
	v_exp_f32_e32 v127, v32
	v_sub_f32_e32 v32, v36, v123
	v_exp_f32_e32 v128, v32
	v_sub_f32_e32 v32, v37, v123
	v_exp_f32_e32 v37, v32
	global_load_dwordx4 v[32:35], v[130:131], off
	v_exp_f32_e32 v36, v132
	ds_read_b128 v[130:133], v142 offset:26624
	v_sub_f32_e32 v48, v48, v123
	v_sub_f32_e32 v49, v49, v123
	v_sub_f32_e32 v50, v50, v123
	v_sub_f32_e32 v51, v51, v123
	v_sub_f32_e32 v52, v52, v123
	v_sub_f32_e32 v53, v53, v123
	v_sub_f32_e32 v54, v54, v123
	v_sub_f32_e32 v55, v55, v123
	v_exp_f32_e32 v48, v48
	v_exp_f32_e32 v49, v49
	v_exp_f32_e32 v50, v50
	v_exp_f32_e32 v51, v51
	v_exp_f32_e32 v52, v52
	v_exp_f32_e32 v53, v53
	v_exp_f32_e32 v54, v54
	v_exp_f32_e32 v55, v55
	v_mul_f32_e32 v16, v16, v36
	v_mul_f32_e32 v17, v17, v36
	v_mul_f32_e32 v18, v18, v36
	v_mul_f32_e32 v19, v19, v36
	v_mul_f32_e32 v20, v20, v36
	v_mul_f32_e32 v21, v21, v36
	v_mul_f32_e32 v22, v22, v36
	v_mul_f32_e32 v23, v23, v36
	v_mul_f32_e32 v24, v24, v36
	v_mul_f32_e32 v25, v25, v36
	v_mul_f32_e32 v26, v26, v36
	v_mul_f32_e32 v27, v27, v36
	v_mul_f32_e32 v28, v28, v36
	v_mul_f32_e32 v29, v29, v36
	v_mul_f32_e32 v30, v30, v36
	v_mul_f32_e32 v31, v31, v36
	v_cvt_pk_bf16_f32 v134, v48, v49
	v_cvt_pk_bf16_f32 v135, v50, v51
	v_cvt_pk_bf16_f32 v136, v52, v53
	v_cvt_pk_bf16_f32 v137, v54, v55
	v_sub_f32_e32 v56, v56, v123
	v_sub_f32_e32 v57, v57, v123
	s_waitcnt lgkmcnt(0)
	v_mfma_f32_32x32x16_bf16 v[16:31], v[130:133], v[134:137], v[16:31]
	ds_read_b128 v[130:133], v142 offset:26656
	v_sub_f32_e32 v58, v58, v123
	v_sub_f32_e32 v59, v59, v123
	v_sub_f32_e32 v60, v60, v123
	v_sub_f32_e32 v61, v61, v123
	v_sub_f32_e32 v62, v62, v123
	v_sub_f32_e32 v63, v63, v123
	v_exp_f32_e32 v56, v56
	v_exp_f32_e32 v57, v57
	v_exp_f32_e32 v58, v58
	v_exp_f32_e32 v59, v59
	v_exp_f32_e32 v60, v60
	v_exp_f32_e32 v61, v61
	v_exp_f32_e32 v62, v62
	v_exp_f32_e32 v63, v63
	v_mul_f32_e32 v0, v0, v36
	v_mul_f32_e32 v1, v1, v36
	v_mul_f32_e32 v2, v2, v36
	v_mul_f32_e32 v3, v3, v36
	v_mul_f32_e32 v4, v4, v36
	v_mul_f32_e32 v5, v5, v36
	v_mul_f32_e32 v6, v6, v36
	v_mul_f32_e32 v7, v7, v36
	v_mul_f32_e32 v8, v8, v36
	v_mul_f32_e32 v9, v9, v36
	v_mul_f32_e32 v10, v10, v36
	v_mul_f32_e32 v11, v11, v36
	v_mul_f32_e32 v12, v12, v36
	v_mul_f32_e32 v13, v13, v36
	v_mul_f32_e32 v14, v14, v36
	v_mul_f32_e32 v15, v15, v36
	v_sub_f32_e32 v38, v38, v123
	v_sub_f32_e32 v39, v39, v123
	v_mfma_f32_32x32x16_bf16 v[0:15], v[138:141], v[134:137], v[0:15]
	ds_read_b128 v[134:137], v142 offset:31264
	v_cvt_pk_bf16_f32 v138, v56, v57
	v_cvt_pk_bf16_f32 v139, v58, v59
	v_cvt_pk_bf16_f32 v140, v60, v61
	v_cvt_pk_bf16_f32 v141, v62, v63
	v_exp_f32_e32 v38, v38
	v_exp_f32_e32 v39, v39
	s_waitcnt lgkmcnt(1)
	v_mfma_f32_32x32x16_bf16 v[16:31], v[130:133], v[138:141], v[16:31]
	ds_read_b128 v[130:133], v142 offset:26688
	v_sub_f32_e32 v40, v40, v123
	v_sub_f32_e32 v41, v41, v123
	v_sub_f32_e32 v42, v42, v123
	v_sub_f32_e32 v43, v43, v123
	v_sub_f32_e32 v44, v44, v123
	v_sub_f32_e32 v45, v45, v123
	s_waitcnt lgkmcnt(1)
	v_mfma_f32_32x32x16_bf16 v[0:15], v[134:137], v[138:141], v[0:15]
	v_cvt_pk_bf16_f32 v134, v124, v125
	v_cvt_pk_bf16_f32 v135, v126, v127
	v_cvt_pk_bf16_f32 v136, v128, v37
	v_cvt_pk_bf16_f32 v137, v38, v39
	ds_read_b128 v[138:141], v142 offset:31296
	v_sub_f32_e32 v46, v46, v123
	v_sub_f32_e32 v47, v47, v123
	s_waitcnt lgkmcnt(1)
	v_mfma_f32_32x32x16_bf16 v[16:31], v[130:133], v[134:137], v[16:31]
	ds_read_b128 v[130:133], v142 offset:26720
	v_exp_f32_e32 v40, v40
	v_exp_f32_e32 v41, v41
	v_exp_f32_e32 v42, v42
	v_exp_f32_e32 v43, v43
	v_exp_f32_e32 v44, v44
	v_exp_f32_e32 v45, v45
	v_exp_f32_e32 v46, v46
	v_exp_f32_e32 v47, v47
	s_waitcnt lgkmcnt(1)
	v_mfma_f32_32x32x16_bf16 v[0:15], v[138:141], v[134:137], v[0:15]
	v_cvt_pk_bf16_f32 v134, v40, v41
	v_cvt_pk_bf16_f32 v135, v42, v43
	v_cvt_pk_bf16_f32 v136, v44, v45
	v_cvt_pk_bf16_f32 v137, v46, v47
	s_waitcnt lgkmcnt(0)
	s_nop 0
	v_mfma_f32_32x32x16_bf16 v[16:31], v[130:133], v[134:137], v[16:31]
	ds_read_b128 v[130:133], v142 offset:31328
	s_waitcnt lgkmcnt(0)
	v_mfma_f32_32x32x16_bf16 v[0:15], v[130:133], v[134:137], v[0:15]
	s_and_saveexec_b64 s[4:5], s[0:1]
	s_cbranch_execz .LBB0_1156
	v_add3_u32 v130, s8, v120, v121
	s_waitcnt vmcnt(1)
	ds_write_b128 v130, v[88:91]

.LBB0_1158:
	s_or_b64 exec, exec, s[4:5]
	v_add_f32_e32 v48, 0, v48
	v_add_f32_e32 v48, v49, v48
	v_add_f32_e32 v48, v50, v48
	v_add_f32_e32 v48, v51, v48
	v_add_f32_e32 v48, v52, v48
	v_add_f32_e32 v48, v53, v48
	v_add_f32_e32 v48, v54, v48
	v_add_f32_e32 v48, v55, v48
	v_add_f32_e32 v48, v56, v48
	v_add_f32_e32 v48, v57, v48
	v_add_f32_e32 v48, v58, v48
	v_add_f32_e32 v48, v59, v48
	v_add_f32_e32 v48, v60, v48
	v_add_f32_e32 v48, v61, v48
	v_add_f32_e32 v48, v62, v48
	v_add_f32_e32 v48, v63, v48
	v_add_f32_e32 v48, v124, v48
	v_add_f32_e32 v48, v125, v48
	v_add_f32_e32 v48, v126, v48
	v_add_f32_e32 v48, v127, v48
	v_add_f32_e32 v48, v128, v48
	v_add_f32_e32 v37, v37, v48
	v_add_f32_e32 v37, v38, v37
	v_add_f32_e32 v37, v39, v37
	v_add_f32_e32 v37, v40, v37
	v_add_f32_e32 v37, v41, v37
	v_add_f32_e32 v37, v42, v37
	v_add_f32_e32 v37, v43, v37
	v_add_f32_e32 v37, v44, v37
	v_add_f32_e32 v37, v45, v37
	v_add_f32_e32 v37, v46, v37
	v_add_f32_e32 v124, v47, v37
	s_add_i32 s6, s6, 1
	s_mulk_i32 s7, 0x2400
	s_add_i32 s60, s60, 64
	v_readlane_b32 s4, v253, 49
	v_fmac_f32_e32 v124, v122, v36
	v_add_u32_e32 v36, s7, v117
	s_cmp_eq_u32 s4, s6
	s_waitcnt vmcnt(0)
	ds_write_b128 v36, v[32:35] offset:26624
	s_waitcnt lgkmcnt(0)
	s_barrier
	s_cbranch_scc0 .LBB0_1150
	v_readlane_b32 s0, v253, 49
	s_and_b32 s0, s0, 1
	s_mul_i32 s1, s0, 0x3400
	v_add_u32_e32 v88, s1, v118
	ds_read_b128 v[32:35], v88
	s_mulk_i32 s0, 0x2400
	v_lshlrev_b32_e32 v128, 3, v108
	s_waitcnt lgkmcnt(0)
	v_mfma_f32_32x32x16_bf16 v[48:63], v[32:35], v[84:87], 0
	ds_read_b128 v[32:35], v88 offset:32
	s_waitcnt lgkmcnt(0)
	v_mfma_f32_32x32x16_bf16 v[48:63], v[32:35], v[80:83], v[48:63]
	ds_read_b128 v[32:35], v88 offset:64
	s_waitcnt lgkmcnt(0)
	v_mfma_f32_32x32x16_bf16 v[48:63], v[32:35], v[76:79], v[48:63]
	ds_read_b128 v[32:35], v88 offset:96
	s_waitcnt lgkmcnt(0)
	v_mfma_f32_32x32x16_bf16 v[48:63], v[32:35], v[72:75], v[48:63]
	ds_read_b128 v[32:35], v88 offset:128
	s_waitcnt lgkmcnt(0)
	v_mfma_f32_32x32x16_bf16 v[48:63], v[32:35], v[68:71], v[48:63]
	ds_read_b128 v[32:35], v88 offset:160
	s_waitcnt lgkmcnt(0)
	v_mfma_f32_32x32x16_bf16 v[48:63], v[32:35], v[64:67], v[48:63]
	ds_read_b128 v[32:35], v88 offset:6656
	s_waitcnt lgkmcnt(0)
	v_mfma_f32_32x32x16_bf16 v[32:47], v[32:35], v[84:87], 0
	ds_read_b128 v[84:87], v88 offset:6688
	s_waitcnt lgkmcnt(0)
	v_mfma_f32_32x32x16_bf16 v[32:47], v[84:87], v[80:83], v[32:47]
	ds_read_b128 v[80:83], v88 offset:6720
	s_waitcnt lgkmcnt(0)
	v_mfma_f32_32x32x16_bf16 v[32:47], v[80:83], v[76:79], v[32:47]
	ds_read_b128 v[76:79], v88 offset:6752
	s_nop 1
	v_max_f32_e32 v80, v49, v49
	v_max_f32_e32 v81, v48, v48
	v_max_f32_e32 v80, v81, v80
	s_waitcnt lgkmcnt(0)
	v_mfma_f32_32x32x16_bf16 v[32:47], v[76:79], v[72:75], v[32:47]
	ds_read_b128 v[72:75], v88 offset:6784
	ds_read_b128 v[76:79], v88 offset:6816
	s_waitcnt lgkmcnt(1)
	v_mfma_f32_32x32x16_bf16 v[32:47], v[72:75], v[68:71], v[32:47]
	v_max3_f32 v68, v80, v50, v51
	v_max3_f32 v68, v68, v52, v53
	v_max3_f32 v68, v68, v54, v55
	v_max3_f32 v68, v68, v56, v57
	v_max3_f32 v68, v68, v58, v59
	v_max3_f32 v68, v68, v60, v61
	v_max3_f32 v68, v68, v62, v63
	s_waitcnt lgkmcnt(0)
	v_mfma_f32_32x32x16_bf16 v[32:47], v[76:79], v[64:67], v[32:47]
	v_add_u32_e32 v75, s0, v99
	s_nop 10
	v_max3_f32 v64, v68, v32, v33
	v_max3_f32 v64, v64, v34, v35
	v_max3_f32 v64, v64, v36, v37
	v_max3_f32 v64, v64, v38, v39
	v_max3_f32 v64, v64, v40, v41
	v_max3_f32 v64, v64, v42, v43
	v_max3_f32 v64, v64, v44, v45
	v_max3_f32 v64, v64, v46, v47
	ds_bpermute_b32 v65, v97, v64
	s_waitcnt lgkmcnt(0)
	v_max3_f32 v64, v123, v64, v65
	v_sub_f32_e32 v48, v48, v64
	v_exp_f32_e32 v48, v48
	v_sub_f32_e32 v49, v49, v64
	v_exp_f32_e32 v49, v49
	v_sub_f32_e32 v50, v50, v64
	v_exp_f32_e32 v50, v50
	v_sub_f32_e32 v51, v51, v64
	v_exp_f32_e32 v51, v51
	v_sub_f32_e32 v52, v52, v64
	v_add_f32_e32 v66, 0, v48
	v_exp_f32_e32 v52, v52
	v_sub_f32_e32 v53, v53, v64
	v_add_f32_e32 v66, v49, v66
	v_exp_f32_e32 v53, v53
	v_sub_f32_e32 v54, v54, v64
	v_add_f32_e32 v66, v50, v66
	v_exp_f32_e32 v54, v54
	v_sub_f32_e32 v55, v55, v64
	v_add_f32_e32 v66, v51, v66
	v_exp_f32_e32 v55, v55
	v_sub_f32_e32 v56, v56, v64
	v_add_f32_e32 v66, v52, v66
	v_exp_f32_e32 v67, v56
	v_sub_f32_e32 v56, v57, v64
	v_add_f32_e32 v66, v53, v66
	v_exp_f32_e32 v57, v56
	v_sub_f32_e32 v56, v58, v64
	v_add_f32_e32 v66, v54, v66
	v_exp_f32_e32 v58, v56
	v_sub_f32_e32 v56, v59, v64
	v_sub_f32_e32 v32, v32, v64
	v_exp_f32_e32 v59, v56
	v_sub_f32_e32 v56, v60, v64
	v_exp_f32_e32 v68, v32
	v_sub_f32_e32 v32, v33, v64
	v_add_f32_e32 v33, v55, v66
	v_exp_f32_e32 v60, v56
	v_sub_f32_e32 v56, v61, v64
	v_add_f32_e32 v33, v67, v33
	v_exp_f32_e32 v61, v56
	v_sub_f32_e32 v56, v62, v64
	v_add_f32_e32 v33, v57, v33
	v_exp_f32_e32 v62, v56
	v_sub_f32_e32 v56, v63, v64
	v_add_f32_e32 v33, v58, v33
	v_exp_f32_e32 v63, v56
	v_add_f32_e32 v33, v59, v33
	v_add_f32_e32 v33, v60, v33
	v_exp_f32_e32 v69, v32
	v_sub_f32_e32 v32, v34, v64
	v_add_f32_e32 v33, v61, v33
	v_exp_f32_e32 v70, v32
	v_sub_f32_e32 v32, v35, v64
	v_add_f32_e32 v33, v62, v33
	v_add_f32_e32 v33, v63, v33
	v_exp_f32_e32 v66, v32
	v_sub_f32_e32 v32, v36, v64
	v_add_f32_e32 v33, v68, v33
	v_exp_f32_e32 v71, v32
	v_sub_f32_e32 v32, v37, v64
	v_add_f32_e32 v33, v69, v33
	v_exp_f32_e32 v72, v32
	v_sub_f32_e32 v32, v38, v64
	v_add_f32_e32 v33, v70, v33
	v_exp_f32_e32 v73, v32
	v_add_f32_e32 v32, v66, v33
	v_add_f32_e32 v32, v71, v32
	v_add_f32_e32 v32, v72, v32
	v_sub_f32_e32 v65, v123, v64
	v_add_f32_e32 v74, v73, v32
	v_sub_f32_e32 v32, v39, v64
	v_exp_f32_e32 v56, v65
	v_exp_f32_e32 v65, v32
	ds_read_b128 v[32:35], v75 offset:26624
	v_cvt_pk_bf16_f32 v36, v48, v49
	v_cvt_pk_bf16_f32 v37, v50, v51
	v_cvt_pk_bf16_f32 v38, v52, v53
	v_cvt_pk_bf16_f32 v39, v54, v55
	ds_read_b128 v[48:51], v75 offset:31232
	ds_read_b128 v[52:55], v75 offset:26656
	v_mul_f32_e32 v30, v30, v56
	v_mul_f32_e32 v31, v31, v56
	v_mul_f32_e32 v28, v28, v56
	v_mul_f32_e32 v29, v29, v56
	v_mul_f32_e32 v26, v26, v56
	v_mul_f32_e32 v27, v27, v56
	v_mul_f32_e32 v24, v24, v56
	v_mul_f32_e32 v25, v25, v56
	v_mul_f32_e32 v22, v22, v56
	v_mul_f32_e32 v23, v23, v56
	v_mul_f32_e32 v20, v20, v56
	v_mul_f32_e32 v21, v21, v56
	v_mul_f32_e32 v18, v18, v56
	v_mul_f32_e32 v19, v19, v56
	v_mul_f32_e32 v16, v16, v56
	v_mul_f32_e32 v17, v17, v56
	v_mul_f32_e32 v14, v14, v56
	v_mul_f32_e32 v15, v15, v56
	v_mul_f32_e32 v12, v12, v56
	v_mul_f32_e32 v13, v13, v56
	s_waitcnt lgkmcnt(2)
	v_mfma_f32_32x32x16_bf16 v[16:31], v[32:35], v[36:39], v[16:31]
	v_mul_f32_e64 v10, v10, v56
	v_mul_f32_e64 v11, v11, v56
	v_mul_f32_e64 v8, v8, v56
	v_mul_f32_e64 v9, v9, v56
	v_mul_f32_e64 v6, v6, v56
	v_mul_f32_e64 v7, v7, v56
	v_mul_f32_e32 v4, v4, v56
	v_mul_f32_e32 v5, v5, v56
	v_mul_f32_e32 v2, v2, v56
	v_mul_f32_e32 v3, v3, v56
	v_mul_f32_e32 v0, v0, v56
	v_mul_f32_e32 v1, v1, v56
	ds_read_b128 v[32:35], v75 offset:31264
	v_sub_f32_e32 v40, v40, v64
	s_waitcnt lgkmcnt(2)
	v_mfma_f32_32x32x16_bf16 v[0:15], v[48:51], v[36:39], v[0:15]
	v_exp_f32_e32 v76, v40
	v_sub_f32_e32 v36, v41, v64
	v_exp_f32_e32 v77, v36
	v_cvt_pk_bf16_f32 v36, v67, v57
	v_cvt_pk_bf16_f32 v37, v58, v59
	v_cvt_pk_bf16_f32 v38, v60, v61
	v_cvt_pk_bf16_f32 v39, v62, v63
	v_sub_f32_e32 v40, v42, v64
	ds_read_b128 v[48:51], v75 offset:26688
	s_waitcnt lgkmcnt(2)
	v_mfma_f32_32x32x16_bf16 v[16:31], v[52:55], v[36:39], v[16:31]
	v_exp_f32_e32 v52, v40
	v_add_f32_e32 v40, v65, v74
	v_add_f32_e32 v40, v76, v40
	v_add_f32_e32 v40, v77, v40
	v_add_f32_e32 v53, v52, v40
	v_sub_f32_e32 v54, v43, v64
	v_exp_f32_e32 v54, v54
	s_waitcnt lgkmcnt(1)
	v_mfma_f32_32x32x16_bf16 v[0:15], v[32:35], v[36:39], v[0:15]
	ds_read_b128 v[36:39], v75 offset:31296
	ds_read_b128 v[40:43], v75 offset:26720
	v_sub_f32_e32 v44, v44, v64
	v_cvt_pk_bf16_f32 v32, v68, v69
	v_cvt_pk_bf16_f32 v33, v70, v66
	v_cvt_pk_bf16_f32 v34, v71, v72
	v_cvt_pk_bf16_f32 v35, v73, v65
	v_exp_f32_e32 v44, v44
	v_sub_f32_e32 v45, v45, v64
	s_waitcnt lgkmcnt(2)
	v_mfma_f32_32x32x16_bf16 v[16:31], v[48:51], v[32:35], v[16:31]
	v_exp_f32_e32 v45, v45
	v_sub_f32_e32 v46, v46, v64
	ds_read_b128 v[48:51], v75 offset:31328
	s_waitcnt lgkmcnt(0)
	s_barrier
	v_mfma_f32_32x32x16_bf16 v[0:15], v[36:39], v[32:35], v[0:15]
	v_sub_f32_e32 v32, v47, v64
	v_exp_f32_e32 v36, v46
	v_exp_f32_e32 v37, v32
	v_add_f32_e32 v38, v54, v53
	v_add_f32_e32 v38, v44, v38
	v_add_f32_e32 v38, v45, v38
	v_cvt_pk_bf16_f32 v35, v36, v37
	v_add_f32_e32 v36, v36, v38
	v_add_f32_e32 v36, v37, v36
	v_fmac_f32_e32 v36, v124, v56
	ds_bpermute_b32 v37, v97, v36
	v_cvt_pk_bf16_f32 v32, v76, v77
	v_cvt_pk_bf16_f32 v33, v52, v54
	v_cvt_pk_bf16_f32 v34, v44, v45
	s_nop 1
	v_mfma_f32_32x32x16_bf16 v[16:31], v[40:43], v[32:35], v[16:31]
	v_mfma_f32_32x32x16_bf16 v[0:15], v[48:51], v[32:35], v[0:15]
	s_waitcnt lgkmcnt(0)
	v_add_f32_e32 v34, v36, v37
	v_div_scale_f32 v35, s[0:1], v34, v34, 1.0
	v_rcp_f32_e32 v36, v35
	v_lshlrev_b64 v[32:33], 11, v[100:101]
	v_readlane_b32 s0, v252, 50
	v_lshl_add_u64 v[32:33], s[66:67], 0, v[32:33]
	v_fma_f32 v37, -v35, v36, 1.0
	v_fmac_f32_e32 v36, v37, v36
	v_div_scale_f32 v37, vcc, 1.0, v34, 1.0
	v_mul_f32_e32 v38, v37, v36
	v_fma_f32 v39, -v35, v38, v37
	v_fmac_f32_e32 v38, v39, v36
	v_fma_f32 v35, -v35, v38, v37
	v_div_fmas_f32 v35, v35, v36, v38
	s_lshl_b32 s60, s0, 1
	v_div_fixup_f32 v34, v35, v34, 1.0
	v_lshl_add_u64 v[32:33], v[32:33], 0, s[60:61]
	v_mul_f32_e32 v16, v16, v34
	v_mul_f32_e32 v17, v17, v34
	v_mul_f32_e32 v18, v18, v34
	v_mul_f32_e32 v19, v19, v34
	v_cvt_pk_bf16_f32 v16, v16, v17
	v_cvt_pk_bf16_f32 v17, v18, v19
	v_lshl_add_u64 v[18:19], v[32:33], 0, v[128:129]
	s_mov_b64 s[0:1], 0x2d53d00
	v_lshl_add_u64 v[32:33], v[18:19], 0, s[0:1]
	s_mov_b32 s0, 0x2d53000
	v_add_co_u32_e32 v18, vcc, s0, v18
	v_mul_f32_e32 v0, v0, v34
	v_mul_f32_e32 v1, v1, v34
	v_mul_f32_e32 v2, v2, v34
	v_mul_f32_e32 v3, v3, v34
	v_addc_co_u32_e32 v19, vcc, 0, v19, vcc
	v_cvt_pk_bf16_f32 v0, v0, v1
	v_cvt_pk_bf16_f32 v1, v2, v3
	global_store_dwordx2 v[18:19], v[16:17], off offset:3328
	v_mul_f32_e32 v16, v20, v34
	v_mul_f32_e32 v17, v21, v34
	v_mul_f32_e32 v18, v22, v34
	v_mul_f32_e32 v19, v23, v34
	global_store_dwordx2 v[32:33], v[0:1], off offset:64
	v_mul_f32_e32 v0, v4, v34
	v_mul_f32_e32 v1, v5, v34
	v_mul_f32_e32 v2, v6, v34
	v_mul_f32_e32 v3, v7, v34
	v_cvt_pk_bf16_f32 v16, v16, v17
	v_cvt_pk_bf16_f32 v17, v18, v19
	v_cvt_pk_bf16_f32 v0, v0, v1
	v_cvt_pk_bf16_f32 v1, v2, v3
	global_store_dwordx2 v[32:33], v[16:17], off offset:16
	v_mul_f32_e32 v16, v24, v34
	v_mul_f32_e32 v17, v25, v34
	v_mul_f32_e32 v18, v26, v34
	v_mul_f32_e32 v19, v27, v34
	global_store_dwordx2 v[32:33], v[0:1], off offset:80
	v_mul_f32_e32 v0, v8, v34
	v_mul_f32_e32 v1, v9, v34
	v_mul_f32_e32 v2, v10, v34
	v_mul_f32_e32 v3, v11, v34
	v_cvt_pk_bf16_f32 v16, v16, v17
	v_cvt_pk_bf16_f32 v17, v18, v19
	v_cvt_pk_bf16_f32 v0, v0, v1
	v_cvt_pk_bf16_f32 v1, v2, v3
	global_store_dwordx2 v[32:33], v[16:17], off offset:32
	v_mul_f32_e32 v16, v28, v34
	v_mul_f32_e32 v17, v29, v34
	v_mul_f32_e32 v18, v30, v34
	v_mul_f32_e32 v19, v31, v34
	global_store_dwordx2 v[32:33], v[0:1], off offset:96
	v_mul_f32_e32 v0, v12, v34
	v_mul_f32_e32 v1, v13, v34
	v_mul_f32_e32 v2, v14, v34
	v_mul_f32_e32 v3, v15, v34
	v_cvt_pk_bf16_f32 v16, v16, v17
	v_cvt_pk_bf16_f32 v17, v18, v19
	v_cvt_pk_bf16_f32 v0, v0, v1
	v_cvt_pk_bf16_f32 v1, v2, v3
	s_mov_b64 s[0:1], 0
	global_store_dwordx2 v[32:33], v[16:17], off offset:48
	global_store_dwordx2 v[32:33], v[0:1], off offset:112

.LBB0_1170:
	s_or_b64 exec, exec, s[6:7]
	s_and_b32 s6, s5, 1
	s_mul_i32 s7, s6, 0x2400
	v_add_u32_e32 v122, s7, v91
	ds_read_b128 v[32:35], v122
	ds_read_b128 v[102:105], v122 offset:4640
	s_xor_b32 s8, s6, 1
	s_mulk_i32 s8, 0x2400
	s_waitcnt lgkmcnt(1)
	v_mfma_f32_32x32x16_bf16 v[48:63], v[32:35], v[76:79], 0
	ds_read_b128 v[32:35], v122 offset:32
	s_waitcnt lgkmcnt(0)
	v_mfma_f32_32x32x16_bf16 v[48:63], v[32:35], v[72:75], v[48:63]
	ds_read_b128 v[32:35], v122 offset:64
	s_waitcnt lgkmcnt(0)
	v_mfma_f32_32x32x16_bf16 v[48:63], v[32:35], v[68:71], v[48:63]
	ds_read_b128 v[32:35], v122 offset:96
	s_waitcnt lgkmcnt(0)
	v_mfma_f32_32x32x16_bf16 v[48:63], v[32:35], v[64:67], v[48:63]
	ds_read_b128 v[32:35], v122 offset:4608
	s_waitcnt lgkmcnt(0)
	v_mfma_f32_32x32x16_bf16 v[32:47], v[32:35], v[76:79], 0
	s_nop 8
	v_max_f32_e32 v94, v49, v49
	v_max_f32_e32 v97, v48, v48
	v_max_f32_e32 v94, v97, v94
	v_max3_f32 v94, v94, v50, v51
	v_max3_f32 v94, v94, v52, v53
	v_max3_f32 v94, v94, v54, v55
	v_max3_f32 v94, v94, v56, v57
	v_mfma_f32_32x32x16_bf16 v[32:47], v[102:105], v[72:75], v[32:47]
	ds_read_b128 v[102:105], v122 offset:4672
	ds_read_b128 v[114:117], v122 offset:4704
	v_max3_f32 v94, v94, v58, v59
	v_max3_f32 v94, v94, v60, v61
	v_max3_f32 v94, v94, v62, v63
	ds_read_b128 v[118:121], v122 offset:23040
	s_waitcnt lgkmcnt(2)
	v_mfma_f32_32x32x16_bf16 v[32:47], v[102:105], v[68:71], v[32:47]
	v_lshl_add_u64 v[104:105], s[60:61], 1, v[84:85]
	s_waitcnt lgkmcnt(1)
	v_mfma_f32_32x32x16_bf16 v[32:47], v[114:117], v[64:67], v[32:47]
	s_nop 11
	v_max3_f32 v94, v94, v32, v33
	v_max3_f32 v94, v94, v34, v35
	v_max3_f32 v94, v94, v36, v37
	v_max3_f32 v94, v94, v38, v39
	v_max3_f32 v94, v94, v40, v41
	v_max3_f32 v94, v94, v42, v43
	v_max3_f32 v94, v94, v44, v45
	v_max3_f32 v94, v94, v46, v47
	ds_bpermute_b32 v97, v88, v94
	s_waitcnt lgkmcnt(0)
	v_max3_f32 v94, v95, v94, v97
	v_sub_f32_e32 v32, v32, v94
	v_sub_f32_e32 v106, v95, v94
	v_exp_f32_e32 v95, v32
	v_sub_f32_e32 v32, v33, v94
	v_exp_f32_e32 v97, v32
	v_sub_f32_e32 v32, v34, v94
	v_exp_f32_e32 v99, v32
	v_sub_f32_e32 v32, v35, v94
	v_exp_f32_e32 v102, v32
	v_sub_f32_e32 v32, v36, v94
	v_exp_f32_e32 v103, v32
	v_sub_f32_e32 v32, v37, v94
	v_exp_f32_e32 v37, v32
	global_load_dwordx4 v[32:35], v[104:105], off
	v_exp_f32_e32 v36, v106
	ds_read_b128 v[104:107], v122 offset:18432
	v_sub_f32_e32 v48, v48, v94
	v_sub_f32_e32 v49, v49, v94
	v_sub_f32_e32 v50, v50, v94
	v_sub_f32_e32 v51, v51, v94
	v_sub_f32_e32 v52, v52, v94
	v_sub_f32_e32 v53, v53, v94
	v_sub_f32_e32 v54, v54, v94
	v_sub_f32_e32 v55, v55, v94
	v_exp_f32_e32 v48, v48
	v_exp_f32_e32 v49, v49
	v_exp_f32_e32 v50, v50
	v_exp_f32_e32 v51, v51
	v_exp_f32_e32 v52, v52
	v_exp_f32_e32 v53, v53
	v_exp_f32_e32 v54, v54
	v_exp_f32_e32 v55, v55
	v_mul_f32_e32 v16, v16, v36
	v_mul_f32_e32 v17, v17, v36
	v_mul_f32_e32 v18, v18, v36
	v_mul_f32_e32 v19, v19, v36
	v_mul_f32_e32 v20, v20, v36
	v_mul_f32_e32 v21, v21, v36
	v_mul_f32_e32 v22, v22, v36
	v_mul_f32_e32 v23, v23, v36
	v_mul_f32_e32 v24, v24, v36
	v_mul_f32_e32 v25, v25, v36
	v_mul_f32_e32 v26, v26, v36
	v_mul_f32_e32 v27, v27, v36
	v_mul_f32_e32 v28, v28, v36
	v_mul_f32_e32 v29, v29, v36
	v_mul_f32_e32 v30, v30, v36
	v_mul_f32_e32 v31, v31, v36
	v_cvt_pk_bf16_f32 v114, v48, v49
	v_cvt_pk_bf16_f32 v115, v50, v51
	v_cvt_pk_bf16_f32 v116, v52, v53
	v_cvt_pk_bf16_f32 v117, v54, v55
	v_sub_f32_e32 v56, v56, v94
	v_sub_f32_e32 v57, v57, v94
	s_waitcnt lgkmcnt(0)
	v_mfma_f32_32x32x16_bf16 v[16:31], v[104:107], v[114:117], v[16:31]
	ds_read_b128 v[104:107], v122 offset:18464
	v_sub_f32_e32 v58, v58, v94
	v_sub_f32_e32 v59, v59, v94
	v_sub_f32_e32 v60, v60, v94
	v_sub_f32_e32 v61, v61, v94
	v_sub_f32_e32 v62, v62, v94
	v_sub_f32_e32 v63, v63, v94
	v_exp_f32_e32 v56, v56
	v_exp_f32_e32 v57, v57
	v_exp_f32_e32 v58, v58
	v_exp_f32_e32 v59, v59
	v_exp_f32_e32 v60, v60
	v_exp_f32_e32 v61, v61
	v_exp_f32_e32 v62, v62
	v_exp_f32_e32 v63, v63
	v_mul_f32_e32 v0, v0, v36
	v_mul_f32_e32 v1, v1, v36
	v_mul_f32_e32 v2, v2, v36
	v_mul_f32_e32 v3, v3, v36
	v_mul_f32_e32 v4, v4, v36
	v_mul_f32_e32 v5, v5, v36
	v_mul_f32_e32 v6, v6, v36
	v_mul_f32_e32 v7, v7, v36
	v_mul_f32_e32 v8, v8, v36
	v_mul_f32_e32 v9, v9, v36
	v_mul_f32_e32 v10, v10, v36
	v_mul_f32_e32 v11, v11, v36
	v_mul_f32_e32 v12, v12, v36
	v_mul_f32_e32 v13, v13, v36
	v_mul_f32_e32 v14, v14, v36
	v_mul_f32_e32 v15, v15, v36
	v_sub_f32_e32 v38, v38, v94
	v_sub_f32_e32 v39, v39, v94
	v_mfma_f32_32x32x16_bf16 v[0:15], v[118:121], v[114:117], v[0:15]
	ds_read_b128 v[114:117], v122 offset:23072
	v_cvt_pk_bf16_f32 v118, v56, v57
	v_cvt_pk_bf16_f32 v119, v58, v59
	v_cvt_pk_bf16_f32 v120, v60, v61
	v_cvt_pk_bf16_f32 v121, v62, v63
	v_exp_f32_e32 v38, v38
	v_exp_f32_e32 v39, v39
	s_waitcnt lgkmcnt(1)
	v_mfma_f32_32x32x16_bf16 v[16:31], v[104:107], v[118:121], v[16:31]
	ds_read_b128 v[104:107], v122 offset:18496
	v_sub_f32_e32 v40, v40, v94
	v_sub_f32_e32 v41, v41, v94
	v_sub_f32_e32 v42, v42, v94
	v_sub_f32_e32 v43, v43, v94
	v_sub_f32_e32 v44, v44, v94
	v_sub_f32_e32 v45, v45, v94
	s_waitcnt lgkmcnt(1)
	v_mfma_f32_32x32x16_bf16 v[0:15], v[114:117], v[118:121], v[0:15]
	v_cvt_pk_bf16_f32 v114, v95, v97
	v_cvt_pk_bf16_f32 v115, v99, v102
	v_cvt_pk_bf16_f32 v116, v103, v37
	v_cvt_pk_bf16_f32 v117, v38, v39
	ds_read_b128 v[118:121], v122 offset:23104
	v_sub_f32_e32 v46, v46, v94
	v_sub_f32_e32 v47, v47, v94
	s_waitcnt lgkmcnt(1)
	v_mfma_f32_32x32x16_bf16 v[16:31], v[104:107], v[114:117], v[16:31]
	ds_read_b128 v[104:107], v122 offset:18528
	v_exp_f32_e32 v40, v40
	v_exp_f32_e32 v41, v41
	v_exp_f32_e32 v42, v42
	v_exp_f32_e32 v43, v43
	v_exp_f32_e32 v44, v44
	v_exp_f32_e32 v45, v45
	v_exp_f32_e32 v46, v46
	v_exp_f32_e32 v47, v47
	s_waitcnt lgkmcnt(1)
	v_mfma_f32_32x32x16_bf16 v[0:15], v[118:121], v[114:117], v[0:15]
	v_cvt_pk_bf16_f32 v114, v40, v41
	v_cvt_pk_bf16_f32 v115, v42, v43
	v_cvt_pk_bf16_f32 v116, v44, v45
	v_cvt_pk_bf16_f32 v117, v46, v47
	s_waitcnt lgkmcnt(0)
	s_nop 0
	v_mfma_f32_32x32x16_bf16 v[16:31], v[104:107], v[114:117], v[16:31]
	ds_read_b128 v[104:107], v122 offset:23136
	s_waitcnt lgkmcnt(0)
	v_mfma_f32_32x32x16_bf16 v[0:15], v[104:107], v[114:117], v[0:15]
	s_and_saveexec_b64 s[6:7], s[0:1]
	s_cbranch_execz .LBB0_1172
	v_add_u32_e32 v104, s8, v92
	s_waitcnt vmcnt(1)
	ds_write_b128 v104, v[80:83]
.LBB0_1172:
	s_or_b64 exec, exec, s[6:7]
	v_add_f32_e32 v48, 0, v48
	v_add_f32_e32 v48, v49, v48
	v_add_f32_e32 v48, v50, v48
	v_add_f32_e32 v48, v51, v48
	v_add_f32_e32 v48, v52, v48
	v_add_f32_e32 v48, v53, v48
	v_add_f32_e32 v48, v54, v48
	v_add_f32_e32 v48, v55, v48
	v_add_f32_e32 v48, v56, v48
	v_add_f32_e32 v48, v57, v48
	v_add_f32_e32 v48, v58, v48
	v_add_f32_e32 v48, v59, v48
	v_add_f32_e32 v48, v60, v48
	v_add_f32_e32 v48, v61, v48
	v_add_f32_e32 v48, v62, v48
	v_add_f32_e32 v48, v63, v48
	v_add_f32_e32 v48, v95, v48
	v_add_f32_e32 v48, v97, v48
	v_add_f32_e32 v48, v99, v48
	v_add_f32_e32 v48, v102, v48
	v_add_f32_e32 v48, v103, v48
	v_add_f32_e32 v37, v37, v48
	v_add_f32_e32 v37, v38, v37
	v_add_f32_e32 v37, v39, v37
	v_add_f32_e32 v37, v40, v37
	v_add_f32_e32 v37, v41, v37
	v_add_f32_e32 v37, v42, v37
	v_add_f32_e32 v37, v43, v37
	v_add_f32_e32 v37, v44, v37
	v_add_f32_e32 v37, v45, v37
	v_add_f32_e32 v37, v46, v37
	v_add_f32_e32 v95, v47, v37
	s_add_i32 s5, s5, 1
	s_add_i32 s60, s60, 64
	v_readlane_b32 s6, v253, 49
	v_fmac_f32_e32 v95, v93, v36
	v_add_u32_e32 v36, s8, v90
	s_cmp_eq_u32 s6, s5
	s_waitcnt vmcnt(0)
	ds_write_b128 v36, v[32:35] offset:18432
	s_waitcnt lgkmcnt(0)
	s_barrier
	s_cbranch_scc0 .LBB0_1168
	v_readlane_b32 s0, v253, 49
	s_bitcmp1_b32 s0, 0
	s_cselect_b32 s0, 0x2400, 0
	v_add_u32_e32 v80, s0, v91
	ds_read_b128 v[32:35], v80
	s_mov_b32 s5, s61
	v_lshlrev_b32_e32 v128, 3, v108
	s_waitcnt lgkmcnt(0)
	v_mfma_f32_32x32x16_bf16 v[48:63], v[32:35], v[76:79], 0
	ds_read_b128 v[32:35], v80 offset:32
	s_waitcnt lgkmcnt(0)
	v_mfma_f32_32x32x16_bf16 v[48:63], v[32:35], v[72:75], v[48:63]
	ds_read_b128 v[32:35], v80 offset:64
	s_waitcnt lgkmcnt(0)
	v_mfma_f32_32x32x16_bf16 v[48:63], v[32:35], v[68:71], v[48:63]
	ds_read_b128 v[32:35], v80 offset:96
	s_waitcnt lgkmcnt(0)
	v_mfma_f32_32x32x16_bf16 v[48:63], v[32:35], v[64:67], v[48:63]
	ds_read_b128 v[32:35], v80 offset:4608
	s_waitcnt lgkmcnt(0)
	v_mfma_f32_32x32x16_bf16 v[32:47], v[32:35], v[76:79], 0
	ds_read_b128 v[76:79], v80 offset:4640
	s_nop 7
	v_max_f32_e32 v81, v49, v49
	v_max_f32_e32 v82, v48, v48
	v_max_f32_e32 v81, v82, v81
	s_waitcnt lgkmcnt(0)
	v_mfma_f32_32x32x16_bf16 v[32:47], v[76:79], v[72:75], v[32:47]
	ds_read_b128 v[72:75], v80 offset:4672
	ds_read_b128 v[76:79], v80 offset:4704
	s_waitcnt lgkmcnt(1)
	v_mfma_f32_32x32x16_bf16 v[32:47], v[72:75], v[68:71], v[32:47]
	v_max3_f32 v68, v81, v50, v51
	v_max3_f32 v68, v68, v52, v53
	v_max3_f32 v68, v68, v54, v55
	v_max3_f32 v68, v68, v56, v57
	v_max3_f32 v68, v68, v58, v59
	v_max3_f32 v68, v68, v60, v61
	v_max3_f32 v68, v68, v62, v63
	s_waitcnt lgkmcnt(0)
	v_mfma_f32_32x32x16_bf16 v[32:47], v[76:79], v[64:67], v[32:47]
	s_nop 11
	v_max3_f32 v64, v68, v32, v33
	v_max3_f32 v64, v64, v34, v35
	v_max3_f32 v64, v64, v36, v37
	v_max3_f32 v64, v64, v38, v39
	v_max3_f32 v64, v64, v40, v41
	v_max3_f32 v64, v64, v42, v43
	v_max3_f32 v64, v64, v44, v45
	v_max3_f32 v64, v64, v46, v47
	ds_bpermute_b32 v65, v88, v64
	s_waitcnt lgkmcnt(0)
	v_max3_f32 v64, v94, v64, v65
	v_sub_f32_e32 v48, v48, v64
	v_sub_f32_e32 v49, v49, v64
	v_exp_f32_e32 v48, v48
	v_sub_f32_e32 v50, v50, v64
	v_exp_f32_e32 v49, v49
	v_sub_f32_e32 v51, v51, v64
	v_exp_f32_e32 v50, v50
	v_sub_f32_e32 v52, v52, v64
	v_sub_f32_e32 v56, v56, v64
	v_exp_f32_e32 v51, v51
	v_sub_f32_e32 v53, v53, v64
	v_exp_f32_e32 v52, v52
	v_exp_f32_e32 v66, v56
	v_add_f32_e32 v56, 0, v48
	v_sub_f32_e32 v54, v54, v64
	v_exp_f32_e32 v53, v53
	v_add_f32_e32 v56, v49, v56
	v_sub_f32_e32 v55, v55, v64
	v_exp_f32_e32 v54, v54
	v_add_f32_e32 v56, v50, v56
	v_exp_f32_e32 v55, v55
	v_add_f32_e32 v56, v51, v56
	v_sub_f32_e32 v57, v57, v64
	v_add_f32_e32 v56, v52, v56
	v_sub_f32_e32 v58, v58, v64
	v_exp_f32_e32 v57, v57
	v_add_f32_e32 v56, v53, v56
	v_sub_f32_e32 v59, v59, v64
	v_exp_f32_e32 v58, v58
	v_add_f32_e32 v56, v54, v56
	v_sub_f32_e32 v60, v60, v64
	v_exp_f32_e32 v59, v59
	v_add_f32_e32 v56, v55, v56
	v_sub_f32_e32 v61, v61, v64
	v_exp_f32_e32 v60, v60
	v_add_f32_e32 v56, v66, v56
	v_sub_f32_e32 v62, v62, v64
	v_exp_f32_e32 v61, v61
	v_add_f32_e32 v56, v57, v56
	v_sub_f32_e32 v63, v63, v64
	v_exp_f32_e32 v62, v62
	v_add_f32_e32 v56, v58, v56
	v_exp_f32_e32 v63, v63
	v_add_f32_e32 v56, v59, v56
	v_sub_f32_e32 v32, v32, v64
	v_add_f32_e32 v56, v60, v56
	v_exp_f32_e32 v67, v32
	v_sub_f32_e32 v32, v33, v64
	v_add_f32_e32 v56, v61, v56
	v_exp_f32_e32 v68, v32
	v_sub_f32_e32 v32, v34, v64
	v_add_f32_e32 v56, v62, v56
	v_exp_f32_e32 v69, v32
	v_sub_f32_e32 v33, v35, v64
	v_add_f32_e32 v32, v63, v56
	v_exp_f32_e32 v70, v33
	v_sub_f32_e32 v33, v36, v64
	v_add_f32_e32 v32, v67, v32
	v_exp_f32_e32 v71, v33
	v_sub_f32_e32 v33, v37, v64
	v_add_f32_e32 v32, v68, v32
	v_exp_f32_e32 v72, v33
	v_sub_f32_e32 v33, v38, v64
	v_add_f32_e32 v32, v69, v32
	v_exp_f32_e32 v73, v33
	v_add_f32_e32 v32, v70, v32
	v_add_f32_e32 v32, v71, v32
	v_add_f32_e32 v32, v72, v32
	v_sub_f32_e32 v65, v94, v64
	v_add_f32_e32 v74, v73, v32
	v_sub_f32_e32 v32, v39, v64
	v_exp_f32_e32 v56, v65
	v_exp_f32_e32 v65, v32
	ds_read_b128 v[32:35], v80 offset:18432
	v_cvt_pk_bf16_f32 v36, v48, v49
	v_cvt_pk_bf16_f32 v37, v50, v51
	v_cvt_pk_bf16_f32 v38, v52, v53
	v_cvt_pk_bf16_f32 v39, v54, v55
	ds_read_b128 v[48:51], v80 offset:23040
	ds_read_b128 v[52:55], v80 offset:18464
	v_mul_f32_e32 v30, v30, v56
	v_mul_f32_e32 v31, v31, v56
	v_mul_f32_e32 v28, v28, v56
	v_mul_f32_e32 v29, v29, v56
	v_mul_f32_e32 v26, v26, v56
	v_mul_f32_e32 v27, v27, v56
	v_mul_f32_e32 v24, v24, v56
	v_mul_f32_e32 v25, v25, v56
	v_mul_f32_e32 v22, v22, v56
	v_mul_f32_e32 v23, v23, v56
	v_mul_f32_e32 v20, v20, v56
	v_mul_f32_e32 v21, v21, v56
	v_mul_f32_e32 v18, v18, v56
	v_mul_f32_e32 v19, v19, v56
	v_mul_f32_e32 v16, v16, v56
	v_mul_f32_e32 v17, v17, v56
	v_mul_f32_e32 v14, v14, v56
	v_mul_f32_e32 v15, v15, v56
	v_mul_f32_e32 v12, v12, v56
	v_mul_f32_e32 v13, v13, v56
	s_waitcnt lgkmcnt(2)
	v_mfma_f32_32x32x16_bf16 v[16:31], v[32:35], v[36:39], v[16:31]
	v_mul_f32_e64 v10, v10, v56
	v_mul_f32_e64 v11, v11, v56
	v_mul_f32_e64 v8, v8, v56
	v_mul_f32_e64 v9, v9, v56
	v_mul_f32_e64 v6, v6, v56
	v_mul_f32_e64 v7, v7, v56
	v_mul_f32_e32 v4, v4, v56
	v_mul_f32_e32 v5, v5, v56
	v_mul_f32_e32 v2, v2, v56
	v_mul_f32_e32 v3, v3, v56
	v_mul_f32_e32 v0, v0, v56
	v_mul_f32_e32 v1, v1, v56
	ds_read_b128 v[32:35], v80 offset:23072
	v_sub_f32_e32 v40, v40, v64
	s_waitcnt lgkmcnt(2)
	v_mfma_f32_32x32x16_bf16 v[0:15], v[48:51], v[36:39], v[0:15]
	v_exp_f32_e32 v75, v40
	v_sub_f32_e32 v36, v41, v64
	v_exp_f32_e32 v76, v36
	v_cvt_pk_bf16_f32 v36, v66, v57
	v_cvt_pk_bf16_f32 v37, v58, v59
	v_cvt_pk_bf16_f32 v38, v60, v61
	v_cvt_pk_bf16_f32 v39, v62, v63
	v_sub_f32_e32 v40, v42, v64
	ds_read_b128 v[48:51], v80 offset:18496
	s_waitcnt lgkmcnt(2)
	v_mfma_f32_32x32x16_bf16 v[16:31], v[52:55], v[36:39], v[16:31]
	v_exp_f32_e32 v52, v40
	v_add_f32_e32 v40, v65, v74
	v_add_f32_e32 v40, v75, v40
	v_add_f32_e32 v40, v76, v40
	v_add_f32_e32 v53, v52, v40
	v_sub_f32_e32 v54, v43, v64
	v_exp_f32_e32 v54, v54
	s_waitcnt lgkmcnt(1)
	v_mfma_f32_32x32x16_bf16 v[0:15], v[32:35], v[36:39], v[0:15]
	ds_read_b128 v[36:39], v80 offset:23104
	ds_read_b128 v[40:43], v80 offset:18528
	v_sub_f32_e32 v44, v44, v64
	v_cvt_pk_bf16_f32 v32, v67, v68
	v_cvt_pk_bf16_f32 v33, v69, v70
	v_cvt_pk_bf16_f32 v34, v71, v72
	v_cvt_pk_bf16_f32 v35, v73, v65
	v_exp_f32_e32 v44, v44
	v_sub_f32_e32 v45, v45, v64
	s_waitcnt lgkmcnt(2)
	v_mfma_f32_32x32x16_bf16 v[16:31], v[48:51], v[32:35], v[16:31]
	v_exp_f32_e32 v45, v45
	v_sub_f32_e32 v46, v46, v64
	ds_read_b128 v[48:51], v80 offset:23136
	s_waitcnt lgkmcnt(0)
	s_barrier
	v_mfma_f32_32x32x16_bf16 v[0:15], v[36:39], v[32:35], v[0:15]
	v_sub_f32_e32 v32, v47, v64
	v_exp_f32_e32 v36, v46
	v_exp_f32_e32 v37, v32
	v_add_f32_e32 v38, v54, v53
	v_add_f32_e32 v38, v44, v38
	v_add_f32_e32 v38, v45, v38
	v_cvt_pk_bf16_f32 v35, v36, v37
	v_add_f32_e32 v36, v36, v38
	v_add_f32_e32 v36, v37, v36
	v_fmac_f32_e32 v36, v95, v56
	ds_bpermute_b32 v37, v88, v36
	v_cvt_pk_bf16_f32 v32, v75, v76
	v_cvt_pk_bf16_f32 v33, v52, v54
	v_cvt_pk_bf16_f32 v34, v44, v45
	s_nop 1
	v_mfma_f32_32x32x16_bf16 v[16:31], v[40:43], v[32:35], v[16:31]
	v_mfma_f32_32x32x16_bf16 v[0:15], v[48:51], v[32:35], v[0:15]
	s_waitcnt lgkmcnt(0)
	v_add_f32_e32 v34, v36, v37
	v_div_scale_f32 v35, s[0:1], v34, v34, 1.0
	v_rcp_f32_e32 v36, v35
	v_lshlrev_b64 v[32:33], 11, v[100:101]
	v_lshl_add_u64 v[32:33], s[66:67], 0, v[32:33]
	v_lshl_add_u64 v[32:33], v[32:33], 0, s[4:5]
	v_fma_f32 v37, -v35, v36, 1.0
	v_fmac_f32_e32 v36, v37, v36
	v_div_scale_f32 v37, vcc, 1.0, v34, 1.0
	v_mul_f32_e32 v38, v37, v36
	v_fma_f32 v39, -v35, v38, v37
	v_fmac_f32_e32 v38, v39, v36
	v_fma_f32 v35, -v35, v38, v37
	v_div_fmas_f32 v35, v35, v36, v38
	v_div_fixup_f32 v34, v35, v34, 1.0
	v_mul_f32_e32 v16, v16, v34
	v_mul_f32_e32 v17, v17, v34
	v_mul_f32_e32 v18, v18, v34
	v_mul_f32_e32 v19, v19, v34
	v_cvt_pk_bf16_f32 v16, v16, v17
	v_cvt_pk_bf16_f32 v17, v18, v19
	v_lshl_add_u64 v[18:19], v[32:33], 0, v[128:129]
	s_mov_b64 s[0:1], 0x2d53900
	v_lshl_add_u64 v[32:33], v[18:19], 0, s[0:1]
	s_mov_b32 s0, 0x2d53000
	v_add_co_u32_e32 v18, vcc, s0, v18
	v_mul_f32_e32 v0, v0, v34
	v_mul_f32_e32 v1, v1, v34
	v_mul_f32_e32 v2, v2, v34
	v_mul_f32_e32 v3, v3, v34
	v_addc_co_u32_e32 v19, vcc, 0, v19, vcc
	v_cvt_pk_bf16_f32 v0, v0, v1
	v_cvt_pk_bf16_f32 v1, v2, v3
	global_store_dwordx2 v[18:19], v[16:17], off offset:2304
	v_mul_f32_e32 v16, v20, v34
	v_mul_f32_e32 v17, v21, v34
	v_mul_f32_e32 v18, v22, v34
	v_mul_f32_e32 v19, v23, v34
	global_store_dwordx2 v[32:33], v[0:1], off offset:64
	v_mul_f32_e32 v0, v4, v34
	v_mul_f32_e32 v1, v5, v34
	v_mul_f32_e32 v2, v6, v34
	v_mul_f32_e32 v3, v7, v34
	v_cvt_pk_bf16_f32 v16, v16, v17
	v_cvt_pk_bf16_f32 v17, v18, v19
	v_cvt_pk_bf16_f32 v0, v0, v1
	v_cvt_pk_bf16_f32 v1, v2, v3
	global_store_dwordx2 v[32:33], v[16:17], off offset:16
	v_mul_f32_e32 v16, v24, v34
	v_mul_f32_e32 v17, v25, v34
	v_mul_f32_e32 v18, v26, v34
	v_mul_f32_e32 v19, v27, v34
	global_store_dwordx2 v[32:33], v[0:1], off offset:80
	v_mul_f32_e32 v0, v8, v34
	v_mul_f32_e32 v1, v9, v34
	v_mul_f32_e32 v2, v10, v34
	v_mul_f32_e32 v3, v11, v34
	v_cvt_pk_bf16_f32 v16, v16, v17
	v_cvt_pk_bf16_f32 v17, v18, v19
	v_cvt_pk_bf16_f32 v0, v0, v1
	v_cvt_pk_bf16_f32 v1, v2, v3
	global_store_dwordx2 v[32:33], v[16:17], off offset:32
	v_mul_f32_e32 v16, v28, v34
	v_mul_f32_e32 v17, v29, v34
	v_mul_f32_e32 v18, v30, v34
	v_mul_f32_e32 v19, v31, v34
	global_store_dwordx2 v[32:33], v[0:1], off offset:96
	v_mul_f32_e32 v0, v12, v34
	v_mul_f32_e32 v1, v13, v34
	v_mul_f32_e32 v2, v14, v34
	v_mul_f32_e32 v3, v15, v34
	v_cvt_pk_bf16_f32 v16, v16, v17
	v_cvt_pk_bf16_f32 v17, v18, v19
	v_cvt_pk_bf16_f32 v0, v0, v1
	v_cvt_pk_bf16_f32 v1, v2, v3
	global_store_dwordx2 v[32:33], v[16:17], off offset:48
	global_store_dwordx2 v[32:33], v[0:1], off offset:112
	s_cbranch_execz .LBB0_1176
	s_branch .LBB0_1195

.LBB0_1185:
	s_or_b64 exec, exec, s[4:5]
	s_and_b32 s4, s6, 1
	s_mul_i32 s5, s4, 0x2400
	v_add_u32_e32 v91, s5, v88
	ds_read_b128 v[32:35], v91
	ds_read_b128 v[92:95], v91 offset:32
	v_lshl_add_u64 v[98:99], s[60:61], 1, v[78:79]
	s_xor_b32 s7, s4, 1
	s_mulk_i32 s7, 0x2400
	s_waitcnt lgkmcnt(1)
	v_mfma_f32_32x32x16_bf16 v[48:63], v[32:35], v[68:71], 0
	ds_read_b128 v[32:35], v91 offset:4608
	s_waitcnt lgkmcnt(1)
	v_mfma_f32_32x32x16_bf16 v[48:63], v[92:95], v[64:67], v[48:63]
	ds_read_b128 v[92:95], v91 offset:4640
	s_waitcnt lgkmcnt(1)
	v_mfma_f32_32x32x16_bf16 v[32:47], v[32:35], v[68:71], 0
	s_nop 8
	v_max_f32_e32 v91, v49, v49
	v_max_f32_e32 v97, v48, v48
	v_max_f32_e32 v91, v97, v91
	v_max3_f32 v91, v91, v50, v51
	v_max3_f32 v91, v91, v52, v53
	v_max3_f32 v91, v91, v54, v55
	v_max3_f32 v91, v91, v56, v57
	s_waitcnt lgkmcnt(0)
	v_mfma_f32_32x32x16_bf16 v[32:47], v[92:95], v[64:67], v[32:47]
	v_max3_f32 v91, v91, v58, v59
	v_max3_f32 v91, v91, v60, v61
	v_max3_f32 v91, v91, v62, v63
	s_nop 8
	v_max3_f32 v91, v91, v32, v33
	v_max3_f32 v91, v91, v34, v35
	v_max3_f32 v91, v91, v36, v37
	v_max3_f32 v91, v91, v38, v39
	v_max3_f32 v91, v91, v40, v41
	v_max3_f32 v91, v91, v42, v43
	v_max3_f32 v91, v91, v44, v45
	v_max3_f32 v91, v91, v46, v47
	ds_bpermute_b32 v92, v82, v91
	s_waitcnt lgkmcnt(0)
	v_max3_f32 v91, v86, v91, v92
	v_sub_f32_e32 v32, v32, v91
	v_sub_f32_e32 v97, v86, v91
	v_exp_f32_e32 v86, v32
	v_sub_f32_e32 v32, v33, v91
	v_exp_f32_e32 v92, v32
	v_sub_f32_e32 v32, v34, v91
	v_exp_f32_e32 v93, v32
	v_sub_f32_e32 v32, v35, v91
	v_exp_f32_e32 v94, v32
	v_sub_f32_e32 v32, v36, v91
	v_exp_f32_e32 v95, v32
	v_sub_f32_e32 v32, v37, v91
	v_exp_f32_e32 v37, v32
	global_load_dwordx4 v[32:35], v[98:99], off
	v_exp_f32_e32 v36, v97
	v_add_u32_e32 v97, s5, v84
	ds_read_b128 v[98:101], v97 offset:18432
	ds_read_b128 v[114:117], v97 offset:23040
	v_sub_f32_e32 v48, v48, v91
	v_sub_f32_e32 v49, v49, v91
	v_sub_f32_e32 v50, v50, v91
	v_sub_f32_e32 v51, v51, v91
	v_sub_f32_e32 v52, v52, v91
	v_sub_f32_e32 v53, v53, v91
	v_sub_f32_e32 v54, v54, v91
	v_sub_f32_e32 v55, v55, v91
	v_exp_f32_e32 v48, v48
	v_exp_f32_e32 v49, v49
	v_exp_f32_e32 v50, v50
	v_exp_f32_e32 v51, v51
	v_exp_f32_e32 v52, v52
	v_exp_f32_e32 v53, v53
	v_exp_f32_e32 v54, v54
	v_exp_f32_e32 v55, v55
	v_mul_f32_e32 v0, v0, v36
	v_mul_f32_e32 v1, v1, v36
	v_mul_f32_e32 v2, v2, v36
	v_mul_f32_e32 v3, v3, v36
	v_mul_f32_e32 v4, v4, v36
	v_mul_f32_e32 v5, v5, v36
	v_mul_f32_e32 v6, v6, v36
	v_mul_f32_e32 v7, v7, v36
	v_mul_f32_e32 v8, v8, v36
	v_mul_f32_e32 v9, v9, v36
	v_mul_f32_e32 v10, v10, v36
	v_mul_f32_e32 v11, v11, v36
	v_mul_f32_e32 v12, v12, v36
	v_mul_f32_e32 v13, v13, v36
	v_mul_f32_e32 v14, v14, v36
	v_mul_f32_e32 v15, v15, v36
	v_cvt_pk_bf16_f32 v102, v48, v49
	v_cvt_pk_bf16_f32 v103, v50, v51
	v_cvt_pk_bf16_f32 v104, v52, v53
	v_cvt_pk_bf16_f32 v105, v54, v55
	v_sub_f32_e32 v56, v56, v91
	v_sub_f32_e32 v57, v57, v91
	s_waitcnt lgkmcnt(1)
	v_mfma_f32_32x32x16_bf16 v[0:15], v[98:101], v[102:105], v[0:15]
	ds_read_b128 v[98:101], v97 offset:18464
	v_sub_f32_e32 v58, v58, v91
	v_sub_f32_e32 v59, v59, v91
	v_sub_f32_e32 v60, v60, v91
	v_sub_f32_e32 v61, v61, v91
	v_sub_f32_e32 v62, v62, v91
	v_sub_f32_e32 v63, v63, v91
	v_exp_f32_e32 v56, v56
	v_exp_f32_e32 v57, v57
	v_exp_f32_e32 v58, v58
	v_exp_f32_e32 v59, v59
	v_exp_f32_e32 v60, v60
	v_exp_f32_e32 v61, v61
	v_exp_f32_e32 v62, v62
	v_exp_f32_e32 v63, v63
	v_mul_f32_e32 v16, v16, v36
	v_mul_f32_e32 v17, v17, v36
	v_mul_f32_e32 v18, v18, v36
	v_mul_f32_e32 v19, v19, v36
	v_mul_f32_e32 v20, v20, v36
	v_mul_f32_e32 v21, v21, v36
	v_mul_f32_e32 v22, v22, v36
	v_mul_f32_e32 v23, v23, v36
	v_mul_f32_e32 v24, v24, v36
	v_mul_f32_e32 v25, v25, v36
	v_mul_f32_e32 v26, v26, v36
	v_mul_f32_e32 v27, v27, v36
	v_mul_f32_e32 v28, v28, v36
	v_mul_f32_e32 v29, v29, v36
	v_mul_f32_e32 v30, v30, v36
	v_mul_f32_e32 v31, v31, v36
	v_sub_f32_e32 v38, v38, v91
	v_sub_f32_e32 v39, v39, v91
	s_waitcnt lgkmcnt(1)
	v_mfma_f32_32x32x16_bf16 v[16:31], v[114:117], v[102:105], v[16:31]
	ds_read_b128 v[102:105], v97 offset:23072
	v_cvt_pk_bf16_f32 v114, v56, v57
	v_cvt_pk_bf16_f32 v115, v58, v59
	v_cvt_pk_bf16_f32 v116, v60, v61
	v_cvt_pk_bf16_f32 v117, v62, v63
	v_exp_f32_e32 v38, v38
	v_exp_f32_e32 v39, v39
	s_waitcnt lgkmcnt(1)
	v_mfma_f32_32x32x16_bf16 v[0:15], v[98:101], v[114:117], v[0:15]
	ds_read_b128 v[98:101], v97 offset:18496
	v_sub_f32_e32 v40, v40, v91
	v_sub_f32_e32 v41, v41, v91
	v_sub_f32_e32 v42, v42, v91
	v_sub_f32_e32 v43, v43, v91
	v_sub_f32_e32 v44, v44, v91
	v_sub_f32_e32 v45, v45, v91
	s_waitcnt lgkmcnt(1)
	v_mfma_f32_32x32x16_bf16 v[16:31], v[102:105], v[114:117], v[16:31]
	v_cvt_pk_bf16_f32 v102, v86, v92
	v_cvt_pk_bf16_f32 v103, v93, v94
	v_cvt_pk_bf16_f32 v104, v95, v37
	v_cvt_pk_bf16_f32 v105, v38, v39
	ds_read_b128 v[114:117], v97 offset:23104
	v_sub_f32_e32 v46, v46, v91
	v_sub_f32_e32 v47, v47, v91
	s_waitcnt lgkmcnt(1)
	v_mfma_f32_32x32x16_bf16 v[0:15], v[98:101], v[102:105], v[0:15]
	ds_read_b128 v[98:101], v97 offset:18528
	v_exp_f32_e32 v40, v40
	v_exp_f32_e32 v41, v41
	v_exp_f32_e32 v42, v42
	v_exp_f32_e32 v43, v43
	v_exp_f32_e32 v44, v44
	v_exp_f32_e32 v45, v45
	v_exp_f32_e32 v46, v46
	v_exp_f32_e32 v47, v47
	s_waitcnt lgkmcnt(1)
	v_mfma_f32_32x32x16_bf16 v[16:31], v[114:117], v[102:105], v[16:31]
	v_cvt_pk_bf16_f32 v102, v40, v41
	v_cvt_pk_bf16_f32 v103, v42, v43
	v_cvt_pk_bf16_f32 v104, v44, v45
	v_cvt_pk_bf16_f32 v105, v46, v47
	s_waitcnt lgkmcnt(0)
	s_nop 0
	v_mfma_f32_32x32x16_bf16 v[0:15], v[98:101], v[102:105], v[0:15]
	ds_read_b128 v[98:101], v97 offset:23136
	s_waitcnt lgkmcnt(0)
	v_mfma_f32_32x32x16_bf16 v[16:31], v[98:101], v[102:105], v[16:31]
	s_and_saveexec_b64 s[4:5], s[0:1]
	s_cbranch_execz .LBB0_1187
	v_add_u32_e32 v97, s7, v89
	s_waitcnt vmcnt(1)
	ds_write_b128 v97, v[72:75]
.LBB0_1187:
	s_or_b64 exec, exec, s[4:5]
	v_add_f32_e32 v48, 0, v48
	v_add_f32_e32 v48, v49, v48
	v_add_f32_e32 v48, v50, v48
	v_add_f32_e32 v48, v51, v48
	v_add_f32_e32 v48, v52, v48
	v_add_f32_e32 v48, v53, v48
	v_add_f32_e32 v48, v54, v48
	v_add_f32_e32 v48, v55, v48
	v_add_f32_e32 v48, v56, v48
	v_add_f32_e32 v48, v57, v48
	v_add_f32_e32 v48, v58, v48
	v_add_f32_e32 v48, v59, v48
	v_add_f32_e32 v48, v60, v48
	v_add_f32_e32 v48, v61, v48
	v_add_f32_e32 v48, v62, v48
	v_add_f32_e32 v48, v63, v48
	v_add_f32_e32 v48, v86, v48
	v_add_f32_e32 v48, v92, v48
	v_add_f32_e32 v48, v93, v48
	v_add_f32_e32 v48, v94, v48
	v_add_f32_e32 v48, v95, v48
	v_add_f32_e32 v37, v37, v48
	v_add_f32_e32 v37, v38, v37
	v_add_f32_e32 v37, v39, v37
	v_add_f32_e32 v37, v40, v37
	v_add_f32_e32 v37, v41, v37
	v_add_f32_e32 v37, v42, v37
	v_add_f32_e32 v37, v43, v37
	v_add_f32_e32 v37, v44, v37
	v_add_f32_e32 v37, v45, v37
	v_add_f32_e32 v37, v46, v37
	v_add_f32_e32 v86, v47, v37
	s_add_i32 s6, s6, 1
	s_add_i32 s60, s60, 64
	v_readlane_b32 s4, v253, 49
	v_fmac_f32_e32 v86, v90, v36
	v_add_u32_e32 v36, s7, v87
	s_cmp_eq_u32 s4, s6
	s_waitcnt vmcnt(0)
	ds_write_b128 v36, v[32:35] offset:18432
	s_waitcnt lgkmcnt(0)
	s_barrier
	s_cbranch_scc0 .LBB0_1183
	v_readlane_b32 s0, v253, 49
	s_bitcmp1_b32 s0, 0
	s_cselect_b32 s0, 0x2400, 0
	v_add_u32_e32 v72, s0, v88
	ds_read_b128 v[32:35], v72
	v_add_u32_e32 v74, s0, v84
	v_cmp_gt_u32_e32 vcc, 32, v112
	s_waitcnt lgkmcnt(0)
	v_mfma_f32_32x32x16_bf16 v[48:63], v[32:35], v[68:71], 0
	ds_read_b128 v[32:35], v72 offset:32
	s_waitcnt lgkmcnt(0)
	v_mfma_f32_32x32x16_bf16 v[48:63], v[32:35], v[64:67], v[48:63]
	ds_read_b128 v[32:35], v72 offset:4608
	s_waitcnt lgkmcnt(0)
	v_mfma_f32_32x32x16_bf16 v[32:47], v[32:35], v[68:71], 0
	ds_read_b128 v[68:71], v72 offset:4640
	s_nop 7
	v_max_f32_e32 v72, v49, v49
	v_max_f32_e32 v73, v48, v48
	v_max_f32_e32 v72, v73, v72
	v_max3_f32 v72, v72, v50, v51
	s_waitcnt lgkmcnt(0)
	v_mfma_f32_32x32x16_bf16 v[32:47], v[68:71], v[64:67], v[32:47]
	v_max3_f32 v64, v72, v52, v53
	v_max3_f32 v64, v64, v54, v55
	v_max3_f32 v64, v64, v56, v57
	v_max3_f32 v64, v64, v58, v59
	v_max3_f32 v64, v64, v60, v61
	v_max3_f32 v64, v64, v62, v63
	s_nop 5
	v_max3_f32 v64, v64, v32, v33
	v_max3_f32 v64, v64, v34, v35
	v_max3_f32 v64, v64, v36, v37
	v_max3_f32 v64, v64, v38, v39
	v_max3_f32 v64, v64, v40, v41
	v_max3_f32 v64, v64, v42, v43
	v_max3_f32 v64, v64, v44, v45
	v_max3_f32 v64, v64, v46, v47
	ds_bpermute_b32 v65, v82, v64
	s_waitcnt lgkmcnt(0)
	v_max3_f32 v64, v91, v64, v65
	v_sub_f32_e32 v48, v48, v64
	v_sub_f32_e32 v49, v49, v64
	v_exp_f32_e32 v48, v48
	v_sub_f32_e32 v50, v50, v64
	v_exp_f32_e32 v49, v49
	v_sub_f32_e32 v51, v51, v64
	v_exp_f32_e32 v50, v50
	v_sub_f32_e32 v52, v52, v64
	v_exp_f32_e32 v51, v51
	v_sub_f32_e32 v53, v53, v64
	v_exp_f32_e32 v52, v52
	v_add_f32_e32 v66, 0, v48
	v_sub_f32_e32 v54, v54, v64
	v_exp_f32_e32 v53, v53
	v_add_f32_e32 v66, v49, v66
	v_sub_f32_e32 v55, v55, v64
	v_exp_f32_e32 v54, v54
	v_add_f32_e32 v66, v50, v66
	v_sub_f32_e32 v56, v56, v64
	v_exp_f32_e32 v55, v55
	v_add_f32_e32 v66, v51, v66
	v_sub_f32_e32 v57, v57, v64
	v_exp_f32_e32 v56, v56
	v_add_f32_e32 v66, v52, v66
	v_sub_f32_e32 v58, v58, v64
	v_exp_f32_e32 v57, v57
	v_add_f32_e32 v66, v53, v66
	v_sub_f32_e32 v59, v59, v64
	v_exp_f32_e32 v58, v58
	v_add_f32_e32 v66, v54, v66
	v_exp_f32_e32 v59, v59
	v_add_f32_e32 v66, v55, v66
	v_sub_f32_e32 v60, v60, v64
	v_add_f32_e32 v66, v56, v66
	v_exp_f32_e32 v60, v60
	v_sub_f32_e32 v61, v61, v64
	v_add_f32_e32 v66, v57, v66
	v_exp_f32_e32 v61, v61
	v_sub_f32_e32 v62, v62, v64
	v_add_f32_e32 v66, v58, v66
	v_exp_f32_e32 v62, v62
	v_sub_f32_e32 v63, v63, v64
	v_add_f32_e32 v66, v59, v66
	v_exp_f32_e32 v63, v63
	v_sub_f32_e32 v32, v32, v64
	v_add_f32_e32 v66, v60, v66
	v_exp_f32_e32 v67, v32
	v_sub_f32_e32 v32, v33, v64
	v_add_f32_e32 v66, v61, v66
	v_exp_f32_e32 v33, v32
	v_sub_f32_e32 v34, v34, v64
	v_add_f32_e32 v32, v62, v66
	v_exp_f32_e32 v66, v34
	v_sub_f32_e32 v34, v35, v64
	v_add_f32_e32 v32, v63, v32
	v_exp_f32_e32 v68, v34
	v_sub_f32_e32 v34, v36, v64
	v_add_f32_e32 v32, v67, v32
	v_exp_f32_e32 v69, v34
	v_sub_f32_e32 v34, v37, v64
	v_add_f32_e32 v32, v33, v32
	v_exp_f32_e32 v70, v34
	v_add_f32_e32 v32, v66, v32
	v_add_f32_e32 v32, v68, v32
	v_add_f32_e32 v32, v69, v32
	v_sub_f32_e32 v65, v91, v64
	v_add_f32_e32 v71, v70, v32
	v_sub_f32_e32 v32, v38, v64
	v_sub_f32_e32 v34, v39, v64
	v_exp_f32_e32 v72, v32
	v_exp_f32_e32 v32, v65
	v_exp_f32_e32 v65, v34
	v_sub_f32_e32 v34, v40, v64
	v_exp_f32_e32 v73, v34
	ds_read_b128 v[34:37], v74 offset:18432
	v_mul_f32_e32 v14, v14, v32
	v_mul_f32_e32 v15, v15, v32
	v_mul_f32_e32 v12, v12, v32
	v_mul_f32_e32 v13, v13, v32
	v_mul_f32_e32 v10, v10, v32
	v_mul_f32_e32 v11, v11, v32
	v_mul_f32_e32 v8, v8, v32
	v_mul_f32_e32 v9, v9, v32
	v_mul_f32_e32 v6, v6, v32
	v_mul_f32_e32 v7, v7, v32
	v_mul_f32_e32 v4, v4, v32
	v_mul_f32_e32 v5, v5, v32
	v_mul_f32_e32 v2, v2, v32
	v_mul_f32_e32 v3, v3, v32
	v_mul_f32_e32 v0, v0, v32
	v_mul_f32_e32 v1, v1, v32
	v_cvt_pk_bf16_f32 v48, v48, v49
	v_cvt_pk_bf16_f32 v49, v50, v51
	v_cvt_pk_bf16_f32 v50, v52, v53
	v_cvt_pk_bf16_f32 v51, v54, v55
	ds_read_b128 v[52:55], v74 offset:23040
	v_mul_f32_e32 v30, v30, v32
	v_mul_f32_e32 v31, v31, v32
	s_waitcnt lgkmcnt(1)
	v_mfma_f32_32x32x16_bf16 v[0:15], v[34:37], v[48:51], v[0:15]
	ds_read_b128 v[34:37], v74 offset:18464
	v_mul_f32_e64 v28, v28, v32
	v_mul_f32_e64 v29, v29, v32
	v_mul_f32_e64 v26, v26, v32
	v_mul_f32_e64 v27, v27, v32
	v_mul_f32_e32 v24, v24, v32
	v_mul_f32_e32 v25, v25, v32
	v_mul_f32_e32 v22, v22, v32
	v_mul_f32_e32 v23, v23, v32
	v_mul_f32_e32 v20, v20, v32
	v_mul_f32_e32 v21, v21, v32
	v_mul_f32_e32 v18, v18, v32
	v_mul_f32_e32 v19, v19, v32
	v_mul_f32_e32 v16, v16, v32
	v_mul_f32_e32 v17, v17, v32
	v_sub_f32_e32 v38, v41, v64
	v_cvt_pk_bf16_f32 v39, v58, v59
	s_waitcnt lgkmcnt(1)
	v_mfma_f32_32x32x16_bf16 v[16:31], v[52:55], v[48:51], v[16:31]
	v_exp_f32_e32 v52, v38
	v_cvt_pk_bf16_f32 v38, v56, v57
	v_cvt_pk_bf16_f32 v40, v60, v61
	v_cvt_pk_bf16_f32 v41, v62, v63
	ds_read_b128 v[48:51], v74 offset:23072
	s_waitcnt lgkmcnt(1)
	v_mfma_f32_32x32x16_bf16 v[0:15], v[34:37], v[38:41], v[0:15]
	v_add_f32_e32 v34, v72, v71
	v_add_f32_e32 v34, v65, v34
	v_add_f32_e32 v34, v73, v34
	v_add_f32_e32 v53, v52, v34
	v_sub_f32_e32 v34, v42, v64
	v_exp_f32_e32 v54, v34
	ds_read_b128 v[34:37], v74 offset:18496
	s_waitcnt lgkmcnt(1)
	v_mfma_f32_32x32x16_bf16 v[16:31], v[48:51], v[38:41], v[16:31]
	ds_read_b128 v[48:51], v74 offset:23104
	v_sub_f32_e32 v38, v43, v64
	v_exp_f32_e32 v55, v38
	v_cvt_pk_bf16_f32 v38, v67, v33
	v_cvt_pk_bf16_f32 v39, v66, v68
	v_cvt_pk_bf16_f32 v40, v69, v70
	v_cvt_pk_bf16_f32 v41, v72, v65
	v_sub_f32_e32 v33, v44, v64
	v_exp_f32_e32 v33, v33
	s_waitcnt lgkmcnt(1)
	v_mfma_f32_32x32x16_bf16 v[0:15], v[34:37], v[38:41], v[0:15]
	v_sub_f32_e32 v34, v45, v64
	v_exp_f32_e32 v56, v34
	v_sub_f32_e32 v34, v46, v64
	v_exp_f32_e32 v46, v34
	ds_read_b128 v[34:37], v74 offset:18528
	ds_read_b128 v[42:45], v74 offset:23136
	s_waitcnt lgkmcnt(0)
	v_mfma_f32_32x32x16_bf16 v[16:31], v[48:51], v[38:41], v[16:31]
	v_sub_f32_e32 v38, v47, v64
	v_exp_f32_e32 v47, v38
	v_cvt_pk_bf16_f32 v38, v73, v52
	v_cvt_pk_bf16_f32 v39, v54, v55
	v_cvt_pk_bf16_f32 v40, v33, v56
	v_cvt_pk_bf16_f32 v41, v46, v47
	s_barrier
	s_nop 0
	v_mfma_f32_32x32x16_bf16 v[0:15], v[34:37], v[38:41], v[0:15]
	v_add_f32_e32 v34, v54, v53
	v_add_f32_e32 v34, v55, v34
	v_add_f32_e32 v33, v33, v34
	v_add_f32_e32 v33, v56, v33
	v_add_f32_e32 v33, v46, v33
	v_add_f32_e32 v34, v47, v33
	v_fmac_f32_e32 v34, v86, v32
	v_mfma_f32_32x32x16_bf16 v[16:31], v[42:45], v[38:41], v[16:31]
	ds_bpermute_b32 v35, v82, v34
	v_mov_b32_e32 v32, 0
	v_mov_b32_e32 v33, 0
	s_and_saveexec_b64 s[0:1], vcc
	s_cbranch_execz .LBB0_1190
	v_or_b32_e32 v128, s27, v112
	v_readlane_b32 s36, v250, 21
	v_lshlrev_b64 v[32:33], 2, v[128:129]
	v_readlane_b32 s40, v250, 25
	v_readlane_b32 s41, v250, 26
	v_readlane_b32 s42, v250, 27
	v_readlane_b32 s43, v250, 28
	v_readlane_b32 s44, v250, 29
	v_readlane_b32 s45, v250, 30
	v_readlane_b32 s46, v250, 31
	v_readlane_b32 s47, v250, 32
	v_lshl_add_u64 v[36:37], s[40:41], 0, v[32:33]
	v_lshl_add_u64 v[38:39], s[42:43], 0, v[32:33]
	v_lshl_add_u64 v[40:41], s[44:45], 0, v[32:33]
	v_lshl_add_u64 v[32:33], s[46:47], 0, v[32:33]
	global_load_dword v37, v[36:37], off
	v_readlane_b32 s37, v250, 22
	global_load_dword v39, v[38:39], off
	v_readlane_b32 s38, v250, 23
	global_load_dword v36, v[40:41], off
	global_load_dword v38, v[32:33], off
	v_readlane_b32 s39, v250, 24
	v_readlane_b32 s48, v250, 33
	v_readlane_b32 s49, v250, 34
	v_readlane_b32 s50, v250, 35
	v_readlane_b32 s51, v250, 36
	s_waitcnt vmcnt(0)
	v_pk_mul_f32 v[32:33], v[36:37], v[38:39]
